# speedup vs baseline: 1.0228x; 1.0070x over previous
; __device__ __forceinline__ unsigned cvt_pk_bf16(float lo, float hi) { unsigned r; asm volatile("v_cvt_pk_bf16_f32 %0, %1, %2" : "=v"(r) : "v"(lo), "v"(hi)); return r; }
; __device__ __forceinline__ float sigmoidf_(float v) { return 1.f / (1.f + __expf(-v)); }
; __device__ __forceinline__ float siluf_(float v) { return v / (1.f + __expf(-v)); }
; __device__ __forceinline__ void unpack8(u32x4 w, float* f) {
;     f[0] = __uint_as_float(w.x << 16); f[1] = __uint_as_float(w.x & 0xffff0000u); f[2] = __uint_as_float(w.y << 16); f[3] = __uint_as_float(w.y & 0xffff0000u);
;     f[4] = __uint_as_float(w.z << 16); f[5] = __uint_as_float(w.z & 0xffff0000u); f[6] = __uint_as_float(w.w << 16); f[7] = __uint_as_float(w.w & 0xffff0000u);
;     __device__ __forceinline__ void operator()(const f32x4 (&acc)[2][2][4][2], const Unit& u, int wr, int wc, int fr, int fq) const {
;     ...
;             for (int ai = 0; ai < 2; ++ai) {
; #pragma unroll
;                 for (int m = 0; m < 4; ++m) {
;                     const size_t row = (size_t)(row0 + ai * HALF + m * 16);
;                     const f32x4 v0 = acc[ai][bj][m][0], v1 = acc[ai][bj][m][1];
;                     float a[8] = {v0[0], v0[1], v0[2], v0[3], v1[0], v1[1], v1[2], v1[3]}, g[8], o[8];
;                     unpack8(*(const u32x4*)(R + row * RLD + (MODE == 0 ? 2560 : 1536) + col0), g);
;                     if (MODE == 0) { float y[8]; unpack8(*(const u32x4*)(YG + row * 512 + col0), y);
; #pragma unroll
;                         for (int e = 0; e < 8; ++e) o[e] = y[e] * sigmoidf_(a[e] + bb[e]) * siluf_(g[e]); }
;                     else {
; #pragma unroll
;                         for (int e = 0; e < 8; ++e) o[e] = a[e] * bb[e] * siluf_(g[e]); }
;                     u32x4 w; w.x = cvt_pk_bf16(o[0], o[1]); w.y = cvt_pk_bf16(o[2], o[3]); w.z = cvt_pk_bf16(o[4], o[5]); w.w = cvt_pk_bf16(o[6], o[7]);
;                     *(u32x4*)(Y + row * DM + (MODE == 0 ? 1536 : 1024) + col0) = w;
;                 }
.LBB0_141:
	s_lshl_b64 s[0:1], s[20:21], 2
	s_add_u32 s2, s4, s0
	v_lshl_add_u32 v140, s86, 8, v138
	v_lshl_or_b32 v72, s56, 8, v139
	v_mov_b64_e32 v[142:143], s[14:15]
	s_movk_i32 s4, 0x1800
	s_addc_u32 s3, s5, s1
	v_or_b32_e32 v138, s61, v72
	v_mad_i64_i32 v[136:137], s[0:1], v140, s4, v[142:143]
	s_mov_b64 s[6:7], 0x1400
	v_lshl_add_u64 v[136:137], v[136:137], 0, s[6:7]
	v_lshlrev_b32_e32 v180, 1, v138
	v_lshlrev_b32_e32 v145, 2, v138
	v_ashrrev_i32_e32 v141, 31, v140
	v_lshl_add_u64 v[138:139], v[136:137], 0, v[180:181]
	global_load_dwordx4 v[72:75], v145, s[2:3] offset:16
	global_load_dwordx4 v[80:83], v145, s[2:3]
	v_mul_u32_u24_e32 v214, 0x1800, v140
	v_add_u32_e32 v214, v214, v180
	v_add_u32_e32 v214, 0x1400, v214
	v_lshl_add_u32 v215, v140, 10, v180
	s_add_u32 s0, s14, 0x0
	s_addc_u32 s1, s15, 0
	global_load_dwordx4 v[168:171], v214, s[0:1] offset:0
	s_add_u32 s0, s18, 0x0
	s_addc_u32 s1, s19, 0
	global_load_dwordx4 v[172:175], v215, s[0:1] offset:0
	s_add_u32 s0, s14, 0x18000
	s_addc_u32 s1, s15, 0
	global_load_dwordx4 v[188:191], v214, s[0:1] offset:0
	s_add_u32 s0, s18, 0x4000
	s_addc_u32 s1, s19, 0
	global_load_dwordx4 v[196:199], v215, s[0:1] offset:0
	s_add_u32 s0, s14, 0x30000
	s_addc_u32 s1, s15, 0
	global_load_dwordx4 v[206:209], v214, s[0:1] offset:0
	s_add_u32 s0, s18, 0x8000
	s_addc_u32 s1, s19, 0
	global_load_dwordx4 v[210:213], v215, s[0:1] offset:0
	s_waitcnt vmcnt(4)
	v_mov_b32_e32 v146, v168
	v_mov_b32_e32 v147, v169
	v_mov_b32_e32 v148, v170
	v_mov_b32_e32 v149, v171
	v_lshlrev_b64 v[138:139], 10, v[140:141]
	v_lshl_add_u64 v[138:139], s[18:19], 0, v[138:139]
	v_lshl_add_u64 v[138:139], v[138:139], 0, v[180:181]
	v_mov_b32_e32 v158, v172
	v_mov_b32_e32 v159, v173
	v_mov_b32_e32 v160, v174
	v_mov_b32_e32 v161, v175
	v_add_f32_e32 v128, v128, v72
	v_add_f32_e32 v132, v132, v80
	v_lshlrev_b32_e32 v162, 16, v146
	v_mul_f32_e32 v132, 0xbfb8aa3b, v132
	v_and_b32_e32 v163, 0xffff0000, v146
	v_lshlrev_b32_e32 v156, 16, v147
	v_lshlrev_b32_e32 v164, 16, v158
	v_and_b32_e32 v165, 0xffff0000, v158
	v_exp_f32_e32 v158, v132
	v_mul_f32_e32 v132, 0xbfb8aa3b, v162
	v_lshlrev_b32_e32 v157, 16, v159
	v_and_b32_e32 v155, 0xffff0000, v159
	v_exp_f32_e32 v159, v132
	v_lshlrev_b32_e32 v153, 16, v160
	v_and_b32_e32 v151, 0xffff0000, v160
	v_and_b32_e32 v154, 0xffff0000, v147
	v_pk_add_f32 v[158:159], v[158:159], 1.0 op_sel_hi:[1,0]
	v_lshlrev_b32_e32 v152, 16, v148
	v_div_scale_f32 v132, s[0:1], v159, v159, v162
	v_rcp_f32_e32 v160, v132
	v_and_b32_e32 v150, 0xffff0000, v148
	v_lshlrev_b32_e32 v148, 16, v149
	v_and_b32_e32 v146, 0xffff0000, v149
	v_lshlrev_b32_e32 v149, 16, v161
	v_and_b32_e32 v147, 0xffff0000, v161
	v_fma_f32 v161, -v132, v160, 1.0
	v_fmac_f32_e32 v160, v161, v160
	v_div_scale_f32 v161, vcc, v162, v159, v162
	v_mul_f32_e32 v166, v161, v160
	v_fma_f32 v167, -v132, v166, v161
	v_fmac_f32_e32 v166, v167, v160
	v_fma_f32 v132, -v132, v166, v161
	v_div_fmas_f32 v132, v132, v160, v166
	v_div_fixup_f32 v132, v132, v159, v162
	v_div_scale_f32 v159, s[0:1], v158, v158, 1.0
	v_rcp_f32_e32 v160, v159
	v_add_f32_e32 v133, v133, v81
	v_mul_f32_e32 v133, 0xbfb8aa3b, v133
	v_add_f32_e32 v134, v134, v82
	v_fma_f32 v161, -v159, v160, 1.0
	v_fmac_f32_e32 v160, v161, v160
	v_div_scale_f32 v161, vcc, 1.0, v158, 1.0
	v_mul_f32_e32 v162, v161, v160
	v_fma_f32 v166, -v159, v162, v161
	v_fmac_f32_e32 v162, v166, v160
	v_fma_f32 v159, -v159, v162, v161
	v_div_fmas_f32 v159, v159, v160, v162
	v_div_fixup_f32 v158, v159, v158, 1.0
	v_mul_f32_e32 v158, v158, v164
	v_mul_f32_e32 v132, v158, v132
	v_exp_f32_e32 v158, v133
	v_mul_f32_e32 v133, 0xbfb8aa3b, v163
	v_exp_f32_e32 v159, v133
	v_mul_f32_e32 v134, 0xbfb8aa3b, v134
	v_add_f32_e32 v135, v135, v83
	v_mul_f32_e32 v135, 0xbfb8aa3b, v135
	v_pk_add_f32 v[158:159], v[158:159], 1.0 op_sel_hi:[1,0]
	v_mul_f32_e32 v128, 0xbfb8aa3b, v128
	v_div_scale_f32 v133, s[0:1], v159, v159, v163
	v_rcp_f32_e32 v160, v133
	v_add_f32_e32 v124, v124, v80
	v_mul_f32_e32 v124, 0xbfb8aa3b, v124
	v_add_f32_e32 v125, v125, v81
	v_fma_f32 v161, -v133, v160, 1.0
	v_fmac_f32_e32 v160, v161, v160
	v_div_scale_f32 v161, vcc, v163, v159, v163
	v_mul_f32_e32 v162, v161, v160
	v_fma_f32 v164, -v133, v162, v161
	v_fmac_f32_e32 v162, v164, v160
	v_fma_f32 v133, -v133, v162, v161
	v_div_fmas_f32 v133, v133, v160, v162
	v_div_fixup_f32 v133, v133, v159, v163
	v_div_scale_f32 v159, s[0:1], v158, v158, 1.0
	v_rcp_f32_e32 v160, v159
	v_mul_f32_e32 v125, 0xbfb8aa3b, v125
	v_add_f32_e32 v126, v126, v82
	v_mul_f32_e32 v126, 0xbfb8aa3b, v126
	v_fma_f32 v161, -v159, v160, 1.0
	v_fmac_f32_e32 v160, v161, v160
	v_div_scale_f32 v161, vcc, 1.0, v158, 1.0
	v_mul_f32_e32 v162, v161, v160
	v_fma_f32 v163, -v159, v162, v161
	v_fmac_f32_e32 v162, v163, v160
	v_fma_f32 v159, -v159, v162, v161
	v_div_fmas_f32 v159, v159, v160, v162
	v_div_fixup_f32 v158, v159, v158, 1.0
	v_mul_f32_e32 v158, v158, v165
	v_mul_f32_e32 v133, v158, v133
	v_exp_f32_e32 v158, v134
	v_mul_f32_e32 v134, 0xbfb8aa3b, v156
	v_exp_f32_e32 v159, v134
	v_add_f32_e32 v127, v127, v83
	v_mul_f32_e32 v127, 0xbfb8aa3b, v127
	v_add_f32_e32 v120, v120, v72
	v_pk_add_f32 v[158:159], v[158:159], 1.0 op_sel_hi:[1,0]
	v_mul_f32_e32 v120, 0xbfb8aa3b, v120
	v_div_scale_f32 v134, s[0:1], v159, v159, v156
	v_rcp_f32_e32 v160, v134
	v_add_f32_e32 v116, v116, v80
	v_mul_f32_e32 v116, 0xbfb8aa3b, v116
	v_add_f32_e32 v117, v117, v81
	v_fma_f32 v161, -v134, v160, 1.0
	v_fmac_f32_e32 v160, v161, v160
	v_div_scale_f32 v161, vcc, v156, v159, v156
	v_mul_f32_e32 v162, v161, v160
	v_fma_f32 v163, -v134, v162, v161
	v_fmac_f32_e32 v162, v163, v160
	v_fma_f32 v134, -v134, v162, v161
; __device__ __forceinline__ unsigned cvt_pk_bf16(float lo, float hi) { unsigned r; asm volatile("v_cvt_pk_bf16_f32 %0, %1, %2" : "=v"(r) : "v"(lo), "v"(hi)); return r; }
; __device__ __forceinline__ float sigmoidf_(float v) { return 1.f / (1.f + __expf(-v)); }
; __device__ __forceinline__ float siluf_(float v) { return v / (1.f + __expf(-v)); }
; __device__ __forceinline__ void unpack8(u32x4 w, float* f) {
;     f[0] = __uint_as_float(w.x << 16); f[1] = __uint_as_float(w.x & 0xffff0000u); f[2] = __uint_as_float(w.y << 16); f[3] = __uint_as_float(w.y & 0xffff0000u);
;     f[4] = __uint_as_float(w.z << 16); f[5] = __uint_as_float(w.z & 0xffff0000u); f[6] = __uint_as_float(w.w << 16); f[7] = __uint_as_float(w.w & 0xffff0000u);
;     __device__ __forceinline__ void operator()(const f32x4 (&acc)[2][2][4][2], const Unit& u, int wr, int wc, int fr, int fq) const {
;     ...
;             for (int ai = 0; ai < 2; ++ai) {
; #pragma unroll
;                 for (int m = 0; m < 4; ++m) {
;                     const size_t row = (size_t)(row0 + ai * HALF + m * 16);
;                     const f32x4 v0 = acc[ai][bj][m][0], v1 = acc[ai][bj][m][1];
;                     float a[8] = {v0[0], v0[1], v0[2], v0[3], v1[0], v1[1], v1[2], v1[3]}, g[8], o[8];
;                     unpack8(*(const u32x4*)(R + row * RLD + (MODE == 0 ? 2560 : 1536) + col0), g);
;                     if (MODE == 0) { float y[8]; unpack8(*(const u32x4*)(YG + row * 512 + col0), y);
; #pragma unroll
;                         for (int e = 0; e < 8; ++e) o[e] = y[e] * sigmoidf_(a[e] + bb[e]) * siluf_(g[e]); }
;                     else {
; #pragma unroll
;                         for (int e = 0; e < 8; ++e) o[e] = a[e] * bb[e] * siluf_(g[e]); }
;                     u32x4 w; w.x = cvt_pk_bf16(o[0], o[1]); w.y = cvt_pk_bf16(o[2], o[3]); w.z = cvt_pk_bf16(o[4], o[5]); w.w = cvt_pk_bf16(o[6], o[7]);
;                     *(u32x4*)(Y + row * DM + (MODE == 0 ? 1536 : 1024) + col0) = w;
;                 }
	v_div_fmas_f32 v134, v134, v160, v162
	v_div_fixup_f32 v134, v134, v159, v156
	v_div_scale_f32 v156, s[0:1], v158, v158, 1.0
	v_rcp_f32_e32 v159, v156
	v_mul_f32_e32 v117, 0xbfb8aa3b, v117
	v_add_f32_e32 v118, v118, v82
	v_mul_f32_e32 v118, 0xbfb8aa3b, v118
	v_fma_f32 v160, -v156, v159, 1.0
	v_fmac_f32_e32 v159, v160, v159
	v_div_scale_f32 v160, vcc, 1.0, v158, 1.0
	v_mul_f32_e32 v161, v160, v159
	v_fma_f32 v162, -v156, v161, v160
	v_fmac_f32_e32 v161, v162, v159
	v_fma_f32 v156, -v156, v161, v160
	v_div_fmas_f32 v156, v156, v159, v161
	v_div_fixup_f32 v156, v156, v158, 1.0
	v_mul_f32_e32 v156, v156, v157
	v_mul_f32_e32 v134, v156, v134
	v_exp_f32_e32 v156, v135
	v_mul_f32_e32 v135, 0xbfb8aa3b, v154
	v_exp_f32_e32 v157, v135
	v_add_f32_e32 v119, v119, v83
	v_mul_f32_e32 v119, 0xbfb8aa3b, v119
	v_add_f32_e32 v112, v112, v72
	v_pk_add_f32 v[156:157], v[156:157], 1.0 op_sel_hi:[1,0]
	v_mul_f32_e32 v112, 0xbfb8aa3b, v112
	v_div_scale_f32 v135, s[0:1], v157, v157, v154
	v_rcp_f32_e32 v158, v135
	v_add_f32_e32 v108, v108, v80
	v_mul_f32_e32 v108, 0xbfb8aa3b, v108
	v_add_f32_e32 v109, v109, v81
	v_fma_f32 v159, -v135, v158, 1.0
	v_fmac_f32_e32 v158, v159, v158
	v_div_scale_f32 v159, vcc, v154, v157, v154
	v_mul_f32_e32 v160, v159, v158
	v_fma_f32 v161, -v135, v160, v159
	v_fmac_f32_e32 v160, v161, v158
	v_fma_f32 v135, -v135, v160, v159
	v_div_fmas_f32 v135, v135, v158, v160
	v_div_fixup_f32 v135, v135, v157, v154
	v_div_scale_f32 v154, s[0:1], v156, v156, 1.0
	v_rcp_f32_e32 v157, v154
	v_mul_f32_e32 v109, 0xbfb8aa3b, v109
	v_add_f32_e32 v110, v110, v82
	v_mul_f32_e32 v110, 0xbfb8aa3b, v110
	v_fma_f32 v158, -v154, v157, 1.0
	v_fmac_f32_e32 v157, v158, v157
	v_div_scale_f32 v158, vcc, 1.0, v156, 1.0
	v_mul_f32_e32 v159, v158, v157
	v_fma_f32 v160, -v154, v159, v158
	v_fmac_f32_e32 v159, v160, v157
	v_fma_f32 v154, -v154, v159, v158
	v_div_fmas_f32 v154, v154, v157, v159
	v_div_fixup_f32 v154, v154, v156, 1.0
	v_mul_f32_e32 v154, v154, v155
	v_mul_f32_e32 v135, v154, v135
	v_exp_f32_e32 v154, v128
	v_mul_f32_e32 v128, 0xbfb8aa3b, v152
	v_exp_f32_e32 v155, v128
	v_add_f32_e32 v111, v111, v83
	v_mul_f32_e32 v111, 0xbfb8aa3b, v111
	v_add_f32_e32 v104, v104, v72
	v_pk_add_f32 v[154:155], v[154:155], 1.0 op_sel_hi:[1,0]
	v_mul_f32_e32 v104, 0xbfb8aa3b, v104
	v_div_scale_f32 v128, s[0:1], v155, v155, v152
	v_rcp_f32_e32 v156, v128
	v_add_f32_e32 v100, v100, v80
	v_mul_f32_e32 v100, 0xbfb8aa3b, v100
	v_add_f32_e32 v101, v101, v81
	v_fma_f32 v157, -v128, v156, 1.0
	v_fmac_f32_e32 v156, v157, v156
	v_div_scale_f32 v157, vcc, v152, v155, v152
	v_mul_f32_e32 v158, v157, v156
	v_fma_f32 v159, -v128, v158, v157
	v_fmac_f32_e32 v158, v159, v156
	v_fma_f32 v128, -v128, v158, v157
	v_div_fmas_f32 v128, v128, v156, v158
	v_div_fixup_f32 v128, v128, v155, v152
	v_div_scale_f32 v152, s[0:1], v154, v154, 1.0
	v_rcp_f32_e32 v155, v152
	v_mul_f32_e32 v101, 0xbfb8aa3b, v101
	v_add_f32_e32 v102, v102, v82
	v_mul_f32_e32 v102, 0xbfb8aa3b, v102
	v_fma_f32 v156, -v152, v155, 1.0
	v_fmac_f32_e32 v155, v156, v155
	v_div_scale_f32 v156, vcc, 1.0, v154, 1.0
	v_mul_f32_e32 v157, v156, v155
	v_fma_f32 v158, -v152, v157, v156
	v_fmac_f32_e32 v157, v158, v155
	v_fma_f32 v152, -v152, v157, v156
	v_div_fmas_f32 v152, v152, v155, v157
	v_div_fixup_f32 v152, v152, v154, 1.0
	v_mul_f32_e32 v152, v152, v153
	v_mul_f32_e32 v152, v152, v128
	v_add_f32_e32 v128, v129, v73
	v_mul_f32_e32 v128, 0xbfb8aa3b, v128
	v_mul_f32_e32 v129, 0xbfb8aa3b, v150
	v_exp_f32_e32 v128, v128
	v_exp_f32_e32 v129, v129
	v_add_f32_e32 v103, v103, v83
	v_mul_f32_e32 v103, 0xbfb8aa3b, v103
	v_add_f32_e32 v96, v96, v72
	v_pk_add_f32 v[128:129], v[128:129], 1.0 op_sel_hi:[1,0]
	v_mul_f32_e32 v96, 0xbfb8aa3b, v96
	v_div_scale_f32 v153, s[0:1], v129, v129, v150
	v_rcp_f32_e32 v154, v153
	v_add_f32_e32 v92, v92, v80
	v_mul_f32_e32 v92, 0xbfb8aa3b, v92
	v_add_f32_e32 v93, v93, v81
	v_fma_f32 v155, -v153, v154, 1.0
	v_fmac_f32_e32 v154, v155, v154
	v_div_scale_f32 v155, vcc, v150, v129, v150
	v_mul_f32_e32 v156, v155, v154
	v_fma_f32 v157, -v153, v156, v155
	v_fmac_f32_e32 v156, v157, v154
	v_fma_f32 v153, -v153, v156, v155
	v_div_fmas_f32 v153, v153, v154, v156
	v_div_fixup_f32 v129, v153, v129, v150
	v_div_scale_f32 v150, s[0:1], v128, v128, 1.0
	v_rcp_f32_e32 v153, v150
	v_mul_f32_e32 v93, 0xbfb8aa3b, v93
	v_add_f32_e32 v94, v94, v82
	v_mul_f32_e32 v94, 0xbfb8aa3b, v94
	v_fma_f32 v154, -v150, v153, 1.0
	v_fmac_f32_e32 v153, v154, v153
	v_div_scale_f32 v154, vcc, 1.0, v128, 1.0
	v_mul_f32_e32 v155, v154, v153
	v_fma_f32 v156, -v150, v155, v154
	v_fmac_f32_e32 v155, v156, v153
	v_fma_f32 v150, -v150, v155, v154
	v_div_fmas_f32 v150, v150, v153, v155
	v_div_fixup_f32 v128, v150, v128, 1.0
	v_mul_f32_e32 v128, v128, v151
	v_mul_f32_e32 v150, v128, v129
	v_add_f32_e32 v128, v130, v74
	v_mul_f32_e32 v128, 0xbfb8aa3b, v128
	v_mul_f32_e32 v129, 0xbfb8aa3b, v148
	v_exp_f32_e32 v128, v128
	v_exp_f32_e32 v129, v129
	v_add_f32_e32 v95, v95, v83
	v_mul_f32_e32 v95, 0xbfb8aa3b, v95
	v_add_f32_e32 v88, v88, v72
	v_pk_add_f32 v[128:129], v[128:129], 1.0 op_sel_hi:[1,0]
	v_mul_f32_e32 v88, 0xbfb8aa3b, v88
	v_div_scale_f32 v130, s[0:1], v129, v129, v148
	v_rcp_f32_e32 v151, v130
	v_add_f32_e32 v84, v84, v80
	v_mul_f32_e32 v84, 0xbfb8aa3b, v84
	v_add_f32_e32 v85, v85, v81
	v_fma_f32 v153, -v130, v151, 1.0
	v_fmac_f32_e32 v151, v153, v151
	v_div_scale_f32 v153, vcc, v148, v129, v148
	v_mul_f32_e32 v154, v153, v151
	v_fma_f32 v155, -v130, v154, v153
	v_fmac_f32_e32 v154, v155, v151
	v_fma_f32 v130, -v130, v154, v153
	v_div_fmas_f32 v130, v130, v151, v154
	v_div_fixup_f32 v129, v130, v129, v148
	v_div_scale_f32 v130, s[0:1], v128, v128, 1.0
; __device__ __forceinline__ unsigned cvt_pk_bf16(float lo, float hi) { unsigned r; asm volatile("v_cvt_pk_bf16_f32 %0, %1, %2" : "=v"(r) : "v"(lo), "v"(hi)); return r; }
; __device__ __forceinline__ float sigmoidf_(float v) { return 1.f / (1.f + __expf(-v)); }
; __device__ __forceinline__ float siluf_(float v) { return v / (1.f + __expf(-v)); }
; __device__ __forceinline__ void unpack8(u32x4 w, float* f) {
;     f[0] = __uint_as_float(w.x << 16); f[1] = __uint_as_float(w.x & 0xffff0000u); f[2] = __uint_as_float(w.y << 16); f[3] = __uint_as_float(w.y & 0xffff0000u);
;     f[4] = __uint_as_float(w.z << 16); f[5] = __uint_as_float(w.z & 0xffff0000u); f[6] = __uint_as_float(w.w << 16); f[7] = __uint_as_float(w.w & 0xffff0000u);
;     __device__ __forceinline__ void operator()(const f32x4 (&acc)[2][2][4][2], const Unit& u, int wr, int wc, int fr, int fq) const {
;     ...
;             for (int ai = 0; ai < 2; ++ai) {
; #pragma unroll
;                 for (int m = 0; m < 4; ++m) {
;                     const size_t row = (size_t)(row0 + ai * HALF + m * 16);
;                     const f32x4 v0 = acc[ai][bj][m][0], v1 = acc[ai][bj][m][1];
;                     float a[8] = {v0[0], v0[1], v0[2], v0[3], v1[0], v1[1], v1[2], v1[3]}, g[8], o[8];
;                     unpack8(*(const u32x4*)(R + row * RLD + (MODE == 0 ? 2560 : 1536) + col0), g);
;                     if (MODE == 0) { float y[8]; unpack8(*(const u32x4*)(YG + row * 512 + col0), y);
; #pragma unroll
;                         for (int e = 0; e < 8; ++e) o[e] = y[e] * sigmoidf_(a[e] + bb[e]) * siluf_(g[e]); }
;                     else {
; #pragma unroll
;                         for (int e = 0; e < 8; ++e) o[e] = a[e] * bb[e] * siluf_(g[e]); }
;                     u32x4 w; w.x = cvt_pk_bf16(o[0], o[1]); w.y = cvt_pk_bf16(o[2], o[3]); w.z = cvt_pk_bf16(o[4], o[5]); w.w = cvt_pk_bf16(o[6], o[7]);
;                     *(u32x4*)(Y + row * DM + (MODE == 0 ? 1536 : 1024) + col0) = w;
;                 }
	v_rcp_f32_e32 v148, v130
	v_mul_f32_e32 v85, 0xbfb8aa3b, v85
	v_add_f32_e32 v86, v86, v82
	v_mul_f32_e32 v86, 0xbfb8aa3b, v86
	v_fma_f32 v151, -v130, v148, 1.0
	v_fmac_f32_e32 v148, v151, v148
	v_div_scale_f32 v151, vcc, 1.0, v128, 1.0
	v_mul_f32_e32 v153, v151, v148
	v_fma_f32 v154, -v130, v153, v151
	v_fmac_f32_e32 v153, v154, v148
	v_fma_f32 v130, -v130, v153, v151
	v_div_fmas_f32 v130, v130, v148, v153
	v_div_fixup_f32 v128, v130, v128, 1.0
	v_mul_f32_e32 v128, v128, v149
	v_mul_f32_e32 v148, v128, v129
	v_add_f32_e32 v128, v131, v75
	v_mul_f32_e32 v128, 0xbfb8aa3b, v128
	v_mul_f32_e32 v129, 0xbfb8aa3b, v146
	v_exp_f32_e32 v128, v128
	v_exp_f32_e32 v129, v129
	v_add_f32_e32 v87, v87, v83
	v_mul_f32_e32 v87, 0xbfb8aa3b, v87
	v_add_f32_e32 v76, v76, v72
	v_pk_add_f32 v[128:129], v[128:129], 1.0 op_sel_hi:[1,0]
	v_mul_f32_e32 v76, 0xbfb8aa3b, v76
	v_div_scale_f32 v130, s[0:1], v129, v129, v146
	v_rcp_f32_e32 v131, v130
	v_add_f32_e32 v68, v68, v80
	v_mul_f32_e32 v68, 0xbfb8aa3b, v68
	v_add_f32_e32 v69, v69, v81
	v_fma_f32 v149, -v130, v131, 1.0
	v_fmac_f32_e32 v131, v149, v131
	v_div_scale_f32 v149, vcc, v146, v129, v146
	v_mul_f32_e32 v151, v149, v131
	v_fma_f32 v153, -v130, v151, v149
	v_fmac_f32_e32 v151, v153, v131
	v_fma_f32 v130, -v130, v151, v149
	v_div_fmas_f32 v130, v130, v131, v151
	v_div_fixup_f32 v129, v130, v129, v146
	v_div_scale_f32 v130, s[0:1], v128, v128, 1.0
	v_rcp_f32_e32 v131, v130
	v_mul_f32_e32 v69, 0xbfb8aa3b, v69
	v_add_f32_e32 v70, v70, v82
	v_mul_f32_e32 v70, 0xbfb8aa3b, v70
	v_fma_f32 v146, -v130, v131, 1.0
	v_fmac_f32_e32 v131, v146, v131
	v_div_scale_f32 v146, vcc, 1.0, v128, 1.0
	v_mul_f32_e32 v149, v146, v131
	v_fma_f32 v151, -v130, v149, v146
	v_fmac_f32_e32 v149, v151, v131
	v_fma_f32 v130, -v130, v149, v146
	v_div_fmas_f32 v130, v130, v131, v149
	v_div_fixup_f32 v128, v130, v128, 1.0
	v_mul_f32_e32 v128, v128, v147
	v_mul_f32_e32 v128, v128, v129
	v_cvt_pk_bf16_f32 v130, v132, v133
	v_cvt_pk_bf16_f32 v131, v134, v135
	v_cvt_pk_bf16_f32 v132, v152, v150
	v_cvt_pk_bf16_f32 v133, v148, v128
	v_lshlrev_b64 v[128:129], 12, v[140:141]
	v_lshl_add_u64 v[128:129], s[12:13], 0, v[128:129]
	v_lshl_add_u64 v[128:129], v[128:129], 0, v[180:181]
	v_or_b32_e32 v134, 16, v140
	global_store_dwordx4 v[128:129], v[130:133], off offset:3072
	s_add_u32 s0, s14, 0x48000
	s_addc_u32 s1, s15, 0
	global_load_dwordx4 v[168:171], v214, s[0:1] offset:0
	s_add_u32 s0, s18, 0xc000
	s_addc_u32 s1, s19, 0
	global_load_dwordx4 v[172:175], v215, s[0:1] offset:0
	v_ashrrev_i32_e32 v135, 31, v134
	v_add_f32_e32 v71, v71, v83
	v_mad_i64_i32 v[130:131], s[0:1], v134, s4, v[142:143]
	v_lshl_add_u64 v[130:131], v[130:131], 0, s[6:7]
	v_lshl_add_u64 v[132:133], v[130:131], 0, v[180:181]
	s_waitcnt vmcnt(5)
	v_mov_b32_e32 v150, v188
	v_mov_b32_e32 v151, v189
	v_mov_b32_e32 v152, v190
	v_mov_b32_e32 v153, v191
	v_lshlrev_b64 v[132:133], 10, v[134:135]
	v_lshl_add_u64 v[132:133], s[18:19], 0, v[132:133]
	v_lshl_add_u64 v[132:133], v[132:133], 0, v[180:181]
	v_mul_f32_e32 v71, 0xbfb8aa3b, v71
	v_add_f32_e32 v64, v64, v72
	v_mul_f32_e32 v64, 0xbfb8aa3b, v64
	v_lshlrev_b32_e32 v158, 16, v151
	v_and_b32_e32 v159, 0xffff0000, v151
	v_lshlrev_b32_e32 v151, 16, v152
	v_and_b32_e32 v149, 0xffff0000, v152
	v_lshlrev_b32_e32 v147, 16, v153
	v_and_b32_e32 v141, 0xffff0000, v153
	v_mov_b32_e32 v152, v196
	v_mov_b32_e32 v153, v197
	v_mov_b32_e32 v154, v198
	v_mov_b32_e32 v155, v199
	v_lshlrev_b32_e32 v156, 16, v150
	v_and_b32_e32 v157, 0xffff0000, v150
	v_lshlrev_b32_e32 v160, 16, v152
	v_and_b32_e32 v161, 0xffff0000, v152
	v_lshlrev_b32_e32 v152, 16, v154
	v_and_b32_e32 v150, 0xffff0000, v154
	v_exp_f32_e32 v154, v124
	v_mul_f32_e32 v124, 0xbfb8aa3b, v156
	v_lshlrev_b32_e32 v148, 16, v155
	v_and_b32_e32 v146, 0xffff0000, v155
	v_exp_f32_e32 v155, v124
	v_lshlrev_b32_e32 v162, 16, v153
	v_and_b32_e32 v153, 0xffff0000, v153
	v_pk_add_f32 v[154:155], v[154:155], 1.0 op_sel_hi:[1,0]
	s_nop 0
	v_div_scale_f32 v124, s[0:1], v155, v155, v156
	v_rcp_f32_e32 v163, v124
	s_nop 0
	v_fma_f32 v164, -v124, v163, 1.0
	v_fmac_f32_e32 v163, v164, v163
	v_div_scale_f32 v164, vcc, v156, v155, v156
	v_mul_f32_e32 v165, v164, v163
	v_fma_f32 v166, -v124, v165, v164
	v_fmac_f32_e32 v165, v166, v163
	v_fma_f32 v124, -v124, v165, v164
	v_div_fmas_f32 v124, v124, v163, v165
	v_div_fixup_f32 v124, v124, v155, v156
	v_div_scale_f32 v155, s[0:1], v154, v154, 1.0
	v_rcp_f32_e32 v156, v155
	s_nop 0
	v_fma_f32 v163, -v155, v156, 1.0
	v_fmac_f32_e32 v156, v163, v156
	v_div_scale_f32 v163, vcc, 1.0, v154, 1.0
	v_mul_f32_e32 v164, v163, v156
	v_fma_f32 v165, -v155, v164, v163
	v_fmac_f32_e32 v164, v165, v156
	v_fma_f32 v155, -v155, v164, v163
	v_div_fmas_f32 v155, v155, v156, v164
	v_div_fixup_f32 v154, v155, v154, 1.0
	v_mul_f32_e32 v154, v154, v160
	v_mul_f32_e32 v124, v154, v124
	v_exp_f32_e32 v154, v125
	v_mul_f32_e32 v125, 0xbfb8aa3b, v157
	v_exp_f32_e32 v155, v125
	s_nop 0
	v_pk_add_f32 v[154:155], v[154:155], 1.0 op_sel_hi:[1,0]
	s_nop 0
	v_div_scale_f32 v125, s[0:1], v155, v155, v157
	v_rcp_f32_e32 v156, v125
	s_nop 0
	v_fma_f32 v160, -v125, v156, 1.0
	v_fmac_f32_e32 v156, v160, v156
	v_div_scale_f32 v160, vcc, v157, v155, v157
	v_mul_f32_e32 v163, v160, v156
	v_fma_f32 v164, -v125, v163, v160
	v_fmac_f32_e32 v163, v164, v156
	v_fma_f32 v125, -v125, v163, v160
	v_div_fmas_f32 v125, v125, v156, v163
	v_div_fixup_f32 v125, v125, v155, v157
	v_div_scale_f32 v155, s[0:1], v154, v154, 1.0
	v_rcp_f32_e32 v156, v155
	s_nop 0
	v_fma_f32 v157, -v155, v156, 1.0
	v_fmac_f32_e32 v156, v157, v156
	v_div_scale_f32 v157, vcc, 1.0, v154, 1.0
	v_mul_f32_e32 v160, v157, v156
	v_fma_f32 v163, -v155, v160, v157
; __device__ __forceinline__ unsigned cvt_pk_bf16(float lo, float hi) { unsigned r; asm volatile("v_cvt_pk_bf16_f32 %0, %1, %2" : "=v"(r) : "v"(lo), "v"(hi)); return r; }
; __device__ __forceinline__ float sigmoidf_(float v) { return 1.f / (1.f + __expf(-v)); }
; __device__ __forceinline__ float siluf_(float v) { return v / (1.f + __expf(-v)); }
; __device__ __forceinline__ void unpack8(u32x4 w, float* f) {
;     f[0] = __uint_as_float(w.x << 16); f[1] = __uint_as_float(w.x & 0xffff0000u); f[2] = __uint_as_float(w.y << 16); f[3] = __uint_as_float(w.y & 0xffff0000u);
;     f[4] = __uint_as_float(w.z << 16); f[5] = __uint_as_float(w.z & 0xffff0000u); f[6] = __uint_as_float(w.w << 16); f[7] = __uint_as_float(w.w & 0xffff0000u);
;     __device__ __forceinline__ void operator()(const f32x4 (&acc)[2][2][4][2], const Unit& u, int wr, int wc, int fr, int fq) const {
;     ...
;             for (int ai = 0; ai < 2; ++ai) {
; #pragma unroll
;                 for (int m = 0; m < 4; ++m) {
;                     const size_t row = (size_t)(row0 + ai * HALF + m * 16);
;                     const f32x4 v0 = acc[ai][bj][m][0], v1 = acc[ai][bj][m][1];
;                     float a[8] = {v0[0], v0[1], v0[2], v0[3], v1[0], v1[1], v1[2], v1[3]}, g[8], o[8];
;                     unpack8(*(const u32x4*)(R + row * RLD + (MODE == 0 ? 2560 : 1536) + col0), g);
;                     if (MODE == 0) { float y[8]; unpack8(*(const u32x4*)(YG + row * 512 + col0), y);
; #pragma unroll
;                         for (int e = 0; e < 8; ++e) o[e] = y[e] * sigmoidf_(a[e] + bb[e]) * siluf_(g[e]); }
;                     else {
; #pragma unroll
;                         for (int e = 0; e < 8; ++e) o[e] = a[e] * bb[e] * siluf_(g[e]); }
;                     u32x4 w; w.x = cvt_pk_bf16(o[0], o[1]); w.y = cvt_pk_bf16(o[2], o[3]); w.z = cvt_pk_bf16(o[4], o[5]); w.w = cvt_pk_bf16(o[6], o[7]);
;                     *(u32x4*)(Y + row * DM + (MODE == 0 ? 1536 : 1024) + col0) = w;
;                 }
	v_fmac_f32_e32 v160, v163, v156
	v_fma_f32 v155, -v155, v160, v157
	v_div_fmas_f32 v155, v155, v156, v160
	v_div_fixup_f32 v154, v155, v154, 1.0
	v_mul_f32_e32 v154, v154, v161
	v_mul_f32_e32 v125, v154, v125
	v_exp_f32_e32 v154, v126
	v_mul_f32_e32 v126, 0xbfb8aa3b, v158
	v_exp_f32_e32 v155, v126
	s_nop 0
	v_pk_add_f32 v[154:155], v[154:155], 1.0 op_sel_hi:[1,0]
	s_nop 0
	v_div_scale_f32 v126, s[0:1], v155, v155, v158
	v_rcp_f32_e32 v156, v126
	s_nop 0
	v_fma_f32 v157, -v126, v156, 1.0
	v_fmac_f32_e32 v156, v157, v156
	v_div_scale_f32 v157, vcc, v158, v155, v158
	v_mul_f32_e32 v160, v157, v156
	v_fma_f32 v161, -v126, v160, v157
	v_fmac_f32_e32 v160, v161, v156
	v_fma_f32 v126, -v126, v160, v157
	v_div_fmas_f32 v126, v126, v156, v160
	v_div_fixup_f32 v126, v126, v155, v158
	v_div_scale_f32 v155, s[0:1], v154, v154, 1.0
	v_rcp_f32_e32 v156, v155
	s_nop 0
	v_fma_f32 v157, -v155, v156, 1.0
	v_fmac_f32_e32 v156, v157, v156
	v_div_scale_f32 v157, vcc, 1.0, v154, 1.0
	v_mul_f32_e32 v158, v157, v156
	v_fma_f32 v160, -v155, v158, v157
	v_fmac_f32_e32 v158, v160, v156
	v_fma_f32 v155, -v155, v158, v157
	v_div_fmas_f32 v155, v155, v156, v158
	v_div_fixup_f32 v154, v155, v154, 1.0
	v_mul_f32_e32 v154, v154, v162
	v_mul_f32_e32 v126, v154, v126
	v_exp_f32_e32 v154, v127
	v_mul_f32_e32 v127, 0xbfb8aa3b, v159
	v_exp_f32_e32 v155, v127
	s_nop 0
	v_pk_add_f32 v[154:155], v[154:155], 1.0 op_sel_hi:[1,0]
	s_nop 0
	v_div_scale_f32 v127, s[0:1], v155, v155, v159
	v_rcp_f32_e32 v156, v127
	s_nop 0
	v_fma_f32 v157, -v127, v156, 1.0
	v_fmac_f32_e32 v156, v157, v156
	v_div_scale_f32 v157, vcc, v159, v155, v159
	v_mul_f32_e32 v158, v157, v156
	v_fma_f32 v160, -v127, v158, v157
	v_fmac_f32_e32 v158, v160, v156
	v_fma_f32 v127, -v127, v158, v157
	v_div_fmas_f32 v127, v127, v156, v158
	v_div_fixup_f32 v127, v127, v155, v159
	v_div_scale_f32 v155, s[0:1], v154, v154, 1.0
	v_rcp_f32_e32 v156, v155
	s_nop 0
	v_fma_f32 v157, -v155, v156, 1.0
	v_fmac_f32_e32 v156, v157, v156
	v_div_scale_f32 v157, vcc, 1.0, v154, 1.0
	v_mul_f32_e32 v158, v157, v156
	v_fma_f32 v159, -v155, v158, v157
	v_fmac_f32_e32 v158, v159, v156
	v_fma_f32 v155, -v155, v158, v157
	v_div_fmas_f32 v155, v155, v156, v158
	v_div_fixup_f32 v154, v155, v154, 1.0
	v_mul_f32_e32 v153, v154, v153
	v_exp_f32_e32 v154, v120
	v_mul_f32_e32 v120, 0xbfb8aa3b, v151
	v_exp_f32_e32 v155, v120
	v_mul_f32_e32 v127, v153, v127
	v_pk_add_f32 v[154:155], v[154:155], 1.0 op_sel_hi:[1,0]
	s_nop 0
	v_div_scale_f32 v120, s[0:1], v155, v155, v151
	v_rcp_f32_e32 v153, v120
	s_nop 0
	v_fma_f32 v156, -v120, v153, 1.0
	v_fmac_f32_e32 v153, v156, v153
	v_div_scale_f32 v156, vcc, v151, v155, v151
	v_mul_f32_e32 v157, v156, v153
	v_fma_f32 v158, -v120, v157, v156
	v_fmac_f32_e32 v157, v158, v153
	v_fma_f32 v120, -v120, v157, v156
	v_div_fmas_f32 v120, v120, v153, v157
	v_div_fixup_f32 v120, v120, v155, v151
	v_div_scale_f32 v151, s[0:1], v154, v154, 1.0
	v_rcp_f32_e32 v153, v151
	s_nop 0
	v_fma_f32 v155, -v151, v153, 1.0
	v_fmac_f32_e32 v153, v155, v153
	v_div_scale_f32 v155, vcc, 1.0, v154, 1.0
	v_mul_f32_e32 v156, v155, v153
	v_fma_f32 v157, -v151, v156, v155
	v_fmac_f32_e32 v156, v157, v153
	v_fma_f32 v151, -v151, v156, v155
	v_div_fmas_f32 v151, v151, v153, v156
	v_div_fixup_f32 v151, v151, v154, 1.0
	v_mul_f32_e32 v151, v151, v152
	v_mul_f32_e32 v151, v151, v120
	v_add_f32_e32 v120, v121, v73
	v_mul_f32_e32 v120, 0xbfb8aa3b, v120
	v_mul_f32_e32 v121, 0xbfb8aa3b, v149
	v_exp_f32_e32 v120, v120
	v_exp_f32_e32 v121, v121
	s_nop 0
	v_pk_add_f32 v[120:121], v[120:121], 1.0 op_sel_hi:[1,0]
	s_nop 0
	v_div_scale_f32 v152, s[0:1], v121, v121, v149
	v_rcp_f32_e32 v153, v152
	s_nop 0
	v_fma_f32 v154, -v152, v153, 1.0
	v_fmac_f32_e32 v153, v154, v153
	v_div_scale_f32 v154, vcc, v149, v121, v149
	v_mul_f32_e32 v155, v154, v153
	v_fma_f32 v156, -v152, v155, v154
	v_fmac_f32_e32 v155, v156, v153
	v_fma_f32 v152, -v152, v155, v154
	v_div_fmas_f32 v152, v152, v153, v155
	v_div_fixup_f32 v121, v152, v121, v149
	v_div_scale_f32 v149, s[0:1], v120, v120, 1.0
	v_rcp_f32_e32 v152, v149
	s_nop 0
	v_fma_f32 v153, -v149, v152, 1.0
	v_fmac_f32_e32 v152, v153, v152
	v_div_scale_f32 v153, vcc, 1.0, v120, 1.0
	v_mul_f32_e32 v154, v153, v152
	v_fma_f32 v155, -v149, v154, v153
	v_fmac_f32_e32 v154, v155, v152
	v_fma_f32 v149, -v149, v154, v153
	v_div_fmas_f32 v149, v149, v152, v154
	v_div_fixup_f32 v120, v149, v120, 1.0
	v_mul_f32_e32 v120, v120, v150
	v_mul_f32_e32 v149, v120, v121
	v_add_f32_e32 v120, v122, v74
	v_mul_f32_e32 v120, 0xbfb8aa3b, v120
	v_mul_f32_e32 v121, 0xbfb8aa3b, v147
	v_exp_f32_e32 v120, v120
	v_exp_f32_e32 v121, v121
	s_nop 0
	v_pk_add_f32 v[120:121], v[120:121], 1.0 op_sel_hi:[1,0]
	s_nop 0
	v_div_scale_f32 v122, s[0:1], v121, v121, v147
	v_rcp_f32_e32 v150, v122
	s_nop 0
	v_fma_f32 v152, -v122, v150, 1.0
	v_fmac_f32_e32 v150, v152, v150
	v_div_scale_f32 v152, vcc, v147, v121, v147
	v_mul_f32_e32 v153, v152, v150
	v_fma_f32 v154, -v122, v153, v152
	v_fmac_f32_e32 v153, v154, v150
	v_fma_f32 v122, -v122, v153, v152
	v_div_fmas_f32 v122, v122, v150, v153
	v_div_fixup_f32 v121, v122, v121, v147
	v_div_scale_f32 v122, s[0:1], v120, v120, 1.0
	v_rcp_f32_e32 v147, v122
	s_nop 0
	v_fma_f32 v150, -v122, v147, 1.0
	v_fmac_f32_e32 v147, v150, v147
	v_div_scale_f32 v150, vcc, 1.0, v120, 1.0
	v_mul_f32_e32 v152, v150, v147
	v_fma_f32 v153, -v122, v152, v150
	v_fmac_f32_e32 v152, v153, v147
	v_fma_f32 v122, -v122, v152, v150
	v_div_fmas_f32 v122, v122, v147, v152
	v_div_fixup_f32 v120, v122, v120, 1.0
	v_mul_f32_e32 v120, v120, v148
	v_mul_f32_e32 v147, v120, v121
	v_add_f32_e32 v120, v123, v75
	v_mul_f32_e32 v120, 0xbfb8aa3b, v120
; __device__ __forceinline__ unsigned cvt_pk_bf16(float lo, float hi) { unsigned r; asm volatile("v_cvt_pk_bf16_f32 %0, %1, %2" : "=v"(r) : "v"(lo), "v"(hi)); return r; }
; __device__ __forceinline__ float sigmoidf_(float v) { return 1.f / (1.f + __expf(-v)); }
; __device__ __forceinline__ float siluf_(float v) { return v / (1.f + __expf(-v)); }
; __device__ __forceinline__ void unpack8(u32x4 w, float* f) {
;     f[0] = __uint_as_float(w.x << 16); f[1] = __uint_as_float(w.x & 0xffff0000u); f[2] = __uint_as_float(w.y << 16); f[3] = __uint_as_float(w.y & 0xffff0000u);
;     f[4] = __uint_as_float(w.z << 16); f[5] = __uint_as_float(w.z & 0xffff0000u); f[6] = __uint_as_float(w.w << 16); f[7] = __uint_as_float(w.w & 0xffff0000u);
;     __device__ __forceinline__ void operator()(const f32x4 (&acc)[2][2][4][2], const Unit& u, int wr, int wc, int fr, int fq) const {
;     ...
;             for (int ai = 0; ai < 2; ++ai) {
; #pragma unroll
;                 for (int m = 0; m < 4; ++m) {
;                     const size_t row = (size_t)(row0 + ai * HALF + m * 16);
;                     const f32x4 v0 = acc[ai][bj][m][0], v1 = acc[ai][bj][m][1];
;                     float a[8] = {v0[0], v0[1], v0[2], v0[3], v1[0], v1[1], v1[2], v1[3]}, g[8], o[8];
;                     unpack8(*(const u32x4*)(R + row * RLD + (MODE == 0 ? 2560 : 1536) + col0), g);
;                     if (MODE == 0) { float y[8]; unpack8(*(const u32x4*)(YG + row * 512 + col0), y);
; #pragma unroll
;                         for (int e = 0; e < 8; ++e) o[e] = y[e] * sigmoidf_(a[e] + bb[e]) * siluf_(g[e]); }
;                     else {
; #pragma unroll
;                         for (int e = 0; e < 8; ++e) o[e] = a[e] * bb[e] * siluf_(g[e]); }
;                     u32x4 w; w.x = cvt_pk_bf16(o[0], o[1]); w.y = cvt_pk_bf16(o[2], o[3]); w.z = cvt_pk_bf16(o[4], o[5]); w.w = cvt_pk_bf16(o[6], o[7]);
;                     *(u32x4*)(Y + row * DM + (MODE == 0 ? 1536 : 1024) + col0) = w;
;                 }
	v_mul_f32_e32 v121, 0xbfb8aa3b, v141
	v_exp_f32_e32 v120, v120
	v_exp_f32_e32 v121, v121
	s_nop 0
	v_pk_add_f32 v[120:121], v[120:121], 1.0 op_sel_hi:[1,0]
	s_nop 0
	v_div_scale_f32 v122, s[0:1], v121, v121, v141
	v_rcp_f32_e32 v123, v122
	s_nop 0
	v_fma_f32 v148, -v122, v123, 1.0
	v_fmac_f32_e32 v123, v148, v123
	v_div_scale_f32 v148, vcc, v141, v121, v141
	v_mul_f32_e32 v150, v148, v123
	v_fma_f32 v152, -v122, v150, v148
	v_fmac_f32_e32 v150, v152, v123
	v_fma_f32 v122, -v122, v150, v148
	v_div_fmas_f32 v122, v122, v123, v150
	v_div_fixup_f32 v121, v122, v121, v141
	v_div_scale_f32 v122, s[0:1], v120, v120, 1.0
	v_rcp_f32_e32 v123, v122
	s_nop 0
	v_fma_f32 v141, -v122, v123, 1.0
	v_fmac_f32_e32 v123, v141, v123
	v_div_scale_f32 v141, vcc, 1.0, v120, 1.0
	v_mul_f32_e32 v148, v141, v123
	v_fma_f32 v150, -v122, v148, v141
	v_fmac_f32_e32 v148, v150, v123
	v_fma_f32 v122, -v122, v148, v141
	v_div_fmas_f32 v122, v122, v123, v148
	v_div_fixup_f32 v120, v122, v120, 1.0
	v_mul_f32_e32 v120, v120, v146
	v_mul_f32_e32 v120, v120, v121
	v_cvt_pk_bf16_f32 v122, v124, v125
	v_cvt_pk_bf16_f32 v123, v126, v127
	v_cvt_pk_bf16_f32 v124, v151, v149
	v_cvt_pk_bf16_f32 v125, v147, v120
	v_lshlrev_b64 v[120:121], 12, v[134:135]
	v_lshl_add_u64 v[120:121], s[12:13], 0, v[120:121]
	v_lshl_add_u64 v[120:121], v[120:121], 0, v[180:181]
	v_or_b32_e32 v126, 32, v140
	global_store_dwordx4 v[120:121], v[122:125], off offset:3072
	s_add_u32 s0, s14, 0xc0000
	s_addc_u32 s1, s15, 0
	global_load_dwordx4 v[188:191], v214, s[0:1] offset:0
	s_add_u32 s0, s18, 0x20000
	s_addc_u32 s1, s19, 0
	global_load_dwordx4 v[196:199], v215, s[0:1] offset:0
	v_ashrrev_i32_e32 v127, 31, v126
	s_nop 0
	v_mad_i64_i32 v[122:123], s[0:1], v126, s4, v[142:143]
	v_lshl_add_u64 v[122:123], v[122:123], 0, s[6:7]
	v_lshl_add_u64 v[124:125], v[122:123], 0, v[180:181]
	s_waitcnt vmcnt(6)
	v_mov_b32_e32 v148, v206
	v_mov_b32_e32 v149, v207
	v_mov_b32_e32 v150, v208
	v_mov_b32_e32 v151, v209
	v_lshlrev_b64 v[124:125], 10, v[126:127]
	v_lshl_add_u64 v[124:125], s[18:19], 0, v[124:125]
	v_lshl_add_u64 v[124:125], v[124:125], 0, v[180:181]
	v_lshlrev_b32_e32 v156, 16, v149
	v_and_b32_e32 v157, 0xffff0000, v149
	v_lshlrev_b32_e32 v149, 16, v150
	v_and_b32_e32 v147, 0xffff0000, v150
	v_lshlrev_b32_e32 v141, 16, v151
	v_and_b32_e32 v134, 0xffff0000, v151
	v_mov_b32_e32 v150, v210
	v_mov_b32_e32 v151, v211
	v_mov_b32_e32 v152, v212
	v_mov_b32_e32 v153, v213
	v_lshlrev_b32_e32 v154, 16, v148
	v_and_b32_e32 v155, 0xffff0000, v148
	v_lshlrev_b32_e32 v158, 16, v150
	v_and_b32_e32 v159, 0xffff0000, v150
	v_lshlrev_b32_e32 v150, 16, v152
	v_and_b32_e32 v148, 0xffff0000, v152
	v_exp_f32_e32 v152, v116
	v_mul_f32_e32 v116, 0xbfb8aa3b, v154
	v_lshlrev_b32_e32 v146, 16, v153
	v_and_b32_e32 v135, 0xffff0000, v153
	v_exp_f32_e32 v153, v116
	v_lshlrev_b32_e32 v160, 16, v151
	v_and_b32_e32 v151, 0xffff0000, v151
	v_pk_add_f32 v[152:153], v[152:153], 1.0 op_sel_hi:[1,0]
	s_nop 0
	v_div_scale_f32 v116, s[0:1], v153, v153, v154
	v_rcp_f32_e32 v161, v116
	s_nop 0
	v_fma_f32 v162, -v116, v161, 1.0
	v_fmac_f32_e32 v161, v162, v161
	v_div_scale_f32 v162, vcc, v154, v153, v154
	v_mul_f32_e32 v163, v162, v161
	v_fma_f32 v164, -v116, v163, v162
	v_fmac_f32_e32 v163, v164, v161
	v_fma_f32 v116, -v116, v163, v162
	v_div_fmas_f32 v116, v116, v161, v163
	v_div_fixup_f32 v116, v116, v153, v154
	v_div_scale_f32 v153, s[0:1], v152, v152, 1.0
	v_rcp_f32_e32 v154, v153
	s_nop 0
	v_fma_f32 v161, -v153, v154, 1.0
	v_fmac_f32_e32 v154, v161, v154
	v_div_scale_f32 v161, vcc, 1.0, v152, 1.0
	v_mul_f32_e32 v162, v161, v154
	v_fma_f32 v163, -v153, v162, v161
	v_fmac_f32_e32 v162, v163, v154
	v_fma_f32 v153, -v153, v162, v161
	v_div_fmas_f32 v153, v153, v154, v162
	v_div_fixup_f32 v152, v153, v152, 1.0
	v_mul_f32_e32 v152, v152, v158
	v_mul_f32_e32 v116, v152, v116
	v_exp_f32_e32 v152, v117
	v_mul_f32_e32 v117, 0xbfb8aa3b, v155
	v_exp_f32_e32 v153, v117
	s_nop 0
	v_pk_add_f32 v[152:153], v[152:153], 1.0 op_sel_hi:[1,0]
	s_nop 0
	v_div_scale_f32 v117, s[0:1], v153, v153, v155
	v_rcp_f32_e32 v154, v117
	s_nop 0
	v_fma_f32 v158, -v117, v154, 1.0
	v_fmac_f32_e32 v154, v158, v154
	v_div_scale_f32 v158, vcc, v155, v153, v155
	v_mul_f32_e32 v161, v158, v154
	v_fma_f32 v162, -v117, v161, v158
	v_fmac_f32_e32 v161, v162, v154
	v_fma_f32 v117, -v117, v161, v158
	v_div_fmas_f32 v117, v117, v154, v161
	v_div_fixup_f32 v117, v117, v153, v155
	v_div_scale_f32 v153, s[0:1], v152, v152, 1.0
	v_rcp_f32_e32 v154, v153
	s_nop 0
	v_fma_f32 v155, -v153, v154, 1.0
	v_fmac_f32_e32 v154, v155, v154
	v_div_scale_f32 v155, vcc, 1.0, v152, 1.0
	v_mul_f32_e32 v158, v155, v154
	v_fma_f32 v161, -v153, v158, v155
	v_fmac_f32_e32 v158, v161, v154
	v_fma_f32 v153, -v153, v158, v155
	v_div_fmas_f32 v153, v153, v154, v158
	v_div_fixup_f32 v152, v153, v152, 1.0
	v_mul_f32_e32 v152, v152, v159
	v_mul_f32_e32 v117, v152, v117
	v_exp_f32_e32 v152, v118
	v_mul_f32_e32 v118, 0xbfb8aa3b, v156
	v_exp_f32_e32 v153, v118
	s_nop 0
	v_pk_add_f32 v[152:153], v[152:153], 1.0 op_sel_hi:[1,0]
	s_nop 0
	v_div_scale_f32 v118, s[0:1], v153, v153, v156
	v_rcp_f32_e32 v154, v118
	s_nop 0
	v_fma_f32 v155, -v118, v154, 1.0
	v_fmac_f32_e32 v154, v155, v154
	v_div_scale_f32 v155, vcc, v156, v153, v156
	v_mul_f32_e32 v158, v155, v154
	v_fma_f32 v159, -v118, v158, v155
	v_fmac_f32_e32 v158, v159, v154
	v_fma_f32 v118, -v118, v158, v155
	v_div_fmas_f32 v118, v118, v154, v158
	v_div_fixup_f32 v118, v118, v153, v156
	v_div_scale_f32 v153, s[0:1], v152, v152, 1.0
	v_rcp_f32_e32 v154, v153
	s_nop 0
	v_fma_f32 v155, -v153, v154, 1.0
	v_fmac_f32_e32 v154, v155, v154
	v_div_scale_f32 v155, vcc, 1.0, v152, 1.0
; __device__ __forceinline__ unsigned cvt_pk_bf16(float lo, float hi) { unsigned r; asm volatile("v_cvt_pk_bf16_f32 %0, %1, %2" : "=v"(r) : "v"(lo), "v"(hi)); return r; }
; __device__ __forceinline__ float sigmoidf_(float v) { return 1.f / (1.f + __expf(-v)); }
; __device__ __forceinline__ float siluf_(float v) { return v / (1.f + __expf(-v)); }
; __device__ __forceinline__ void unpack8(u32x4 w, float* f) {
;     f[0] = __uint_as_float(w.x << 16); f[1] = __uint_as_float(w.x & 0xffff0000u); f[2] = __uint_as_float(w.y << 16); f[3] = __uint_as_float(w.y & 0xffff0000u);
;     f[4] = __uint_as_float(w.z << 16); f[5] = __uint_as_float(w.z & 0xffff0000u); f[6] = __uint_as_float(w.w << 16); f[7] = __uint_as_float(w.w & 0xffff0000u);
;     __device__ __forceinline__ void operator()(const f32x4 (&acc)[2][2][4][2], const Unit& u, int wr, int wc, int fr, int fq) const {
;     ...
;             for (int ai = 0; ai < 2; ++ai) {
; #pragma unroll
;                 for (int m = 0; m < 4; ++m) {
;                     const size_t row = (size_t)(row0 + ai * HALF + m * 16);
;                     const f32x4 v0 = acc[ai][bj][m][0], v1 = acc[ai][bj][m][1];
;                     float a[8] = {v0[0], v0[1], v0[2], v0[3], v1[0], v1[1], v1[2], v1[3]}, g[8], o[8];
;                     unpack8(*(const u32x4*)(R + row * RLD + (MODE == 0 ? 2560 : 1536) + col0), g);
;                     if (MODE == 0) { float y[8]; unpack8(*(const u32x4*)(YG + row * 512 + col0), y);
; #pragma unroll
;                         for (int e = 0; e < 8; ++e) o[e] = y[e] * sigmoidf_(a[e] + bb[e]) * siluf_(g[e]); }
;                     else {
; #pragma unroll
;                         for (int e = 0; e < 8; ++e) o[e] = a[e] * bb[e] * siluf_(g[e]); }
;                     u32x4 w; w.x = cvt_pk_bf16(o[0], o[1]); w.y = cvt_pk_bf16(o[2], o[3]); w.z = cvt_pk_bf16(o[4], o[5]); w.w = cvt_pk_bf16(o[6], o[7]);
;                     *(u32x4*)(Y + row * DM + (MODE == 0 ? 1536 : 1024) + col0) = w;
;                 }
	v_mul_f32_e32 v156, v155, v154
	v_fma_f32 v158, -v153, v156, v155
	v_fmac_f32_e32 v156, v158, v154
	v_fma_f32 v153, -v153, v156, v155
	v_div_fmas_f32 v153, v153, v154, v156
	v_div_fixup_f32 v152, v153, v152, 1.0
	v_mul_f32_e32 v152, v152, v160
	v_mul_f32_e32 v118, v152, v118
	v_exp_f32_e32 v152, v119
	v_mul_f32_e32 v119, 0xbfb8aa3b, v157
	v_exp_f32_e32 v153, v119
	s_nop 0
	v_pk_add_f32 v[152:153], v[152:153], 1.0 op_sel_hi:[1,0]
	s_nop 0
	v_div_scale_f32 v119, s[0:1], v153, v153, v157
	v_rcp_f32_e32 v154, v119
	s_nop 0
	v_fma_f32 v155, -v119, v154, 1.0
	v_fmac_f32_e32 v154, v155, v154
	v_div_scale_f32 v155, vcc, v157, v153, v157
	v_mul_f32_e32 v156, v155, v154
	v_fma_f32 v158, -v119, v156, v155
	v_fmac_f32_e32 v156, v158, v154
	v_fma_f32 v119, -v119, v156, v155
	v_div_fmas_f32 v119, v119, v154, v156
	v_div_fixup_f32 v119, v119, v153, v157
	v_div_scale_f32 v153, s[0:1], v152, v152, 1.0
	v_rcp_f32_e32 v154, v153
	s_nop 0
	v_fma_f32 v155, -v153, v154, 1.0
	v_fmac_f32_e32 v154, v155, v154
	v_div_scale_f32 v155, vcc, 1.0, v152, 1.0
	v_mul_f32_e32 v156, v155, v154
	v_fma_f32 v157, -v153, v156, v155
	v_fmac_f32_e32 v156, v157, v154
	v_fma_f32 v153, -v153, v156, v155
	v_div_fmas_f32 v153, v153, v154, v156
	v_div_fixup_f32 v152, v153, v152, 1.0
	v_mul_f32_e32 v151, v152, v151
	v_exp_f32_e32 v152, v112
	v_mul_f32_e32 v112, 0xbfb8aa3b, v149
	v_exp_f32_e32 v153, v112
	v_mul_f32_e32 v119, v151, v119
	v_pk_add_f32 v[152:153], v[152:153], 1.0 op_sel_hi:[1,0]
	s_nop 0
	v_div_scale_f32 v112, s[0:1], v153, v153, v149
	v_rcp_f32_e32 v151, v112
	s_nop 0
	v_fma_f32 v154, -v112, v151, 1.0
	v_fmac_f32_e32 v151, v154, v151
	v_div_scale_f32 v154, vcc, v149, v153, v149
	v_mul_f32_e32 v155, v154, v151
	v_fma_f32 v156, -v112, v155, v154
	v_fmac_f32_e32 v155, v156, v151
	v_fma_f32 v112, -v112, v155, v154
	v_div_fmas_f32 v112, v112, v151, v155
	v_div_fixup_f32 v112, v112, v153, v149
	v_div_scale_f32 v149, s[0:1], v152, v152, 1.0
	v_rcp_f32_e32 v151, v149
	s_nop 0
	v_fma_f32 v153, -v149, v151, 1.0
	v_fmac_f32_e32 v151, v153, v151
	v_div_scale_f32 v153, vcc, 1.0, v152, 1.0
	v_mul_f32_e32 v154, v153, v151
	v_fma_f32 v155, -v149, v154, v153
	v_fmac_f32_e32 v154, v155, v151
	v_fma_f32 v149, -v149, v154, v153
	v_div_fmas_f32 v149, v149, v151, v154
	v_div_fixup_f32 v149, v149, v152, 1.0
	v_mul_f32_e32 v149, v149, v150
	v_mul_f32_e32 v149, v149, v112
	v_add_f32_e32 v112, v113, v73
	v_mul_f32_e32 v112, 0xbfb8aa3b, v112
	v_mul_f32_e32 v113, 0xbfb8aa3b, v147
	v_exp_f32_e32 v112, v112
	v_exp_f32_e32 v113, v113
	s_nop 0
	v_pk_add_f32 v[112:113], v[112:113], 1.0 op_sel_hi:[1,0]
	s_nop 0
	v_div_scale_f32 v150, s[0:1], v113, v113, v147
	v_rcp_f32_e32 v151, v150
	s_nop 0
	v_fma_f32 v152, -v150, v151, 1.0
	v_fmac_f32_e32 v151, v152, v151
	v_div_scale_f32 v152, vcc, v147, v113, v147
	v_mul_f32_e32 v153, v152, v151
	v_fma_f32 v154, -v150, v153, v152
	v_fmac_f32_e32 v153, v154, v151
	v_fma_f32 v150, -v150, v153, v152
	v_div_fmas_f32 v150, v150, v151, v153
	v_div_fixup_f32 v113, v150, v113, v147
	v_div_scale_f32 v147, s[0:1], v112, v112, 1.0
	v_rcp_f32_e32 v150, v147
	s_nop 0
	v_fma_f32 v151, -v147, v150, 1.0
	v_fmac_f32_e32 v150, v151, v150
	v_div_scale_f32 v151, vcc, 1.0, v112, 1.0
	v_mul_f32_e32 v152, v151, v150
	v_fma_f32 v153, -v147, v152, v151
	v_fmac_f32_e32 v152, v153, v150
	v_fma_f32 v147, -v147, v152, v151
	v_div_fmas_f32 v147, v147, v150, v152
	v_div_fixup_f32 v112, v147, v112, 1.0
	v_mul_f32_e32 v112, v112, v148
	v_mul_f32_e32 v147, v112, v113
	v_add_f32_e32 v112, v114, v74
	v_mul_f32_e32 v112, 0xbfb8aa3b, v112
	v_mul_f32_e32 v113, 0xbfb8aa3b, v141
	v_exp_f32_e32 v112, v112
	v_exp_f32_e32 v113, v113
	s_nop 0
	v_pk_add_f32 v[112:113], v[112:113], 1.0 op_sel_hi:[1,0]
	s_nop 0
	v_div_scale_f32 v114, s[0:1], v113, v113, v141
	v_rcp_f32_e32 v148, v114
	s_nop 0
	v_fma_f32 v150, -v114, v148, 1.0
	v_fmac_f32_e32 v148, v150, v148
	v_div_scale_f32 v150, vcc, v141, v113, v141
	v_mul_f32_e32 v151, v150, v148
	v_fma_f32 v152, -v114, v151, v150
	v_fmac_f32_e32 v151, v152, v148
	v_fma_f32 v114, -v114, v151, v150
	v_div_fmas_f32 v114, v114, v148, v151
	v_div_fixup_f32 v113, v114, v113, v141
	v_div_scale_f32 v114, s[0:1], v112, v112, 1.0
	v_rcp_f32_e32 v141, v114
	s_nop 0
	v_fma_f32 v148, -v114, v141, 1.0
	v_fmac_f32_e32 v141, v148, v141
	v_div_scale_f32 v148, vcc, 1.0, v112, 1.0
	v_mul_f32_e32 v150, v148, v141
	v_fma_f32 v151, -v114, v150, v148
	v_fmac_f32_e32 v150, v151, v141
	v_fma_f32 v114, -v114, v150, v148
	v_div_fmas_f32 v114, v114, v141, v150
	v_div_fixup_f32 v112, v114, v112, 1.0
	v_mul_f32_e32 v112, v112, v146
	v_mul_f32_e32 v141, v112, v113
	v_add_f32_e32 v112, v115, v75
	v_mul_f32_e32 v112, 0xbfb8aa3b, v112
	v_mul_f32_e32 v113, 0xbfb8aa3b, v134
	v_exp_f32_e32 v112, v112
	v_exp_f32_e32 v113, v113
	s_nop 0
	v_pk_add_f32 v[112:113], v[112:113], 1.0 op_sel_hi:[1,0]
	s_nop 0
	v_div_scale_f32 v114, s[0:1], v113, v113, v134
	v_rcp_f32_e32 v115, v114
	s_nop 0
	v_fma_f32 v146, -v114, v115, 1.0
	v_fmac_f32_e32 v115, v146, v115
	v_div_scale_f32 v146, vcc, v134, v113, v134
	v_mul_f32_e32 v148, v146, v115
	v_fma_f32 v150, -v114, v148, v146
	v_fmac_f32_e32 v148, v150, v115
	v_fma_f32 v114, -v114, v148, v146
	v_div_fmas_f32 v114, v114, v115, v148
	v_div_fixup_f32 v113, v114, v113, v134
	v_div_scale_f32 v114, s[0:1], v112, v112, 1.0
	v_rcp_f32_e32 v115, v114
	s_nop 0
	v_fma_f32 v134, -v114, v115, 1.0
	v_fmac_f32_e32 v115, v134, v115
	v_div_scale_f32 v134, vcc, 1.0, v112, 1.0
	v_mul_f32_e32 v146, v134, v115
	v_fma_f32 v148, -v114, v146, v134
	v_fmac_f32_e32 v146, v148, v115
	v_fma_f32 v114, -v114, v146, v134
	v_div_fmas_f32 v114, v114, v115, v146
	v_div_fixup_f32 v112, v114, v112, 1.0
	v_mul_f32_e32 v112, v112, v135
	v_mul_f32_e32 v112, v112, v113
	v_cvt_pk_bf16_f32 v114, v116, v117
	v_cvt_pk_bf16_f32 v115, v118, v119
	v_cvt_pk_bf16_f32 v116, v149, v147
	v_cvt_pk_bf16_f32 v117, v141, v112
	v_lshlrev_b64 v[112:113], 12, v[126:127]
	v_lshl_add_u64 v[112:113], s[12:13], 0, v[112:113]
	v_lshl_add_u64 v[112:113], v[112:113], 0, v[180:181]
	v_or_b32_e32 v118, 48, v140
	global_store_dwordx4 v[112:113], v[114:117], off offset:3072
	s_add_u32 s0, s14, 0xd8000
	s_addc_u32 s1, s15, 0
	global_load_dwordx4 v[206:209], v214, s[0:1] offset:0
	s_add_u32 s0, s18, 0x24000
	s_addc_u32 s1, s19, 0
	global_load_dwordx4 v[210:213], v215, s[0:1] offset:0
	v_ashrrev_i32_e32 v119, 31, v118
	s_nop 0
	v_mad_i64_i32 v[114:115], s[0:1], v118, s4, v[142:143]
	v_lshl_add_u64 v[114:115], v[114:115], 0, s[6:7]
	v_lshl_add_u64 v[116:117], v[114:115], 0, v[180:181]
	s_waitcnt vmcnt(6)
; __device__ __forceinline__ unsigned cvt_pk_bf16(float lo, float hi) { unsigned r; asm volatile("v_cvt_pk_bf16_f32 %0, %1, %2" : "=v"(r) : "v"(lo), "v"(hi)); return r; }
; __device__ __forceinline__ float sigmoidf_(float v) { return 1.f / (1.f + __expf(-v)); }
; __device__ __forceinline__ float siluf_(float v) { return v / (1.f + __expf(-v)); }
; __device__ __forceinline__ void unpack8(u32x4 w, float* f) {
;     f[0] = __uint_as_float(w.x << 16); f[1] = __uint_as_float(w.x & 0xffff0000u); f[2] = __uint_as_float(w.y << 16); f[3] = __uint_as_float(w.y & 0xffff0000u);
;     f[4] = __uint_as_float(w.z << 16); f[5] = __uint_as_float(w.z & 0xffff0000u); f[6] = __uint_as_float(w.w << 16); f[7] = __uint_as_float(w.w & 0xffff0000u);
;     __device__ __forceinline__ void operator()(const f32x4 (&acc)[2][2][4][2], const Unit& u, int wr, int wc, int fr, int fq) const {
;     ...
;             for (int ai = 0; ai < 2; ++ai) {
; #pragma unroll
;                 for (int m = 0; m < 4; ++m) {
;                     const size_t row = (size_t)(row0 + ai * HALF + m * 16);
;                     const f32x4 v0 = acc[ai][bj][m][0], v1 = acc[ai][bj][m][1];
;                     float a[8] = {v0[0], v0[1], v0[2], v0[3], v1[0], v1[1], v1[2], v1[3]}, g[8], o[8];
;                     unpack8(*(const u32x4*)(R + row * RLD + (MODE == 0 ? 2560 : 1536) + col0), g);
;                     if (MODE == 0) { float y[8]; unpack8(*(const u32x4*)(YG + row * 512 + col0), y);
; #pragma unroll
;                         for (int e = 0; e < 8; ++e) o[e] = y[e] * sigmoidf_(a[e] + bb[e]) * siluf_(g[e]); }
;                     else {
; #pragma unroll
;                         for (int e = 0; e < 8; ++e) o[e] = a[e] * bb[e] * siluf_(g[e]); }
;                     u32x4 w; w.x = cvt_pk_bf16(o[0], o[1]); w.y = cvt_pk_bf16(o[2], o[3]); w.z = cvt_pk_bf16(o[4], o[5]); w.w = cvt_pk_bf16(o[6], o[7]);
;                     *(u32x4*)(Y + row * DM + (MODE == 0 ? 1536 : 1024) + col0) = w;
;                 }
	v_mov_b32_e32 v146, v168
	v_mov_b32_e32 v147, v169
	v_mov_b32_e32 v148, v170
	v_mov_b32_e32 v149, v171
	v_lshlrev_b64 v[116:117], 10, v[118:119]
	v_lshl_add_u64 v[116:117], s[18:19], 0, v[116:117]
	v_lshl_add_u64 v[116:117], v[116:117], 0, v[180:181]
	v_lshlrev_b32_e32 v154, 16, v147
	v_and_b32_e32 v155, 0xffff0000, v147
	v_lshlrev_b32_e32 v147, 16, v148
	v_and_b32_e32 v141, 0xffff0000, v148
	v_lshlrev_b32_e32 v134, 16, v149
	v_and_b32_e32 v126, 0xffff0000, v149
	v_mov_b32_e32 v148, v172
	v_mov_b32_e32 v149, v173
	v_mov_b32_e32 v150, v174
	v_mov_b32_e32 v151, v175
	v_lshlrev_b32_e32 v152, 16, v146
	v_and_b32_e32 v153, 0xffff0000, v146
	v_lshlrev_b32_e32 v156, 16, v148
	v_and_b32_e32 v157, 0xffff0000, v148
	v_lshlrev_b32_e32 v148, 16, v150
	v_and_b32_e32 v146, 0xffff0000, v150
	v_exp_f32_e32 v150, v108
	v_mul_f32_e32 v108, 0xbfb8aa3b, v152
	v_lshlrev_b32_e32 v135, 16, v151
	v_and_b32_e32 v127, 0xffff0000, v151
	v_exp_f32_e32 v151, v108
	v_lshlrev_b32_e32 v158, 16, v149
	v_and_b32_e32 v149, 0xffff0000, v149
	v_pk_add_f32 v[150:151], v[150:151], 1.0 op_sel_hi:[1,0]
	s_nop 0
	v_div_scale_f32 v108, s[0:1], v151, v151, v152
	v_rcp_f32_e32 v159, v108
	s_nop 0
	v_fma_f32 v160, -v108, v159, 1.0
	v_fmac_f32_e32 v159, v160, v159
	v_div_scale_f32 v160, vcc, v152, v151, v152
	v_mul_f32_e32 v161, v160, v159
	v_fma_f32 v162, -v108, v161, v160
	v_fmac_f32_e32 v161, v162, v159
	v_fma_f32 v108, -v108, v161, v160
	v_div_fmas_f32 v108, v108, v159, v161
	v_div_fixup_f32 v108, v108, v151, v152
	v_div_scale_f32 v151, s[0:1], v150, v150, 1.0
	v_rcp_f32_e32 v152, v151
	s_nop 0
	v_fma_f32 v159, -v151, v152, 1.0
	v_fmac_f32_e32 v152, v159, v152
	v_div_scale_f32 v159, vcc, 1.0, v150, 1.0
	v_mul_f32_e32 v160, v159, v152
	v_fma_f32 v161, -v151, v160, v159
	v_fmac_f32_e32 v160, v161, v152
	v_fma_f32 v151, -v151, v160, v159
	v_div_fmas_f32 v151, v151, v152, v160
	v_div_fixup_f32 v150, v151, v150, 1.0
	v_mul_f32_e32 v150, v150, v156
	v_mul_f32_e32 v108, v150, v108
	v_exp_f32_e32 v150, v109
	v_mul_f32_e32 v109, 0xbfb8aa3b, v153
	v_exp_f32_e32 v151, v109
	s_nop 0
	v_pk_add_f32 v[150:151], v[150:151], 1.0 op_sel_hi:[1,0]
	s_nop 0
	v_div_scale_f32 v109, s[0:1], v151, v151, v153
	v_rcp_f32_e32 v152, v109
	s_nop 0
	v_fma_f32 v156, -v109, v152, 1.0
	v_fmac_f32_e32 v152, v156, v152
	v_div_scale_f32 v156, vcc, v153, v151, v153
	v_mul_f32_e32 v159, v156, v152
	v_fma_f32 v160, -v109, v159, v156
	v_fmac_f32_e32 v159, v160, v152
	v_fma_f32 v109, -v109, v159, v156
	v_div_fmas_f32 v109, v109, v152, v159
	v_div_fixup_f32 v109, v109, v151, v153
	v_div_scale_f32 v151, s[0:1], v150, v150, 1.0
	v_rcp_f32_e32 v152, v151
	s_nop 0
	v_fma_f32 v153, -v151, v152, 1.0
	v_fmac_f32_e32 v152, v153, v152
	v_div_scale_f32 v153, vcc, 1.0, v150, 1.0
	v_mul_f32_e32 v156, v153, v152
	v_fma_f32 v159, -v151, v156, v153
	v_fmac_f32_e32 v156, v159, v152
	v_fma_f32 v151, -v151, v156, v153
	v_div_fmas_f32 v151, v151, v152, v156
	v_div_fixup_f32 v150, v151, v150, 1.0
	v_mul_f32_e32 v150, v150, v157
	v_mul_f32_e32 v109, v150, v109
	v_exp_f32_e32 v150, v110
	v_mul_f32_e32 v110, 0xbfb8aa3b, v154
	v_exp_f32_e32 v151, v110
	s_nop 0
	v_pk_add_f32 v[150:151], v[150:151], 1.0 op_sel_hi:[1,0]
	s_nop 0
	v_div_scale_f32 v110, s[0:1], v151, v151, v154
	v_rcp_f32_e32 v152, v110
	s_nop 0
	v_fma_f32 v153, -v110, v152, 1.0
	v_fmac_f32_e32 v152, v153, v152
	v_div_scale_f32 v153, vcc, v154, v151, v154
	v_mul_f32_e32 v156, v153, v152
	v_fma_f32 v157, -v110, v156, v153
	v_fmac_f32_e32 v156, v157, v152
	v_fma_f32 v110, -v110, v156, v153
	v_div_fmas_f32 v110, v110, v152, v156
	v_div_fixup_f32 v110, v110, v151, v154
	v_div_scale_f32 v151, s[0:1], v150, v150, 1.0
	v_rcp_f32_e32 v152, v151
	s_nop 0
	v_fma_f32 v153, -v151, v152, 1.0
	v_fmac_f32_e32 v152, v153, v152
	v_div_scale_f32 v153, vcc, 1.0, v150, 1.0
	v_mul_f32_e32 v154, v153, v152
	v_fma_f32 v156, -v151, v154, v153
	v_fmac_f32_e32 v154, v156, v152
	v_fma_f32 v151, -v151, v154, v153
	v_div_fmas_f32 v151, v151, v152, v154
	v_div_fixup_f32 v150, v151, v150, 1.0
	v_mul_f32_e32 v150, v150, v158
	v_mul_f32_e32 v110, v150, v110
	v_exp_f32_e32 v150, v111
	v_mul_f32_e32 v111, 0xbfb8aa3b, v155
	v_exp_f32_e32 v151, v111
	s_nop 0
	v_pk_add_f32 v[150:151], v[150:151], 1.0 op_sel_hi:[1,0]
	s_nop 0
	v_div_scale_f32 v111, s[0:1], v151, v151, v155
	v_rcp_f32_e32 v152, v111
	s_nop 0
	v_fma_f32 v153, -v111, v152, 1.0
	v_fmac_f32_e32 v152, v153, v152
	v_div_scale_f32 v153, vcc, v155, v151, v155
	v_mul_f32_e32 v154, v153, v152
	v_fma_f32 v156, -v111, v154, v153
	v_fmac_f32_e32 v154, v156, v152
	v_fma_f32 v111, -v111, v154, v153
	v_div_fmas_f32 v111, v111, v152, v154
	v_div_fixup_f32 v111, v111, v151, v155
	v_div_scale_f32 v151, s[0:1], v150, v150, 1.0
	v_rcp_f32_e32 v152, v151
	s_nop 0
	v_fma_f32 v153, -v151, v152, 1.0
	v_fmac_f32_e32 v152, v153, v152
	v_div_scale_f32 v153, vcc, 1.0, v150, 1.0
	v_mul_f32_e32 v154, v153, v152
	v_fma_f32 v155, -v151, v154, v153
	v_fmac_f32_e32 v154, v155, v152
	v_fma_f32 v151, -v151, v154, v153
	v_div_fmas_f32 v151, v151, v152, v154
	v_div_fixup_f32 v150, v151, v150, 1.0
	v_mul_f32_e32 v149, v150, v149
	v_exp_f32_e32 v150, v104
	v_mul_f32_e32 v104, 0xbfb8aa3b, v147
	v_exp_f32_e32 v151, v104
	v_mul_f32_e32 v111, v149, v111
	v_pk_add_f32 v[150:151], v[150:151], 1.0 op_sel_hi:[1,0]
	s_nop 0
	v_div_scale_f32 v104, s[0:1], v151, v151, v147
	v_rcp_f32_e32 v149, v104
	s_nop 0
	v_fma_f32 v152, -v104, v149, 1.0
	v_fmac_f32_e32 v149, v152, v149
	v_div_scale_f32 v152, vcc, v147, v151, v147
	v_mul_f32_e32 v153, v152, v149
	v_fma_f32 v154, -v104, v153, v152
	v_fmac_f32_e32 v153, v154, v149
	v_fma_f32 v104, -v104, v153, v152
	v_div_fmas_f32 v104, v104, v149, v153
; __device__ __forceinline__ unsigned cvt_pk_bf16(float lo, float hi) { unsigned r; asm volatile("v_cvt_pk_bf16_f32 %0, %1, %2" : "=v"(r) : "v"(lo), "v"(hi)); return r; }
; __device__ __forceinline__ float sigmoidf_(float v) { return 1.f / (1.f + __expf(-v)); }
; __device__ __forceinline__ float siluf_(float v) { return v / (1.f + __expf(-v)); }
; __device__ __forceinline__ void unpack8(u32x4 w, float* f) {
;     f[0] = __uint_as_float(w.x << 16); f[1] = __uint_as_float(w.x & 0xffff0000u); f[2] = __uint_as_float(w.y << 16); f[3] = __uint_as_float(w.y & 0xffff0000u);
;     f[4] = __uint_as_float(w.z << 16); f[5] = __uint_as_float(w.z & 0xffff0000u); f[6] = __uint_as_float(w.w << 16); f[7] = __uint_as_float(w.w & 0xffff0000u);
;     __device__ __forceinline__ void operator()(const f32x4 (&acc)[2][2][4][2], const Unit& u, int wr, int wc, int fr, int fq) const {
;     ...
;             for (int ai = 0; ai < 2; ++ai) {
; #pragma unroll
;                 for (int m = 0; m < 4; ++m) {
;                     const size_t row = (size_t)(row0 + ai * HALF + m * 16);
;                     const f32x4 v0 = acc[ai][bj][m][0], v1 = acc[ai][bj][m][1];
;                     float a[8] = {v0[0], v0[1], v0[2], v0[3], v1[0], v1[1], v1[2], v1[3]}, g[8], o[8];
;                     unpack8(*(const u32x4*)(R + row * RLD + (MODE == 0 ? 2560 : 1536) + col0), g);
;                     if (MODE == 0) { float y[8]; unpack8(*(const u32x4*)(YG + row * 512 + col0), y);
; #pragma unroll
;                         for (int e = 0; e < 8; ++e) o[e] = y[e] * sigmoidf_(a[e] + bb[e]) * siluf_(g[e]); }
;                     else {
; #pragma unroll
;                         for (int e = 0; e < 8; ++e) o[e] = a[e] * bb[e] * siluf_(g[e]); }
;                     u32x4 w; w.x = cvt_pk_bf16(o[0], o[1]); w.y = cvt_pk_bf16(o[2], o[3]); w.z = cvt_pk_bf16(o[4], o[5]); w.w = cvt_pk_bf16(o[6], o[7]);
;                     *(u32x4*)(Y + row * DM + (MODE == 0 ? 1536 : 1024) + col0) = w;
;                 }
	v_div_fixup_f32 v104, v104, v151, v147
	v_div_scale_f32 v147, s[0:1], v150, v150, 1.0
	v_rcp_f32_e32 v149, v147
	s_nop 0
	v_fma_f32 v151, -v147, v149, 1.0
	v_fmac_f32_e32 v149, v151, v149
	v_div_scale_f32 v151, vcc, 1.0, v150, 1.0
	v_mul_f32_e32 v152, v151, v149
	v_fma_f32 v153, -v147, v152, v151
	v_fmac_f32_e32 v152, v153, v149
	v_fma_f32 v147, -v147, v152, v151
	v_div_fmas_f32 v147, v147, v149, v152
	v_div_fixup_f32 v147, v147, v150, 1.0
	v_mul_f32_e32 v147, v147, v148
	v_mul_f32_e32 v147, v147, v104
	v_add_f32_e32 v104, v105, v73
	v_mul_f32_e32 v104, 0xbfb8aa3b, v104
	v_mul_f32_e32 v105, 0xbfb8aa3b, v141
	v_exp_f32_e32 v104, v104
	v_exp_f32_e32 v105, v105
	s_nop 0
	v_pk_add_f32 v[104:105], v[104:105], 1.0 op_sel_hi:[1,0]
	s_nop 0
	v_div_scale_f32 v148, s[0:1], v105, v105, v141
	v_rcp_f32_e32 v149, v148
	s_nop 0
	v_fma_f32 v150, -v148, v149, 1.0
	v_fmac_f32_e32 v149, v150, v149
	v_div_scale_f32 v150, vcc, v141, v105, v141
	v_mul_f32_e32 v151, v150, v149
	v_fma_f32 v152, -v148, v151, v150
	v_fmac_f32_e32 v151, v152, v149
	v_fma_f32 v148, -v148, v151, v150
	v_div_fmas_f32 v148, v148, v149, v151
	v_div_fixup_f32 v105, v148, v105, v141
	v_div_scale_f32 v141, s[0:1], v104, v104, 1.0
	v_rcp_f32_e32 v148, v141
	s_nop 0
	v_fma_f32 v149, -v141, v148, 1.0
	v_fmac_f32_e32 v148, v149, v148
	v_div_scale_f32 v149, vcc, 1.0, v104, 1.0
	v_mul_f32_e32 v150, v149, v148
	v_fma_f32 v151, -v141, v150, v149
	v_fmac_f32_e32 v150, v151, v148
	v_fma_f32 v141, -v141, v150, v149
	v_div_fmas_f32 v141, v141, v148, v150
	v_div_fixup_f32 v104, v141, v104, 1.0
	v_mul_f32_e32 v104, v104, v146
	v_mul_f32_e32 v141, v104, v105
	v_add_f32_e32 v104, v106, v74
	v_mul_f32_e32 v104, 0xbfb8aa3b, v104
	v_mul_f32_e32 v105, 0xbfb8aa3b, v134
	v_exp_f32_e32 v104, v104
	v_exp_f32_e32 v105, v105
	s_nop 0
	v_pk_add_f32 v[104:105], v[104:105], 1.0 op_sel_hi:[1,0]
	s_nop 0
	v_div_scale_f32 v106, s[0:1], v105, v105, v134
	v_rcp_f32_e32 v146, v106
	s_nop 0
	v_fma_f32 v148, -v106, v146, 1.0
	v_fmac_f32_e32 v146, v148, v146
	v_div_scale_f32 v148, vcc, v134, v105, v134
	v_mul_f32_e32 v149, v148, v146
	v_fma_f32 v150, -v106, v149, v148
	v_fmac_f32_e32 v149, v150, v146
	v_fma_f32 v106, -v106, v149, v148
	v_div_fmas_f32 v106, v106, v146, v149
	v_div_fixup_f32 v105, v106, v105, v134
	v_div_scale_f32 v106, s[0:1], v104, v104, 1.0
	v_rcp_f32_e32 v134, v106
	s_nop 0
	v_fma_f32 v146, -v106, v134, 1.0
	v_fmac_f32_e32 v134, v146, v134
	v_div_scale_f32 v146, vcc, 1.0, v104, 1.0
	v_mul_f32_e32 v148, v146, v134
	v_fma_f32 v149, -v106, v148, v146
	v_fmac_f32_e32 v148, v149, v134
	v_fma_f32 v106, -v106, v148, v146
	v_div_fmas_f32 v106, v106, v134, v148
	v_div_fixup_f32 v104, v106, v104, 1.0
	v_mul_f32_e32 v104, v104, v135
	v_mul_f32_e32 v134, v104, v105
	v_add_f32_e32 v104, v107, v75
	v_mul_f32_e32 v104, 0xbfb8aa3b, v104
	v_mul_f32_e32 v105, 0xbfb8aa3b, v126
	v_exp_f32_e32 v104, v104
	v_exp_f32_e32 v105, v105
	s_nop 0
	v_pk_add_f32 v[104:105], v[104:105], 1.0 op_sel_hi:[1,0]
	s_nop 0
	v_div_scale_f32 v106, s[0:1], v105, v105, v126
	v_rcp_f32_e32 v107, v106
	s_nop 0
	v_fma_f32 v135, -v106, v107, 1.0
	v_fmac_f32_e32 v107, v135, v107
	v_div_scale_f32 v135, vcc, v126, v105, v126
	v_mul_f32_e32 v146, v135, v107
	v_fma_f32 v148, -v106, v146, v135
	v_fmac_f32_e32 v146, v148, v107
	v_fma_f32 v106, -v106, v146, v135
	v_div_fmas_f32 v106, v106, v107, v146
	v_div_fixup_f32 v105, v106, v105, v126
	v_div_scale_f32 v106, s[0:1], v104, v104, 1.0
	v_rcp_f32_e32 v107, v106
	s_nop 0
	v_fma_f32 v126, -v106, v107, 1.0
	v_fmac_f32_e32 v107, v126, v107
	v_div_scale_f32 v126, vcc, 1.0, v104, 1.0
	v_mul_f32_e32 v135, v126, v107
	v_fma_f32 v146, -v106, v135, v126
	v_fmac_f32_e32 v135, v146, v107
	v_fma_f32 v106, -v106, v135, v126
	v_div_fmas_f32 v106, v106, v107, v135
	v_div_fixup_f32 v104, v106, v104, 1.0
	v_mul_f32_e32 v104, v104, v127
	v_mul_f32_e32 v104, v104, v105
	v_cvt_pk_bf16_f32 v106, v108, v109
	v_cvt_pk_bf16_f32 v107, v110, v111
	v_cvt_pk_bf16_f32 v108, v147, v141
	v_cvt_pk_bf16_f32 v109, v134, v104
	v_lshlrev_b64 v[104:105], 12, v[118:119]
	v_lshl_add_u64 v[104:105], s[12:13], 0, v[104:105]
	v_lshl_add_u64 v[104:105], v[104:105], 0, v[180:181]
	v_add_u32_e32 v110, 0x80, v140
	global_store_dwordx4 v[104:105], v[106:109], off offset:3072
	s_add_u32 s0, s14, 0xf0000
	s_addc_u32 s1, s15, 0
	global_load_dwordx4 v[168:171], v214, s[0:1] offset:0
	s_add_u32 s0, s18, 0x28000
	s_addc_u32 s1, s19, 0
	global_load_dwordx4 v[172:175], v215, s[0:1] offset:0
	v_ashrrev_i32_e32 v111, 31, v110
	s_nop 0
	v_mad_i64_i32 v[106:107], s[0:1], v110, s4, v[142:143]
	v_lshl_add_u64 v[106:107], v[106:107], 0, s[6:7]
	v_lshl_add_u64 v[108:109], v[106:107], 0, v[180:181]
	s_waitcnt vmcnt(6)
; __device__ __forceinline__ unsigned cvt_pk_bf16(float lo, float hi) { unsigned r; asm volatile("v_cvt_pk_bf16_f32 %0, %1, %2" : "=v"(r) : "v"(lo), "v"(hi)); return r; }
; __device__ __forceinline__ float sigmoidf_(float v) { return 1.f / (1.f + __expf(-v)); }
; __device__ __forceinline__ float siluf_(float v) { return v / (1.f + __expf(-v)); }
;     __device__ __forceinline__ void operator()(const f32x4 (&acc)[2][2][4][2], const Unit& u, int wr, int wc, int fr, int fq) const {
;     ...
;                     const size_t row = (size_t)(row0 + ai * HALF + m * 16);
;                     const f32x4 v0 = acc[ai][bj][m][0], v1 = acc[ai][bj][m][1];
;                     float a[8] = {v0[0], v0[1], v0[2], v0[3], v1[0], v1[1], v1[2], v1[3]}, g[8], o[8];
;                     unpack8(*(const u32x4*)(R + row * RLD + (MODE == 0 ? 2560 : 1536) + col0), g);
;                     if (MODE == 0) { float y[8]; unpack8(*(const u32x4*)(YG + row * 512 + col0), y);
; #pragma unroll
;                         for (int e = 0; e < 8; ++e) o[e] = y[e] * sigmoidf_(a[e] + bb[e]) * siluf_(g[e]); }
;                     else {
; #pragma unroll
;                         for (int e = 0; e < 8; ++e) o[e] = a[e] * bb[e] * siluf_(g[e]); }
;                     u32x4 w; w.x = cvt_pk_bf16(o[0], o[1]); w.y = cvt_pk_bf16(o[2], o[3]); w.z = cvt_pk_bf16(o[4], o[5]); w.w = cvt_pk_bf16(o[6], o[7]);
;                     *(u32x4*)(Y + row * DM + (MODE == 0 ? 1536 : 1024) + col0) = w;
	v_mov_b32_e32 v146, v188
	v_mov_b32_e32 v147, v189
	v_mov_b32_e32 v148, v190
	v_mov_b32_e32 v149, v191
	v_lshlrev_b64 v[108:109], 10, v[110:111]
	v_lshl_add_u64 v[108:109], s[18:19], 0, v[108:109]
	v_lshl_add_u64 v[108:109], v[108:109], 0, v[180:181]
	v_lshlrev_b32_e32 v150, 16, v146
	v_and_b32_e32 v151, 0xffff0000, v146
	v_lshlrev_b32_e32 v152, 16, v147
	v_and_b32_e32 v153, 0xffff0000, v147
	v_lshlrev_b32_e32 v141, 16, v148
	v_and_b32_e32 v134, 0xffff0000, v148
	v_lshlrev_b32_e32 v126, 16, v149
	v_and_b32_e32 v118, 0xffff0000, v149
	v_mov_b32_e32 v146, v196
	v_mov_b32_e32 v147, v197
	v_mov_b32_e32 v148, v198
	v_mov_b32_e32 v149, v199
	v_lshlrev_b32_e32 v154, 16, v146
	v_and_b32_e32 v155, 0xffff0000, v146
	v_lshlrev_b32_e32 v146, 16, v148
	v_and_b32_e32 v135, 0xffff0000, v148
	v_exp_f32_e32 v148, v100
	v_mul_f32_e32 v100, 0xbfb8aa3b, v150
	v_lshlrev_b32_e32 v127, 16, v149
	v_and_b32_e32 v119, 0xffff0000, v149
	v_exp_f32_e32 v149, v100
	v_lshlrev_b32_e32 v156, 16, v147
	v_and_b32_e32 v147, 0xffff0000, v147
	v_pk_add_f32 v[148:149], v[148:149], 1.0 op_sel_hi:[1,0]
	s_nop 0
	v_div_scale_f32 v100, s[0:1], v149, v149, v150
	v_rcp_f32_e32 v157, v100
	s_nop 0
	v_fma_f32 v158, -v100, v157, 1.0
	v_fmac_f32_e32 v157, v158, v157
	v_div_scale_f32 v158, vcc, v150, v149, v150
	v_mul_f32_e32 v159, v158, v157
	v_fma_f32 v160, -v100, v159, v158
	v_fmac_f32_e32 v159, v160, v157
	v_fma_f32 v100, -v100, v159, v158
	v_div_fmas_f32 v100, v100, v157, v159
	v_div_fixup_f32 v100, v100, v149, v150
	v_div_scale_f32 v149, s[0:1], v148, v148, 1.0
	v_rcp_f32_e32 v150, v149
	s_nop 0
	v_fma_f32 v157, -v149, v150, 1.0
	v_fmac_f32_e32 v150, v157, v150
	v_div_scale_f32 v157, vcc, 1.0, v148, 1.0
	v_mul_f32_e32 v158, v157, v150
	v_fma_f32 v159, -v149, v158, v157
	v_fmac_f32_e32 v158, v159, v150
	v_fma_f32 v149, -v149, v158, v157
	v_div_fmas_f32 v149, v149, v150, v158
	v_div_fixup_f32 v148, v149, v148, 1.0
	v_mul_f32_e32 v148, v148, v154
	v_mul_f32_e32 v100, v148, v100
	v_exp_f32_e32 v148, v101
	v_mul_f32_e32 v101, 0xbfb8aa3b, v151
	v_exp_f32_e32 v149, v101
	s_nop 0
	v_pk_add_f32 v[148:149], v[148:149], 1.0 op_sel_hi:[1,0]
	s_nop 0
	v_div_scale_f32 v101, s[0:1], v149, v149, v151
	v_rcp_f32_e32 v150, v101
	s_nop 0
	v_fma_f32 v154, -v101, v150, 1.0
	v_fmac_f32_e32 v150, v154, v150
	v_div_scale_f32 v154, vcc, v151, v149, v151
	v_mul_f32_e32 v157, v154, v150
	v_fma_f32 v158, -v101, v157, v154
	v_fmac_f32_e32 v157, v158, v150
	v_fma_f32 v101, -v101, v157, v154
	v_div_fmas_f32 v101, v101, v150, v157
	v_div_fixup_f32 v101, v101, v149, v151
	v_div_scale_f32 v149, s[0:1], v148, v148, 1.0
	v_rcp_f32_e32 v150, v149
	s_nop 0
	v_fma_f32 v151, -v149, v150, 1.0
	v_fmac_f32_e32 v150, v151, v150
	v_div_scale_f32 v151, vcc, 1.0, v148, 1.0
	v_mul_f32_e32 v154, v151, v150
	v_fma_f32 v157, -v149, v154, v151
	v_fmac_f32_e32 v154, v157, v150
	v_fma_f32 v149, -v149, v154, v151
	v_div_fmas_f32 v149, v149, v150, v154
	v_div_fixup_f32 v148, v149, v148, 1.0
	v_mul_f32_e32 v148, v148, v155
	v_mul_f32_e32 v101, v148, v101
	v_exp_f32_e32 v148, v102
	v_mul_f32_e32 v102, 0xbfb8aa3b, v152
	v_exp_f32_e32 v149, v102
	s_nop 0
	v_pk_add_f32 v[148:149], v[148:149], 1.0 op_sel_hi:[1,0]
	s_nop 0
	v_div_scale_f32 v102, s[0:1], v149, v149, v152
	v_rcp_f32_e32 v150, v102
	s_nop 0
	v_fma_f32 v151, -v102, v150, 1.0
	v_fmac_f32_e32 v150, v151, v150
	v_div_scale_f32 v151, vcc, v152, v149, v152
	v_mul_f32_e32 v154, v151, v150
	v_fma_f32 v155, -v102, v154, v151
	v_fmac_f32_e32 v154, v155, v150
	v_fma_f32 v102, -v102, v154, v151
	v_div_fmas_f32 v102, v102, v150, v154
	v_div_fixup_f32 v102, v102, v149, v152
	v_div_scale_f32 v149, s[0:1], v148, v148, 1.0
	v_rcp_f32_e32 v150, v149
	s_nop 0
	v_fma_f32 v151, -v149, v150, 1.0
	v_fmac_f32_e32 v150, v151, v150
	v_div_scale_f32 v151, vcc, 1.0, v148, 1.0
	v_mul_f32_e32 v152, v151, v150
	v_fma_f32 v154, -v149, v152, v151
	v_fmac_f32_e32 v152, v154, v150
	v_fma_f32 v149, -v149, v152, v151
	v_div_fmas_f32 v149, v149, v150, v152
	v_div_fixup_f32 v148, v149, v148, 1.0
	v_mul_f32_e32 v148, v148, v156
	v_mul_f32_e32 v102, v148, v102
	v_exp_f32_e32 v148, v103
	v_mul_f32_e32 v103, 0xbfb8aa3b, v153
	v_exp_f32_e32 v149, v103
	s_nop 0
	v_pk_add_f32 v[148:149], v[148:149], 1.0 op_sel_hi:[1,0]
	s_nop 0
	v_div_scale_f32 v103, s[0:1], v149, v149, v153
	v_rcp_f32_e32 v150, v103
	s_nop 0
	v_fma_f32 v151, -v103, v150, 1.0
	v_fmac_f32_e32 v150, v151, v150
	v_div_scale_f32 v151, vcc, v153, v149, v153
	v_mul_f32_e32 v152, v151, v150
	v_fma_f32 v154, -v103, v152, v151
	v_fmac_f32_e32 v152, v154, v150
	v_fma_f32 v103, -v103, v152, v151
	v_div_fmas_f32 v103, v103, v150, v152
	v_div_fixup_f32 v103, v103, v149, v153
	v_div_scale_f32 v149, s[0:1], v148, v148, 1.0
	v_rcp_f32_e32 v150, v149
	s_nop 0
	v_fma_f32 v151, -v149, v150, 1.0
	v_fmac_f32_e32 v150, v151, v150
	v_div_scale_f32 v151, vcc, 1.0, v148, 1.0
	v_mul_f32_e32 v152, v151, v150
	v_fma_f32 v153, -v149, v152, v151
	v_fmac_f32_e32 v152, v153, v150
	v_fma_f32 v149, -v149, v152, v151
	v_div_fmas_f32 v149, v149, v150, v152
	v_div_fixup_f32 v148, v149, v148, 1.0
	v_mul_f32_e32 v147, v148, v147
	v_exp_f32_e32 v148, v96
	v_mul_f32_e32 v96, 0xbfb8aa3b, v141
	v_exp_f32_e32 v149, v96
	v_mul_f32_e32 v103, v147, v103
	v_pk_add_f32 v[148:149], v[148:149], 1.0 op_sel_hi:[1,0]
	s_nop 0
	v_div_scale_f32 v96, s[0:1], v149, v149, v141
	v_rcp_f32_e32 v147, v96
	s_nop 0
	v_fma_f32 v150, -v96, v147, 1.0
	v_fmac_f32_e32 v147, v150, v147
	v_div_scale_f32 v150, vcc, v141, v149, v141
	v_mul_f32_e32 v151, v150, v147
	v_fma_f32 v152, -v96, v151, v150
	v_fmac_f32_e32 v151, v152, v147
	v_fma_f32 v96, -v96, v151, v150
	v_div_fmas_f32 v96, v96, v147, v151
	v_div_fixup_f32 v96, v96, v149, v141
; __device__ __forceinline__ unsigned cvt_pk_bf16(float lo, float hi) { unsigned r; asm volatile("v_cvt_pk_bf16_f32 %0, %1, %2" : "=v"(r) : "v"(lo), "v"(hi)); return r; }
; __device__ __forceinline__ float sigmoidf_(float v) { return 1.f / (1.f + __expf(-v)); }
; __device__ __forceinline__ float siluf_(float v) { return v / (1.f + __expf(-v)); }
;     __device__ __forceinline__ void operator()(const f32x4 (&acc)[2][2][4][2], const Unit& u, int wr, int wc, int fr, int fq) const {
;     ...
;                     const size_t row = (size_t)(row0 + ai * HALF + m * 16);
;                     const f32x4 v0 = acc[ai][bj][m][0], v1 = acc[ai][bj][m][1];
;                     float a[8] = {v0[0], v0[1], v0[2], v0[3], v1[0], v1[1], v1[2], v1[3]}, g[8], o[8];
;                     unpack8(*(const u32x4*)(R + row * RLD + (MODE == 0 ? 2560 : 1536) + col0), g);
;                     if (MODE == 0) { float y[8]; unpack8(*(const u32x4*)(YG + row * 512 + col0), y);
; #pragma unroll
;                         for (int e = 0; e < 8; ++e) o[e] = y[e] * sigmoidf_(a[e] + bb[e]) * siluf_(g[e]); }
;                     else {
; #pragma unroll
;                         for (int e = 0; e < 8; ++e) o[e] = a[e] * bb[e] * siluf_(g[e]); }
;                     u32x4 w; w.x = cvt_pk_bf16(o[0], o[1]); w.y = cvt_pk_bf16(o[2], o[3]); w.z = cvt_pk_bf16(o[4], o[5]); w.w = cvt_pk_bf16(o[6], o[7]);
;                     *(u32x4*)(Y + row * DM + (MODE == 0 ? 1536 : 1024) + col0) = w;
	v_div_scale_f32 v141, s[0:1], v148, v148, 1.0
	v_rcp_f32_e32 v147, v141
	s_nop 0
	v_fma_f32 v149, -v141, v147, 1.0
	v_fmac_f32_e32 v147, v149, v147
	v_div_scale_f32 v149, vcc, 1.0, v148, 1.0
	v_mul_f32_e32 v150, v149, v147
	v_fma_f32 v151, -v141, v150, v149
	v_fmac_f32_e32 v150, v151, v147
	v_fma_f32 v141, -v141, v150, v149
	v_div_fmas_f32 v141, v141, v147, v150
	v_div_fixup_f32 v141, v141, v148, 1.0
	v_mul_f32_e32 v141, v141, v146
	v_mul_f32_e32 v141, v141, v96
	v_add_f32_e32 v96, v97, v73
	v_mul_f32_e32 v96, 0xbfb8aa3b, v96
	v_mul_f32_e32 v97, 0xbfb8aa3b, v134
	v_exp_f32_e32 v96, v96
	v_exp_f32_e32 v97, v97
	s_nop 0
	v_pk_add_f32 v[96:97], v[96:97], 1.0 op_sel_hi:[1,0]
	s_nop 0
	v_div_scale_f32 v146, s[0:1], v97, v97, v134
	v_rcp_f32_e32 v147, v146
	s_nop 0
	v_fma_f32 v148, -v146, v147, 1.0
	v_fmac_f32_e32 v147, v148, v147
	v_div_scale_f32 v148, vcc, v134, v97, v134
	v_mul_f32_e32 v149, v148, v147
	v_fma_f32 v150, -v146, v149, v148
	v_fmac_f32_e32 v149, v150, v147
	v_fma_f32 v146, -v146, v149, v148
	v_div_fmas_f32 v146, v146, v147, v149
	v_div_fixup_f32 v97, v146, v97, v134
	v_div_scale_f32 v134, s[0:1], v96, v96, 1.0
	v_rcp_f32_e32 v146, v134
	s_nop 0
	v_fma_f32 v147, -v134, v146, 1.0
	v_fmac_f32_e32 v146, v147, v146
	v_div_scale_f32 v147, vcc, 1.0, v96, 1.0
	v_mul_f32_e32 v148, v147, v146
	v_fma_f32 v149, -v134, v148, v147
	v_fmac_f32_e32 v148, v149, v146
	v_fma_f32 v134, -v134, v148, v147
	v_div_fmas_f32 v134, v134, v146, v148
	v_div_fixup_f32 v96, v134, v96, 1.0
	v_mul_f32_e32 v96, v96, v135
	v_mul_f32_e32 v134, v96, v97
	v_add_f32_e32 v96, v98, v74
	v_mul_f32_e32 v96, 0xbfb8aa3b, v96
	v_mul_f32_e32 v97, 0xbfb8aa3b, v126
	v_exp_f32_e32 v96, v96
	v_exp_f32_e32 v97, v97
	s_nop 0
	v_pk_add_f32 v[96:97], v[96:97], 1.0 op_sel_hi:[1,0]
	s_nop 0
	v_div_scale_f32 v98, s[0:1], v97, v97, v126
	v_rcp_f32_e32 v135, v98
	s_nop 0
	v_fma_f32 v146, -v98, v135, 1.0
	v_fmac_f32_e32 v135, v146, v135
	v_div_scale_f32 v146, vcc, v126, v97, v126
	v_mul_f32_e32 v147, v146, v135
	v_fma_f32 v148, -v98, v147, v146
	v_fmac_f32_e32 v147, v148, v135
	v_fma_f32 v98, -v98, v147, v146
	v_div_fmas_f32 v98, v98, v135, v147
	v_div_fixup_f32 v97, v98, v97, v126
	v_div_scale_f32 v98, s[0:1], v96, v96, 1.0
	v_rcp_f32_e32 v126, v98
	s_nop 0
	v_fma_f32 v135, -v98, v126, 1.0
	v_fmac_f32_e32 v126, v135, v126
	v_div_scale_f32 v135, vcc, 1.0, v96, 1.0
	v_mul_f32_e32 v146, v135, v126
	v_fma_f32 v147, -v98, v146, v135
	v_fmac_f32_e32 v146, v147, v126
	v_fma_f32 v98, -v98, v146, v135
	v_div_fmas_f32 v98, v98, v126, v146
	v_div_fixup_f32 v96, v98, v96, 1.0
	v_mul_f32_e32 v96, v96, v127
	v_mul_f32_e32 v126, v96, v97
	v_add_f32_e32 v96, v99, v75
	v_mul_f32_e32 v96, 0xbfb8aa3b, v96
	v_mul_f32_e32 v97, 0xbfb8aa3b, v118
	v_exp_f32_e32 v96, v96
	v_exp_f32_e32 v97, v97
	s_nop 0
	v_pk_add_f32 v[96:97], v[96:97], 1.0 op_sel_hi:[1,0]
	s_nop 0
	v_div_scale_f32 v98, s[0:1], v97, v97, v118
	v_rcp_f32_e32 v99, v98
	s_nop 0
	v_fma_f32 v127, -v98, v99, 1.0
	v_fmac_f32_e32 v99, v127, v99
	v_div_scale_f32 v127, vcc, v118, v97, v118
	v_mul_f32_e32 v135, v127, v99
	v_fma_f32 v146, -v98, v135, v127
	v_fmac_f32_e32 v135, v146, v99
	v_fma_f32 v98, -v98, v135, v127
	v_div_fmas_f32 v98, v98, v99, v135
	v_div_fixup_f32 v97, v98, v97, v118
	v_div_scale_f32 v98, s[0:1], v96, v96, 1.0
	v_rcp_f32_e32 v99, v98
	s_nop 0
	v_fma_f32 v118, -v98, v99, 1.0
	v_fmac_f32_e32 v99, v118, v99
	v_div_scale_f32 v118, vcc, 1.0, v96, 1.0
	v_mul_f32_e32 v127, v118, v99
	v_fma_f32 v135, -v98, v127, v118
	v_fmac_f32_e32 v127, v135, v99
	v_fma_f32 v98, -v98, v127, v118
	v_div_fmas_f32 v98, v98, v99, v127
	v_div_fixup_f32 v96, v98, v96, 1.0
	v_mul_f32_e32 v96, v96, v119
	v_mul_f32_e32 v96, v96, v97
	v_cvt_pk_bf16_f32 v98, v100, v101
	v_cvt_pk_bf16_f32 v99, v102, v103
	v_cvt_pk_bf16_f32 v100, v141, v134
	v_cvt_pk_bf16_f32 v101, v126, v96
	v_lshlrev_b64 v[96:97], 12, v[110:111]
	v_lshl_add_u64 v[96:97], s[12:13], 0, v[96:97]
	v_lshl_add_u64 v[96:97], v[96:97], 0, v[180:181]
	v_add_u32_e32 v102, 0x90, v140
	global_store_dwordx4 v[96:97], v[98:101], off offset:3072
	s_add_u32 s0, s14, 0x108000
	s_addc_u32 s1, s15, 0
	global_load_dwordx4 v[188:191], v214, s[0:1] offset:0
	s_add_u32 s0, s18, 0x2c000
	s_addc_u32 s1, s19, 0
	global_load_dwordx4 v[196:199], v215, s[0:1] offset:0
	v_ashrrev_i32_e32 v103, 31, v102
	s_nop 0
	v_mad_i64_i32 v[98:99], s[0:1], v102, s4, v[142:143]
	v_lshl_add_u64 v[98:99], v[98:99], 0, s[6:7]
	v_lshl_add_u64 v[100:101], v[98:99], 0, v[180:181]
	s_waitcnt vmcnt(6)
; __device__ __forceinline__ unsigned cvt_pk_bf16(float lo, float hi) { unsigned r; asm volatile("v_cvt_pk_bf16_f32 %0, %1, %2" : "=v"(r) : "v"(lo), "v"(hi)); return r; }
; __device__ __forceinline__ float sigmoidf_(float v) { return 1.f / (1.f + __expf(-v)); }
; __device__ __forceinline__ float siluf_(float v) { return v / (1.f + __expf(-v)); }
;     __device__ __forceinline__ void operator()(const f32x4 (&acc)[2][2][4][2], const Unit& u, int wr, int wc, int fr, int fq) const {
;     ...
;                     const size_t row = (size_t)(row0 + ai * HALF + m * 16);
;                     const f32x4 v0 = acc[ai][bj][m][0], v1 = acc[ai][bj][m][1];
;                     float a[8] = {v0[0], v0[1], v0[2], v0[3], v1[0], v1[1], v1[2], v1[3]}, g[8], o[8];
;                     unpack8(*(const u32x4*)(R + row * RLD + (MODE == 0 ? 2560 : 1536) + col0), g);
;                     if (MODE == 0) { float y[8]; unpack8(*(const u32x4*)(YG + row * 512 + col0), y);
; #pragma unroll
;                         for (int e = 0; e < 8; ++e) o[e] = y[e] * sigmoidf_(a[e] + bb[e]) * siluf_(g[e]); }
;                     else {
; #pragma unroll
;                         for (int e = 0; e < 8; ++e) o[e] = a[e] * bb[e] * siluf_(g[e]); }
;                     u32x4 w; w.x = cvt_pk_bf16(o[0], o[1]); w.y = cvt_pk_bf16(o[2], o[3]); w.z = cvt_pk_bf16(o[4], o[5]); w.w = cvt_pk_bf16(o[6], o[7]);
;                     *(u32x4*)(Y + row * DM + (MODE == 0 ? 1536 : 1024) + col0) = w;
	v_mov_b32_e32 v146, v206
	v_mov_b32_e32 v147, v207
	v_mov_b32_e32 v148, v208
	v_mov_b32_e32 v149, v209
	v_lshlrev_b64 v[100:101], 10, v[102:103]
	v_lshl_add_u64 v[100:101], s[18:19], 0, v[100:101]
	v_lshl_add_u64 v[100:101], v[100:101], 0, v[180:181]
	v_lshlrev_b32_e32 v141, 16, v146
	v_and_b32_e32 v150, 0xffff0000, v146
	v_lshlrev_b32_e32 v151, 16, v147
	v_and_b32_e32 v152, 0xffff0000, v147
	v_lshlrev_b32_e32 v134, 16, v148
	v_and_b32_e32 v126, 0xffff0000, v148
	v_lshlrev_b32_e32 v118, 16, v149
	v_and_b32_e32 v110, 0xffff0000, v149
	v_mov_b32_e32 v146, v210
	v_mov_b32_e32 v147, v211
	v_mov_b32_e32 v148, v212
	v_mov_b32_e32 v149, v213
	v_lshlrev_b32_e32 v153, 16, v146
	v_and_b32_e32 v154, 0xffff0000, v146
	v_exp_f32_e32 v146, v92
	v_mul_f32_e32 v92, 0xbfb8aa3b, v141
	v_lshlrev_b32_e32 v155, 16, v147
	v_and_b32_e32 v156, 0xffff0000, v147
	v_exp_f32_e32 v147, v92
	v_lshlrev_b32_e32 v135, 16, v148
	v_and_b32_e32 v127, 0xffff0000, v148
	v_lshlrev_b32_e32 v119, 16, v149
	v_pk_add_f32 v[146:147], v[146:147], 1.0 op_sel_hi:[1,0]
	v_and_b32_e32 v111, 0xffff0000, v149
	v_div_scale_f32 v92, s[0:1], v147, v147, v141
	v_rcp_f32_e32 v148, v92
	s_nop 0
	v_fma_f32 v149, -v92, v148, 1.0
	v_fmac_f32_e32 v148, v149, v148
	v_div_scale_f32 v149, vcc, v141, v147, v141
	v_mul_f32_e32 v157, v149, v148
	v_fma_f32 v158, -v92, v157, v149
	v_fmac_f32_e32 v157, v158, v148
	v_fma_f32 v92, -v92, v157, v149
	v_div_fmas_f32 v92, v92, v148, v157
	v_div_fixup_f32 v92, v92, v147, v141
	v_div_scale_f32 v141, s[0:1], v146, v146, 1.0
	v_rcp_f32_e32 v147, v141
	s_nop 0
	v_fma_f32 v148, -v141, v147, 1.0
	v_fmac_f32_e32 v147, v148, v147
	v_div_scale_f32 v148, vcc, 1.0, v146, 1.0
	v_mul_f32_e32 v149, v148, v147
	v_fma_f32 v157, -v141, v149, v148
	v_fmac_f32_e32 v149, v157, v147
	v_fma_f32 v141, -v141, v149, v148
	v_div_fmas_f32 v141, v141, v147, v149
	v_div_fixup_f32 v141, v141, v146, 1.0
	v_exp_f32_e32 v146, v93
	v_mul_f32_e32 v93, 0xbfb8aa3b, v150
	v_exp_f32_e32 v147, v93
	v_mul_f32_e32 v141, v141, v153
	v_mul_f32_e32 v92, v141, v92
	v_pk_add_f32 v[146:147], v[146:147], 1.0 op_sel_hi:[1,0]
	s_nop 0
	v_div_scale_f32 v93, s[0:1], v147, v147, v150
	v_rcp_f32_e32 v141, v93
	s_nop 0
	v_fma_f32 v148, -v93, v141, 1.0
	v_fmac_f32_e32 v141, v148, v141
	v_div_scale_f32 v148, vcc, v150, v147, v150
	v_mul_f32_e32 v149, v148, v141
	v_fma_f32 v153, -v93, v149, v148
	v_fmac_f32_e32 v149, v153, v141
	v_fma_f32 v93, -v93, v149, v148
	v_div_fmas_f32 v93, v93, v141, v149
	v_div_scale_f32 v141, s[0:1], v146, v146, 1.0
	v_div_fixup_f32 v93, v93, v147, v150
	v_rcp_f32_e32 v147, v141
	s_nop 0
	v_fma_f32 v148, -v141, v147, 1.0
	v_fmac_f32_e32 v147, v148, v147
	v_div_scale_f32 v148, vcc, 1.0, v146, 1.0
	v_mul_f32_e32 v149, v148, v147
	v_fma_f32 v150, -v141, v149, v148
	v_fmac_f32_e32 v149, v150, v147
	v_fma_f32 v141, -v141, v149, v148
	v_div_fmas_f32 v141, v141, v147, v149
	v_div_fixup_f32 v141, v141, v146, 1.0
	v_exp_f32_e32 v146, v94
	v_mul_f32_e32 v94, 0xbfb8aa3b, v151
	v_exp_f32_e32 v147, v94
	v_mul_f32_e32 v141, v141, v154
	v_mul_f32_e32 v93, v141, v93
	v_pk_add_f32 v[146:147], v[146:147], 1.0 op_sel_hi:[1,0]
	s_nop 0
	v_div_scale_f32 v94, s[0:1], v147, v147, v151
	v_rcp_f32_e32 v141, v94
	s_nop 0
	v_fma_f32 v148, -v94, v141, 1.0
	v_fmac_f32_e32 v141, v148, v141
	v_div_scale_f32 v148, vcc, v151, v147, v151
	v_mul_f32_e32 v149, v148, v141
	v_fma_f32 v150, -v94, v149, v148
	v_fmac_f32_e32 v149, v150, v141
	v_fma_f32 v94, -v94, v149, v148
	v_div_fmas_f32 v94, v94, v141, v149
	v_div_scale_f32 v141, s[0:1], v146, v146, 1.0
	v_div_fixup_f32 v94, v94, v147, v151
	v_rcp_f32_e32 v147, v141
	s_nop 0
	v_fma_f32 v148, -v141, v147, 1.0
	v_fmac_f32_e32 v147, v148, v147
	v_div_scale_f32 v148, vcc, 1.0, v146, 1.0
	v_mul_f32_e32 v149, v148, v147
	v_fma_f32 v150, -v141, v149, v148
	v_fmac_f32_e32 v149, v150, v147
	v_fma_f32 v141, -v141, v149, v148
	v_div_fmas_f32 v141, v141, v147, v149
	v_div_fixup_f32 v141, v141, v146, 1.0
	v_exp_f32_e32 v146, v95
	v_mul_f32_e32 v95, 0xbfb8aa3b, v152
	v_exp_f32_e32 v147, v95
	v_mul_f32_e32 v141, v141, v155
	v_mul_f32_e32 v94, v141, v94
	v_pk_add_f32 v[146:147], v[146:147], 1.0 op_sel_hi:[1,0]
	s_nop 0
	v_div_scale_f32 v95, s[0:1], v147, v147, v152
	v_rcp_f32_e32 v141, v95
	s_nop 0
	v_fma_f32 v148, -v95, v141, 1.0
	v_fmac_f32_e32 v141, v148, v141
	v_div_scale_f32 v148, vcc, v152, v147, v152
	v_mul_f32_e32 v149, v148, v141
	v_fma_f32 v150, -v95, v149, v148
	v_fmac_f32_e32 v149, v150, v141
	v_fma_f32 v95, -v95, v149, v148
	v_div_fmas_f32 v95, v95, v141, v149
	v_div_scale_f32 v141, s[0:1], v146, v146, 1.0
	v_div_fixup_f32 v95, v95, v147, v152
	v_rcp_f32_e32 v147, v141
	s_nop 0
	v_fma_f32 v148, -v141, v147, 1.0
	v_fmac_f32_e32 v147, v148, v147
	v_div_scale_f32 v148, vcc, 1.0, v146, 1.0
	v_mul_f32_e32 v149, v148, v147
	v_fma_f32 v150, -v141, v149, v148
	v_fmac_f32_e32 v149, v150, v147
	v_fma_f32 v141, -v141, v149, v148
	v_div_fmas_f32 v141, v141, v147, v149
	v_div_fixup_f32 v141, v141, v146, 1.0
	v_exp_f32_e32 v146, v88
	v_mul_f32_e32 v88, 0xbfb8aa3b, v134
	v_exp_f32_e32 v147, v88
	v_mul_f32_e32 v141, v141, v156
	v_mul_f32_e32 v95, v141, v95
	v_pk_add_f32 v[146:147], v[146:147], 1.0 op_sel_hi:[1,0]
	s_nop 0
	v_div_scale_f32 v88, s[0:1], v147, v147, v134
	v_rcp_f32_e32 v141, v88
	s_nop 0
	v_fma_f32 v148, -v88, v141, 1.0
	v_fmac_f32_e32 v141, v148, v141
	v_div_scale_f32 v148, vcc, v134, v147, v134
	v_mul_f32_e32 v149, v148, v141
	v_fma_f32 v150, -v88, v149, v148
	v_fmac_f32_e32 v149, v150, v141
	v_fma_f32 v88, -v88, v149, v148
	v_div_fmas_f32 v88, v88, v141, v149
	v_div_fixup_f32 v88, v88, v147, v134
	v_div_scale_f32 v134, s[0:1], v146, v146, 1.0
	v_rcp_f32_e32 v141, v134
	s_nop 0
; __device__ __forceinline__ unsigned cvt_pk_bf16(float lo, float hi) { unsigned r; asm volatile("v_cvt_pk_bf16_f32 %0, %1, %2" : "=v"(r) : "v"(lo), "v"(hi)); return r; }
; __device__ __forceinline__ float sigmoidf_(float v) { return 1.f / (1.f + __expf(-v)); }
; __device__ __forceinline__ float siluf_(float v) { return v / (1.f + __expf(-v)); }
;     __device__ __forceinline__ void operator()(const f32x4 (&acc)[2][2][4][2], const Unit& u, int wr, int wc, int fr, int fq) const {
;     ...
;                     const size_t row = (size_t)(row0 + ai * HALF + m * 16);
;                     const f32x4 v0 = acc[ai][bj][m][0], v1 = acc[ai][bj][m][1];
;                     float a[8] = {v0[0], v0[1], v0[2], v0[3], v1[0], v1[1], v1[2], v1[3]}, g[8], o[8];
;                     unpack8(*(const u32x4*)(R + row * RLD + (MODE == 0 ? 2560 : 1536) + col0), g);
;                     if (MODE == 0) { float y[8]; unpack8(*(const u32x4*)(YG + row * 512 + col0), y);
; #pragma unroll
;                         for (int e = 0; e < 8; ++e) o[e] = y[e] * sigmoidf_(a[e] + bb[e]) * siluf_(g[e]); }
;                     else {
; #pragma unroll
;                         for (int e = 0; e < 8; ++e) o[e] = a[e] * bb[e] * siluf_(g[e]); }
;                     u32x4 w; w.x = cvt_pk_bf16(o[0], o[1]); w.y = cvt_pk_bf16(o[2], o[3]); w.z = cvt_pk_bf16(o[4], o[5]); w.w = cvt_pk_bf16(o[6], o[7]);
;                     *(u32x4*)(Y + row * DM + (MODE == 0 ? 1536 : 1024) + col0) = w;
	v_fma_f32 v147, -v134, v141, 1.0
	v_fmac_f32_e32 v141, v147, v141
	v_div_scale_f32 v147, vcc, 1.0, v146, 1.0
	v_mul_f32_e32 v148, v147, v141
	v_fma_f32 v149, -v134, v148, v147
	v_fmac_f32_e32 v148, v149, v141
	v_fma_f32 v134, -v134, v148, v147
	v_div_fmas_f32 v134, v134, v141, v148
	v_div_fixup_f32 v134, v134, v146, 1.0
	v_mul_f32_e32 v134, v134, v135
	v_mul_f32_e32 v134, v134, v88
	v_add_f32_e32 v88, v89, v73
	v_mul_f32_e32 v88, 0xbfb8aa3b, v88
	v_mul_f32_e32 v89, 0xbfb8aa3b, v126
	v_exp_f32_e32 v88, v88
	v_exp_f32_e32 v89, v89
	s_nop 0
	v_pk_add_f32 v[88:89], v[88:89], 1.0 op_sel_hi:[1,0]
	s_nop 0
	v_div_scale_f32 v135, s[0:1], v89, v89, v126
	v_rcp_f32_e32 v141, v135
	s_nop 0
	v_fma_f32 v146, -v135, v141, 1.0
	v_fmac_f32_e32 v141, v146, v141
	v_div_scale_f32 v146, vcc, v126, v89, v126
	v_mul_f32_e32 v147, v146, v141
	v_fma_f32 v148, -v135, v147, v146
	v_fmac_f32_e32 v147, v148, v141
	v_fma_f32 v135, -v135, v147, v146
	v_div_fmas_f32 v135, v135, v141, v147
	v_div_fixup_f32 v89, v135, v89, v126
	v_div_scale_f32 v126, s[0:1], v88, v88, 1.0
	v_rcp_f32_e32 v135, v126
	s_nop 0
	v_fma_f32 v141, -v126, v135, 1.0
	v_fmac_f32_e32 v135, v141, v135
	v_div_scale_f32 v141, vcc, 1.0, v88, 1.0
	v_mul_f32_e32 v146, v141, v135
	v_fma_f32 v147, -v126, v146, v141
	v_fmac_f32_e32 v146, v147, v135
	v_fma_f32 v126, -v126, v146, v141
	v_div_fmas_f32 v126, v126, v135, v146
	v_div_fixup_f32 v88, v126, v88, 1.0
	v_mul_f32_e32 v88, v88, v127
	v_mul_f32_e32 v126, v88, v89
	v_add_f32_e32 v88, v90, v74
	v_mul_f32_e32 v88, 0xbfb8aa3b, v88
	v_mul_f32_e32 v89, 0xbfb8aa3b, v118
	v_exp_f32_e32 v88, v88
	v_exp_f32_e32 v89, v89
	s_nop 0
	v_pk_add_f32 v[88:89], v[88:89], 1.0 op_sel_hi:[1,0]
	s_nop 0
	v_div_scale_f32 v90, s[0:1], v89, v89, v118
	v_rcp_f32_e32 v127, v90
	s_nop 0
	v_fma_f32 v135, -v90, v127, 1.0
	v_fmac_f32_e32 v127, v135, v127
	v_div_scale_f32 v135, vcc, v118, v89, v118
	v_mul_f32_e32 v141, v135, v127
	v_fma_f32 v146, -v90, v141, v135
	v_fmac_f32_e32 v141, v146, v127
	v_fma_f32 v90, -v90, v141, v135
	v_div_fmas_f32 v90, v90, v127, v141
	v_div_fixup_f32 v89, v90, v89, v118
	v_div_scale_f32 v90, s[0:1], v88, v88, 1.0
	v_rcp_f32_e32 v118, v90
	s_nop 0
	v_fma_f32 v127, -v90, v118, 1.0
	v_fmac_f32_e32 v118, v127, v118
	v_div_scale_f32 v127, vcc, 1.0, v88, 1.0
	v_mul_f32_e32 v135, v127, v118
	v_fma_f32 v141, -v90, v135, v127
	v_fmac_f32_e32 v135, v141, v118
	v_fma_f32 v90, -v90, v135, v127
	v_div_fmas_f32 v90, v90, v118, v135
	v_div_fixup_f32 v88, v90, v88, 1.0
	v_mul_f32_e32 v88, v88, v119
	v_mul_f32_e32 v118, v88, v89
	v_add_f32_e32 v88, v91, v75
	v_mul_f32_e32 v88, 0xbfb8aa3b, v88
	v_mul_f32_e32 v89, 0xbfb8aa3b, v110
	v_exp_f32_e32 v88, v88
	v_exp_f32_e32 v89, v89
	s_nop 0
	v_pk_add_f32 v[88:89], v[88:89], 1.0 op_sel_hi:[1,0]
	s_nop 0
	v_div_scale_f32 v90, s[0:1], v89, v89, v110
	v_rcp_f32_e32 v91, v90
	s_nop 0
	v_fma_f32 v119, -v90, v91, 1.0
	v_fmac_f32_e32 v91, v119, v91
	v_div_scale_f32 v119, vcc, v110, v89, v110
	v_mul_f32_e32 v127, v119, v91
	v_fma_f32 v135, -v90, v127, v119
	v_fmac_f32_e32 v127, v135, v91
	v_fma_f32 v90, -v90, v127, v119
	v_div_fmas_f32 v90, v90, v91, v127
	v_div_fixup_f32 v89, v90, v89, v110
	v_div_scale_f32 v90, s[0:1], v88, v88, 1.0
	v_rcp_f32_e32 v91, v90
	s_nop 0
	v_fma_f32 v110, -v90, v91, 1.0
	v_fmac_f32_e32 v91, v110, v91
	v_div_scale_f32 v110, vcc, 1.0, v88, 1.0
	v_mul_f32_e32 v119, v110, v91
	v_fma_f32 v127, -v90, v119, v110
	v_fmac_f32_e32 v119, v127, v91
	v_fma_f32 v90, -v90, v119, v110
	v_div_fmas_f32 v90, v90, v91, v119
	v_div_fixup_f32 v88, v90, v88, 1.0
	v_mul_f32_e32 v88, v88, v111
	v_mul_f32_e32 v88, v88, v89
	v_cvt_pk_bf16_f32 v90, v92, v93
	v_cvt_pk_bf16_f32 v91, v94, v95
	v_cvt_pk_bf16_f32 v92, v134, v126
	v_cvt_pk_bf16_f32 v93, v118, v88
	v_lshlrev_b64 v[88:89], 12, v[102:103]
	v_lshl_add_u64 v[88:89], s[12:13], 0, v[88:89]
	v_lshl_add_u64 v[88:89], v[88:89], 0, v[180:181]
	v_add_u32_e32 v94, 0xa0, v140
	global_store_dwordx4 v[88:89], v[90:93], off offset:3072
	s_add_u32 s0, s14, 0x0
	s_addc_u32 s1, s15, 0
	global_load_dwordx4 v[206:209], v214, s[0:1] offset:256
	s_add_u32 s0, s18, 0x0
	s_addc_u32 s1, s19, 0
	global_load_dwordx4 v[210:213], v215, s[0:1] offset:256
	v_ashrrev_i32_e32 v95, 31, v94
	v_exp_f32_e32 v134, v84
	v_mad_i64_i32 v[90:91], s[0:1], v94, s4, v[142:143]
	v_lshl_add_u64 v[90:91], v[90:91], 0, s[6:7]
	v_lshl_add_u64 v[92:93], v[90:91], 0, v[180:181]
	s_waitcnt vmcnt(6)
; __device__ __forceinline__ unsigned cvt_pk_bf16(float lo, float hi) { unsigned r; asm volatile("v_cvt_pk_bf16_f32 %0, %1, %2" : "=v"(r) : "v"(lo), "v"(hi)); return r; }
; __device__ __forceinline__ float sigmoidf_(float v) { return 1.f / (1.f + __expf(-v)); }
; __device__ __forceinline__ float siluf_(float v) { return v / (1.f + __expf(-v)); }
;     __device__ __forceinline__ void operator()(const f32x4 (&acc)[2][2][4][2], const Unit& u, int wr, int wc, int fr, int fq) const {
;     ...
;                     const size_t row = (size_t)(row0 + ai * HALF + m * 16);
;                     const f32x4 v0 = acc[ai][bj][m][0], v1 = acc[ai][bj][m][1];
;                     float a[8] = {v0[0], v0[1], v0[2], v0[3], v1[0], v1[1], v1[2], v1[3]}, g[8], o[8];
;                     unpack8(*(const u32x4*)(R + row * RLD + (MODE == 0 ? 2560 : 1536) + col0), g);
;                     if (MODE == 0) { float y[8]; unpack8(*(const u32x4*)(YG + row * 512 + col0), y);
; #pragma unroll
;                         for (int e = 0; e < 8; ++e) o[e] = y[e] * sigmoidf_(a[e] + bb[e]) * siluf_(g[e]); }
;                     else {
; #pragma unroll
;                         for (int e = 0; e < 8; ++e) o[e] = a[e] * bb[e] * siluf_(g[e]); }
;                     u32x4 w; w.x = cvt_pk_bf16(o[0], o[1]); w.y = cvt_pk_bf16(o[2], o[3]); w.z = cvt_pk_bf16(o[4], o[5]); w.w = cvt_pk_bf16(o[6], o[7]);
;                     *(u32x4*)(Y + row * DM + (MODE == 0 ? 1536 : 1024) + col0) = w;
	v_mov_b32_e32 v146, v168
	v_mov_b32_e32 v147, v169
	v_mov_b32_e32 v148, v170
	v_mov_b32_e32 v149, v171
	v_lshlrev_b64 v[92:93], 10, v[94:95]
	v_lshl_add_u64 v[92:93], s[18:19], 0, v[92:93]
	v_lshl_add_u64 v[92:93], v[92:93], 0, v[180:181]
	v_lshlrev_b32_e32 v141, 16, v146
	v_and_b32_e32 v150, 0xffff0000, v146
	v_lshlrev_b32_e32 v151, 16, v147
	v_and_b32_e32 v152, 0xffff0000, v147
	v_lshlrev_b32_e32 v126, 16, v148
	v_and_b32_e32 v118, 0xffff0000, v148
	v_lshlrev_b32_e32 v110, 16, v149
	v_and_b32_e32 v102, 0xffff0000, v149
	v_mov_b32_e32 v146, v172
	v_mov_b32_e32 v147, v173
	v_mov_b32_e32 v148, v174
	v_mov_b32_e32 v149, v175
	v_mul_f32_e32 v84, 0xbfb8aa3b, v141
	v_exp_f32_e32 v135, v84
	v_lshlrev_b32_e32 v127, 16, v148
	v_pk_add_f32 v[134:135], v[134:135], 1.0 op_sel_hi:[1,0]
	v_and_b32_e32 v119, 0xffff0000, v148
	v_div_scale_f32 v84, s[0:1], v135, v135, v141
	v_rcp_f32_e32 v148, v84
	v_lshlrev_b32_e32 v111, 16, v149
	v_and_b32_e32 v103, 0xffff0000, v149
	v_lshlrev_b32_e32 v153, 16, v146
	v_fma_f32 v149, -v84, v148, 1.0
	v_fmac_f32_e32 v148, v149, v148
	v_div_scale_f32 v149, vcc, v141, v135, v141
	v_mul_f32_e32 v155, v149, v148
	v_fma_f32 v156, -v84, v155, v149
	v_fmac_f32_e32 v155, v156, v148
	v_fma_f32 v84, -v84, v155, v149
	v_div_fmas_f32 v84, v84, v148, v155
	v_div_fixup_f32 v84, v84, v135, v141
	v_div_scale_f32 v135, s[0:1], v134, v134, 1.0
	v_rcp_f32_e32 v141, v135
	v_and_b32_e32 v146, 0xffff0000, v146
	v_lshlrev_b32_e32 v154, 16, v147
	v_and_b32_e32 v147, 0xffff0000, v147
	v_fma_f32 v148, -v135, v141, 1.0
	v_fmac_f32_e32 v141, v148, v141
	v_div_scale_f32 v148, vcc, 1.0, v134, 1.0
	v_mul_f32_e32 v149, v148, v141
	v_fma_f32 v155, -v135, v149, v148
	v_fmac_f32_e32 v149, v155, v141
	v_fma_f32 v135, -v135, v149, v148
	v_div_fmas_f32 v135, v135, v141, v149
	v_div_fixup_f32 v134, v135, v134, 1.0
	v_mul_f32_e32 v134, v134, v153
	v_mul_f32_e32 v84, v134, v84
	v_exp_f32_e32 v134, v85
	v_mul_f32_e32 v85, 0xbfb8aa3b, v150
	v_exp_f32_e32 v135, v85
	s_nop 0
	v_pk_add_f32 v[134:135], v[134:135], 1.0 op_sel_hi:[1,0]
	s_nop 0
	v_div_scale_f32 v85, s[0:1], v135, v135, v150
	v_rcp_f32_e32 v141, v85
	s_nop 0
	v_fma_f32 v148, -v85, v141, 1.0
	v_fmac_f32_e32 v141, v148, v141
	v_div_scale_f32 v148, vcc, v150, v135, v150
	v_mul_f32_e32 v149, v148, v141
	v_fma_f32 v153, -v85, v149, v148
	v_fmac_f32_e32 v149, v153, v141
	v_fma_f32 v85, -v85, v149, v148
	v_div_fmas_f32 v85, v85, v141, v149
	v_div_fixup_f32 v85, v85, v135, v150
	v_div_scale_f32 v135, s[0:1], v134, v134, 1.0
	v_rcp_f32_e32 v141, v135
	s_nop 0
	v_fma_f32 v148, -v135, v141, 1.0
	v_fmac_f32_e32 v141, v148, v141
	v_div_scale_f32 v148, vcc, 1.0, v134, 1.0
	v_mul_f32_e32 v149, v148, v141
	v_fma_f32 v150, -v135, v149, v148
	v_fmac_f32_e32 v149, v150, v141
	v_fma_f32 v135, -v135, v149, v148
	v_div_fmas_f32 v135, v135, v141, v149
	v_div_fixup_f32 v134, v135, v134, 1.0
	v_mul_f32_e32 v134, v134, v146
	v_mul_f32_e32 v85, v134, v85
	v_exp_f32_e32 v134, v86
	v_mul_f32_e32 v86, 0xbfb8aa3b, v151
	v_exp_f32_e32 v135, v86
	v_cvt_pk_bf16_f32 v84, v84, v85
	s_nop 0
	v_pk_add_f32 v[134:135], v[134:135], 1.0 op_sel_hi:[1,0]
	s_nop 0
	v_div_scale_f32 v86, s[0:1], v135, v135, v151
	v_rcp_f32_e32 v141, v86
	s_nop 0
	v_fma_f32 v146, -v86, v141, 1.0
	v_fmac_f32_e32 v141, v146, v141
	v_div_scale_f32 v146, vcc, v151, v135, v151
	v_mul_f32_e32 v148, v146, v141
	v_fma_f32 v149, -v86, v148, v146
	v_fmac_f32_e32 v148, v149, v141
	v_fma_f32 v86, -v86, v148, v146
	v_div_fmas_f32 v86, v86, v141, v148
	v_div_fixup_f32 v86, v86, v135, v151
	v_div_scale_f32 v135, s[0:1], v134, v134, 1.0
	v_rcp_f32_e32 v141, v135
	s_nop 0
	v_fma_f32 v146, -v135, v141, 1.0
	v_fmac_f32_e32 v141, v146, v141
	v_div_scale_f32 v146, vcc, 1.0, v134, 1.0
	v_mul_f32_e32 v148, v146, v141
	v_fma_f32 v149, -v135, v148, v146
	v_fmac_f32_e32 v148, v149, v141
	v_fma_f32 v135, -v135, v148, v146
	v_div_fmas_f32 v135, v135, v141, v148
	v_div_fixup_f32 v134, v135, v134, 1.0
	v_mul_f32_e32 v134, v134, v154
	v_mul_f32_e32 v86, v134, v86
	v_exp_f32_e32 v134, v87
	v_mul_f32_e32 v87, 0xbfb8aa3b, v152
	v_exp_f32_e32 v135, v87
	s_nop 0
	v_pk_add_f32 v[134:135], v[134:135], 1.0 op_sel_hi:[1,0]
	s_nop 0
	v_div_scale_f32 v87, s[0:1], v135, v135, v152
	v_rcp_f32_e32 v141, v87
	s_nop 0
	v_fma_f32 v146, -v87, v141, 1.0
	v_fmac_f32_e32 v141, v146, v141
	v_div_scale_f32 v146, vcc, v152, v135, v152
	v_mul_f32_e32 v148, v146, v141
	v_fma_f32 v149, -v87, v148, v146
	v_fmac_f32_e32 v148, v149, v141
	v_fma_f32 v87, -v87, v148, v146
	v_div_fmas_f32 v87, v87, v141, v148
	v_div_fixup_f32 v87, v87, v135, v152
	v_div_scale_f32 v135, s[0:1], v134, v134, 1.0
	v_rcp_f32_e32 v141, v135
	s_nop 0
	v_fma_f32 v146, -v135, v141, 1.0
	v_fmac_f32_e32 v141, v146, v141
	v_div_scale_f32 v146, vcc, 1.0, v134, 1.0
	v_mul_f32_e32 v148, v146, v141
	v_fma_f32 v149, -v135, v148, v146
	v_fmac_f32_e32 v148, v149, v141
	v_fma_f32 v135, -v135, v148, v146
	v_div_fmas_f32 v135, v135, v141, v148
	v_div_fixup_f32 v134, v135, v134, 1.0
	v_mul_f32_e32 v134, v134, v147
	v_mul_f32_e32 v87, v134, v87
	v_exp_f32_e32 v134, v76
	v_mul_f32_e32 v76, 0xbfb8aa3b, v126
	v_exp_f32_e32 v135, v76
	v_cvt_pk_bf16_f32 v85, v86, v87
	s_nop 0
	v_pk_add_f32 v[134:135], v[134:135], 1.0 op_sel_hi:[1,0]
	s_nop 0
	v_div_scale_f32 v76, s[0:1], v135, v135, v126
	v_rcp_f32_e32 v141, v76
	s_nop 0
	v_fma_f32 v146, -v76, v141, 1.0
	v_fmac_f32_e32 v141, v146, v141
	v_div_scale_f32 v146, vcc, v126, v135, v126
	v_mul_f32_e32 v147, v146, v141
	v_fma_f32 v148, -v76, v147, v146
	v_fmac_f32_e32 v147, v148, v141
	v_fma_f32 v76, -v76, v147, v146
	v_div_fmas_f32 v76, v76, v141, v147
	v_div_fixup_f32 v76, v76, v135, v126
	v_div_scale_f32 v126, s[0:1], v134, v134, 1.0
; __device__ __forceinline__ unsigned cvt_pk_bf16(float lo, float hi) { unsigned r; asm volatile("v_cvt_pk_bf16_f32 %0, %1, %2" : "=v"(r) : "v"(lo), "v"(hi)); return r; }
; __device__ __forceinline__ float sigmoidf_(float v) { return 1.f / (1.f + __expf(-v)); }
; __device__ __forceinline__ float siluf_(float v) { return v / (1.f + __expf(-v)); }
;     __device__ __forceinline__ void operator()(const f32x4 (&acc)[2][2][4][2], const Unit& u, int wr, int wc, int fr, int fq) const {
;     ...
;                     const size_t row = (size_t)(row0 + ai * HALF + m * 16);
;                     const f32x4 v0 = acc[ai][bj][m][0], v1 = acc[ai][bj][m][1];
;                     float a[8] = {v0[0], v0[1], v0[2], v0[3], v1[0], v1[1], v1[2], v1[3]}, g[8], o[8];
;                     unpack8(*(const u32x4*)(R + row * RLD + (MODE == 0 ? 2560 : 1536) + col0), g);
;                     if (MODE == 0) { float y[8]; unpack8(*(const u32x4*)(YG + row * 512 + col0), y);
; #pragma unroll
;                         for (int e = 0; e < 8; ++e) o[e] = y[e] * sigmoidf_(a[e] + bb[e]) * siluf_(g[e]); }
;                     else {
; #pragma unroll
;                         for (int e = 0; e < 8; ++e) o[e] = a[e] * bb[e] * siluf_(g[e]); }
;                     u32x4 w; w.x = cvt_pk_bf16(o[0], o[1]); w.y = cvt_pk_bf16(o[2], o[3]); w.z = cvt_pk_bf16(o[4], o[5]); w.w = cvt_pk_bf16(o[6], o[7]);
;                     *(u32x4*)(Y + row * DM + (MODE == 0 ? 1536 : 1024) + col0) = w;
	v_rcp_f32_e32 v135, v126
	s_nop 0
	v_fma_f32 v141, -v126, v135, 1.0
	v_fmac_f32_e32 v135, v141, v135
	v_div_scale_f32 v141, vcc, 1.0, v134, 1.0
	v_mul_f32_e32 v146, v141, v135
	v_fma_f32 v147, -v126, v146, v141
	v_fmac_f32_e32 v146, v147, v135
	v_fma_f32 v126, -v126, v146, v141
	v_div_fmas_f32 v126, v126, v135, v146
	v_div_fixup_f32 v126, v126, v134, 1.0
	v_mul_f32_e32 v126, v126, v127
	v_mul_f32_e32 v126, v126, v76
	v_add_f32_e32 v76, v77, v73
	v_mul_f32_e32 v76, 0xbfb8aa3b, v76
	v_mul_f32_e32 v77, 0xbfb8aa3b, v118
	v_exp_f32_e32 v76, v76
	v_exp_f32_e32 v77, v77
	s_nop 0
	v_pk_add_f32 v[76:77], v[76:77], 1.0 op_sel_hi:[1,0]
	s_nop 0
	v_div_scale_f32 v127, s[0:1], v77, v77, v118
	v_rcp_f32_e32 v134, v127
	s_nop 0
	v_fma_f32 v135, -v127, v134, 1.0
	v_fmac_f32_e32 v134, v135, v134
	v_div_scale_f32 v135, vcc, v118, v77, v118
	v_mul_f32_e32 v141, v135, v134
	v_fma_f32 v146, -v127, v141, v135
	v_fmac_f32_e32 v141, v146, v134
	v_fma_f32 v127, -v127, v141, v135
	v_div_fmas_f32 v127, v127, v134, v141
	v_div_fixup_f32 v77, v127, v77, v118
	v_div_scale_f32 v118, s[0:1], v76, v76, 1.0
	v_rcp_f32_e32 v127, v118
	s_nop 0
	v_fma_f32 v134, -v118, v127, 1.0
	v_fmac_f32_e32 v127, v134, v127
	v_div_scale_f32 v134, vcc, 1.0, v76, 1.0
	v_mul_f32_e32 v135, v134, v127
	v_fma_f32 v141, -v118, v135, v134
	v_fmac_f32_e32 v135, v141, v127
	v_fma_f32 v118, -v118, v135, v134
	v_div_fmas_f32 v118, v118, v127, v135
	v_div_fixup_f32 v76, v118, v76, 1.0
	v_mul_f32_e32 v76, v76, v119
	v_mul_f32_e32 v118, v76, v77
	v_add_f32_e32 v76, v78, v74
	v_mul_f32_e32 v76, 0xbfb8aa3b, v76
	v_mul_f32_e32 v77, 0xbfb8aa3b, v110
	v_exp_f32_e32 v76, v76
	v_exp_f32_e32 v77, v77
	v_cvt_pk_bf16_f32 v86, v126, v118
	v_exp_f32_e32 v126, v68
	v_pk_add_f32 v[76:77], v[76:77], 1.0 op_sel_hi:[1,0]
	s_nop 0
	v_div_scale_f32 v78, s[0:1], v77, v77, v110
	v_rcp_f32_e32 v119, v78
	s_nop 0
	v_fma_f32 v127, -v78, v119, 1.0
	v_fmac_f32_e32 v119, v127, v119
	v_div_scale_f32 v127, vcc, v110, v77, v110
	v_mul_f32_e32 v134, v127, v119
	v_fma_f32 v135, -v78, v134, v127
	v_fmac_f32_e32 v134, v135, v119
	v_fma_f32 v78, -v78, v134, v127
	v_div_fmas_f32 v78, v78, v119, v134
	v_div_fixup_f32 v77, v78, v77, v110
	v_div_scale_f32 v78, s[0:1], v76, v76, 1.0
	v_rcp_f32_e32 v110, v78
	s_nop 0
	v_fma_f32 v119, -v78, v110, 1.0
	v_fmac_f32_e32 v110, v119, v110
	v_div_scale_f32 v119, vcc, 1.0, v76, 1.0
	v_mul_f32_e32 v127, v119, v110
	v_fma_f32 v134, -v78, v127, v119
	v_fmac_f32_e32 v127, v134, v110
	v_fma_f32 v78, -v78, v127, v119
	v_div_fmas_f32 v78, v78, v110, v127
	v_div_fixup_f32 v76, v78, v76, 1.0
	v_mul_f32_e32 v76, v76, v111
	v_mul_f32_e32 v78, v76, v77
	v_add_f32_e32 v76, v79, v75
	v_mul_f32_e32 v76, 0xbfb8aa3b, v76
	v_mul_f32_e32 v77, 0xbfb8aa3b, v102
	v_exp_f32_e32 v76, v76
	v_exp_f32_e32 v77, v77
	s_nop 0
	v_pk_add_f32 v[76:77], v[76:77], 1.0 op_sel_hi:[1,0]
	s_nop 0
	v_div_scale_f32 v79, s[0:1], v77, v77, v102
	v_rcp_f32_e32 v110, v79
	s_nop 0
	v_fma_f32 v111, -v79, v110, 1.0
	v_fmac_f32_e32 v110, v111, v110
	v_div_scale_f32 v111, vcc, v102, v77, v102
	v_mul_f32_e32 v119, v111, v110
	v_fma_f32 v127, -v79, v119, v111
	v_fmac_f32_e32 v119, v127, v110
	v_fma_f32 v79, -v79, v119, v111
	v_div_fmas_f32 v79, v79, v110, v119
	v_div_fixup_f32 v77, v79, v77, v102
	v_div_scale_f32 v79, s[0:1], v76, v76, 1.0
	v_rcp_f32_e32 v102, v79
	s_nop 0
	v_fma_f32 v110, -v79, v102, 1.0
	v_fmac_f32_e32 v102, v110, v102
	v_div_scale_f32 v110, vcc, 1.0, v76, 1.0
	v_mul_f32_e32 v111, v110, v102
	v_fma_f32 v119, -v79, v111, v110
	v_fmac_f32_e32 v111, v119, v102
	v_fma_f32 v79, -v79, v111, v110
	v_div_fmas_f32 v79, v79, v102, v111
	v_div_fixup_f32 v76, v79, v76, 1.0
	v_mul_f32_e32 v76, v76, v103
	v_mul_f32_e32 v76, v76, v77
	v_cvt_pk_bf16_f32 v87, v78, v76
	v_lshlrev_b64 v[76:77], 12, v[94:95]
	v_lshl_add_u64 v[76:77], s[12:13], 0, v[76:77]
	v_lshl_add_u64 v[76:77], v[76:77], 0, v[180:181]
	global_store_dwordx4 v[76:77], v[84:87], off offset:3072
	s_add_u32 s0, s14, 0x18000
	s_addc_u32 s1, s15, 0
	global_load_dwordx4 v[168:171], v214, s[0:1] offset:256
	s_add_u32 s0, s18, 0x4000
	s_addc_u32 s1, s19, 0
	global_load_dwordx4 v[172:175], v215, s[0:1] offset:256
	s_nop 1
	v_add_u32_e32 v86, 0xb0, v140
	v_mad_i64_i32 v[78:79], s[0:1], v86, s4, v[142:143]
	v_lshl_add_u64 v[78:79], v[78:79], 0, s[6:7]
	v_lshl_add_u64 v[84:85], v[78:79], 0, v[180:181]
	s_waitcnt vmcnt(6)
; __device__ __forceinline__ unsigned cvt_pk_bf16(float lo, float hi) { unsigned r; asm volatile("v_cvt_pk_bf16_f32 %0, %1, %2" : "=v"(r) : "v"(lo), "v"(hi)); return r; }
; __device__ __forceinline__ float sigmoidf_(float v) { return 1.f / (1.f + __expf(-v)); }
; __device__ __forceinline__ float siluf_(float v) { return v / (1.f + __expf(-v)); }
;     __device__ __forceinline__ void operator()(const f32x4 (&acc)[2][2][4][2], const Unit& u, int wr, int wc, int fr, int fq) const {
;     ...
;                     const size_t row = (size_t)(row0 + ai * HALF + m * 16);
;                     const f32x4 v0 = acc[ai][bj][m][0], v1 = acc[ai][bj][m][1];
;                     float a[8] = {v0[0], v0[1], v0[2], v0[3], v1[0], v1[1], v1[2], v1[3]}, g[8], o[8];
;                     unpack8(*(const u32x4*)(R + row * RLD + (MODE == 0 ? 2560 : 1536) + col0), g);
;                     if (MODE == 0) { float y[8]; unpack8(*(const u32x4*)(YG + row * 512 + col0), y);
; #pragma unroll
;                         for (int e = 0; e < 8; ++e) o[e] = y[e] * sigmoidf_(a[e] + bb[e]) * siluf_(g[e]); }
;                     else {
; #pragma unroll
;                         for (int e = 0; e < 8; ++e) o[e] = a[e] * bb[e] * siluf_(g[e]); }
;                     u32x4 w; w.x = cvt_pk_bf16(o[0], o[1]); w.y = cvt_pk_bf16(o[2], o[3]); w.z = cvt_pk_bf16(o[4], o[5]); w.w = cvt_pk_bf16(o[6], o[7]);
;                     *(u32x4*)(Y + row * DM + (MODE == 0 ? 1536 : 1024) + col0) = w;
	v_mov_b32_e32 v140, v188
	v_mov_b32_e32 v141, v189
	v_mov_b32_e32 v142, v190
	v_mov_b32_e32 v143, v191
	v_ashrrev_i32_e32 v87, 31, v86
	v_lshlrev_b64 v[84:85], 10, v[86:87]
	v_lshl_add_u64 v[84:85], s[18:19], 0, v[84:85]
	v_lshl_add_u64 v[84:85], v[84:85], 0, v[180:181]
	v_lshlrev_b32_e32 v134, 16, v140
	v_and_b32_e32 v135, 0xffff0000, v140
	v_lshlrev_b32_e32 v146, 16, v141
	v_and_b32_e32 v147, 0xffff0000, v141
	v_lshlrev_b32_e32 v118, 16, v142
	v_and_b32_e32 v110, 0xffff0000, v142
	v_lshlrev_b32_e32 v102, 16, v143
	v_and_b32_e32 v94, 0xffff0000, v143
	v_mov_b32_e32 v140, v196
	v_mov_b32_e32 v141, v197
	v_mov_b32_e32 v142, v198
	v_mov_b32_e32 v143, v199
	v_mul_f32_e32 v68, 0xbfb8aa3b, v134
	v_exp_f32_e32 v127, v68
	v_lshlrev_b32_e32 v119, 16, v142
	v_pk_add_f32 v[126:127], v[126:127], 1.0 op_sel_hi:[1,0]
	v_and_b32_e32 v111, 0xffff0000, v142
	v_div_scale_f32 v68, s[0:1], v127, v127, v134
	v_rcp_f32_e32 v80, v68
	v_lshlrev_b32_e32 v103, 16, v143
	v_and_b32_e32 v95, 0xffff0000, v143
	v_lshlrev_b32_e32 v148, 16, v140
	v_fma_f32 v142, -v68, v80, 1.0
	v_fmac_f32_e32 v80, v142, v80
	v_div_scale_f32 v142, vcc, v134, v127, v134
	v_mul_f32_e32 v143, v142, v80
	v_fma_f32 v150, -v68, v143, v142
	v_fmac_f32_e32 v143, v150, v80
	v_fma_f32 v68, -v68, v143, v142
	v_div_fmas_f32 v68, v68, v80, v143
	v_div_scale_f32 v80, s[0:1], v126, v126, 1.0
	v_div_fixup_f32 v68, v68, v127, v134
	v_rcp_f32_e32 v127, v80
	v_and_b32_e32 v140, 0xffff0000, v140
	v_lshlrev_b32_e32 v149, 16, v141
	v_and_b32_e32 v141, 0xffff0000, v141
	v_fma_f32 v134, -v80, v127, 1.0
	v_fmac_f32_e32 v127, v134, v127
	v_div_scale_f32 v134, vcc, 1.0, v126, 1.0
	v_mul_f32_e32 v142, v134, v127
	v_fma_f32 v143, -v80, v142, v134
	v_fmac_f32_e32 v142, v143, v127
	v_fma_f32 v80, -v80, v142, v134
	v_div_fmas_f32 v80, v80, v127, v142
	v_div_fixup_f32 v80, v80, v126, 1.0
	v_mul_f32_e32 v80, v80, v148
	v_mul_f32_e32 v68, v80, v68
	v_exp_f32_e32 v80, v69
	v_mul_f32_e32 v69, 0xbfb8aa3b, v135
	v_exp_f32_e32 v81, v69
	s_nop 0
	v_pk_add_f32 v[80:81], v[80:81], 1.0 op_sel_hi:[1,0]
	s_nop 0
	v_div_scale_f32 v69, s[0:1], v81, v81, v135
	v_rcp_f32_e32 v126, v69
	s_nop 0
	v_fma_f32 v127, -v69, v126, 1.0
	v_fmac_f32_e32 v126, v127, v126
	v_div_scale_f32 v127, vcc, v135, v81, v135
	v_mul_f32_e32 v134, v127, v126
	v_fma_f32 v142, -v69, v134, v127
	v_fmac_f32_e32 v134, v142, v126
	v_fma_f32 v69, -v69, v134, v127
	v_div_fmas_f32 v69, v69, v126, v134
	v_div_fixup_f32 v69, v69, v81, v135
	v_div_scale_f32 v81, s[0:1], v80, v80, 1.0
	v_rcp_f32_e32 v126, v81
	s_nop 0
	v_fma_f32 v127, -v81, v126, 1.0
	v_fmac_f32_e32 v126, v127, v126
	v_div_scale_f32 v127, vcc, 1.0, v80, 1.0
	v_mul_f32_e32 v134, v127, v126
	v_fma_f32 v135, -v81, v134, v127
	v_fmac_f32_e32 v134, v135, v126
	v_fma_f32 v81, -v81, v134, v127
	v_div_fmas_f32 v81, v81, v126, v134
	v_div_fixup_f32 v80, v81, v80, 1.0
	v_mul_f32_e32 v80, v80, v140
	v_mul_f32_e32 v69, v80, v69
	v_exp_f32_e32 v80, v70
	v_mul_f32_e32 v70, 0xbfb8aa3b, v146
	v_exp_f32_e32 v81, v70
	s_nop 0
	v_pk_add_f32 v[80:81], v[80:81], 1.0 op_sel_hi:[1,0]
	s_nop 0
	v_div_scale_f32 v70, s[0:1], v81, v81, v146
	v_rcp_f32_e32 v82, v70
	s_nop 0
	v_fma_f32 v126, -v70, v82, 1.0
	v_fmac_f32_e32 v82, v126, v82
	v_div_scale_f32 v126, vcc, v146, v81, v146
	v_mul_f32_e32 v127, v126, v82
	v_fma_f32 v134, -v70, v127, v126
	v_fmac_f32_e32 v127, v134, v82
	v_fma_f32 v70, -v70, v127, v126
	v_div_fmas_f32 v70, v70, v82, v127
	v_div_fixup_f32 v70, v70, v81, v146
	v_div_scale_f32 v81, s[0:1], v80, v80, 1.0
	v_rcp_f32_e32 v82, v81
	s_nop 0
	v_fma_f32 v126, -v81, v82, 1.0
	v_fmac_f32_e32 v82, v126, v82
	v_div_scale_f32 v126, vcc, 1.0, v80, 1.0
	v_mul_f32_e32 v127, v126, v82
	v_fma_f32 v134, -v81, v127, v126
	v_fmac_f32_e32 v127, v134, v82
	v_fma_f32 v81, -v81, v127, v126
	v_div_fmas_f32 v81, v81, v82, v127
	v_div_fixup_f32 v80, v81, v80, 1.0
	v_mul_f32_e32 v80, v80, v149
	v_mul_f32_e32 v70, v80, v70
	v_exp_f32_e32 v80, v71
	v_mul_f32_e32 v71, 0xbfb8aa3b, v147
	v_exp_f32_e32 v81, v71
	s_nop 0
	v_pk_add_f32 v[80:81], v[80:81], 1.0 op_sel_hi:[1,0]
	s_nop 0
	v_div_scale_f32 v71, s[0:1], v81, v81, v147
	v_rcp_f32_e32 v82, v71
	s_nop 0
	v_fma_f32 v83, -v71, v82, 1.0
	v_fmac_f32_e32 v82, v83, v82
	v_div_scale_f32 v83, vcc, v147, v81, v147
	v_mul_f32_e32 v126, v83, v82
	v_fma_f32 v127, -v71, v126, v83
	v_fmac_f32_e32 v126, v127, v82
	v_fma_f32 v71, -v71, v126, v83
	v_div_fmas_f32 v71, v71, v82, v126
	v_div_fixup_f32 v71, v71, v81, v147
	v_div_scale_f32 v81, s[0:1], v80, v80, 1.0
	v_rcp_f32_e32 v82, v81
	s_nop 0
	v_fma_f32 v83, -v81, v82, 1.0
	v_fmac_f32_e32 v82, v83, v82
	v_div_scale_f32 v83, vcc, 1.0, v80, 1.0
	v_mul_f32_e32 v126, v83, v82
	v_fma_f32 v127, -v81, v126, v83
	v_fmac_f32_e32 v126, v127, v82
	v_fma_f32 v81, -v81, v126, v83
	v_div_fmas_f32 v81, v81, v82, v126
	v_div_fixup_f32 v80, v81, v80, 1.0
	v_mul_f32_e32 v80, v80, v141
	v_mul_f32_e32 v71, v80, v71
	v_exp_f32_e32 v80, v64
	v_mul_f32_e32 v64, 0xbfb8aa3b, v118
	v_exp_f32_e32 v81, v64
	s_nop 0
	v_pk_add_f32 v[80:81], v[80:81], 1.0 op_sel_hi:[1,0]
	s_nop 0
	v_div_scale_f32 v64, s[0:1], v81, v81, v118
	v_rcp_f32_e32 v72, v64
	s_nop 0
	v_fma_f32 v82, -v64, v72, 1.0
	v_fmac_f32_e32 v72, v82, v72
	v_div_scale_f32 v82, vcc, v118, v81, v118
	v_mul_f32_e32 v83, v82, v72
	v_fma_f32 v126, -v64, v83, v82
	v_fmac_f32_e32 v83, v126, v72
	v_fma_f32 v64, -v64, v83, v82
	v_div_fmas_f32 v64, v64, v72, v83
	v_div_scale_f32 v72, s[0:1], v80, v80, 1.0
	v_div_fixup_f32 v64, v64, v81, v118
	v_rcp_f32_e32 v81, v72
	s_nop 0
	v_fma_f32 v82, -v72, v81, 1.0
	v_fmac_f32_e32 v81, v82, v81
	v_div_scale_f32 v82, vcc, 1.0, v80, 1.0
	v_mul_f32_e32 v83, v82, v81
	v_fma_f32 v118, -v72, v83, v82
; __device__ __forceinline__ unsigned cvt_pk_bf16(float lo, float hi) { unsigned r; asm volatile("v_cvt_pk_bf16_f32 %0, %1, %2" : "=v"(r) : "v"(lo), "v"(hi)); return r; }
; __device__ __forceinline__ float sigmoidf_(float v) { return 1.f / (1.f + __expf(-v)); }
; __device__ __forceinline__ float siluf_(float v) { return v / (1.f + __expf(-v)); }
;     __device__ __forceinline__ void operator()(const f32x4 (&acc)[2][2][4][2], const Unit& u, int wr, int wc, int fr, int fq) const {
;     ...
;             const int col0 = u.pn * BM + bj * HALF + wc * 32 + 8 * fq;
;             const f32x4 b0 = *(const f32x4*)(bias + col0), b1 = *(const f32x4*)(bias + col0 + 4);
;             float bb[8] = {b0[0], b0[1], b0[2], b0[3], b1[0], b1[1], b1[2], b1[3]};
; #pragma unroll
;             for (int ai = 0; ai < 2; ++ai) {
; #pragma unroll
;                 for (int m = 0; m < 4; ++m) {
;                     const size_t row = (size_t)(row0 + ai * HALF + m * 16);
;                     const f32x4 v0 = acc[ai][bj][m][0], v1 = acc[ai][bj][m][1];
;                     float a[8] = {v0[0], v0[1], v0[2], v0[3], v1[0], v1[1], v1[2], v1[3]}, g[8], o[8];
;                     unpack8(*(const u32x4*)(R + row * RLD + (MODE == 0 ? 2560 : 1536) + col0), g);
;                     if (MODE == 0) { float y[8]; unpack8(*(const u32x4*)(YG + row * 512 + col0), y);
; #pragma unroll
;                         for (int e = 0; e < 8; ++e) o[e] = y[e] * sigmoidf_(a[e] + bb[e]) * siluf_(g[e]); }
;                     else {
; #pragma unroll
;                         for (int e = 0; e < 8; ++e) o[e] = a[e] * bb[e] * siluf_(g[e]); }
;                     u32x4 w; w.x = cvt_pk_bf16(o[0], o[1]); w.y = cvt_pk_bf16(o[2], o[3]); w.z = cvt_pk_bf16(o[4], o[5]); w.w = cvt_pk_bf16(o[6], o[7]);
;                     *(u32x4*)(Y + row * DM + (MODE == 0 ? 1536 : 1024) + col0) = w;
	v_fmac_f32_e32 v83, v118, v81
	v_fma_f32 v72, -v72, v83, v82
	v_div_fmas_f32 v72, v72, v81, v83
	v_div_fixup_f32 v72, v72, v80, 1.0
	v_mul_f32_e32 v72, v72, v119
	v_mul_f32_e32 v72, v72, v64
	v_add_f32_e32 v64, v65, v73
	v_mul_f32_e32 v64, 0xbfb8aa3b, v64
	v_mul_f32_e32 v65, 0xbfb8aa3b, v110
	v_exp_f32_e32 v64, v64
	v_exp_f32_e32 v65, v65
	s_nop 0
	v_pk_add_f32 v[64:65], v[64:65], 1.0 op_sel_hi:[1,0]
	s_nop 0
	v_div_scale_f32 v73, s[0:1], v65, v65, v110
	v_rcp_f32_e32 v80, v73
	s_nop 0
	v_fma_f32 v81, -v73, v80, 1.0
	v_fmac_f32_e32 v80, v81, v80
	v_div_scale_f32 v81, vcc, v110, v65, v110
	v_mul_f32_e32 v82, v81, v80
	v_fma_f32 v83, -v73, v82, v81
	v_fmac_f32_e32 v82, v83, v80
	v_fma_f32 v73, -v73, v82, v81
	v_div_fmas_f32 v73, v73, v80, v82
	v_div_fixup_f32 v65, v73, v65, v110
	v_div_scale_f32 v73, s[0:1], v64, v64, 1.0
	v_rcp_f32_e32 v80, v73
	s_nop 0
	v_fma_f32 v81, -v73, v80, 1.0
	v_fmac_f32_e32 v80, v81, v80
	v_div_scale_f32 v81, vcc, 1.0, v64, 1.0
	v_mul_f32_e32 v82, v81, v80
	v_fma_f32 v83, -v73, v82, v81
	v_fmac_f32_e32 v82, v83, v80
	v_fma_f32 v73, -v73, v82, v81
	v_div_fmas_f32 v73, v73, v80, v82
	v_div_fixup_f32 v64, v73, v64, 1.0
	v_mul_f32_e32 v64, v64, v111
	v_mul_f32_e32 v73, v64, v65
	v_add_f32_e32 v64, v66, v74
	v_mul_f32_e32 v64, 0xbfb8aa3b, v64
	v_mul_f32_e32 v65, 0xbfb8aa3b, v102
	v_exp_f32_e32 v64, v64
	v_exp_f32_e32 v65, v65
	s_nop 0
	v_pk_add_f32 v[64:65], v[64:65], 1.0 op_sel_hi:[1,0]
	s_nop 0
	v_div_scale_f32 v66, s[0:1], v65, v65, v102
	v_rcp_f32_e32 v74, v66
	s_nop 0
	v_fma_f32 v80, -v66, v74, 1.0
	v_fmac_f32_e32 v74, v80, v74
	v_div_scale_f32 v80, vcc, v102, v65, v102
	v_mul_f32_e32 v81, v80, v74
	v_fma_f32 v82, -v66, v81, v80
	v_fmac_f32_e32 v81, v82, v74
	v_fma_f32 v66, -v66, v81, v80
	v_div_fmas_f32 v66, v66, v74, v81
	v_div_fixup_f32 v65, v66, v65, v102
	v_div_scale_f32 v66, s[0:1], v64, v64, 1.0
	v_rcp_f32_e32 v74, v66
	s_nop 0
	v_fma_f32 v80, -v66, v74, 1.0
	v_fmac_f32_e32 v74, v80, v74
	v_div_scale_f32 v80, vcc, 1.0, v64, 1.0
	v_mul_f32_e32 v81, v80, v74
	v_fma_f32 v82, -v66, v81, v80
	v_fmac_f32_e32 v81, v82, v74
	v_fma_f32 v66, -v66, v81, v80
	v_div_fmas_f32 v66, v66, v74, v81
	v_div_fixup_f32 v64, v66, v64, 1.0
	v_mul_f32_e32 v64, v64, v103
	v_mul_f32_e32 v74, v64, v65
	v_add_f32_e32 v64, v67, v75
	v_mul_f32_e32 v64, 0xbfb8aa3b, v64
	v_mul_f32_e32 v65, 0xbfb8aa3b, v94
	v_exp_f32_e32 v64, v64
	v_exp_f32_e32 v65, v65
	s_nop 0
	v_pk_add_f32 v[64:65], v[64:65], 1.0 op_sel_hi:[1,0]
	s_nop 0
	v_div_scale_f32 v66, s[0:1], v65, v65, v94
	v_rcp_f32_e32 v67, v66
	s_nop 0
	v_fma_f32 v75, -v66, v67, 1.0
	v_fmac_f32_e32 v67, v75, v67
	v_div_scale_f32 v75, vcc, v94, v65, v94
	v_mul_f32_e32 v80, v75, v67
	v_fma_f32 v81, -v66, v80, v75
	v_fmac_f32_e32 v80, v81, v67
	v_fma_f32 v66, -v66, v80, v75
	v_div_fmas_f32 v66, v66, v67, v80
	v_div_fixup_f32 v65, v66, v65, v94
	v_div_scale_f32 v66, s[0:1], v64, v64, 1.0
	v_rcp_f32_e32 v67, v66
	s_nop 0
	v_fma_f32 v75, -v66, v67, 1.0
	v_fmac_f32_e32 v67, v75, v67
	v_div_scale_f32 v75, vcc, 1.0, v64, 1.0
	v_mul_f32_e32 v80, v75, v67
	v_fma_f32 v81, -v66, v80, v75
	v_fmac_f32_e32 v80, v81, v67
	v_fma_f32 v66, -v66, v80, v75
	v_div_fmas_f32 v66, v66, v67, v80
	v_div_fixup_f32 v64, v66, v64, 1.0
	v_mul_f32_e32 v64, v64, v95
	v_mul_f32_e32 v67, v64, v65
	v_cvt_pk_bf16_f32 v64, v68, v69
	v_lshlrev_b64 v[68:69], 12, v[86:87]
	v_lshl_add_u64 v[68:69], s[12:13], 0, v[68:69]
	v_cvt_pk_bf16_f32 v65, v70, v71
	v_cvt_pk_bf16_f32 v66, v72, v73
	v_lshl_add_u64 v[72:73], v[68:69], 0, v[180:181]
	v_cvt_pk_bf16_f32 v67, v74, v67
	global_store_dwordx4 v[72:73], v[64:67], off offset:3072
	s_add_u32 s0, s14, 0x30000
	s_addc_u32 s1, s15, 0
	global_load_dwordx4 v[188:191], v214, s[0:1] offset:256
	s_add_u32 s0, s18, 0x8000
	s_addc_u32 s1, s19, 0
	global_load_dwordx4 v[196:199], v215, s[0:1] offset:256
	v_or_b32_e32 v180, 0x100, v180
	global_load_dwordx4 v[64:67], v145, s[2:3] offset:528
	global_load_dwordx4 v[68:71], v145, s[2:3] offset:512
	v_lshl_add_u64 v[74:75], v[136:137], 0, v[180:181]
	s_waitcnt vmcnt(0)
	v_mov_b32_e32 v80, v206
	v_mov_b32_e32 v81, v207
	v_mov_b32_e32 v82, v208
	v_mov_b32_e32 v83, v209
	v_mov_b32_e32 v134, v210
	v_mov_b32_e32 v135, v211
	v_mov_b32_e32 v136, v212
	v_mov_b32_e32 v137, v213
	v_add_f32_e32 v56, v56, v64
	v_add_f32_e32 v60, v60, v68
	v_mul_f32_e32 v60, 0xbfb8aa3b, v60
	v_lshlrev_b32_e32 v102, 16, v80
	v_exp_f32_e32 v94, v60
	v_mul_f32_e32 v60, 0xbfb8aa3b, v102
	v_exp_f32_e32 v95, v60
	v_lshlrev_b32_e32 v118, 16, v134
	v_and_b32_e32 v119, 0xffff0000, v134
	v_lshlrev_b32_e32 v126, 16, v135
	v_pk_add_f32 v[94:95], v[94:95], 1.0 op_sel_hi:[1,0]
	v_and_b32_e32 v127, 0xffff0000, v135
	v_div_scale_f32 v60, s[0:1], v95, v95, v102
	v_rcp_f32_e32 v134, v60
	v_and_b32_e32 v103, 0xffff0000, v80
	v_lshlrev_b32_e32 v80, 16, v83
	v_and_b32_e32 v74, 0xffff0000, v83
	v_fma_f32 v135, -v60, v134, 1.0
	v_fmac_f32_e32 v134, v135, v134
	v_div_scale_f32 v135, vcc, v102, v95, v102
	v_lshlrev_b32_e32 v87, 16, v136
	v_and_b32_e32 v83, 0xffff0000, v136
	v_mul_f32_e32 v136, v135, v134
	v_lshlrev_b32_e32 v110, 16, v81
	v_and_b32_e32 v111, 0xffff0000, v81
	v_lshlrev_b32_e32 v81, 16, v137
	v_and_b32_e32 v75, 0xffff0000, v137
	v_fma_f32 v137, -v60, v136, v135
	v_fmac_f32_e32 v136, v137, v134
	v_fma_f32 v60, -v60, v136, v135
	v_div_fmas_f32 v60, v60, v134, v136
	v_div_fixup_f32 v60, v60, v95, v102
	v_div_scale_f32 v95, s[0:1], v94, v94, 1.0
	v_rcp_f32_e32 v102, v95
	v_add_f32_e32 v61, v61, v69
	v_mul_f32_e32 v61, 0xbfb8aa3b, v61
	v_add_f32_e32 v62, v62, v70
	v_fma_f32 v134, -v95, v102, 1.0
	v_fmac_f32_e32 v102, v134, v102
	v_div_scale_f32 v134, vcc, 1.0, v94, 1.0
	v_mul_f32_e32 v135, v134, v102
; __device__ __forceinline__ float sigmoidf_(float v) { return 1.f / (1.f + __expf(-v)); }
; __device__ __forceinline__ float siluf_(float v) { return v / (1.f + __expf(-v)); }
;     __device__ __forceinline__ void operator()(const f32x4 (&acc)[2][2][4][2], const Unit& u, int wr, int wc, int fr, int fq) const {
;     ...
;                     const size_t row = (size_t)(row0 + ai * HALF + m * 16);
;                     const f32x4 v0 = acc[ai][bj][m][0], v1 = acc[ai][bj][m][1];
;                     float a[8] = {v0[0], v0[1], v0[2], v0[3], v1[0], v1[1], v1[2], v1[3]}, g[8], o[8];
;                     unpack8(*(const u32x4*)(R + row * RLD + (MODE == 0 ? 2560 : 1536) + col0), g);
;                     if (MODE == 0) { float y[8]; unpack8(*(const u32x4*)(YG + row * 512 + col0), y);
; #pragma unroll
;                         for (int e = 0; e < 8; ++e) o[e] = y[e] * sigmoidf_(a[e] + bb[e]) * siluf_(g[e]); }
;                     else {
; #pragma unroll
;                         for (int e = 0; e < 8; ++e) o[e] = a[e] * bb[e] * siluf_(g[e]); }
	v_fma_f32 v136, -v95, v135, v134
	v_fmac_f32_e32 v135, v136, v102
	v_fma_f32 v95, -v95, v135, v134
	v_div_fmas_f32 v95, v95, v102, v135
	v_div_fixup_f32 v94, v95, v94, 1.0
	v_mul_f32_e32 v94, v94, v118
	v_mul_f32_e32 v60, v94, v60
	v_exp_f32_e32 v94, v61
	v_mul_f32_e32 v61, 0xbfb8aa3b, v103
	v_exp_f32_e32 v95, v61
	v_mul_f32_e32 v62, 0xbfb8aa3b, v62
	v_add_f32_e32 v63, v63, v71
	v_mul_f32_e32 v63, 0xbfb8aa3b, v63
	v_pk_add_f32 v[94:95], v[94:95], 1.0 op_sel_hi:[1,0]
	v_lshlrev_b32_e32 v86, 16, v82
	v_div_scale_f32 v61, s[0:1], v95, v95, v103
	v_rcp_f32_e32 v102, v61
	v_mul_f32_e32 v56, 0xbfb8aa3b, v56
	v_and_b32_e32 v82, 0xffff0000, v82
	v_add_f32_e32 v52, v52, v68
	v_fma_f32 v118, -v61, v102, 1.0
	v_fmac_f32_e32 v102, v118, v102
	v_div_scale_f32 v118, vcc, v103, v95, v103
	v_mul_f32_e32 v134, v118, v102
	v_fma_f32 v135, -v61, v134, v118
	v_fmac_f32_e32 v134, v135, v102
	v_fma_f32 v61, -v61, v134, v118
	v_div_fmas_f32 v61, v61, v102, v134
	v_div_fixup_f32 v61, v61, v95, v103
	v_div_scale_f32 v95, s[0:1], v94, v94, 1.0
	v_rcp_f32_e32 v102, v95
	v_mul_f32_e32 v52, 0xbfb8aa3b, v52
	v_add_f32_e32 v53, v53, v69
	v_mul_f32_e32 v53, 0xbfb8aa3b, v53
	v_fma_f32 v103, -v95, v102, 1.0
	v_fmac_f32_e32 v102, v103, v102
	v_div_scale_f32 v103, vcc, 1.0, v94, 1.0
	v_mul_f32_e32 v118, v103, v102
	v_fma_f32 v134, -v95, v118, v103
	v_fmac_f32_e32 v118, v134, v102
	v_fma_f32 v95, -v95, v118, v103
	v_div_fmas_f32 v95, v95, v102, v118
	v_div_fixup_f32 v94, v95, v94, 1.0
	v_mul_f32_e32 v94, v94, v119
	v_mul_f32_e32 v61, v94, v61
	v_exp_f32_e32 v94, v62
	v_mul_f32_e32 v62, 0xbfb8aa3b, v110
	v_exp_f32_e32 v95, v62
	v_add_f32_e32 v54, v54, v70
	v_mul_f32_e32 v54, 0xbfb8aa3b, v54
	v_add_f32_e32 v55, v55, v71
	v_pk_add_f32 v[94:95], v[94:95], 1.0 op_sel_hi:[1,0]
	v_mul_f32_e32 v55, 0xbfb8aa3b, v55
	v_div_scale_f32 v62, s[0:1], v95, v95, v110
	v_rcp_f32_e32 v102, v62
	v_add_f32_e32 v48, v48, v64
	v_mul_f32_e32 v48, 0xbfb8aa3b, v48
	v_add_f32_e32 v44, v44, v68
	v_fma_f32 v103, -v62, v102, 1.0
	v_fmac_f32_e32 v102, v103, v102
	v_div_scale_f32 v103, vcc, v110, v95, v110
	v_mul_f32_e32 v118, v103, v102
	v_fma_f32 v119, -v62, v118, v103
	v_fmac_f32_e32 v118, v119, v102
	v_fma_f32 v62, -v62, v118, v103
	v_div_fmas_f32 v62, v62, v102, v118
	v_div_fixup_f32 v62, v62, v95, v110
	v_div_scale_f32 v95, s[0:1], v94, v94, 1.0
	v_rcp_f32_e32 v102, v95
	v_mul_f32_e32 v44, 0xbfb8aa3b, v44
	v_add_f32_e32 v45, v45, v69
	v_mul_f32_e32 v45, 0xbfb8aa3b, v45
	v_fma_f32 v103, -v95, v102, 1.0
	v_fmac_f32_e32 v102, v103, v102
	v_div_scale_f32 v103, vcc, 1.0, v94, 1.0
	v_mul_f32_e32 v110, v103, v102
	v_fma_f32 v118, -v95, v110, v103
	v_fmac_f32_e32 v110, v118, v102
	v_fma_f32 v95, -v95, v110, v103
	v_div_fmas_f32 v95, v95, v102, v110
	v_div_fixup_f32 v94, v95, v94, 1.0
	v_mul_f32_e32 v94, v94, v126
	v_mul_f32_e32 v62, v94, v62
	v_exp_f32_e32 v94, v63
	v_mul_f32_e32 v63, 0xbfb8aa3b, v111
	v_exp_f32_e32 v95, v63
	v_add_f32_e32 v46, v46, v70
	v_mul_f32_e32 v46, 0xbfb8aa3b, v46
	v_add_f32_e32 v47, v47, v71
	v_pk_add_f32 v[94:95], v[94:95], 1.0 op_sel_hi:[1,0]
	v_mul_f32_e32 v47, 0xbfb8aa3b, v47
	v_div_scale_f32 v63, s[0:1], v95, v95, v111
	v_rcp_f32_e32 v102, v63
	v_add_f32_e32 v40, v40, v64
	v_mul_f32_e32 v40, 0xbfb8aa3b, v40
	v_add_f32_e32 v36, v36, v68
	v_fma_f32 v103, -v63, v102, 1.0
	v_fmac_f32_e32 v102, v103, v102
	v_div_scale_f32 v103, vcc, v111, v95, v111
	v_mul_f32_e32 v110, v103, v102
	v_fma_f32 v118, -v63, v110, v103
	v_fmac_f32_e32 v110, v118, v102
	v_fma_f32 v63, -v63, v110, v103
	v_div_fmas_f32 v63, v63, v102, v110
	v_div_fixup_f32 v63, v63, v95, v111
	v_div_scale_f32 v95, s[0:1], v94, v94, 1.0
	v_rcp_f32_e32 v102, v95
	v_mul_f32_e32 v36, 0xbfb8aa3b, v36
	v_add_f32_e32 v37, v37, v69
	v_mul_f32_e32 v37, 0xbfb8aa3b, v37
	v_fma_f32 v103, -v95, v102, 1.0
	v_fmac_f32_e32 v102, v103, v102
	v_div_scale_f32 v103, vcc, 1.0, v94, 1.0
	v_mul_f32_e32 v110, v103, v102
	v_fma_f32 v111, -v95, v110, v103
	v_fmac_f32_e32 v110, v111, v102
	v_fma_f32 v95, -v95, v110, v103
	v_div_fmas_f32 v95, v95, v102, v110
	v_div_fixup_f32 v94, v95, v94, 1.0
	v_mul_f32_e32 v94, v94, v127
	v_mul_f32_e32 v63, v94, v63
	v_exp_f32_e32 v94, v56
	v_mul_f32_e32 v56, 0xbfb8aa3b, v86
	v_exp_f32_e32 v95, v56
	v_add_f32_e32 v38, v38, v70
	v_mul_f32_e32 v38, 0xbfb8aa3b, v38
	v_add_f32_e32 v39, v39, v71
	v_pk_add_f32 v[94:95], v[94:95], 1.0 op_sel_hi:[1,0]
	v_mul_f32_e32 v39, 0xbfb8aa3b, v39
	v_div_scale_f32 v56, s[0:1], v95, v95, v86
	v_rcp_f32_e32 v102, v56
	v_add_f32_e32 v32, v32, v64
	v_mul_f32_e32 v32, 0xbfb8aa3b, v32
	v_add_f32_e32 v28, v28, v68
	v_fma_f32 v103, -v56, v102, 1.0
	v_fmac_f32_e32 v102, v103, v102
	v_div_scale_f32 v103, vcc, v86, v95, v86
	v_mul_f32_e32 v110, v103, v102
	v_fma_f32 v111, -v56, v110, v103
	v_fmac_f32_e32 v110, v111, v102
	v_fma_f32 v56, -v56, v110, v103
	v_div_fmas_f32 v56, v56, v102, v110
	v_div_fixup_f32 v56, v56, v95, v86
	v_div_scale_f32 v86, s[0:1], v94, v94, 1.0
	v_rcp_f32_e32 v95, v86
	v_mul_f32_e32 v28, 0xbfb8aa3b, v28
	v_add_f32_e32 v29, v29, v69
	v_mul_f32_e32 v29, 0xbfb8aa3b, v29
	v_fma_f32 v102, -v86, v95, 1.0
	v_fmac_f32_e32 v95, v102, v95
	v_div_scale_f32 v102, vcc, 1.0, v94, 1.0
	v_mul_f32_e32 v103, v102, v95
	v_fma_f32 v110, -v86, v103, v102
	v_fmac_f32_e32 v103, v110, v95
	v_fma_f32 v86, -v86, v103, v102
	v_div_fmas_f32 v86, v86, v95, v103
	v_div_fixup_f32 v86, v86, v94, 1.0
	v_mul_f32_e32 v86, v86, v87
	v_mul_f32_e32 v86, v86, v56
	v_add_f32_e32 v56, v57, v65
	v_mul_f32_e32 v56, 0xbfb8aa3b, v56
	v_mul_f32_e32 v57, 0xbfb8aa3b, v82
	v_exp_f32_e32 v56, v56
	v_exp_f32_e32 v57, v57
	v_add_f32_e32 v30, v30, v70
	v_mul_f32_e32 v30, 0xbfb8aa3b, v30
	v_add_f32_e32 v31, v31, v71
; __device__ __forceinline__ unsigned cvt_pk_bf16(float lo, float hi) { unsigned r; asm volatile("v_cvt_pk_bf16_f32 %0, %1, %2" : "=v"(r) : "v"(lo), "v"(hi)); return r; }
; __device__ __forceinline__ float sigmoidf_(float v) { return 1.f / (1.f + __expf(-v)); }
; __device__ __forceinline__ float siluf_(float v) { return v / (1.f + __expf(-v)); }
;     __device__ __forceinline__ void operator()(const f32x4 (&acc)[2][2][4][2], const Unit& u, int wr, int wc, int fr, int fq) const {
;     ...
;                     const size_t row = (size_t)(row0 + ai * HALF + m * 16);
;                     const f32x4 v0 = acc[ai][bj][m][0], v1 = acc[ai][bj][m][1];
;                     float a[8] = {v0[0], v0[1], v0[2], v0[3], v1[0], v1[1], v1[2], v1[3]}, g[8], o[8];
;                     unpack8(*(const u32x4*)(R + row * RLD + (MODE == 0 ? 2560 : 1536) + col0), g);
;                     if (MODE == 0) { float y[8]; unpack8(*(const u32x4*)(YG + row * 512 + col0), y);
; #pragma unroll
;                         for (int e = 0; e < 8; ++e) o[e] = y[e] * sigmoidf_(a[e] + bb[e]) * siluf_(g[e]); }
;                     else {
; #pragma unroll
;                         for (int e = 0; e < 8; ++e) o[e] = a[e] * bb[e] * siluf_(g[e]); }
;                     u32x4 w; w.x = cvt_pk_bf16(o[0], o[1]); w.y = cvt_pk_bf16(o[2], o[3]); w.z = cvt_pk_bf16(o[4], o[5]); w.w = cvt_pk_bf16(o[6], o[7]);
;                     *(u32x4*)(Y + row * DM + (MODE == 0 ? 1536 : 1024) + col0) = w;
	v_pk_add_f32 v[56:57], v[56:57], 1.0 op_sel_hi:[1,0]
	v_mul_f32_e32 v31, 0xbfb8aa3b, v31
	v_div_scale_f32 v87, s[0:1], v57, v57, v82
	v_rcp_f32_e32 v94, v87
	v_add_f32_e32 v24, v24, v64
	v_mul_f32_e32 v24, 0xbfb8aa3b, v24
	v_add_f32_e32 v20, v20, v68
	v_fma_f32 v95, -v87, v94, 1.0
	v_fmac_f32_e32 v94, v95, v94
	v_div_scale_f32 v95, vcc, v82, v57, v82
	v_mul_f32_e32 v102, v95, v94
	v_fma_f32 v103, -v87, v102, v95
	v_fmac_f32_e32 v102, v103, v94
	v_fma_f32 v87, -v87, v102, v95
	v_div_fmas_f32 v87, v87, v94, v102
	v_div_fixup_f32 v57, v87, v57, v82
	v_div_scale_f32 v82, s[0:1], v56, v56, 1.0
	v_rcp_f32_e32 v87, v82
	v_mul_f32_e32 v20, 0xbfb8aa3b, v20
	v_add_f32_e32 v21, v21, v69
	v_mul_f32_e32 v21, 0xbfb8aa3b, v21
	v_fma_f32 v94, -v82, v87, 1.0
	v_fmac_f32_e32 v87, v94, v87
	v_div_scale_f32 v94, vcc, 1.0, v56, 1.0
	v_mul_f32_e32 v95, v94, v87
	v_fma_f32 v102, -v82, v95, v94
	v_fmac_f32_e32 v95, v102, v87
	v_fma_f32 v82, -v82, v95, v94
	v_div_fmas_f32 v82, v82, v87, v95
	v_div_fixup_f32 v56, v82, v56, 1.0
	v_mul_f32_e32 v56, v56, v83
	v_mul_f32_e32 v82, v56, v57
	v_add_f32_e32 v56, v58, v66
	v_mul_f32_e32 v56, 0xbfb8aa3b, v56
	v_mul_f32_e32 v57, 0xbfb8aa3b, v80
	v_exp_f32_e32 v56, v56
	v_exp_f32_e32 v57, v57
	v_add_f32_e32 v22, v22, v70
	v_mul_f32_e32 v22, 0xbfb8aa3b, v22
	v_add_f32_e32 v23, v23, v71
	v_pk_add_f32 v[56:57], v[56:57], 1.0 op_sel_hi:[1,0]
	v_mul_f32_e32 v23, 0xbfb8aa3b, v23
	v_div_scale_f32 v58, s[0:1], v57, v57, v80
	v_rcp_f32_e32 v83, v58
	v_add_f32_e32 v16, v16, v64
	v_mul_f32_e32 v16, 0xbfb8aa3b, v16
	v_add_f32_e32 v12, v12, v68
	v_fma_f32 v87, -v58, v83, 1.0
	v_fmac_f32_e32 v83, v87, v83
	v_div_scale_f32 v87, vcc, v80, v57, v80
	v_mul_f32_e32 v94, v87, v83
	v_fma_f32 v95, -v58, v94, v87
	v_fmac_f32_e32 v94, v95, v83
	v_fma_f32 v58, -v58, v94, v87
	v_div_fmas_f32 v58, v58, v83, v94
	v_div_fixup_f32 v57, v58, v57, v80
	v_div_scale_f32 v58, s[0:1], v56, v56, 1.0
	v_rcp_f32_e32 v80, v58
	v_mul_f32_e32 v12, 0xbfb8aa3b, v12
	v_add_f32_e32 v13, v13, v69
	v_mul_f32_e32 v13, 0xbfb8aa3b, v13
	v_fma_f32 v83, -v58, v80, 1.0
	v_fmac_f32_e32 v80, v83, v80
	v_div_scale_f32 v83, vcc, 1.0, v56, 1.0
	v_mul_f32_e32 v87, v83, v80
	v_fma_f32 v94, -v58, v87, v83
	v_fmac_f32_e32 v87, v94, v80
	v_fma_f32 v58, -v58, v87, v83
	v_div_fmas_f32 v58, v58, v80, v87
	v_div_fixup_f32 v56, v58, v56, 1.0
	v_mul_f32_e32 v56, v56, v81
	v_mul_f32_e32 v80, v56, v57
	v_add_f32_e32 v56, v59, v67
	v_mul_f32_e32 v56, 0xbfb8aa3b, v56
	v_mul_f32_e32 v57, 0xbfb8aa3b, v74
	v_exp_f32_e32 v56, v56
	v_exp_f32_e32 v57, v57
	v_add_f32_e32 v14, v14, v70
	v_mul_f32_e32 v14, 0xbfb8aa3b, v14
	v_add_f32_e32 v15, v15, v71
	v_pk_add_f32 v[56:57], v[56:57], 1.0 op_sel_hi:[1,0]
	v_mul_f32_e32 v15, 0xbfb8aa3b, v15
	v_div_scale_f32 v58, s[0:1], v57, v57, v74
	v_rcp_f32_e32 v59, v58
	v_add_f32_e32 v8, v8, v64
	v_mul_f32_e32 v8, 0xbfb8aa3b, v8
	v_add_f32_e32 v4, v4, v68
	v_fma_f32 v81, -v58, v59, 1.0
	v_fmac_f32_e32 v59, v81, v59
	v_div_scale_f32 v81, vcc, v74, v57, v74
	v_mul_f32_e32 v83, v81, v59
	v_fma_f32 v87, -v58, v83, v81
	v_fmac_f32_e32 v83, v87, v59
	v_fma_f32 v58, -v58, v83, v81
	v_div_fmas_f32 v58, v58, v59, v83
	v_div_fixup_f32 v57, v58, v57, v74
	v_div_scale_f32 v58, s[0:1], v56, v56, 1.0
	v_rcp_f32_e32 v59, v58
	v_mul_f32_e32 v4, 0xbfb8aa3b, v4
	v_add_f32_e32 v5, v5, v69
	v_mul_f32_e32 v5, 0xbfb8aa3b, v5
	v_fma_f32 v74, -v58, v59, 1.0
	v_fmac_f32_e32 v59, v74, v59
	v_div_scale_f32 v74, vcc, 1.0, v56, 1.0
	v_mul_f32_e32 v81, v74, v59
	v_fma_f32 v83, -v58, v81, v74
	v_fmac_f32_e32 v81, v83, v59
	v_fma_f32 v58, -v58, v81, v74
	v_div_fmas_f32 v58, v58, v59, v81
	v_div_fixup_f32 v56, v58, v56, 1.0
	v_mul_f32_e32 v56, v56, v75
	v_mul_f32_e32 v59, v56, v57
	v_cvt_pk_bf16_f32 v56, v60, v61
	v_cvt_pk_bf16_f32 v57, v62, v63
	v_cvt_pk_bf16_f32 v58, v86, v82
	v_cvt_pk_bf16_f32 v59, v80, v59
	global_store_dwordx4 v[128:129], v[56:59], off offset:3328
	s_add_u32 s0, s14, 0x48000
	s_addc_u32 s1, s15, 0
	global_load_dwordx4 v[206:209], v214, s[0:1] offset:256
	s_add_u32 s0, s18, 0xc000
	s_addc_u32 s1, s19, 0
	global_load_dwordx4 v[210:213], v215, s[0:1] offset:256
	s_waitcnt vmcnt(6)
	v_mov_b32_e32 v80, v172
	v_mov_b32_e32 v81, v173
	v_mov_b32_e32 v82, v174
	v_mov_b32_e32 v83, v175
	v_exp_f32_e32 v74, v52
	v_lshl_add_u64 v[56:57], v[130:131], 0, v[180:181]
	v_mov_b32_e32 v56, v168
	v_mov_b32_e32 v57, v169
	v_mov_b32_e32 v58, v170
	v_mov_b32_e32 v59, v171
	v_add_f32_e32 v6, v6, v70
	v_mul_f32_e32 v6, 0xbfb8aa3b, v6
	v_add_f32_e32 v7, v7, v71
	v_mul_f32_e32 v7, 0xbfb8aa3b, v7
	v_add_f32_e32 v0, v0, v64
	v_mul_f32_e32 v0, 0xbfb8aa3b, v0
	v_lshlrev_b32_e32 v63, 16, v82
	v_and_b32_e32 v61, 0xffff0000, v82
	v_lshlrev_b32_e32 v102, 16, v80
	v_lshlrev_b32_e32 v86, 16, v56
	v_mul_f32_e32 v52, 0xbfb8aa3b, v86
	v_exp_f32_e32 v75, v52
	v_and_b32_e32 v87, 0xffff0000, v56
	v_lshlrev_b32_e32 v94, 16, v57
	v_and_b32_e32 v95, 0xffff0000, v57
	v_pk_add_f32 v[74:75], v[74:75], 1.0 op_sel_hi:[1,0]
	v_lshlrev_b32_e32 v62, 16, v58
	v_div_scale_f32 v52, s[0:1], v75, v75, v86
	v_rcp_f32_e32 v82, v52
	v_and_b32_e32 v60, 0xffff0000, v58
	v_lshlrev_b32_e32 v58, 16, v59
	v_and_b32_e32 v56, 0xffff0000, v59
	v_lshlrev_b32_e32 v59, 16, v83
	v_and_b32_e32 v57, 0xffff0000, v83
	v_fma_f32 v83, -v52, v82, 1.0
	v_fmac_f32_e32 v82, v83, v82
	v_div_scale_f32 v83, vcc, v86, v75, v86
	v_mul_f32_e32 v110, v83, v82
	v_fma_f32 v111, -v52, v110, v83
	v_fmac_f32_e32 v110, v111, v82
	v_fma_f32 v52, -v52, v110, v83
	v_div_fmas_f32 v52, v52, v82, v110
	v_div_fixup_f32 v52, v52, v75, v86
	v_div_scale_f32 v75, s[0:1], v74, v74, 1.0
	v_rcp_f32_e32 v82, v75
	v_and_b32_e32 v80, 0xffff0000, v80
	v_lshlrev_b32_e32 v103, 16, v81
; __device__ __forceinline__ unsigned cvt_pk_bf16(float lo, float hi) { unsigned r; asm volatile("v_cvt_pk_bf16_f32 %0, %1, %2" : "=v"(r) : "v"(lo), "v"(hi)); return r; }
; __device__ __forceinline__ float sigmoidf_(float v) { return 1.f / (1.f + __expf(-v)); }
; __device__ __forceinline__ float siluf_(float v) { return v / (1.f + __expf(-v)); }
;     __device__ __forceinline__ void operator()(const f32x4 (&acc)[2][2][4][2], const Unit& u, int wr, int wc, int fr, int fq) const {
;     ...
;                     const size_t row = (size_t)(row0 + ai * HALF + m * 16);
;                     const f32x4 v0 = acc[ai][bj][m][0], v1 = acc[ai][bj][m][1];
;                     float a[8] = {v0[0], v0[1], v0[2], v0[3], v1[0], v1[1], v1[2], v1[3]}, g[8], o[8];
;                     unpack8(*(const u32x4*)(R + row * RLD + (MODE == 0 ? 2560 : 1536) + col0), g);
;                     if (MODE == 0) { float y[8]; unpack8(*(const u32x4*)(YG + row * 512 + col0), y);
; #pragma unroll
;                         for (int e = 0; e < 8; ++e) o[e] = y[e] * sigmoidf_(a[e] + bb[e]) * siluf_(g[e]); }
;                     else {
; #pragma unroll
;                         for (int e = 0; e < 8; ++e) o[e] = a[e] * bb[e] * siluf_(g[e]); }
;                     u32x4 w; w.x = cvt_pk_bf16(o[0], o[1]); w.y = cvt_pk_bf16(o[2], o[3]); w.z = cvt_pk_bf16(o[4], o[5]); w.w = cvt_pk_bf16(o[6], o[7]);
;                     *(u32x4*)(Y + row * DM + (MODE == 0 ? 1536 : 1024) + col0) = w;
	v_and_b32_e32 v81, 0xffff0000, v81
	v_fma_f32 v83, -v75, v82, 1.0
	v_fmac_f32_e32 v82, v83, v82
	v_div_scale_f32 v83, vcc, 1.0, v74, 1.0
	v_mul_f32_e32 v86, v83, v82
	v_fma_f32 v110, -v75, v86, v83
	v_fmac_f32_e32 v86, v110, v82
	v_fma_f32 v75, -v75, v86, v83
	v_div_fmas_f32 v75, v75, v82, v86
	v_div_fixup_f32 v74, v75, v74, 1.0
	v_mul_f32_e32 v74, v74, v102
	v_mul_f32_e32 v52, v74, v52
	v_exp_f32_e32 v74, v53
	v_mul_f32_e32 v53, 0xbfb8aa3b, v87
	v_exp_f32_e32 v75, v53
	s_nop 0
	v_pk_add_f32 v[74:75], v[74:75], 1.0 op_sel_hi:[1,0]
	s_nop 0
	v_div_scale_f32 v53, s[0:1], v75, v75, v87
	v_rcp_f32_e32 v82, v53
	s_nop 0
	v_fma_f32 v83, -v53, v82, 1.0
	v_fmac_f32_e32 v82, v83, v82
	v_div_scale_f32 v83, vcc, v87, v75, v87
	v_mul_f32_e32 v86, v83, v82
	v_fma_f32 v102, -v53, v86, v83
	v_fmac_f32_e32 v86, v102, v82
	v_fma_f32 v53, -v53, v86, v83
	v_div_fmas_f32 v53, v53, v82, v86
	v_div_fixup_f32 v53, v53, v75, v87
	v_div_scale_f32 v75, s[0:1], v74, v74, 1.0
	v_rcp_f32_e32 v82, v75
	s_nop 0
	v_fma_f32 v83, -v75, v82, 1.0
	v_fmac_f32_e32 v82, v83, v82
	v_div_scale_f32 v83, vcc, 1.0, v74, 1.0
	v_mul_f32_e32 v86, v83, v82
	v_fma_f32 v87, -v75, v86, v83
	v_fmac_f32_e32 v86, v87, v82
	v_fma_f32 v75, -v75, v86, v83
	v_div_fmas_f32 v75, v75, v82, v86
	v_div_fixup_f32 v74, v75, v74, 1.0
	v_mul_f32_e32 v74, v74, v80
	v_mul_f32_e32 v53, v74, v53
	v_exp_f32_e32 v74, v54
	v_mul_f32_e32 v54, 0xbfb8aa3b, v94
	v_exp_f32_e32 v75, v54
	s_nop 0
	v_pk_add_f32 v[74:75], v[74:75], 1.0 op_sel_hi:[1,0]
	s_nop 0
	v_div_scale_f32 v54, s[0:1], v75, v75, v94
	v_rcp_f32_e32 v80, v54
	s_nop 0
	v_fma_f32 v82, -v54, v80, 1.0
	v_fmac_f32_e32 v80, v82, v80
	v_div_scale_f32 v82, vcc, v94, v75, v94
	v_mul_f32_e32 v83, v82, v80
	v_fma_f32 v86, -v54, v83, v82
	v_fmac_f32_e32 v83, v86, v80
	v_fma_f32 v54, -v54, v83, v82
	v_div_fmas_f32 v54, v54, v80, v83
	v_div_fixup_f32 v54, v54, v75, v94
	v_div_scale_f32 v75, s[0:1], v74, v74, 1.0
	v_rcp_f32_e32 v80, v75
	s_nop 0
	v_fma_f32 v82, -v75, v80, 1.0
	v_fmac_f32_e32 v80, v82, v80
	v_div_scale_f32 v82, vcc, 1.0, v74, 1.0
	v_mul_f32_e32 v83, v82, v80
	v_fma_f32 v86, -v75, v83, v82
	v_fmac_f32_e32 v83, v86, v80
	v_fma_f32 v75, -v75, v83, v82
	v_div_fmas_f32 v75, v75, v80, v83
	v_div_fixup_f32 v74, v75, v74, 1.0
	v_mul_f32_e32 v74, v74, v103
	v_mul_f32_e32 v54, v74, v54
	v_exp_f32_e32 v74, v55
	v_mul_f32_e32 v55, 0xbfb8aa3b, v95
	v_exp_f32_e32 v75, v55
	s_nop 0
	v_pk_add_f32 v[74:75], v[74:75], 1.0 op_sel_hi:[1,0]
	s_nop 0
	v_div_scale_f32 v55, s[0:1], v75, v75, v95
	v_rcp_f32_e32 v80, v55
	s_nop 0
	v_fma_f32 v82, -v55, v80, 1.0
	v_fmac_f32_e32 v80, v82, v80
	v_div_scale_f32 v82, vcc, v95, v75, v95
	v_mul_f32_e32 v83, v82, v80
	v_fma_f32 v86, -v55, v83, v82
	v_fmac_f32_e32 v83, v86, v80
	v_fma_f32 v55, -v55, v83, v82
	v_div_fmas_f32 v55, v55, v80, v83
	v_div_fixup_f32 v55, v55, v75, v95
	v_div_scale_f32 v75, s[0:1], v74, v74, 1.0
	v_rcp_f32_e32 v80, v75
	s_nop 0
	v_fma_f32 v82, -v75, v80, 1.0
	v_fmac_f32_e32 v80, v82, v80
	v_div_scale_f32 v82, vcc, 1.0, v74, 1.0
	v_mul_f32_e32 v83, v82, v80
	v_fma_f32 v86, -v75, v83, v82
	v_fmac_f32_e32 v83, v86, v80
	v_fma_f32 v75, -v75, v83, v82
	v_div_fmas_f32 v75, v75, v80, v83
	v_div_fixup_f32 v74, v75, v74, 1.0
	v_mul_f32_e32 v74, v74, v81
	v_mul_f32_e32 v55, v74, v55
	v_exp_f32_e32 v74, v48
	v_mul_f32_e32 v48, 0xbfb8aa3b, v62
	v_exp_f32_e32 v75, v48
	s_nop 0
	v_pk_add_f32 v[74:75], v[74:75], 1.0 op_sel_hi:[1,0]
	s_nop 0
	v_div_scale_f32 v48, s[0:1], v75, v75, v62
	v_rcp_f32_e32 v80, v48
	s_nop 0
	v_fma_f32 v81, -v48, v80, 1.0
	v_fmac_f32_e32 v80, v81, v80
	v_div_scale_f32 v81, vcc, v62, v75, v62
	v_mul_f32_e32 v82, v81, v80
	v_fma_f32 v83, -v48, v82, v81
	v_fmac_f32_e32 v82, v83, v80
	v_fma_f32 v48, -v48, v82, v81
	v_div_fmas_f32 v48, v48, v80, v82
	v_div_fixup_f32 v48, v48, v75, v62
	v_div_scale_f32 v62, s[0:1], v74, v74, 1.0
	v_rcp_f32_e32 v75, v62
	s_nop 0
	v_fma_f32 v80, -v62, v75, 1.0
	v_fmac_f32_e32 v75, v80, v75
	v_div_scale_f32 v80, vcc, 1.0, v74, 1.0
	v_mul_f32_e32 v81, v80, v75
	v_fma_f32 v82, -v62, v81, v80
	v_fmac_f32_e32 v81, v82, v75
	v_fma_f32 v62, -v62, v81, v80
	v_div_fmas_f32 v62, v62, v75, v81
	v_div_fixup_f32 v62, v62, v74, 1.0
	v_mul_f32_e32 v62, v62, v63
	v_mul_f32_e32 v62, v62, v48
	v_add_f32_e32 v48, v49, v65
	v_mul_f32_e32 v48, 0xbfb8aa3b, v48
	v_mul_f32_e32 v49, 0xbfb8aa3b, v60
	v_exp_f32_e32 v48, v48
	v_exp_f32_e32 v49, v49
	s_nop 0
	v_pk_add_f32 v[48:49], v[48:49], 1.0 op_sel_hi:[1,0]
	s_nop 0
	v_div_scale_f32 v63, s[0:1], v49, v49, v60
	v_rcp_f32_e32 v74, v63
	s_nop 0
	v_fma_f32 v75, -v63, v74, 1.0
	v_fmac_f32_e32 v74, v75, v74
	v_div_scale_f32 v75, vcc, v60, v49, v60
	v_mul_f32_e32 v80, v75, v74
	v_fma_f32 v81, -v63, v80, v75
	v_fmac_f32_e32 v80, v81, v74
	v_fma_f32 v63, -v63, v80, v75
	v_div_fmas_f32 v63, v63, v74, v80
	v_div_fixup_f32 v49, v63, v49, v60
	v_div_scale_f32 v60, s[0:1], v48, v48, 1.0
	v_rcp_f32_e32 v63, v60
	s_nop 0
	v_fma_f32 v74, -v60, v63, 1.0
	v_fmac_f32_e32 v63, v74, v63
	v_div_scale_f32 v74, vcc, 1.0, v48, 1.0
	v_mul_f32_e32 v75, v74, v63
	v_fma_f32 v80, -v60, v75, v74
	v_fmac_f32_e32 v75, v80, v63
	v_fma_f32 v60, -v60, v75, v74
	v_div_fmas_f32 v60, v60, v63, v75
	v_div_fixup_f32 v48, v60, v48, 1.0
	v_mul_f32_e32 v48, v48, v61
	v_mul_f32_e32 v60, v48, v49
	v_add_f32_e32 v48, v50, v66
	v_mul_f32_e32 v48, 0xbfb8aa3b, v48
	v_mul_f32_e32 v49, 0xbfb8aa3b, v58
	v_exp_f32_e32 v48, v48
	v_exp_f32_e32 v49, v49
	s_nop 0
	v_pk_add_f32 v[48:49], v[48:49], 1.0 op_sel_hi:[1,0]
	s_nop 0
	v_div_scale_f32 v50, s[0:1], v49, v49, v58
	v_rcp_f32_e32 v61, v50
	s_nop 0
	v_fma_f32 v63, -v50, v61, 1.0
	v_fmac_f32_e32 v61, v63, v61
	v_div_scale_f32 v63, vcc, v58, v49, v58
; __device__ __forceinline__ unsigned cvt_pk_bf16(float lo, float hi) { unsigned r; asm volatile("v_cvt_pk_bf16_f32 %0, %1, %2" : "=v"(r) : "v"(lo), "v"(hi)); return r; }
; __device__ __forceinline__ float sigmoidf_(float v) { return 1.f / (1.f + __expf(-v)); }
; __device__ __forceinline__ float siluf_(float v) { return v / (1.f + __expf(-v)); }
;     __device__ __forceinline__ void operator()(const f32x4 (&acc)[2][2][4][2], const Unit& u, int wr, int wc, int fr, int fq) const {
;     ...
;                     const size_t row = (size_t)(row0 + ai * HALF + m * 16);
;                     const f32x4 v0 = acc[ai][bj][m][0], v1 = acc[ai][bj][m][1];
;                     float a[8] = {v0[0], v0[1], v0[2], v0[3], v1[0], v1[1], v1[2], v1[3]}, g[8], o[8];
;                     unpack8(*(const u32x4*)(R + row * RLD + (MODE == 0 ? 2560 : 1536) + col0), g);
;                     if (MODE == 0) { float y[8]; unpack8(*(const u32x4*)(YG + row * 512 + col0), y);
; #pragma unroll
;                         for (int e = 0; e < 8; ++e) o[e] = y[e] * sigmoidf_(a[e] + bb[e]) * siluf_(g[e]); }
;                     else {
; #pragma unroll
;                         for (int e = 0; e < 8; ++e) o[e] = a[e] * bb[e] * siluf_(g[e]); }
;                     u32x4 w; w.x = cvt_pk_bf16(o[0], o[1]); w.y = cvt_pk_bf16(o[2], o[3]); w.z = cvt_pk_bf16(o[4], o[5]); w.w = cvt_pk_bf16(o[6], o[7]);
;                     *(u32x4*)(Y + row * DM + (MODE == 0 ? 1536 : 1024) + col0) = w;
	v_mul_f32_e32 v74, v63, v61
	v_fma_f32 v75, -v50, v74, v63
	v_fmac_f32_e32 v74, v75, v61
	v_fma_f32 v50, -v50, v74, v63
	v_div_fmas_f32 v50, v50, v61, v74
	v_div_fixup_f32 v49, v50, v49, v58
	v_div_scale_f32 v50, s[0:1], v48, v48, 1.0
	v_rcp_f32_e32 v58, v50
	s_nop 0
	v_fma_f32 v61, -v50, v58, 1.0
	v_fmac_f32_e32 v58, v61, v58
	v_div_scale_f32 v61, vcc, 1.0, v48, 1.0
	v_mul_f32_e32 v63, v61, v58
	v_fma_f32 v74, -v50, v63, v61
	v_fmac_f32_e32 v63, v74, v58
	v_fma_f32 v50, -v50, v63, v61
	v_div_fmas_f32 v50, v50, v58, v63
	v_div_fixup_f32 v48, v50, v48, 1.0
	v_mul_f32_e32 v48, v48, v59
	v_mul_f32_e32 v58, v48, v49
	v_add_f32_e32 v48, v51, v67
	v_mul_f32_e32 v48, 0xbfb8aa3b, v48
	v_mul_f32_e32 v49, 0xbfb8aa3b, v56
	v_exp_f32_e32 v48, v48
	v_exp_f32_e32 v49, v49
	s_nop 0
	v_pk_add_f32 v[48:49], v[48:49], 1.0 op_sel_hi:[1,0]
	s_nop 0
	v_div_scale_f32 v50, s[0:1], v49, v49, v56
	v_rcp_f32_e32 v51, v50
	s_nop 0
	v_fma_f32 v59, -v50, v51, 1.0
	v_fmac_f32_e32 v51, v59, v51
	v_div_scale_f32 v59, vcc, v56, v49, v56
	v_mul_f32_e32 v61, v59, v51
	v_fma_f32 v63, -v50, v61, v59
	v_fmac_f32_e32 v61, v63, v51
	v_fma_f32 v50, -v50, v61, v59
	v_div_fmas_f32 v50, v50, v51, v61
	v_div_fixup_f32 v49, v50, v49, v56
	v_div_scale_f32 v50, s[0:1], v48, v48, 1.0
	v_rcp_f32_e32 v51, v50
	s_nop 0
	v_fma_f32 v56, -v50, v51, 1.0
	v_fmac_f32_e32 v51, v56, v51
	v_div_scale_f32 v56, vcc, 1.0, v48, 1.0
	v_mul_f32_e32 v59, v56, v51
	v_fma_f32 v61, -v50, v59, v56
	v_fmac_f32_e32 v59, v61, v51
	v_fma_f32 v50, -v50, v59, v56
	v_div_fmas_f32 v50, v50, v51, v59
	v_div_fixup_f32 v48, v50, v48, 1.0
	v_mul_f32_e32 v48, v48, v57
	v_mul_f32_e32 v51, v48, v49
	v_cvt_pk_bf16_f32 v48, v52, v53
	v_cvt_pk_bf16_f32 v49, v54, v55
	v_cvt_pk_bf16_f32 v50, v62, v60
	v_cvt_pk_bf16_f32 v51, v58, v51
	global_store_dwordx4 v[120:121], v[48:51], off offset:3328
	s_add_u32 s0, s14, 0xc0000
	s_addc_u32 s1, s15, 0
	global_load_dwordx4 v[168:171], v214, s[0:1] offset:256
	s_add_u32 s0, s18, 0x20000
	s_addc_u32 s1, s19, 0
	global_load_dwordx4 v[172:175], v215, s[0:1] offset:256
	s_waitcnt vmcnt(6)
	v_mov_b32_e32 v56, v196
	v_mov_b32_e32 v57, v197
	v_mov_b32_e32 v58, v198
	v_mov_b32_e32 v59, v199
	v_lshlrev_b32_e32 v74, 16, v56
	v_lshl_add_u64 v[48:49], v[122:123], 0, v[180:181]
	v_mov_b32_e32 v48, v188
	v_mov_b32_e32 v49, v189
	v_mov_b32_e32 v50, v190
	v_mov_b32_e32 v51, v191
	v_and_b32_e32 v75, 0xffff0000, v56
	v_exp_f32_e32 v56, v44
	v_lshlrev_b32_e32 v80, 16, v57
	v_and_b32_e32 v81, 0xffff0000, v57
	v_lshlrev_b32_e32 v55, 16, v58
	v_and_b32_e32 v53, 0xffff0000, v58
	v_lshlrev_b32_e32 v60, 16, v48
	v_mul_f32_e32 v44, 0xbfb8aa3b, v60
	v_exp_f32_e32 v57, v44
	v_and_b32_e32 v61, 0xffff0000, v48
	v_lshlrev_b32_e32 v62, 16, v49
	v_and_b32_e32 v63, 0xffff0000, v49
	v_pk_add_f32 v[56:57], v[56:57], 1.0 op_sel_hi:[1,0]
	v_lshlrev_b32_e32 v54, 16, v50
	v_div_scale_f32 v44, s[0:1], v57, v57, v60
	v_rcp_f32_e32 v58, v44
	v_and_b32_e32 v52, 0xffff0000, v50
	v_lshlrev_b32_e32 v50, 16, v51
	v_and_b32_e32 v48, 0xffff0000, v51
	v_lshlrev_b32_e32 v51, 16, v59
	v_and_b32_e32 v49, 0xffff0000, v59
	v_fma_f32 v59, -v44, v58, 1.0
	v_fmac_f32_e32 v58, v59, v58
	v_div_scale_f32 v59, vcc, v60, v57, v60
	v_mul_f32_e32 v82, v59, v58
	v_fma_f32 v83, -v44, v82, v59
	v_fmac_f32_e32 v82, v83, v58
	v_fma_f32 v44, -v44, v82, v59
	v_div_fmas_f32 v44, v44, v58, v82
	v_div_fixup_f32 v44, v44, v57, v60
	v_div_scale_f32 v57, s[0:1], v56, v56, 1.0
	v_rcp_f32_e32 v58, v57
	s_nop 0
	v_fma_f32 v59, -v57, v58, 1.0
	v_fmac_f32_e32 v58, v59, v58
	v_div_scale_f32 v59, vcc, 1.0, v56, 1.0
	v_mul_f32_e32 v60, v59, v58
	v_fma_f32 v82, -v57, v60, v59
	v_fmac_f32_e32 v60, v82, v58
	v_fma_f32 v57, -v57, v60, v59
	v_div_fmas_f32 v57, v57, v58, v60
	v_div_fixup_f32 v56, v57, v56, 1.0
	v_mul_f32_e32 v56, v56, v74
	v_mul_f32_e32 v44, v56, v44
	v_exp_f32_e32 v56, v45
	v_mul_f32_e32 v45, 0xbfb8aa3b, v61
	v_exp_f32_e32 v57, v45
	s_nop 0
	v_pk_add_f32 v[56:57], v[56:57], 1.0 op_sel_hi:[1,0]
	s_nop 0
	v_div_scale_f32 v45, s[0:1], v57, v57, v61
	v_rcp_f32_e32 v58, v45
	s_nop 0
	v_fma_f32 v59, -v45, v58, 1.0
	v_fmac_f32_e32 v58, v59, v58
	v_div_scale_f32 v59, vcc, v61, v57, v61
	v_mul_f32_e32 v60, v59, v58
	v_fma_f32 v74, -v45, v60, v59
	v_fmac_f32_e32 v60, v74, v58
	v_fma_f32 v45, -v45, v60, v59
	v_div_fmas_f32 v45, v45, v58, v60
	v_div_fixup_f32 v45, v45, v57, v61
	v_div_scale_f32 v57, s[0:1], v56, v56, 1.0
	v_rcp_f32_e32 v58, v57
	s_nop 0
	v_fma_f32 v59, -v57, v58, 1.0
	v_fmac_f32_e32 v58, v59, v58
	v_div_scale_f32 v59, vcc, 1.0, v56, 1.0
	v_mul_f32_e32 v60, v59, v58
	v_fma_f32 v61, -v57, v60, v59
	v_fmac_f32_e32 v60, v61, v58
	v_fma_f32 v57, -v57, v60, v59
	v_div_fmas_f32 v57, v57, v58, v60
	v_div_fixup_f32 v56, v57, v56, 1.0
	v_mul_f32_e32 v56, v56, v75
	v_mul_f32_e32 v45, v56, v45
	v_exp_f32_e32 v56, v46
	v_mul_f32_e32 v46, 0xbfb8aa3b, v62
	v_exp_f32_e32 v57, v46
	s_nop 0
	v_pk_add_f32 v[56:57], v[56:57], 1.0 op_sel_hi:[1,0]
	s_nop 0
	v_div_scale_f32 v46, s[0:1], v57, v57, v62
	v_rcp_f32_e32 v58, v46
	s_nop 0
	v_fma_f32 v59, -v46, v58, 1.0
	v_fmac_f32_e32 v58, v59, v58
	v_div_scale_f32 v59, vcc, v62, v57, v62
	v_mul_f32_e32 v60, v59, v58
	v_fma_f32 v61, -v46, v60, v59
	v_fmac_f32_e32 v60, v61, v58
	v_fma_f32 v46, -v46, v60, v59
	v_div_fmas_f32 v46, v46, v58, v60
	v_div_fixup_f32 v46, v46, v57, v62
	v_div_scale_f32 v57, s[0:1], v56, v56, 1.0
	v_rcp_f32_e32 v58, v57
	s_nop 0
	v_fma_f32 v59, -v57, v58, 1.0
	v_fmac_f32_e32 v58, v59, v58
	v_div_scale_f32 v59, vcc, 1.0, v56, 1.0
	v_mul_f32_e32 v60, v59, v58
	v_fma_f32 v61, -v57, v60, v59
	v_fmac_f32_e32 v60, v61, v58
	v_fma_f32 v57, -v57, v60, v59
	v_div_fmas_f32 v57, v57, v58, v60
	v_div_fixup_f32 v56, v57, v56, 1.0
; __device__ __forceinline__ unsigned cvt_pk_bf16(float lo, float hi) { unsigned r; asm volatile("v_cvt_pk_bf16_f32 %0, %1, %2" : "=v"(r) : "v"(lo), "v"(hi)); return r; }
; __device__ __forceinline__ float sigmoidf_(float v) { return 1.f / (1.f + __expf(-v)); }
; __device__ __forceinline__ float siluf_(float v) { return v / (1.f + __expf(-v)); }
;     __device__ __forceinline__ void operator()(const f32x4 (&acc)[2][2][4][2], const Unit& u, int wr, int wc, int fr, int fq) const {
;     ...
;                     const size_t row = (size_t)(row0 + ai * HALF + m * 16);
;                     const f32x4 v0 = acc[ai][bj][m][0], v1 = acc[ai][bj][m][1];
;                     float a[8] = {v0[0], v0[1], v0[2], v0[3], v1[0], v1[1], v1[2], v1[3]}, g[8], o[8];
;                     unpack8(*(const u32x4*)(R + row * RLD + (MODE == 0 ? 2560 : 1536) + col0), g);
;                     if (MODE == 0) { float y[8]; unpack8(*(const u32x4*)(YG + row * 512 + col0), y);
; #pragma unroll
;                         for (int e = 0; e < 8; ++e) o[e] = y[e] * sigmoidf_(a[e] + bb[e]) * siluf_(g[e]); }
;                     else {
; #pragma unroll
;                         for (int e = 0; e < 8; ++e) o[e] = a[e] * bb[e] * siluf_(g[e]); }
;                     u32x4 w; w.x = cvt_pk_bf16(o[0], o[1]); w.y = cvt_pk_bf16(o[2], o[3]); w.z = cvt_pk_bf16(o[4], o[5]); w.w = cvt_pk_bf16(o[6], o[7]);
;                     *(u32x4*)(Y + row * DM + (MODE == 0 ? 1536 : 1024) + col0) = w;
	v_mul_f32_e32 v56, v56, v80
	v_mul_f32_e32 v46, v56, v46
	v_exp_f32_e32 v56, v47
	v_mul_f32_e32 v47, 0xbfb8aa3b, v63
	v_exp_f32_e32 v57, v47
	s_nop 0
	v_pk_add_f32 v[56:57], v[56:57], 1.0 op_sel_hi:[1,0]
	s_nop 0
	v_div_scale_f32 v47, s[0:1], v57, v57, v63
	v_rcp_f32_e32 v58, v47
	s_nop 0
	v_fma_f32 v59, -v47, v58, 1.0
	v_fmac_f32_e32 v58, v59, v58
	v_div_scale_f32 v59, vcc, v63, v57, v63
	v_mul_f32_e32 v60, v59, v58
	v_fma_f32 v61, -v47, v60, v59
	v_fmac_f32_e32 v60, v61, v58
	v_fma_f32 v47, -v47, v60, v59
	v_div_fmas_f32 v47, v47, v58, v60
	v_div_fixup_f32 v47, v47, v57, v63
	v_div_scale_f32 v57, s[0:1], v56, v56, 1.0
	v_rcp_f32_e32 v58, v57
	s_nop 0
	v_fma_f32 v59, -v57, v58, 1.0
	v_fmac_f32_e32 v58, v59, v58
	v_div_scale_f32 v59, vcc, 1.0, v56, 1.0
	v_mul_f32_e32 v60, v59, v58
	v_fma_f32 v61, -v57, v60, v59
	v_fmac_f32_e32 v60, v61, v58
	v_fma_f32 v57, -v57, v60, v59
	v_div_fmas_f32 v57, v57, v58, v60
	v_div_fixup_f32 v56, v57, v56, 1.0
	v_mul_f32_e32 v56, v56, v81
	v_mul_f32_e32 v47, v56, v47
	v_exp_f32_e32 v56, v40
	v_mul_f32_e32 v40, 0xbfb8aa3b, v54
	v_exp_f32_e32 v57, v40
	s_nop 0
	v_pk_add_f32 v[56:57], v[56:57], 1.0 op_sel_hi:[1,0]
	s_nop 0
	v_div_scale_f32 v40, s[0:1], v57, v57, v54
	v_rcp_f32_e32 v58, v40
	s_nop 0
	v_fma_f32 v59, -v40, v58, 1.0
	v_fmac_f32_e32 v58, v59, v58
	v_div_scale_f32 v59, vcc, v54, v57, v54
	v_mul_f32_e32 v60, v59, v58
	v_fma_f32 v61, -v40, v60, v59
	v_fmac_f32_e32 v60, v61, v58
	v_fma_f32 v40, -v40, v60, v59
	v_div_fmas_f32 v40, v40, v58, v60
	v_div_fixup_f32 v40, v40, v57, v54
	v_div_scale_f32 v54, s[0:1], v56, v56, 1.0
	v_rcp_f32_e32 v57, v54
	s_nop 0
	v_fma_f32 v58, -v54, v57, 1.0
	v_fmac_f32_e32 v57, v58, v57
	v_div_scale_f32 v58, vcc, 1.0, v56, 1.0
	v_mul_f32_e32 v59, v58, v57
	v_fma_f32 v60, -v54, v59, v58
	v_fmac_f32_e32 v59, v60, v57
	v_fma_f32 v54, -v54, v59, v58
	v_div_fmas_f32 v54, v54, v57, v59
	v_div_fixup_f32 v54, v54, v56, 1.0
	v_mul_f32_e32 v54, v54, v55
	v_mul_f32_e32 v54, v54, v40
	v_add_f32_e32 v40, v41, v65
	v_mul_f32_e32 v40, 0xbfb8aa3b, v40
	v_mul_f32_e32 v41, 0xbfb8aa3b, v52
	v_exp_f32_e32 v40, v40
	v_exp_f32_e32 v41, v41
	s_nop 0
	v_pk_add_f32 v[40:41], v[40:41], 1.0 op_sel_hi:[1,0]
	s_nop 0
	v_div_scale_f32 v55, s[0:1], v41, v41, v52
	v_rcp_f32_e32 v56, v55
	s_nop 0
	v_fma_f32 v57, -v55, v56, 1.0
	v_fmac_f32_e32 v56, v57, v56
	v_div_scale_f32 v57, vcc, v52, v41, v52
	v_mul_f32_e32 v58, v57, v56
	v_fma_f32 v59, -v55, v58, v57
	v_fmac_f32_e32 v58, v59, v56
	v_fma_f32 v55, -v55, v58, v57
	v_div_fmas_f32 v55, v55, v56, v58
	v_div_fixup_f32 v41, v55, v41, v52
	v_div_scale_f32 v52, s[0:1], v40, v40, 1.0
	v_rcp_f32_e32 v55, v52
	s_nop 0
	v_fma_f32 v56, -v52, v55, 1.0
	v_fmac_f32_e32 v55, v56, v55
	v_div_scale_f32 v56, vcc, 1.0, v40, 1.0
	v_mul_f32_e32 v57, v56, v55
	v_fma_f32 v58, -v52, v57, v56
	v_fmac_f32_e32 v57, v58, v55
	v_fma_f32 v52, -v52, v57, v56
	v_div_fmas_f32 v52, v52, v55, v57
	v_div_fixup_f32 v40, v52, v40, 1.0
	v_mul_f32_e32 v40, v40, v53
	v_mul_f32_e32 v52, v40, v41
	v_add_f32_e32 v40, v42, v66
	v_mul_f32_e32 v40, 0xbfb8aa3b, v40
	v_mul_f32_e32 v41, 0xbfb8aa3b, v50
	v_exp_f32_e32 v40, v40
	v_exp_f32_e32 v41, v41
	s_nop 0
	v_pk_add_f32 v[40:41], v[40:41], 1.0 op_sel_hi:[1,0]
	s_nop 0
	v_div_scale_f32 v42, s[0:1], v41, v41, v50
	v_rcp_f32_e32 v53, v42
	s_nop 0
	v_fma_f32 v55, -v42, v53, 1.0
	v_fmac_f32_e32 v53, v55, v53
	v_div_scale_f32 v55, vcc, v50, v41, v50
	v_mul_f32_e32 v56, v55, v53
	v_fma_f32 v57, -v42, v56, v55
	v_fmac_f32_e32 v56, v57, v53
	v_fma_f32 v42, -v42, v56, v55
	v_div_fmas_f32 v42, v42, v53, v56
	v_div_fixup_f32 v41, v42, v41, v50
	v_div_scale_f32 v42, s[0:1], v40, v40, 1.0
	v_rcp_f32_e32 v50, v42
	s_nop 0
	v_fma_f32 v53, -v42, v50, 1.0
	v_fmac_f32_e32 v50, v53, v50
	v_div_scale_f32 v53, vcc, 1.0, v40, 1.0
	v_mul_f32_e32 v55, v53, v50
	v_fma_f32 v56, -v42, v55, v53
	v_fmac_f32_e32 v55, v56, v50
	v_fma_f32 v42, -v42, v55, v53
	v_div_fmas_f32 v42, v42, v50, v55
	v_div_fixup_f32 v40, v42, v40, 1.0
	v_mul_f32_e32 v40, v40, v51
	v_mul_f32_e32 v50, v40, v41
	v_add_f32_e32 v40, v43, v67
	v_mul_f32_e32 v40, 0xbfb8aa3b, v40
	v_mul_f32_e32 v41, 0xbfb8aa3b, v48
	v_exp_f32_e32 v40, v40
	v_exp_f32_e32 v41, v41
	s_nop 0
	v_pk_add_f32 v[40:41], v[40:41], 1.0 op_sel_hi:[1,0]
	s_nop 0
	v_div_scale_f32 v42, s[0:1], v41, v41, v48
	v_rcp_f32_e32 v43, v42
	s_nop 0
	v_fma_f32 v51, -v42, v43, 1.0
	v_fmac_f32_e32 v43, v51, v43
	v_div_scale_f32 v51, vcc, v48, v41, v48
	v_mul_f32_e32 v53, v51, v43
	v_fma_f32 v55, -v42, v53, v51
	v_fmac_f32_e32 v53, v55, v43
	v_fma_f32 v42, -v42, v53, v51
	v_div_fmas_f32 v42, v42, v43, v53
	v_div_fixup_f32 v41, v42, v41, v48
	v_div_scale_f32 v42, s[0:1], v40, v40, 1.0
	v_rcp_f32_e32 v43, v42
	s_nop 0
	v_fma_f32 v48, -v42, v43, 1.0
	v_fmac_f32_e32 v43, v48, v43
	v_div_scale_f32 v48, vcc, 1.0, v40, 1.0
	v_mul_f32_e32 v51, v48, v43
	v_fma_f32 v53, -v42, v51, v48
	v_fmac_f32_e32 v51, v53, v43
	v_fma_f32 v42, -v42, v51, v48
	v_div_fmas_f32 v42, v42, v43, v51
	v_div_fixup_f32 v40, v42, v40, 1.0
	v_mul_f32_e32 v40, v40, v49
	v_mul_f32_e32 v43, v40, v41
	v_cvt_pk_bf16_f32 v40, v44, v45
	v_cvt_pk_bf16_f32 v41, v46, v47
	v_cvt_pk_bf16_f32 v42, v54, v52
	v_cvt_pk_bf16_f32 v43, v50, v43
	global_store_dwordx4 v[112:113], v[40:43], off offset:3328
	s_add_u32 s0, s14, 0xd8000
	s_addc_u32 s1, s15, 0
	global_load_dwordx4 v[188:191], v214, s[0:1] offset:256
	s_add_u32 s0, s18, 0x24000
	s_addc_u32 s1, s19, 0
	global_load_dwordx4 v[196:199], v215, s[0:1] offset:256
	s_waitcnt vmcnt(6)
; __device__ __forceinline__ unsigned cvt_pk_bf16(float lo, float hi) { unsigned r; asm volatile("v_cvt_pk_bf16_f32 %0, %1, %2" : "=v"(r) : "v"(lo), "v"(hi)); return r; }
; __device__ __forceinline__ float sigmoidf_(float v) { return 1.f / (1.f + __expf(-v)); }
; __device__ __forceinline__ float siluf_(float v) { return v / (1.f + __expf(-v)); }
;     __device__ __forceinline__ void operator()(const f32x4 (&acc)[2][2][4][2], const Unit& u, int wr, int wc, int fr, int fq) const {
;     ...
;                     const size_t row = (size_t)(row0 + ai * HALF + m * 16);
;                     const f32x4 v0 = acc[ai][bj][m][0], v1 = acc[ai][bj][m][1];
;                     float a[8] = {v0[0], v0[1], v0[2], v0[3], v1[0], v1[1], v1[2], v1[3]}, g[8], o[8];
;                     unpack8(*(const u32x4*)(R + row * RLD + (MODE == 0 ? 2560 : 1536) + col0), g);
;                     if (MODE == 0) { float y[8]; unpack8(*(const u32x4*)(YG + row * 512 + col0), y);
; #pragma unroll
;                         for (int e = 0; e < 8; ++e) o[e] = y[e] * sigmoidf_(a[e] + bb[e]) * siluf_(g[e]); }
;                     else {
; #pragma unroll
;                         for (int e = 0; e < 8; ++e) o[e] = a[e] * bb[e] * siluf_(g[e]); }
;                     u32x4 w; w.x = cvt_pk_bf16(o[0], o[1]); w.y = cvt_pk_bf16(o[2], o[3]); w.z = cvt_pk_bf16(o[4], o[5]); w.w = cvt_pk_bf16(o[6], o[7]);
;                     *(u32x4*)(Y + row * DM + (MODE == 0 ? 1536 : 1024) + col0) = w;
	v_mov_b32_e32 v48, v210
	v_mov_b32_e32 v49, v211
	v_mov_b32_e32 v50, v212
	v_mov_b32_e32 v51, v213
	v_lshlrev_b32_e32 v56, 16, v48
	v_lshl_add_u64 v[40:41], v[114:115], 0, v[180:181]
	v_mov_b32_e32 v40, v206
	v_mov_b32_e32 v41, v207
	v_mov_b32_e32 v42, v208
	v_mov_b32_e32 v43, v209
	v_and_b32_e32 v57, 0xffff0000, v48
	v_exp_f32_e32 v48, v36
	v_lshlrev_b32_e32 v58, 16, v49
	v_and_b32_e32 v59, 0xffff0000, v49
	v_lshlrev_b32_e32 v47, 16, v50
	v_and_b32_e32 v45, 0xffff0000, v50
	v_lshlrev_b32_e32 v52, 16, v40
	v_mul_f32_e32 v36, 0xbfb8aa3b, v52
	v_exp_f32_e32 v49, v36
	v_and_b32_e32 v53, 0xffff0000, v40
	v_lshlrev_b32_e32 v54, 16, v41
	v_and_b32_e32 v55, 0xffff0000, v41
	v_pk_add_f32 v[48:49], v[48:49], 1.0 op_sel_hi:[1,0]
	v_lshlrev_b32_e32 v46, 16, v42
	v_div_scale_f32 v36, s[0:1], v49, v49, v52
	v_rcp_f32_e32 v50, v36
	v_and_b32_e32 v44, 0xffff0000, v42
	v_lshlrev_b32_e32 v42, 16, v43
	v_and_b32_e32 v40, 0xffff0000, v43
	v_lshlrev_b32_e32 v43, 16, v51
	v_and_b32_e32 v41, 0xffff0000, v51
	v_fma_f32 v51, -v36, v50, 1.0
	v_fmac_f32_e32 v50, v51, v50
	v_div_scale_f32 v51, vcc, v52, v49, v52
	v_mul_f32_e32 v60, v51, v50
	v_fma_f32 v61, -v36, v60, v51
	v_fmac_f32_e32 v60, v61, v50
	v_fma_f32 v36, -v36, v60, v51
	v_div_fmas_f32 v36, v36, v50, v60
	v_div_fixup_f32 v36, v36, v49, v52
	v_div_scale_f32 v49, s[0:1], v48, v48, 1.0
	v_rcp_f32_e32 v50, v49
	s_nop 0
	v_fma_f32 v51, -v49, v50, 1.0
	v_fmac_f32_e32 v50, v51, v50
	v_div_scale_f32 v51, vcc, 1.0, v48, 1.0
	v_mul_f32_e32 v52, v51, v50
	v_fma_f32 v60, -v49, v52, v51
	v_fmac_f32_e32 v52, v60, v50
	v_fma_f32 v49, -v49, v52, v51
	v_div_fmas_f32 v49, v49, v50, v52
	v_div_fixup_f32 v48, v49, v48, 1.0
	v_mul_f32_e32 v48, v48, v56
	v_mul_f32_e32 v36, v48, v36
	v_exp_f32_e32 v48, v37
	v_mul_f32_e32 v37, 0xbfb8aa3b, v53
	v_exp_f32_e32 v49, v37
	s_nop 0
	v_pk_add_f32 v[48:49], v[48:49], 1.0 op_sel_hi:[1,0]
	s_nop 0
	v_div_scale_f32 v37, s[0:1], v49, v49, v53
	v_rcp_f32_e32 v50, v37
	s_nop 0
	v_fma_f32 v51, -v37, v50, 1.0
	v_fmac_f32_e32 v50, v51, v50
	v_div_scale_f32 v51, vcc, v53, v49, v53
	v_mul_f32_e32 v52, v51, v50
	v_fma_f32 v56, -v37, v52, v51
	v_fmac_f32_e32 v52, v56, v50
	v_fma_f32 v37, -v37, v52, v51
	v_div_fmas_f32 v37, v37, v50, v52
	v_div_fixup_f32 v37, v37, v49, v53
	v_div_scale_f32 v49, s[0:1], v48, v48, 1.0
	v_rcp_f32_e32 v50, v49
	s_nop 0
	v_fma_f32 v51, -v49, v50, 1.0
	v_fmac_f32_e32 v50, v51, v50
	v_div_scale_f32 v51, vcc, 1.0, v48, 1.0
	v_mul_f32_e32 v52, v51, v50
	v_fma_f32 v53, -v49, v52, v51
	v_fmac_f32_e32 v52, v53, v50
	v_fma_f32 v49, -v49, v52, v51
	v_div_fmas_f32 v49, v49, v50, v52
	v_div_fixup_f32 v48, v49, v48, 1.0
	v_mul_f32_e32 v48, v48, v57
	v_mul_f32_e32 v37, v48, v37
	v_exp_f32_e32 v48, v38
	v_mul_f32_e32 v38, 0xbfb8aa3b, v54
	v_exp_f32_e32 v49, v38
	s_nop 0
	v_pk_add_f32 v[48:49], v[48:49], 1.0 op_sel_hi:[1,0]
	s_nop 0
	v_div_scale_f32 v38, s[0:1], v49, v49, v54
	v_rcp_f32_e32 v50, v38
	s_nop 0
	v_fma_f32 v51, -v38, v50, 1.0
	v_fmac_f32_e32 v50, v51, v50
	v_div_scale_f32 v51, vcc, v54, v49, v54
	v_mul_f32_e32 v52, v51, v50
	v_fma_f32 v53, -v38, v52, v51
	v_fmac_f32_e32 v52, v53, v50
	v_fma_f32 v38, -v38, v52, v51
	v_div_fmas_f32 v38, v38, v50, v52
	v_div_fixup_f32 v38, v38, v49, v54
	v_div_scale_f32 v49, s[0:1], v48, v48, 1.0
	v_rcp_f32_e32 v50, v49
	s_nop 0
	v_fma_f32 v51, -v49, v50, 1.0
	v_fmac_f32_e32 v50, v51, v50
	v_div_scale_f32 v51, vcc, 1.0, v48, 1.0
	v_mul_f32_e32 v52, v51, v50
	v_fma_f32 v53, -v49, v52, v51
	v_fmac_f32_e32 v52, v53, v50
	v_fma_f32 v49, -v49, v52, v51
	v_div_fmas_f32 v49, v49, v50, v52
	v_div_fixup_f32 v48, v49, v48, 1.0
	v_mul_f32_e32 v48, v48, v58
	v_mul_f32_e32 v38, v48, v38
	v_exp_f32_e32 v48, v39
	v_mul_f32_e32 v39, 0xbfb8aa3b, v55
	v_exp_f32_e32 v49, v39
	s_nop 0
	v_pk_add_f32 v[48:49], v[48:49], 1.0 op_sel_hi:[1,0]
	s_nop 0
	v_div_scale_f32 v39, s[0:1], v49, v49, v55
	v_rcp_f32_e32 v50, v39
	s_nop 0
	v_fma_f32 v51, -v39, v50, 1.0
	v_fmac_f32_e32 v50, v51, v50
	v_div_scale_f32 v51, vcc, v55, v49, v55
	v_mul_f32_e32 v52, v51, v50
	v_fma_f32 v53, -v39, v52, v51
	v_fmac_f32_e32 v52, v53, v50
	v_fma_f32 v39, -v39, v52, v51
	v_div_fmas_f32 v39, v39, v50, v52
	v_div_fixup_f32 v39, v39, v49, v55
	v_div_scale_f32 v49, s[0:1], v48, v48, 1.0
	v_rcp_f32_e32 v50, v49
	s_nop 0
	v_fma_f32 v51, -v49, v50, 1.0
	v_fmac_f32_e32 v50, v51, v50
	v_div_scale_f32 v51, vcc, 1.0, v48, 1.0
	v_mul_f32_e32 v52, v51, v50
	v_fma_f32 v53, -v49, v52, v51
	v_fmac_f32_e32 v52, v53, v50
	v_fma_f32 v49, -v49, v52, v51
	v_div_fmas_f32 v49, v49, v50, v52
	v_div_fixup_f32 v48, v49, v48, 1.0
	v_mul_f32_e32 v48, v48, v59
	v_mul_f32_e32 v39, v48, v39
	v_exp_f32_e32 v48, v32
	v_mul_f32_e32 v32, 0xbfb8aa3b, v46
	v_exp_f32_e32 v49, v32
	s_nop 0
	v_pk_add_f32 v[48:49], v[48:49], 1.0 op_sel_hi:[1,0]
	s_nop 0
	v_div_scale_f32 v32, s[0:1], v49, v49, v46
	v_rcp_f32_e32 v50, v32
	s_nop 0
	v_fma_f32 v51, -v32, v50, 1.0
	v_fmac_f32_e32 v50, v51, v50
	v_div_scale_f32 v51, vcc, v46, v49, v46
	v_mul_f32_e32 v52, v51, v50
	v_fma_f32 v53, -v32, v52, v51
	v_fmac_f32_e32 v52, v53, v50
	v_fma_f32 v32, -v32, v52, v51
	v_div_fmas_f32 v32, v32, v50, v52
	v_div_fixup_f32 v32, v32, v49, v46
	v_div_scale_f32 v46, s[0:1], v48, v48, 1.0
	v_rcp_f32_e32 v49, v46
	s_nop 0
	v_fma_f32 v50, -v46, v49, 1.0
	v_fmac_f32_e32 v49, v50, v49
	v_div_scale_f32 v50, vcc, 1.0, v48, 1.0
	v_mul_f32_e32 v51, v50, v49
	v_fma_f32 v52, -v46, v51, v50
	v_fmac_f32_e32 v51, v52, v49
	v_fma_f32 v46, -v46, v51, v50
	v_div_fmas_f32 v46, v46, v49, v51
	v_div_fixup_f32 v46, v46, v48, 1.0
	v_mul_f32_e32 v46, v46, v47
	v_mul_f32_e32 v46, v46, v32
	v_add_f32_e32 v32, v33, v65
	v_mul_f32_e32 v32, 0xbfb8aa3b, v32
	v_mul_f32_e32 v33, 0xbfb8aa3b, v44
; __device__ __forceinline__ unsigned cvt_pk_bf16(float lo, float hi) { unsigned r; asm volatile("v_cvt_pk_bf16_f32 %0, %1, %2" : "=v"(r) : "v"(lo), "v"(hi)); return r; }
; __device__ __forceinline__ float sigmoidf_(float v) { return 1.f / (1.f + __expf(-v)); }
; __device__ __forceinline__ float siluf_(float v) { return v / (1.f + __expf(-v)); }
;     __device__ __forceinline__ void operator()(const f32x4 (&acc)[2][2][4][2], const Unit& u, int wr, int wc, int fr, int fq) const {
;     ...
;                     const size_t row = (size_t)(row0 + ai * HALF + m * 16);
;                     const f32x4 v0 = acc[ai][bj][m][0], v1 = acc[ai][bj][m][1];
;                     float a[8] = {v0[0], v0[1], v0[2], v0[3], v1[0], v1[1], v1[2], v1[3]}, g[8], o[8];
;                     unpack8(*(const u32x4*)(R + row * RLD + (MODE == 0 ? 2560 : 1536) + col0), g);
;                     if (MODE == 0) { float y[8]; unpack8(*(const u32x4*)(YG + row * 512 + col0), y);
; #pragma unroll
;                         for (int e = 0; e < 8; ++e) o[e] = y[e] * sigmoidf_(a[e] + bb[e]) * siluf_(g[e]); }
;                     else {
; #pragma unroll
;                         for (int e = 0; e < 8; ++e) o[e] = a[e] * bb[e] * siluf_(g[e]); }
;                     u32x4 w; w.x = cvt_pk_bf16(o[0], o[1]); w.y = cvt_pk_bf16(o[2], o[3]); w.z = cvt_pk_bf16(o[4], o[5]); w.w = cvt_pk_bf16(o[6], o[7]);
;                     *(u32x4*)(Y + row * DM + (MODE == 0 ? 1536 : 1024) + col0) = w;
	v_exp_f32_e32 v32, v32
	v_exp_f32_e32 v33, v33
	s_nop 0
	v_pk_add_f32 v[32:33], v[32:33], 1.0 op_sel_hi:[1,0]
	s_nop 0
	v_div_scale_f32 v47, s[0:1], v33, v33, v44
	v_rcp_f32_e32 v48, v47
	s_nop 0
	v_fma_f32 v49, -v47, v48, 1.0
	v_fmac_f32_e32 v48, v49, v48
	v_div_scale_f32 v49, vcc, v44, v33, v44
	v_mul_f32_e32 v50, v49, v48
	v_fma_f32 v51, -v47, v50, v49
	v_fmac_f32_e32 v50, v51, v48
	v_fma_f32 v47, -v47, v50, v49
	v_div_fmas_f32 v47, v47, v48, v50
	v_div_fixup_f32 v33, v47, v33, v44
	v_div_scale_f32 v44, s[0:1], v32, v32, 1.0
	v_rcp_f32_e32 v47, v44
	s_nop 0
	v_fma_f32 v48, -v44, v47, 1.0
	v_fmac_f32_e32 v47, v48, v47
	v_div_scale_f32 v48, vcc, 1.0, v32, 1.0
	v_mul_f32_e32 v49, v48, v47
	v_fma_f32 v50, -v44, v49, v48
	v_fmac_f32_e32 v49, v50, v47
	v_fma_f32 v44, -v44, v49, v48
	v_div_fmas_f32 v44, v44, v47, v49
	v_div_fixup_f32 v32, v44, v32, 1.0
	v_mul_f32_e32 v32, v32, v45
	v_mul_f32_e32 v44, v32, v33
	v_add_f32_e32 v32, v34, v66
	v_mul_f32_e32 v32, 0xbfb8aa3b, v32
	v_mul_f32_e32 v33, 0xbfb8aa3b, v42
	v_exp_f32_e32 v32, v32
	v_exp_f32_e32 v33, v33
	s_nop 0
	v_pk_add_f32 v[32:33], v[32:33], 1.0 op_sel_hi:[1,0]
	s_nop 0
	v_div_scale_f32 v34, s[0:1], v33, v33, v42
	v_rcp_f32_e32 v45, v34
	s_nop 0
	v_fma_f32 v47, -v34, v45, 1.0
	v_fmac_f32_e32 v45, v47, v45
	v_div_scale_f32 v47, vcc, v42, v33, v42
	v_mul_f32_e32 v48, v47, v45
	v_fma_f32 v49, -v34, v48, v47
	v_fmac_f32_e32 v48, v49, v45
	v_fma_f32 v34, -v34, v48, v47
	v_div_fmas_f32 v34, v34, v45, v48
	v_div_fixup_f32 v33, v34, v33, v42
	v_div_scale_f32 v34, s[0:1], v32, v32, 1.0
	v_rcp_f32_e32 v42, v34
	s_nop 0
	v_fma_f32 v45, -v34, v42, 1.0
	v_fmac_f32_e32 v42, v45, v42
	v_div_scale_f32 v45, vcc, 1.0, v32, 1.0
	v_mul_f32_e32 v47, v45, v42
	v_fma_f32 v48, -v34, v47, v45
	v_fmac_f32_e32 v47, v48, v42
	v_fma_f32 v34, -v34, v47, v45
	v_div_fmas_f32 v34, v34, v42, v47
	v_div_fixup_f32 v32, v34, v32, 1.0
	v_mul_f32_e32 v32, v32, v43
	v_mul_f32_e32 v42, v32, v33
	v_add_f32_e32 v32, v35, v67
	v_mul_f32_e32 v32, 0xbfb8aa3b, v32
	v_mul_f32_e32 v33, 0xbfb8aa3b, v40
	v_exp_f32_e32 v32, v32
	v_exp_f32_e32 v33, v33
	s_nop 0
	v_pk_add_f32 v[32:33], v[32:33], 1.0 op_sel_hi:[1,0]
	s_nop 0
	v_div_scale_f32 v34, s[0:1], v33, v33, v40
	v_rcp_f32_e32 v35, v34
	s_nop 0
	v_fma_f32 v43, -v34, v35, 1.0
	v_fmac_f32_e32 v35, v43, v35
	v_div_scale_f32 v43, vcc, v40, v33, v40
	v_mul_f32_e32 v45, v43, v35
	v_fma_f32 v47, -v34, v45, v43
	v_fmac_f32_e32 v45, v47, v35
	v_fma_f32 v34, -v34, v45, v43
	v_div_fmas_f32 v34, v34, v35, v45
	v_div_fixup_f32 v33, v34, v33, v40
	v_div_scale_f32 v34, s[0:1], v32, v32, 1.0
	v_rcp_f32_e32 v35, v34
	s_nop 0
	v_fma_f32 v40, -v34, v35, 1.0
	v_fmac_f32_e32 v35, v40, v35
	v_div_scale_f32 v40, vcc, 1.0, v32, 1.0
	v_mul_f32_e32 v43, v40, v35
	v_fma_f32 v45, -v34, v43, v40
	v_fmac_f32_e32 v43, v45, v35
	v_fma_f32 v34, -v34, v43, v40
	v_div_fmas_f32 v34, v34, v35, v43
	v_div_fixup_f32 v32, v34, v32, 1.0
	v_mul_f32_e32 v32, v32, v41
	v_mul_f32_e32 v35, v32, v33
	v_cvt_pk_bf16_f32 v32, v36, v37
	v_cvt_pk_bf16_f32 v33, v38, v39
	v_cvt_pk_bf16_f32 v34, v46, v44
	v_cvt_pk_bf16_f32 v35, v42, v35
	global_store_dwordx4 v[104:105], v[32:35], off offset:3328
	s_add_u32 s0, s14, 0xf0000
	s_addc_u32 s1, s15, 0
	global_load_dwordx4 v[206:209], v214, s[0:1] offset:256
	s_add_u32 s0, s18, 0x28000
	s_addc_u32 s1, s19, 0
	global_load_dwordx4 v[210:213], v215, s[0:1] offset:256
	s_waitcnt vmcnt(6)
	v_mov_b32_e32 v40, v172
	v_mov_b32_e32 v41, v173
	v_mov_b32_e32 v42, v174
	v_mov_b32_e32 v43, v175
	v_lshlrev_b32_e32 v48, 16, v40
	v_lshl_add_u64 v[32:33], v[106:107], 0, v[180:181]
	v_mov_b32_e32 v32, v168
	v_mov_b32_e32 v33, v169
	v_mov_b32_e32 v34, v170
	v_mov_b32_e32 v35, v171
	v_and_b32_e32 v49, 0xffff0000, v40
	v_exp_f32_e32 v40, v28
	v_lshlrev_b32_e32 v50, 16, v41
	v_and_b32_e32 v51, 0xffff0000, v41
	v_lshlrev_b32_e32 v39, 16, v42
	v_and_b32_e32 v37, 0xffff0000, v42
	v_lshlrev_b32_e32 v44, 16, v32
	v_mul_f32_e32 v28, 0xbfb8aa3b, v44
	v_exp_f32_e32 v41, v28
	v_and_b32_e32 v45, 0xffff0000, v32
	v_lshlrev_b32_e32 v46, 16, v33
	v_and_b32_e32 v47, 0xffff0000, v33
	v_pk_add_f32 v[40:41], v[40:41], 1.0 op_sel_hi:[1,0]
	v_lshlrev_b32_e32 v38, 16, v34
	v_div_scale_f32 v28, s[0:1], v41, v41, v44
	v_rcp_f32_e32 v42, v28
	v_and_b32_e32 v36, 0xffff0000, v34
	v_lshlrev_b32_e32 v34, 16, v35
	v_and_b32_e32 v32, 0xffff0000, v35
	v_lshlrev_b32_e32 v35, 16, v43
	v_and_b32_e32 v33, 0xffff0000, v43
	v_fma_f32 v43, -v28, v42, 1.0
	v_fmac_f32_e32 v42, v43, v42
	v_div_scale_f32 v43, vcc, v44, v41, v44
	v_mul_f32_e32 v52, v43, v42
	v_fma_f32 v53, -v28, v52, v43
	v_fmac_f32_e32 v52, v53, v42
	v_fma_f32 v28, -v28, v52, v43
	v_div_fmas_f32 v28, v28, v42, v52
	v_div_fixup_f32 v28, v28, v41, v44
	v_div_scale_f32 v41, s[0:1], v40, v40, 1.0
	v_rcp_f32_e32 v42, v41
	s_nop 0
	v_fma_f32 v43, -v41, v42, 1.0
	v_fmac_f32_e32 v42, v43, v42
	v_div_scale_f32 v43, vcc, 1.0, v40, 1.0
	v_mul_f32_e32 v44, v43, v42
	v_fma_f32 v52, -v41, v44, v43
	v_fmac_f32_e32 v44, v52, v42
	v_fma_f32 v41, -v41, v44, v43
	v_div_fmas_f32 v41, v41, v42, v44
	v_div_fixup_f32 v40, v41, v40, 1.0
	v_mul_f32_e32 v40, v40, v48
	v_mul_f32_e32 v28, v40, v28
	v_exp_f32_e32 v40, v29
	v_mul_f32_e32 v29, 0xbfb8aa3b, v45
	v_exp_f32_e32 v41, v29
	s_nop 0
	v_pk_add_f32 v[40:41], v[40:41], 1.0 op_sel_hi:[1,0]
	s_nop 0
	v_div_scale_f32 v29, s[0:1], v41, v41, v45
	v_rcp_f32_e32 v42, v29
	s_nop 0
	v_fma_f32 v43, -v29, v42, 1.0
	v_fmac_f32_e32 v42, v43, v42
	v_div_scale_f32 v43, vcc, v45, v41, v45
	v_mul_f32_e32 v44, v43, v42
	v_fma_f32 v48, -v29, v44, v43
	v_fmac_f32_e32 v44, v48, v42
	v_fma_f32 v29, -v29, v44, v43
	v_div_fmas_f32 v29, v29, v42, v44
	v_div_fixup_f32 v29, v29, v41, v45
; __device__ __forceinline__ unsigned cvt_pk_bf16(float lo, float hi) { unsigned r; asm volatile("v_cvt_pk_bf16_f32 %0, %1, %2" : "=v"(r) : "v"(lo), "v"(hi)); return r; }
; __device__ __forceinline__ float sigmoidf_(float v) { return 1.f / (1.f + __expf(-v)); }
; __device__ __forceinline__ float siluf_(float v) { return v / (1.f + __expf(-v)); }
;     __device__ __forceinline__ void operator()(const f32x4 (&acc)[2][2][4][2], const Unit& u, int wr, int wc, int fr, int fq) const {
;     ...
;                     const size_t row = (size_t)(row0 + ai * HALF + m * 16);
;                     const f32x4 v0 = acc[ai][bj][m][0], v1 = acc[ai][bj][m][1];
;                     float a[8] = {v0[0], v0[1], v0[2], v0[3], v1[0], v1[1], v1[2], v1[3]}, g[8], o[8];
;                     unpack8(*(const u32x4*)(R + row * RLD + (MODE == 0 ? 2560 : 1536) + col0), g);
;                     if (MODE == 0) { float y[8]; unpack8(*(const u32x4*)(YG + row * 512 + col0), y);
; #pragma unroll
;                         for (int e = 0; e < 8; ++e) o[e] = y[e] * sigmoidf_(a[e] + bb[e]) * siluf_(g[e]); }
;                     else {
; #pragma unroll
;                         for (int e = 0; e < 8; ++e) o[e] = a[e] * bb[e] * siluf_(g[e]); }
;                     u32x4 w; w.x = cvt_pk_bf16(o[0], o[1]); w.y = cvt_pk_bf16(o[2], o[3]); w.z = cvt_pk_bf16(o[4], o[5]); w.w = cvt_pk_bf16(o[6], o[7]);
;                     *(u32x4*)(Y + row * DM + (MODE == 0 ? 1536 : 1024) + col0) = w;
	v_div_scale_f32 v41, s[0:1], v40, v40, 1.0
	v_rcp_f32_e32 v42, v41
	s_nop 0
	v_fma_f32 v43, -v41, v42, 1.0
	v_fmac_f32_e32 v42, v43, v42
	v_div_scale_f32 v43, vcc, 1.0, v40, 1.0
	v_mul_f32_e32 v44, v43, v42
	v_fma_f32 v45, -v41, v44, v43
	v_fmac_f32_e32 v44, v45, v42
	v_fma_f32 v41, -v41, v44, v43
	v_div_fmas_f32 v41, v41, v42, v44
	v_div_fixup_f32 v40, v41, v40, 1.0
	v_mul_f32_e32 v40, v40, v49
	v_mul_f32_e32 v29, v40, v29
	v_exp_f32_e32 v40, v30
	v_mul_f32_e32 v30, 0xbfb8aa3b, v46
	v_exp_f32_e32 v41, v30
	s_nop 0
	v_pk_add_f32 v[40:41], v[40:41], 1.0 op_sel_hi:[1,0]
	s_nop 0
	v_div_scale_f32 v30, s[0:1], v41, v41, v46
	v_rcp_f32_e32 v42, v30
	s_nop 0
	v_fma_f32 v43, -v30, v42, 1.0
	v_fmac_f32_e32 v42, v43, v42
	v_div_scale_f32 v43, vcc, v46, v41, v46
	v_mul_f32_e32 v44, v43, v42
	v_fma_f32 v45, -v30, v44, v43
	v_fmac_f32_e32 v44, v45, v42
	v_fma_f32 v30, -v30, v44, v43
	v_div_fmas_f32 v30, v30, v42, v44
	v_div_fixup_f32 v30, v30, v41, v46
	v_div_scale_f32 v41, s[0:1], v40, v40, 1.0
	v_rcp_f32_e32 v42, v41
	s_nop 0
	v_fma_f32 v43, -v41, v42, 1.0
	v_fmac_f32_e32 v42, v43, v42
	v_div_scale_f32 v43, vcc, 1.0, v40, 1.0
	v_mul_f32_e32 v44, v43, v42
	v_fma_f32 v45, -v41, v44, v43
	v_fmac_f32_e32 v44, v45, v42
	v_fma_f32 v41, -v41, v44, v43
	v_div_fmas_f32 v41, v41, v42, v44
	v_div_fixup_f32 v40, v41, v40, 1.0
	v_mul_f32_e32 v40, v40, v50
	v_mul_f32_e32 v30, v40, v30
	v_exp_f32_e32 v40, v31
	v_mul_f32_e32 v31, 0xbfb8aa3b, v47
	v_exp_f32_e32 v41, v31
	s_nop 0
	v_pk_add_f32 v[40:41], v[40:41], 1.0 op_sel_hi:[1,0]
	s_nop 0
	v_div_scale_f32 v31, s[0:1], v41, v41, v47
	v_rcp_f32_e32 v42, v31
	s_nop 0
	v_fma_f32 v43, -v31, v42, 1.0
	v_fmac_f32_e32 v42, v43, v42
	v_div_scale_f32 v43, vcc, v47, v41, v47
	v_mul_f32_e32 v44, v43, v42
	v_fma_f32 v45, -v31, v44, v43
	v_fmac_f32_e32 v44, v45, v42
	v_fma_f32 v31, -v31, v44, v43
	v_div_fmas_f32 v31, v31, v42, v44
	v_div_fixup_f32 v31, v31, v41, v47
	v_div_scale_f32 v41, s[0:1], v40, v40, 1.0
	v_rcp_f32_e32 v42, v41
	s_nop 0
	v_fma_f32 v43, -v41, v42, 1.0
	v_fmac_f32_e32 v42, v43, v42
	v_div_scale_f32 v43, vcc, 1.0, v40, 1.0
	v_mul_f32_e32 v44, v43, v42
	v_fma_f32 v45, -v41, v44, v43
	v_fmac_f32_e32 v44, v45, v42
	v_fma_f32 v41, -v41, v44, v43
	v_div_fmas_f32 v41, v41, v42, v44
	v_div_fixup_f32 v40, v41, v40, 1.0
	v_mul_f32_e32 v40, v40, v51
	v_mul_f32_e32 v31, v40, v31
	v_exp_f32_e32 v40, v24
	v_mul_f32_e32 v24, 0xbfb8aa3b, v38
	v_exp_f32_e32 v41, v24
	s_nop 0
	v_pk_add_f32 v[40:41], v[40:41], 1.0 op_sel_hi:[1,0]
	s_nop 0
	v_div_scale_f32 v24, s[0:1], v41, v41, v38
	v_rcp_f32_e32 v42, v24
	s_nop 0
	v_fma_f32 v43, -v24, v42, 1.0
	v_fmac_f32_e32 v42, v43, v42
	v_div_scale_f32 v43, vcc, v38, v41, v38
	v_mul_f32_e32 v44, v43, v42
	v_fma_f32 v45, -v24, v44, v43
	v_fmac_f32_e32 v44, v45, v42
	v_fma_f32 v24, -v24, v44, v43
	v_div_fmas_f32 v24, v24, v42, v44
	v_div_fixup_f32 v24, v24, v41, v38
	v_div_scale_f32 v38, s[0:1], v40, v40, 1.0
	v_rcp_f32_e32 v41, v38
	s_nop 0
	v_fma_f32 v42, -v38, v41, 1.0
	v_fmac_f32_e32 v41, v42, v41
	v_div_scale_f32 v42, vcc, 1.0, v40, 1.0
	v_mul_f32_e32 v43, v42, v41
	v_fma_f32 v44, -v38, v43, v42
	v_fmac_f32_e32 v43, v44, v41
	v_fma_f32 v38, -v38, v43, v42
	v_div_fmas_f32 v38, v38, v41, v43
	v_div_fixup_f32 v38, v38, v40, 1.0
	v_mul_f32_e32 v38, v38, v39
	v_mul_f32_e32 v38, v38, v24
	v_add_f32_e32 v24, v25, v65
	v_mul_f32_e32 v24, 0xbfb8aa3b, v24
	v_mul_f32_e32 v25, 0xbfb8aa3b, v36
	v_exp_f32_e32 v24, v24
	v_exp_f32_e32 v25, v25
	s_nop 0
	v_pk_add_f32 v[24:25], v[24:25], 1.0 op_sel_hi:[1,0]
	s_nop 0
	v_div_scale_f32 v39, s[0:1], v25, v25, v36
	v_rcp_f32_e32 v40, v39
	s_nop 0
	v_fma_f32 v41, -v39, v40, 1.0
	v_fmac_f32_e32 v40, v41, v40
	v_div_scale_f32 v41, vcc, v36, v25, v36
	v_mul_f32_e32 v42, v41, v40
	v_fma_f32 v43, -v39, v42, v41
	v_fmac_f32_e32 v42, v43, v40
	v_fma_f32 v39, -v39, v42, v41
	v_div_fmas_f32 v39, v39, v40, v42
	v_div_fixup_f32 v25, v39, v25, v36
	v_div_scale_f32 v36, s[0:1], v24, v24, 1.0
	v_rcp_f32_e32 v39, v36
	s_nop 0
	v_fma_f32 v40, -v36, v39, 1.0
	v_fmac_f32_e32 v39, v40, v39
	v_div_scale_f32 v40, vcc, 1.0, v24, 1.0
	v_mul_f32_e32 v41, v40, v39
	v_fma_f32 v42, -v36, v41, v40
	v_fmac_f32_e32 v41, v42, v39
	v_fma_f32 v36, -v36, v41, v40
	v_div_fmas_f32 v36, v36, v39, v41
	v_div_fixup_f32 v24, v36, v24, 1.0
	v_mul_f32_e32 v24, v24, v37
	v_mul_f32_e32 v36, v24, v25
	v_add_f32_e32 v24, v26, v66
	v_mul_f32_e32 v24, 0xbfb8aa3b, v24
	v_mul_f32_e32 v25, 0xbfb8aa3b, v34
	v_exp_f32_e32 v24, v24
	v_exp_f32_e32 v25, v25
	s_nop 0
	v_pk_add_f32 v[24:25], v[24:25], 1.0 op_sel_hi:[1,0]
	s_nop 0
	v_div_scale_f32 v26, s[0:1], v25, v25, v34
	v_rcp_f32_e32 v37, v26
	s_nop 0
	v_fma_f32 v39, -v26, v37, 1.0
	v_fmac_f32_e32 v37, v39, v37
	v_div_scale_f32 v39, vcc, v34, v25, v34
	v_mul_f32_e32 v40, v39, v37
	v_fma_f32 v41, -v26, v40, v39
	v_fmac_f32_e32 v40, v41, v37
	v_fma_f32 v26, -v26, v40, v39
	v_div_fmas_f32 v26, v26, v37, v40
	v_div_fixup_f32 v25, v26, v25, v34
	v_div_scale_f32 v26, s[0:1], v24, v24, 1.0
	v_rcp_f32_e32 v34, v26
	s_nop 0
	v_fma_f32 v37, -v26, v34, 1.0
	v_fmac_f32_e32 v34, v37, v34
	v_div_scale_f32 v37, vcc, 1.0, v24, 1.0
	v_mul_f32_e32 v39, v37, v34
	v_fma_f32 v40, -v26, v39, v37
	v_fmac_f32_e32 v39, v40, v34
	v_fma_f32 v26, -v26, v39, v37
	v_div_fmas_f32 v26, v26, v34, v39
	v_div_fixup_f32 v24, v26, v24, 1.0
	v_mul_f32_e32 v24, v24, v35
	v_mul_f32_e32 v34, v24, v25
	v_add_f32_e32 v24, v27, v67
	v_mul_f32_e32 v24, 0xbfb8aa3b, v24
	v_mul_f32_e32 v25, 0xbfb8aa3b, v32
	v_exp_f32_e32 v24, v24
	v_exp_f32_e32 v25, v25
	s_nop 0
	v_pk_add_f32 v[24:25], v[24:25], 1.0 op_sel_hi:[1,0]
	s_nop 0
	v_div_scale_f32 v26, s[0:1], v25, v25, v32
	v_rcp_f32_e32 v27, v26
	s_nop 0
	v_fma_f32 v35, -v26, v27, 1.0
	v_fmac_f32_e32 v27, v35, v27
	v_div_scale_f32 v35, vcc, v32, v25, v32
	v_mul_f32_e32 v37, v35, v27
	v_fma_f32 v39, -v26, v37, v35
	v_fmac_f32_e32 v37, v39, v27
	v_fma_f32 v26, -v26, v37, v35
	v_div_fmas_f32 v26, v26, v27, v37
	v_div_fixup_f32 v25, v26, v25, v32
	v_div_scale_f32 v26, s[0:1], v24, v24, 1.0
	v_rcp_f32_e32 v27, v26
	s_nop 0
	v_fma_f32 v32, -v26, v27, 1.0
	v_fmac_f32_e32 v27, v32, v27
	v_div_scale_f32 v32, vcc, 1.0, v24, 1.0
	v_mul_f32_e32 v35, v32, v27
	v_fma_f32 v37, -v26, v35, v32
	v_fmac_f32_e32 v35, v37, v27
	v_fma_f32 v26, -v26, v35, v32
	v_div_fmas_f32 v26, v26, v27, v35
	v_div_fixup_f32 v24, v26, v24, 1.0
	v_mul_f32_e32 v24, v24, v33
	v_mul_f32_e32 v27, v24, v25
	v_cvt_pk_bf16_f32 v24, v28, v29
	v_cvt_pk_bf16_f32 v25, v30, v31
	v_cvt_pk_bf16_f32 v26, v38, v36
	v_cvt_pk_bf16_f32 v27, v34, v27
	global_store_dwordx4 v[96:97], v[24:27], off offset:3328
	s_add_u32 s0, s14, 0x108000
	s_addc_u32 s1, s15, 0
	global_load_dwordx4 v[168:171], v214, s[0:1] offset:256
	s_add_u32 s0, s18, 0x2c000
	s_addc_u32 s1, s19, 0
	global_load_dwordx4 v[172:175], v215, s[0:1] offset:256
	s_waitcnt vmcnt(6)
; __device__ __forceinline__ unsigned cvt_pk_bf16(float lo, float hi) { unsigned r; asm volatile("v_cvt_pk_bf16_f32 %0, %1, %2" : "=v"(r) : "v"(lo), "v"(hi)); return r; }
; __device__ __forceinline__ float sigmoidf_(float v) { return 1.f / (1.f + __expf(-v)); }
; __device__ __forceinline__ float siluf_(float v) { return v / (1.f + __expf(-v)); }
;     __device__ __forceinline__ void operator()(const f32x4 (&acc)[2][2][4][2], const Unit& u, int wr, int wc, int fr, int fq) const {
;     ...
;                     const size_t row = (size_t)(row0 + ai * HALF + m * 16);
;                     const f32x4 v0 = acc[ai][bj][m][0], v1 = acc[ai][bj][m][1];
;                     float a[8] = {v0[0], v0[1], v0[2], v0[3], v1[0], v1[1], v1[2], v1[3]}, g[8], o[8];
;                     unpack8(*(const u32x4*)(R + row * RLD + (MODE == 0 ? 2560 : 1536) + col0), g);
;                     if (MODE == 0) { float y[8]; unpack8(*(const u32x4*)(YG + row * 512 + col0), y);
; #pragma unroll
;                         for (int e = 0; e < 8; ++e) o[e] = y[e] * sigmoidf_(a[e] + bb[e]) * siluf_(g[e]); }
;                     else {
; #pragma unroll
;                         for (int e = 0; e < 8; ++e) o[e] = a[e] * bb[e] * siluf_(g[e]); }
;                     u32x4 w; w.x = cvt_pk_bf16(o[0], o[1]); w.y = cvt_pk_bf16(o[2], o[3]); w.z = cvt_pk_bf16(o[4], o[5]); w.w = cvt_pk_bf16(o[6], o[7]);
;                     *(u32x4*)(Y + row * DM + (MODE == 0 ? 1536 : 1024) + col0) = w;
	v_mov_b32_e32 v32, v196
	v_mov_b32_e32 v33, v197
	v_mov_b32_e32 v34, v198
	v_mov_b32_e32 v35, v199
	v_lshlrev_b32_e32 v40, 16, v32
	v_lshl_add_u64 v[24:25], v[98:99], 0, v[180:181]
	v_mov_b32_e32 v24, v188
	v_mov_b32_e32 v25, v189
	v_mov_b32_e32 v26, v190
	v_mov_b32_e32 v27, v191
	v_and_b32_e32 v41, 0xffff0000, v32
	v_exp_f32_e32 v32, v20
	v_lshlrev_b32_e32 v42, 16, v33
	v_and_b32_e32 v43, 0xffff0000, v33
	v_lshlrev_b32_e32 v31, 16, v34
	v_and_b32_e32 v29, 0xffff0000, v34
	v_lshlrev_b32_e32 v36, 16, v24
	v_mul_f32_e32 v20, 0xbfb8aa3b, v36
	v_exp_f32_e32 v33, v20
	v_and_b32_e32 v37, 0xffff0000, v24
	v_lshlrev_b32_e32 v38, 16, v25
	v_and_b32_e32 v39, 0xffff0000, v25
	v_pk_add_f32 v[32:33], v[32:33], 1.0 op_sel_hi:[1,0]
	v_lshlrev_b32_e32 v30, 16, v26
	v_div_scale_f32 v20, s[0:1], v33, v33, v36
	v_rcp_f32_e32 v34, v20
	v_and_b32_e32 v28, 0xffff0000, v26
	v_lshlrev_b32_e32 v26, 16, v27
	v_and_b32_e32 v24, 0xffff0000, v27
	v_lshlrev_b32_e32 v27, 16, v35
	v_and_b32_e32 v25, 0xffff0000, v35
	v_fma_f32 v35, -v20, v34, 1.0
	v_fmac_f32_e32 v34, v35, v34
	v_div_scale_f32 v35, vcc, v36, v33, v36
	v_mul_f32_e32 v44, v35, v34
	v_fma_f32 v45, -v20, v44, v35
	v_fmac_f32_e32 v44, v45, v34
	v_fma_f32 v20, -v20, v44, v35
	v_div_fmas_f32 v20, v20, v34, v44
	v_div_fixup_f32 v20, v20, v33, v36
	v_div_scale_f32 v33, s[0:1], v32, v32, 1.0
	v_rcp_f32_e32 v34, v33
	s_nop 0
	v_fma_f32 v35, -v33, v34, 1.0
	v_fmac_f32_e32 v34, v35, v34
	v_div_scale_f32 v35, vcc, 1.0, v32, 1.0
	v_mul_f32_e32 v36, v35, v34
	v_fma_f32 v44, -v33, v36, v35
	v_fmac_f32_e32 v36, v44, v34
	v_fma_f32 v33, -v33, v36, v35
	v_div_fmas_f32 v33, v33, v34, v36
	v_div_fixup_f32 v32, v33, v32, 1.0
	v_mul_f32_e32 v32, v32, v40
	v_mul_f32_e32 v20, v32, v20
	v_exp_f32_e32 v32, v21
	v_mul_f32_e32 v21, 0xbfb8aa3b, v37
	v_exp_f32_e32 v33, v21
	s_nop 0
	v_pk_add_f32 v[32:33], v[32:33], 1.0 op_sel_hi:[1,0]
	s_nop 0
	v_div_scale_f32 v21, s[0:1], v33, v33, v37
	v_rcp_f32_e32 v34, v21
	s_nop 0
	v_fma_f32 v35, -v21, v34, 1.0
	v_fmac_f32_e32 v34, v35, v34
	v_div_scale_f32 v35, vcc, v37, v33, v37
	v_mul_f32_e32 v36, v35, v34
	v_fma_f32 v40, -v21, v36, v35
	v_fmac_f32_e32 v36, v40, v34
	v_fma_f32 v21, -v21, v36, v35
	v_div_fmas_f32 v21, v21, v34, v36
	v_div_fixup_f32 v21, v21, v33, v37
	v_div_scale_f32 v33, s[0:1], v32, v32, 1.0
	v_rcp_f32_e32 v34, v33
	s_nop 0
	v_fma_f32 v35, -v33, v34, 1.0
	v_fmac_f32_e32 v34, v35, v34
	v_div_scale_f32 v35, vcc, 1.0, v32, 1.0
	v_mul_f32_e32 v36, v35, v34
	v_fma_f32 v37, -v33, v36, v35
	v_fmac_f32_e32 v36, v37, v34
	v_fma_f32 v33, -v33, v36, v35
	v_div_fmas_f32 v33, v33, v34, v36
	v_div_fixup_f32 v32, v33, v32, 1.0
	v_mul_f32_e32 v32, v32, v41
	v_mul_f32_e32 v21, v32, v21
	v_exp_f32_e32 v32, v22
	v_mul_f32_e32 v22, 0xbfb8aa3b, v38
	v_exp_f32_e32 v33, v22
	s_nop 0
	v_pk_add_f32 v[32:33], v[32:33], 1.0 op_sel_hi:[1,0]
	s_nop 0
	v_div_scale_f32 v22, s[0:1], v33, v33, v38
	v_rcp_f32_e32 v34, v22
	s_nop 0
	v_fma_f32 v35, -v22, v34, 1.0
	v_fmac_f32_e32 v34, v35, v34
	v_div_scale_f32 v35, vcc, v38, v33, v38
	v_mul_f32_e32 v36, v35, v34
	v_fma_f32 v37, -v22, v36, v35
	v_fmac_f32_e32 v36, v37, v34
	v_fma_f32 v22, -v22, v36, v35
	v_div_fmas_f32 v22, v22, v34, v36
	v_div_fixup_f32 v22, v22, v33, v38
	v_div_scale_f32 v33, s[0:1], v32, v32, 1.0
	v_rcp_f32_e32 v34, v33
	s_nop 0
	v_fma_f32 v35, -v33, v34, 1.0
	v_fmac_f32_e32 v34, v35, v34
	v_div_scale_f32 v35, vcc, 1.0, v32, 1.0
	v_mul_f32_e32 v36, v35, v34
	v_fma_f32 v37, -v33, v36, v35
	v_fmac_f32_e32 v36, v37, v34
	v_fma_f32 v33, -v33, v36, v35
	v_div_fmas_f32 v33, v33, v34, v36
	v_div_fixup_f32 v32, v33, v32, 1.0
	v_mul_f32_e32 v32, v32, v42
	v_mul_f32_e32 v22, v32, v22
	v_exp_f32_e32 v32, v23
	v_mul_f32_e32 v23, 0xbfb8aa3b, v39
	v_exp_f32_e32 v33, v23
	s_nop 0
	v_pk_add_f32 v[32:33], v[32:33], 1.0 op_sel_hi:[1,0]
	s_nop 0
	v_div_scale_f32 v23, s[0:1], v33, v33, v39
	v_rcp_f32_e32 v34, v23
	s_nop 0
	v_fma_f32 v35, -v23, v34, 1.0
	v_fmac_f32_e32 v34, v35, v34
	v_div_scale_f32 v35, vcc, v39, v33, v39
	v_mul_f32_e32 v36, v35, v34
	v_fma_f32 v37, -v23, v36, v35
	v_fmac_f32_e32 v36, v37, v34
	v_fma_f32 v23, -v23, v36, v35
	v_div_fmas_f32 v23, v23, v34, v36
	v_div_fixup_f32 v23, v23, v33, v39
	v_div_scale_f32 v33, s[0:1], v32, v32, 1.0
	v_rcp_f32_e32 v34, v33
	s_nop 0
	v_fma_f32 v35, -v33, v34, 1.0
	v_fmac_f32_e32 v34, v35, v34
	v_div_scale_f32 v35, vcc, 1.0, v32, 1.0
	v_mul_f32_e32 v36, v35, v34
	v_fma_f32 v37, -v33, v36, v35
	v_fmac_f32_e32 v36, v37, v34
	v_fma_f32 v33, -v33, v36, v35
	v_div_fmas_f32 v33, v33, v34, v36
	v_div_fixup_f32 v32, v33, v32, 1.0
	v_mul_f32_e32 v32, v32, v43
	v_mul_f32_e32 v23, v32, v23
	v_exp_f32_e32 v32, v16
	v_mul_f32_e32 v16, 0xbfb8aa3b, v30
	v_exp_f32_e32 v33, v16
	s_nop 0
	v_pk_add_f32 v[32:33], v[32:33], 1.0 op_sel_hi:[1,0]
	s_nop 0
	v_div_scale_f32 v16, s[0:1], v33, v33, v30
	v_rcp_f32_e32 v34, v16
	s_nop 0
	v_fma_f32 v35, -v16, v34, 1.0
	v_fmac_f32_e32 v34, v35, v34
	v_div_scale_f32 v35, vcc, v30, v33, v30
	v_mul_f32_e32 v36, v35, v34
	v_fma_f32 v37, -v16, v36, v35
	v_fmac_f32_e32 v36, v37, v34
	v_fma_f32 v16, -v16, v36, v35
	v_div_fmas_f32 v16, v16, v34, v36
	v_div_fixup_f32 v16, v16, v33, v30
	v_div_scale_f32 v30, s[0:1], v32, v32, 1.0
	v_rcp_f32_e32 v33, v30
	s_nop 0
	v_fma_f32 v34, -v30, v33, 1.0
	v_fmac_f32_e32 v33, v34, v33
	v_div_scale_f32 v34, vcc, 1.0, v32, 1.0
	v_mul_f32_e32 v35, v34, v33
	v_fma_f32 v36, -v30, v35, v34
	v_fmac_f32_e32 v35, v36, v33
	v_fma_f32 v30, -v30, v35, v34
	v_div_fmas_f32 v30, v30, v33, v35
	v_div_fixup_f32 v30, v30, v32, 1.0
	v_mul_f32_e32 v30, v30, v31
	v_mul_f32_e32 v30, v30, v16
	v_add_f32_e32 v16, v17, v65
	v_mul_f32_e32 v16, 0xbfb8aa3b, v16
	v_mul_f32_e32 v17, 0xbfb8aa3b, v28
; __device__ __forceinline__ unsigned cvt_pk_bf16(float lo, float hi) { unsigned r; asm volatile("v_cvt_pk_bf16_f32 %0, %1, %2" : "=v"(r) : "v"(lo), "v"(hi)); return r; }
; __device__ __forceinline__ float sigmoidf_(float v) { return 1.f / (1.f + __expf(-v)); }
; __device__ __forceinline__ float siluf_(float v) { return v / (1.f + __expf(-v)); }
;     __device__ __forceinline__ void operator()(const f32x4 (&acc)[2][2][4][2], const Unit& u, int wr, int wc, int fr, int fq) const {
;     ...
;                     const size_t row = (size_t)(row0 + ai * HALF + m * 16);
;                     const f32x4 v0 = acc[ai][bj][m][0], v1 = acc[ai][bj][m][1];
;                     float a[8] = {v0[0], v0[1], v0[2], v0[3], v1[0], v1[1], v1[2], v1[3]}, g[8], o[8];
;                     unpack8(*(const u32x4*)(R + row * RLD + (MODE == 0 ? 2560 : 1536) + col0), g);
;                     if (MODE == 0) { float y[8]; unpack8(*(const u32x4*)(YG + row * 512 + col0), y);
; #pragma unroll
;                         for (int e = 0; e < 8; ++e) o[e] = y[e] * sigmoidf_(a[e] + bb[e]) * siluf_(g[e]); }
;                     else {
; #pragma unroll
;                         for (int e = 0; e < 8; ++e) o[e] = a[e] * bb[e] * siluf_(g[e]); }
;                     u32x4 w; w.x = cvt_pk_bf16(o[0], o[1]); w.y = cvt_pk_bf16(o[2], o[3]); w.z = cvt_pk_bf16(o[4], o[5]); w.w = cvt_pk_bf16(o[6], o[7]);
;                     *(u32x4*)(Y + row * DM + (MODE == 0 ? 1536 : 1024) + col0) = w;
	v_exp_f32_e32 v16, v16
	v_exp_f32_e32 v17, v17
	s_nop 0
	v_pk_add_f32 v[16:17], v[16:17], 1.0 op_sel_hi:[1,0]
	s_nop 0
	v_div_scale_f32 v31, s[0:1], v17, v17, v28
	v_rcp_f32_e32 v32, v31
	s_nop 0
	v_fma_f32 v33, -v31, v32, 1.0
	v_fmac_f32_e32 v32, v33, v32
	v_div_scale_f32 v33, vcc, v28, v17, v28
	v_mul_f32_e32 v34, v33, v32
	v_fma_f32 v35, -v31, v34, v33
	v_fmac_f32_e32 v34, v35, v32
	v_fma_f32 v31, -v31, v34, v33
	v_div_fmas_f32 v31, v31, v32, v34
	v_div_fixup_f32 v17, v31, v17, v28
	v_div_scale_f32 v28, s[0:1], v16, v16, 1.0
	v_rcp_f32_e32 v31, v28
	s_nop 0
	v_fma_f32 v32, -v28, v31, 1.0
	v_fmac_f32_e32 v31, v32, v31
	v_div_scale_f32 v32, vcc, 1.0, v16, 1.0
	v_mul_f32_e32 v33, v32, v31
	v_fma_f32 v34, -v28, v33, v32
	v_fmac_f32_e32 v33, v34, v31
	v_fma_f32 v28, -v28, v33, v32
	v_div_fmas_f32 v28, v28, v31, v33
	v_div_fixup_f32 v16, v28, v16, 1.0
	v_mul_f32_e32 v16, v16, v29
	v_mul_f32_e32 v28, v16, v17
	v_add_f32_e32 v16, v18, v66
	v_mul_f32_e32 v16, 0xbfb8aa3b, v16
	v_mul_f32_e32 v17, 0xbfb8aa3b, v26
	v_exp_f32_e32 v16, v16
	v_exp_f32_e32 v17, v17
	s_nop 0
	v_pk_add_f32 v[16:17], v[16:17], 1.0 op_sel_hi:[1,0]
	s_nop 0
	v_div_scale_f32 v18, s[0:1], v17, v17, v26
	v_rcp_f32_e32 v29, v18
	s_nop 0
	v_fma_f32 v31, -v18, v29, 1.0
	v_fmac_f32_e32 v29, v31, v29
	v_div_scale_f32 v31, vcc, v26, v17, v26
	v_mul_f32_e32 v32, v31, v29
	v_fma_f32 v33, -v18, v32, v31
	v_fmac_f32_e32 v32, v33, v29
	v_fma_f32 v18, -v18, v32, v31
	v_div_fmas_f32 v18, v18, v29, v32
	v_div_fixup_f32 v17, v18, v17, v26
	v_div_scale_f32 v18, s[0:1], v16, v16, 1.0
	v_rcp_f32_e32 v26, v18
	s_nop 0
	v_fma_f32 v29, -v18, v26, 1.0
	v_fmac_f32_e32 v26, v29, v26
	v_div_scale_f32 v29, vcc, 1.0, v16, 1.0
	v_mul_f32_e32 v31, v29, v26
	v_fma_f32 v32, -v18, v31, v29
	v_fmac_f32_e32 v31, v32, v26
	v_fma_f32 v18, -v18, v31, v29
	v_div_fmas_f32 v18, v18, v26, v31
	v_div_fixup_f32 v16, v18, v16, 1.0
	v_mul_f32_e32 v16, v16, v27
	v_mul_f32_e32 v26, v16, v17
	v_add_f32_e32 v16, v19, v67
	v_mul_f32_e32 v16, 0xbfb8aa3b, v16
	v_mul_f32_e32 v17, 0xbfb8aa3b, v24
	v_exp_f32_e32 v16, v16
	v_exp_f32_e32 v17, v17
	s_nop 0
	v_pk_add_f32 v[16:17], v[16:17], 1.0 op_sel_hi:[1,0]
	s_nop 0
	v_div_scale_f32 v18, s[0:1], v17, v17, v24
	v_rcp_f32_e32 v19, v18
	s_nop 0
	v_fma_f32 v27, -v18, v19, 1.0
	v_fmac_f32_e32 v19, v27, v19
	v_div_scale_f32 v27, vcc, v24, v17, v24
	v_mul_f32_e32 v29, v27, v19
	v_fma_f32 v31, -v18, v29, v27
	v_fmac_f32_e32 v29, v31, v19
	v_fma_f32 v18, -v18, v29, v27
	v_div_fmas_f32 v18, v18, v19, v29
	v_div_fixup_f32 v17, v18, v17, v24
	v_div_scale_f32 v18, s[0:1], v16, v16, 1.0
	v_rcp_f32_e32 v19, v18
	s_nop 0
	v_fma_f32 v24, -v18, v19, 1.0
	v_fmac_f32_e32 v19, v24, v19
	v_div_scale_f32 v24, vcc, 1.0, v16, 1.0
	v_mul_f32_e32 v27, v24, v19
	v_fma_f32 v29, -v18, v27, v24
	v_fmac_f32_e32 v27, v29, v19
	v_fma_f32 v18, -v18, v27, v24
	v_div_fmas_f32 v18, v18, v19, v27
	v_div_fixup_f32 v16, v18, v16, 1.0
	v_mul_f32_e32 v16, v16, v25
	v_mul_f32_e32 v19, v16, v17
	v_cvt_pk_bf16_f32 v16, v20, v21
	v_cvt_pk_bf16_f32 v17, v22, v23
	v_cvt_pk_bf16_f32 v18, v30, v28
	v_cvt_pk_bf16_f32 v19, v26, v19
	global_store_dwordx4 v[88:89], v[16:19], off offset:3328
	s_waitcnt vmcnt(4)
	v_mov_b32_e32 v24, v210
	v_mov_b32_e32 v25, v211
	v_mov_b32_e32 v26, v212
	v_mov_b32_e32 v27, v213
	v_lshlrev_b32_e32 v32, 16, v24
	v_lshl_add_u64 v[16:17], v[90:91], 0, v[180:181]
	v_mov_b32_e32 v16, v206
	v_mov_b32_e32 v17, v207
	v_mov_b32_e32 v18, v208
	v_mov_b32_e32 v19, v209
	v_and_b32_e32 v33, 0xffff0000, v24
	v_exp_f32_e32 v24, v12
	v_lshlrev_b32_e32 v34, 16, v25
	v_and_b32_e32 v35, 0xffff0000, v25
	v_lshlrev_b32_e32 v23, 16, v26
	v_and_b32_e32 v21, 0xffff0000, v26
	v_lshlrev_b32_e32 v28, 16, v16
	v_mul_f32_e32 v12, 0xbfb8aa3b, v28
	v_exp_f32_e32 v25, v12
	v_and_b32_e32 v29, 0xffff0000, v16
	v_lshlrev_b32_e32 v30, 16, v17
	v_and_b32_e32 v31, 0xffff0000, v17
	v_pk_add_f32 v[24:25], v[24:25], 1.0 op_sel_hi:[1,0]
	v_lshlrev_b32_e32 v22, 16, v18
	v_div_scale_f32 v12, s[0:1], v25, v25, v28
	v_rcp_f32_e32 v26, v12
	v_and_b32_e32 v20, 0xffff0000, v18
	v_lshlrev_b32_e32 v18, 16, v19
	v_and_b32_e32 v16, 0xffff0000, v19
	v_lshlrev_b32_e32 v19, 16, v27
	v_and_b32_e32 v17, 0xffff0000, v27
	v_fma_f32 v27, -v12, v26, 1.0
	v_fmac_f32_e32 v26, v27, v26
	v_div_scale_f32 v27, vcc, v28, v25, v28
	v_mul_f32_e32 v36, v27, v26
	v_fma_f32 v37, -v12, v36, v27
	v_fmac_f32_e32 v36, v37, v26
	v_fma_f32 v12, -v12, v36, v27
	v_div_fmas_f32 v12, v12, v26, v36
	v_div_fixup_f32 v12, v12, v25, v28
	v_div_scale_f32 v25, s[0:1], v24, v24, 1.0
	v_rcp_f32_e32 v26, v25
	s_nop 0
	v_fma_f32 v27, -v25, v26, 1.0
	v_fmac_f32_e32 v26, v27, v26
	v_div_scale_f32 v27, vcc, 1.0, v24, 1.0
	v_mul_f32_e32 v28, v27, v26
	v_fma_f32 v36, -v25, v28, v27
	v_fmac_f32_e32 v28, v36, v26
	v_fma_f32 v25, -v25, v28, v27
	v_div_fmas_f32 v25, v25, v26, v28
	v_div_fixup_f32 v24, v25, v24, 1.0
	v_mul_f32_e32 v24, v24, v32
	v_mul_f32_e32 v12, v24, v12
	v_exp_f32_e32 v24, v13
	v_mul_f32_e32 v13, 0xbfb8aa3b, v29
	v_exp_f32_e32 v25, v13
	s_nop 0
	v_pk_add_f32 v[24:25], v[24:25], 1.0 op_sel_hi:[1,0]
	s_nop 0
	v_div_scale_f32 v13, s[0:1], v25, v25, v29
	v_rcp_f32_e32 v26, v13
	s_nop 0
	v_fma_f32 v27, -v13, v26, 1.0
	v_fmac_f32_e32 v26, v27, v26
	v_div_scale_f32 v27, vcc, v29, v25, v29
	v_mul_f32_e32 v28, v27, v26
	v_fma_f32 v32, -v13, v28, v27
	v_fmac_f32_e32 v28, v32, v26
	v_fma_f32 v13, -v13, v28, v27
	v_div_fmas_f32 v13, v13, v26, v28
	v_div_fixup_f32 v13, v13, v25, v29
	v_div_scale_f32 v25, s[0:1], v24, v24, 1.0
	v_rcp_f32_e32 v26, v25
	s_nop 0
	v_fma_f32 v27, -v25, v26, 1.0
	v_fmac_f32_e32 v26, v27, v26
	v_div_scale_f32 v27, vcc, 1.0, v24, 1.0
	v_mul_f32_e32 v28, v27, v26
; __device__ __forceinline__ unsigned cvt_pk_bf16(float lo, float hi) { unsigned r; asm volatile("v_cvt_pk_bf16_f32 %0, %1, %2" : "=v"(r) : "v"(lo), "v"(hi)); return r; }
; __device__ __forceinline__ float sigmoidf_(float v) { return 1.f / (1.f + __expf(-v)); }
; __device__ __forceinline__ float siluf_(float v) { return v / (1.f + __expf(-v)); }
;     __device__ __forceinline__ void operator()(const f32x4 (&acc)[2][2][4][2], const Unit& u, int wr, int wc, int fr, int fq) const {
;     ...
;                     const size_t row = (size_t)(row0 + ai * HALF + m * 16);
;                     const f32x4 v0 = acc[ai][bj][m][0], v1 = acc[ai][bj][m][1];
;                     float a[8] = {v0[0], v0[1], v0[2], v0[3], v1[0], v1[1], v1[2], v1[3]}, g[8], o[8];
;                     unpack8(*(const u32x4*)(R + row * RLD + (MODE == 0 ? 2560 : 1536) + col0), g);
;                     if (MODE == 0) { float y[8]; unpack8(*(const u32x4*)(YG + row * 512 + col0), y);
; #pragma unroll
;                         for (int e = 0; e < 8; ++e) o[e] = y[e] * sigmoidf_(a[e] + bb[e]) * siluf_(g[e]); }
;                     else {
; #pragma unroll
;                         for (int e = 0; e < 8; ++e) o[e] = a[e] * bb[e] * siluf_(g[e]); }
;                     u32x4 w; w.x = cvt_pk_bf16(o[0], o[1]); w.y = cvt_pk_bf16(o[2], o[3]); w.z = cvt_pk_bf16(o[4], o[5]); w.w = cvt_pk_bf16(o[6], o[7]);
;                     *(u32x4*)(Y + row * DM + (MODE == 0 ? 1536 : 1024) + col0) = w;
	v_fma_f32 v29, -v25, v28, v27
	v_fmac_f32_e32 v28, v29, v26
	v_fma_f32 v25, -v25, v28, v27
	v_div_fmas_f32 v25, v25, v26, v28
	v_div_fixup_f32 v24, v25, v24, 1.0
	v_mul_f32_e32 v24, v24, v33
	v_mul_f32_e32 v13, v24, v13
	v_exp_f32_e32 v24, v14
	v_mul_f32_e32 v14, 0xbfb8aa3b, v30
	v_exp_f32_e32 v25, v14
	s_nop 0
	v_pk_add_f32 v[24:25], v[24:25], 1.0 op_sel_hi:[1,0]
	s_nop 0
	v_div_scale_f32 v14, s[0:1], v25, v25, v30
	v_rcp_f32_e32 v26, v14
	s_nop 0
	v_fma_f32 v27, -v14, v26, 1.0
	v_fmac_f32_e32 v26, v27, v26
	v_div_scale_f32 v27, vcc, v30, v25, v30
	v_mul_f32_e32 v28, v27, v26
	v_fma_f32 v29, -v14, v28, v27
	v_fmac_f32_e32 v28, v29, v26
	v_fma_f32 v14, -v14, v28, v27
	v_div_fmas_f32 v14, v14, v26, v28
	v_div_fixup_f32 v14, v14, v25, v30
	v_div_scale_f32 v25, s[0:1], v24, v24, 1.0
	v_rcp_f32_e32 v26, v25
	s_nop 0
	v_fma_f32 v27, -v25, v26, 1.0
	v_fmac_f32_e32 v26, v27, v26
	v_div_scale_f32 v27, vcc, 1.0, v24, 1.0
	v_mul_f32_e32 v28, v27, v26
	v_fma_f32 v29, -v25, v28, v27
	v_fmac_f32_e32 v28, v29, v26
	v_fma_f32 v25, -v25, v28, v27
	v_div_fmas_f32 v25, v25, v26, v28
	v_div_fixup_f32 v24, v25, v24, 1.0
	v_mul_f32_e32 v24, v24, v34
	v_mul_f32_e32 v14, v24, v14
	v_exp_f32_e32 v24, v15
	v_mul_f32_e32 v15, 0xbfb8aa3b, v31
	v_exp_f32_e32 v25, v15
	s_nop 0
	v_pk_add_f32 v[24:25], v[24:25], 1.0 op_sel_hi:[1,0]
	s_nop 0
	v_div_scale_f32 v15, s[0:1], v25, v25, v31
	v_rcp_f32_e32 v26, v15
	s_nop 0
	v_fma_f32 v27, -v15, v26, 1.0
	v_fmac_f32_e32 v26, v27, v26
	v_div_scale_f32 v27, vcc, v31, v25, v31
	v_mul_f32_e32 v28, v27, v26
	v_fma_f32 v29, -v15, v28, v27
	v_fmac_f32_e32 v28, v29, v26
	v_fma_f32 v15, -v15, v28, v27
	v_div_fmas_f32 v15, v15, v26, v28
	v_div_fixup_f32 v15, v15, v25, v31
	v_div_scale_f32 v25, s[0:1], v24, v24, 1.0
	v_rcp_f32_e32 v26, v25
	s_nop 0
	v_fma_f32 v27, -v25, v26, 1.0
	v_fmac_f32_e32 v26, v27, v26
	v_div_scale_f32 v27, vcc, 1.0, v24, 1.0
	v_mul_f32_e32 v28, v27, v26
	v_fma_f32 v29, -v25, v28, v27
	v_fmac_f32_e32 v28, v29, v26
	v_fma_f32 v25, -v25, v28, v27
	v_div_fmas_f32 v25, v25, v26, v28
	v_div_fixup_f32 v24, v25, v24, 1.0
	v_mul_f32_e32 v24, v24, v35
	v_mul_f32_e32 v15, v24, v15
	v_exp_f32_e32 v24, v8
	v_mul_f32_e32 v8, 0xbfb8aa3b, v22
	v_exp_f32_e32 v25, v8
	s_nop 0
	v_pk_add_f32 v[24:25], v[24:25], 1.0 op_sel_hi:[1,0]
	s_nop 0
	v_div_scale_f32 v8, s[0:1], v25, v25, v22
	v_rcp_f32_e32 v26, v8
	s_nop 0
	v_fma_f32 v27, -v8, v26, 1.0
	v_fmac_f32_e32 v26, v27, v26
	v_div_scale_f32 v27, vcc, v22, v25, v22
	v_mul_f32_e32 v28, v27, v26
	v_fma_f32 v29, -v8, v28, v27
	v_fmac_f32_e32 v28, v29, v26
	v_fma_f32 v8, -v8, v28, v27
	v_div_fmas_f32 v8, v8, v26, v28
	v_div_fixup_f32 v8, v8, v25, v22
	v_div_scale_f32 v22, s[0:1], v24, v24, 1.0
	v_rcp_f32_e32 v25, v22
	s_nop 0
	v_fma_f32 v26, -v22, v25, 1.0
	v_fmac_f32_e32 v25, v26, v25
	v_div_scale_f32 v26, vcc, 1.0, v24, 1.0
	v_mul_f32_e32 v27, v26, v25
	v_fma_f32 v28, -v22, v27, v26
	v_fmac_f32_e32 v27, v28, v25
	v_fma_f32 v22, -v22, v27, v26
	v_div_fmas_f32 v22, v22, v25, v27
	v_div_fixup_f32 v22, v22, v24, 1.0
	v_mul_f32_e32 v22, v22, v23
	v_mul_f32_e32 v22, v22, v8
	v_add_f32_e32 v8, v9, v65
	v_mul_f32_e32 v8, 0xbfb8aa3b, v8
	v_mul_f32_e32 v9, 0xbfb8aa3b, v20
	v_exp_f32_e32 v8, v8
	v_exp_f32_e32 v9, v9
	s_nop 0
	v_pk_add_f32 v[8:9], v[8:9], 1.0 op_sel_hi:[1,0]
	s_nop 0
	v_div_scale_f32 v23, s[0:1], v9, v9, v20
	v_rcp_f32_e32 v24, v23
	s_nop 0
	v_fma_f32 v25, -v23, v24, 1.0
	v_fmac_f32_e32 v24, v25, v24
	v_div_scale_f32 v25, vcc, v20, v9, v20
	v_mul_f32_e32 v26, v25, v24
	v_fma_f32 v27, -v23, v26, v25
	v_fmac_f32_e32 v26, v27, v24
	v_fma_f32 v23, -v23, v26, v25
	v_div_fmas_f32 v23, v23, v24, v26
	v_div_fixup_f32 v9, v23, v9, v20
	v_div_scale_f32 v20, s[0:1], v8, v8, 1.0
	v_rcp_f32_e32 v23, v20
	s_nop 0
	v_fma_f32 v24, -v20, v23, 1.0
	v_fmac_f32_e32 v23, v24, v23
	v_div_scale_f32 v24, vcc, 1.0, v8, 1.0
	v_mul_f32_e32 v25, v24, v23
	v_fma_f32 v26, -v20, v25, v24
	v_fmac_f32_e32 v25, v26, v23
	v_fma_f32 v20, -v20, v25, v24
	v_div_fmas_f32 v20, v20, v23, v25
	v_div_fixup_f32 v8, v20, v8, 1.0
	v_mul_f32_e32 v8, v8, v21
	v_mul_f32_e32 v20, v8, v9
	v_add_f32_e32 v8, v10, v66
	v_mul_f32_e32 v8, 0xbfb8aa3b, v8
	v_mul_f32_e32 v9, 0xbfb8aa3b, v18
	v_exp_f32_e32 v8, v8
	v_exp_f32_e32 v9, v9
	s_nop 0
	v_pk_add_f32 v[8:9], v[8:9], 1.0 op_sel_hi:[1,0]
	s_nop 0
	v_div_scale_f32 v10, s[0:1], v9, v9, v18
	v_rcp_f32_e32 v21, v10
	s_nop 0
	v_fma_f32 v23, -v10, v21, 1.0
	v_fmac_f32_e32 v21, v23, v21
	v_div_scale_f32 v23, vcc, v18, v9, v18
	v_mul_f32_e32 v24, v23, v21
	v_fma_f32 v25, -v10, v24, v23
	v_fmac_f32_e32 v24, v25, v21
	v_fma_f32 v10, -v10, v24, v23
	v_div_fmas_f32 v10, v10, v21, v24
	v_div_fixup_f32 v9, v10, v9, v18
	v_div_scale_f32 v10, s[0:1], v8, v8, 1.0
	v_rcp_f32_e32 v18, v10
	s_nop 0
	v_fma_f32 v21, -v10, v18, 1.0
	v_fmac_f32_e32 v18, v21, v18
	v_div_scale_f32 v21, vcc, 1.0, v8, 1.0
	v_mul_f32_e32 v23, v21, v18
	v_fma_f32 v24, -v10, v23, v21
	v_fmac_f32_e32 v23, v24, v18
	v_fma_f32 v10, -v10, v23, v21
	v_div_fmas_f32 v10, v10, v18, v23
	v_div_fixup_f32 v8, v10, v8, 1.0
	v_mul_f32_e32 v8, v8, v19
	v_mul_f32_e32 v18, v8, v9
	v_add_f32_e32 v8, v11, v67
	v_mul_f32_e32 v8, 0xbfb8aa3b, v8
	v_mul_f32_e32 v9, 0xbfb8aa3b, v16
	v_exp_f32_e32 v8, v8
	v_exp_f32_e32 v9, v9
	s_nop 0
	v_pk_add_f32 v[8:9], v[8:9], 1.0 op_sel_hi:[1,0]
	s_nop 0
	v_div_scale_f32 v10, s[0:1], v9, v9, v16
	v_rcp_f32_e32 v11, v10
	s_nop 0
	v_fma_f32 v19, -v10, v11, 1.0
	v_fmac_f32_e32 v11, v19, v11
	v_div_scale_f32 v19, vcc, v16, v9, v16
	v_mul_f32_e32 v21, v19, v11
	v_fma_f32 v23, -v10, v21, v19
	v_fmac_f32_e32 v21, v23, v11
	v_fma_f32 v10, -v10, v21, v19
	v_div_fmas_f32 v10, v10, v11, v21
	v_div_fixup_f32 v9, v10, v9, v16
	v_div_scale_f32 v10, s[0:1], v8, v8, 1.0
	v_rcp_f32_e32 v11, v10
	s_nop 0
	v_fma_f32 v16, -v10, v11, 1.0
	v_fmac_f32_e32 v11, v16, v11
	v_div_scale_f32 v16, vcc, 1.0, v8, 1.0
	v_mul_f32_e32 v19, v16, v11
	v_fma_f32 v21, -v10, v19, v16
	v_fmac_f32_e32 v19, v21, v11
	v_fma_f32 v10, -v10, v19, v16
	v_div_fmas_f32 v10, v10, v11, v19
	v_div_fixup_f32 v8, v10, v8, 1.0
	v_mul_f32_e32 v8, v8, v17
	v_mul_f32_e32 v11, v8, v9
	v_cvt_pk_bf16_f32 v8, v12, v13
	v_cvt_pk_bf16_f32 v9, v14, v15
	v_cvt_pk_bf16_f32 v10, v22, v20
	v_cvt_pk_bf16_f32 v11, v18, v11
	global_store_dwordx4 v[76:77], v[8:11], off offset:3328
	s_waitcnt vmcnt(2)
; __device__ __forceinline__ unsigned cvt_pk_bf16(float lo, float hi) { unsigned r; asm volatile("v_cvt_pk_bf16_f32 %0, %1, %2" : "=v"(r) : "v"(lo), "v"(hi)); return r; }
; __device__ __forceinline__ float sigmoidf_(float v) { return 1.f / (1.f + __expf(-v)); }
; __device__ __forceinline__ float siluf_(float v) { return v / (1.f + __expf(-v)); }
;     __device__ __forceinline__ void operator()(const f32x4 (&acc)[2][2][4][2], const Unit& u, int wr, int wc, int fr, int fq) const {
;     ...
;                     const size_t row = (size_t)(row0 + ai * HALF + m * 16);
;                     const f32x4 v0 = acc[ai][bj][m][0], v1 = acc[ai][bj][m][1];
;                     float a[8] = {v0[0], v0[1], v0[2], v0[3], v1[0], v1[1], v1[2], v1[3]}, g[8], o[8];
;                     unpack8(*(const u32x4*)(R + row * RLD + (MODE == 0 ? 2560 : 1536) + col0), g);
;                     if (MODE == 0) { float y[8]; unpack8(*(const u32x4*)(YG + row * 512 + col0), y);
; #pragma unroll
;                         for (int e = 0; e < 8; ++e) o[e] = y[e] * sigmoidf_(a[e] + bb[e]) * siluf_(g[e]); }
;                     else {
; #pragma unroll
;                         for (int e = 0; e < 8; ++e) o[e] = a[e] * bb[e] * siluf_(g[e]); }
;                     u32x4 w; w.x = cvt_pk_bf16(o[0], o[1]); w.y = cvt_pk_bf16(o[2], o[3]); w.z = cvt_pk_bf16(o[4], o[5]); w.w = cvt_pk_bf16(o[6], o[7]);
;                     *(u32x4*)(Y + row * DM + (MODE == 0 ? 1536 : 1024) + col0) = w;
	v_mov_b32_e32 v16, v172
	v_mov_b32_e32 v17, v173
	v_mov_b32_e32 v18, v174
	v_mov_b32_e32 v19, v175
	v_lshlrev_b32_e32 v24, 16, v16
	v_lshl_add_u64 v[8:9], v[78:79], 0, v[180:181]
	v_mov_b32_e32 v8, v168
	v_mov_b32_e32 v9, v169
	v_mov_b32_e32 v10, v170
	v_mov_b32_e32 v11, v171
	v_and_b32_e32 v25, 0xffff0000, v16
	v_exp_f32_e32 v16, v4
	v_lshlrev_b32_e32 v26, 16, v17
	v_and_b32_e32 v27, 0xffff0000, v17
	v_lshlrev_b32_e32 v15, 16, v18
	v_and_b32_e32 v13, 0xffff0000, v18
	v_lshlrev_b32_e32 v20, 16, v8
	v_mul_f32_e32 v4, 0xbfb8aa3b, v20
	v_exp_f32_e32 v17, v4
	v_and_b32_e32 v21, 0xffff0000, v8
	v_lshlrev_b32_e32 v22, 16, v9
	v_and_b32_e32 v23, 0xffff0000, v9
	v_pk_add_f32 v[16:17], v[16:17], 1.0 op_sel_hi:[1,0]
	v_lshlrev_b32_e32 v14, 16, v10
	v_div_scale_f32 v4, s[0:1], v17, v17, v20
	v_rcp_f32_e32 v18, v4
	v_and_b32_e32 v12, 0xffff0000, v10
	v_lshlrev_b32_e32 v10, 16, v11
	v_and_b32_e32 v8, 0xffff0000, v11
	v_lshlrev_b32_e32 v11, 16, v19
	v_and_b32_e32 v9, 0xffff0000, v19
	v_fma_f32 v19, -v4, v18, 1.0
	v_fmac_f32_e32 v18, v19, v18
	v_div_scale_f32 v19, vcc, v20, v17, v20
	v_mul_f32_e32 v28, v19, v18
	v_fma_f32 v29, -v4, v28, v19
	v_fmac_f32_e32 v28, v29, v18
	v_fma_f32 v4, -v4, v28, v19
	v_div_fmas_f32 v4, v4, v18, v28
	v_div_fixup_f32 v4, v4, v17, v20
	v_div_scale_f32 v17, s[0:1], v16, v16, 1.0
	v_rcp_f32_e32 v18, v17
	s_nop 0
	v_fma_f32 v19, -v17, v18, 1.0
	v_fmac_f32_e32 v18, v19, v18
	v_div_scale_f32 v19, vcc, 1.0, v16, 1.0
	v_mul_f32_e32 v20, v19, v18
	v_fma_f32 v28, -v17, v20, v19
	v_fmac_f32_e32 v20, v28, v18
	v_fma_f32 v17, -v17, v20, v19
	v_div_fmas_f32 v17, v17, v18, v20
	v_div_fixup_f32 v16, v17, v16, 1.0
	v_mul_f32_e32 v16, v16, v24
	v_mul_f32_e32 v4, v16, v4
	v_exp_f32_e32 v16, v5
	v_mul_f32_e32 v5, 0xbfb8aa3b, v21
	v_exp_f32_e32 v17, v5
	s_nop 0
	v_pk_add_f32 v[16:17], v[16:17], 1.0 op_sel_hi:[1,0]
	s_nop 0
	v_div_scale_f32 v5, s[0:1], v17, v17, v21
	v_rcp_f32_e32 v18, v5
	s_nop 0
	v_fma_f32 v19, -v5, v18, 1.0
	v_fmac_f32_e32 v18, v19, v18
	v_div_scale_f32 v19, vcc, v21, v17, v21
	v_mul_f32_e32 v20, v19, v18
	v_fma_f32 v24, -v5, v20, v19
	v_fmac_f32_e32 v20, v24, v18
	v_fma_f32 v5, -v5, v20, v19
	v_div_fmas_f32 v5, v5, v18, v20
	v_div_fixup_f32 v5, v5, v17, v21
	v_div_scale_f32 v17, s[0:1], v16, v16, 1.0
	v_rcp_f32_e32 v18, v17
	s_nop 0
	v_fma_f32 v19, -v17, v18, 1.0
	v_fmac_f32_e32 v18, v19, v18
	v_div_scale_f32 v19, vcc, 1.0, v16, 1.0
	v_mul_f32_e32 v20, v19, v18
	v_fma_f32 v21, -v17, v20, v19
	v_fmac_f32_e32 v20, v21, v18
	v_fma_f32 v17, -v17, v20, v19
	v_div_fmas_f32 v17, v17, v18, v20
	v_div_fixup_f32 v16, v17, v16, 1.0
	v_mul_f32_e32 v16, v16, v25
	v_mul_f32_e32 v5, v16, v5
	v_exp_f32_e32 v16, v6
	v_mul_f32_e32 v6, 0xbfb8aa3b, v22
	v_exp_f32_e32 v17, v6
	s_nop 0
	v_pk_add_f32 v[16:17], v[16:17], 1.0 op_sel_hi:[1,0]
	s_nop 0
	v_div_scale_f32 v6, s[0:1], v17, v17, v22
	v_rcp_f32_e32 v18, v6
	s_nop 0
	v_fma_f32 v19, -v6, v18, 1.0
	v_fmac_f32_e32 v18, v19, v18
	v_div_scale_f32 v19, vcc, v22, v17, v22
	v_mul_f32_e32 v20, v19, v18
	v_fma_f32 v21, -v6, v20, v19
	v_fmac_f32_e32 v20, v21, v18
	v_fma_f32 v6, -v6, v20, v19
	v_div_fmas_f32 v6, v6, v18, v20
	v_div_fixup_f32 v6, v6, v17, v22
	v_div_scale_f32 v17, s[0:1], v16, v16, 1.0
	v_rcp_f32_e32 v18, v17
	s_nop 0
	v_fma_f32 v19, -v17, v18, 1.0
	v_fmac_f32_e32 v18, v19, v18
	v_div_scale_f32 v19, vcc, 1.0, v16, 1.0
	v_mul_f32_e32 v20, v19, v18
	v_fma_f32 v21, -v17, v20, v19
	v_fmac_f32_e32 v20, v21, v18
	v_fma_f32 v17, -v17, v20, v19
	v_div_fmas_f32 v17, v17, v18, v20
	v_div_fixup_f32 v16, v17, v16, 1.0
	v_mul_f32_e32 v16, v16, v26
	v_mul_f32_e32 v6, v16, v6
	v_exp_f32_e32 v16, v7
	v_mul_f32_e32 v7, 0xbfb8aa3b, v23
	v_exp_f32_e32 v17, v7
	s_nop 0
	v_pk_add_f32 v[16:17], v[16:17], 1.0 op_sel_hi:[1,0]
	s_nop 0
	v_div_scale_f32 v7, s[0:1], v17, v17, v23
	v_rcp_f32_e32 v18, v7
	s_nop 0
	v_fma_f32 v19, -v7, v18, 1.0
	v_fmac_f32_e32 v18, v19, v18
	v_div_scale_f32 v19, vcc, v23, v17, v23
	v_mul_f32_e32 v20, v19, v18
	v_fma_f32 v21, -v7, v20, v19
	v_fmac_f32_e32 v20, v21, v18
	v_fma_f32 v7, -v7, v20, v19
	v_div_fmas_f32 v7, v7, v18, v20
	v_div_fixup_f32 v7, v7, v17, v23
	v_div_scale_f32 v17, s[0:1], v16, v16, 1.0
	v_rcp_f32_e32 v18, v17
	s_nop 0
	v_fma_f32 v19, -v17, v18, 1.0
	v_fmac_f32_e32 v18, v19, v18
	v_div_scale_f32 v19, vcc, 1.0, v16, 1.0
	v_mul_f32_e32 v20, v19, v18
; __device__ __forceinline__ unsigned cvt_pk_bf16(float lo, float hi) { unsigned r; asm volatile("v_cvt_pk_bf16_f32 %0, %1, %2" : "=v"(r) : "v"(lo), "v"(hi)); return r; }
; __device__ __forceinline__ float sigmoidf_(float v) { return 1.f / (1.f + __expf(-v)); }
; __device__ __forceinline__ float siluf_(float v) { return v / (1.f + __expf(-v)); }
;     __device__ __forceinline__ void operator()(const f32x4 (&acc)[2][2][4][2], const Unit& u, int wr, int wc, int fr, int fq) const {
;     ...
;                     const size_t row = (size_t)(row0 + ai * HALF + m * 16);
;                     const f32x4 v0 = acc[ai][bj][m][0], v1 = acc[ai][bj][m][1];
;                     float a[8] = {v0[0], v0[1], v0[2], v0[3], v1[0], v1[1], v1[2], v1[3]}, g[8], o[8];
;                     unpack8(*(const u32x4*)(R + row * RLD + (MODE == 0 ? 2560 : 1536) + col0), g);
;                     if (MODE == 0) { float y[8]; unpack8(*(const u32x4*)(YG + row * 512 + col0), y);
; #pragma unroll
;                         for (int e = 0; e < 8; ++e) o[e] = y[e] * sigmoidf_(a[e] + bb[e]) * siluf_(g[e]); }
;                     else {
; #pragma unroll
;                         for (int e = 0; e < 8; ++e) o[e] = a[e] * bb[e] * siluf_(g[e]); }
;                     u32x4 w; w.x = cvt_pk_bf16(o[0], o[1]); w.y = cvt_pk_bf16(o[2], o[3]); w.z = cvt_pk_bf16(o[4], o[5]); w.w = cvt_pk_bf16(o[6], o[7]);
;                     *(u32x4*)(Y + row * DM + (MODE == 0 ? 1536 : 1024) + col0) = w;
	v_fma_f32 v21, -v17, v20, v19
	v_fmac_f32_e32 v20, v21, v18
	v_fma_f32 v17, -v17, v20, v19
	v_div_fmas_f32 v17, v17, v18, v20
	v_div_fixup_f32 v16, v17, v16, 1.0
	v_mul_f32_e32 v16, v16, v27
	v_mul_f32_e32 v7, v16, v7
	v_exp_f32_e32 v16, v0
	v_mul_f32_e32 v0, 0xbfb8aa3b, v14
	v_exp_f32_e32 v17, v0
	s_nop 0
	v_pk_add_f32 v[16:17], v[16:17], 1.0 op_sel_hi:[1,0]
	s_nop 0
	v_div_scale_f32 v0, s[0:1], v17, v17, v14
	v_rcp_f32_e32 v18, v0
	s_nop 0
	v_fma_f32 v19, -v0, v18, 1.0
	v_fmac_f32_e32 v18, v19, v18
	v_div_scale_f32 v19, vcc, v14, v17, v14
	v_mul_f32_e32 v20, v19, v18
	v_fma_f32 v21, -v0, v20, v19
	v_fmac_f32_e32 v20, v21, v18
	v_fma_f32 v0, -v0, v20, v19
	v_div_fmas_f32 v0, v0, v18, v20
	v_div_fixup_f32 v0, v0, v17, v14
	v_div_scale_f32 v14, s[0:1], v16, v16, 1.0
	v_rcp_f32_e32 v17, v14
	s_nop 0
	v_fma_f32 v18, -v14, v17, 1.0
	v_fmac_f32_e32 v17, v18, v17
	v_div_scale_f32 v18, vcc, 1.0, v16, 1.0
	v_mul_f32_e32 v19, v18, v17
	v_fma_f32 v20, -v14, v19, v18
	v_fmac_f32_e32 v19, v20, v17
	v_fma_f32 v14, -v14, v19, v18
	v_div_fmas_f32 v14, v14, v17, v19
	v_div_fixup_f32 v14, v14, v16, 1.0
	v_mul_f32_e32 v14, v14, v15
	v_mul_f32_e32 v14, v14, v0
	v_add_f32_e32 v0, v1, v65
	v_mul_f32_e32 v0, 0xbfb8aa3b, v0
	v_mul_f32_e32 v1, 0xbfb8aa3b, v12
	v_exp_f32_e32 v0, v0
	v_exp_f32_e32 v1, v1
	s_nop 0
	v_pk_add_f32 v[0:1], v[0:1], 1.0 op_sel_hi:[1,0]
	s_nop 0
	v_div_scale_f32 v15, s[0:1], v1, v1, v12
	v_rcp_f32_e32 v16, v15
	s_nop 0
	v_fma_f32 v17, -v15, v16, 1.0
	v_fmac_f32_e32 v16, v17, v16
	v_div_scale_f32 v17, vcc, v12, v1, v12
	v_mul_f32_e32 v18, v17, v16
	v_fma_f32 v19, -v15, v18, v17
	v_fmac_f32_e32 v18, v19, v16
	v_fma_f32 v15, -v15, v18, v17
	v_div_fmas_f32 v15, v15, v16, v18
	v_div_fixup_f32 v1, v15, v1, v12
	v_div_scale_f32 v12, s[0:1], v0, v0, 1.0
	v_rcp_f32_e32 v15, v12
	s_nop 0
	v_fma_f32 v16, -v12, v15, 1.0
	v_fmac_f32_e32 v15, v16, v15
	v_div_scale_f32 v16, vcc, 1.0, v0, 1.0
	v_mul_f32_e32 v17, v16, v15
	v_fma_f32 v18, -v12, v17, v16
	v_fmac_f32_e32 v17, v18, v15
	v_fma_f32 v12, -v12, v17, v16
	v_div_fmas_f32 v12, v12, v15, v17
	v_div_fixup_f32 v0, v12, v0, 1.0
	v_mul_f32_e32 v0, v0, v13
	v_mul_f32_e32 v12, v0, v1
	v_add_f32_e32 v0, v2, v66
	v_mul_f32_e32 v0, 0xbfb8aa3b, v0
	v_mul_f32_e32 v1, 0xbfb8aa3b, v10
	v_exp_f32_e32 v0, v0
	v_exp_f32_e32 v1, v1
	s_nop 0
	v_pk_add_f32 v[0:1], v[0:1], 1.0 op_sel_hi:[1,0]
	s_nop 0
	v_div_scale_f32 v2, s[0:1], v1, v1, v10
	v_rcp_f32_e32 v13, v2
	s_nop 0
	v_fma_f32 v15, -v2, v13, 1.0
	v_fmac_f32_e32 v13, v15, v13
	v_div_scale_f32 v15, vcc, v10, v1, v10
	v_mul_f32_e32 v16, v15, v13
	v_fma_f32 v17, -v2, v16, v15
	v_fmac_f32_e32 v16, v17, v13
	v_fma_f32 v2, -v2, v16, v15
	v_div_fmas_f32 v2, v2, v13, v16
	v_div_fixup_f32 v1, v2, v1, v10
	v_div_scale_f32 v2, s[0:1], v0, v0, 1.0
	v_rcp_f32_e32 v10, v2
	s_nop 0
	v_fma_f32 v13, -v2, v10, 1.0
	v_fmac_f32_e32 v10, v13, v10
	v_div_scale_f32 v13, vcc, 1.0, v0, 1.0
	v_mul_f32_e32 v15, v13, v10
	v_fma_f32 v16, -v2, v15, v13
	v_fmac_f32_e32 v15, v16, v10
	v_fma_f32 v2, -v2, v15, v13
	v_div_fmas_f32 v2, v2, v10, v15
	v_div_fixup_f32 v0, v2, v0, 1.0
	v_mul_f32_e32 v0, v0, v11
	v_mul_f32_e32 v10, v0, v1
	v_add_f32_e32 v0, v3, v67
	v_mul_f32_e32 v0, 0xbfb8aa3b, v0
	v_mul_f32_e32 v1, 0xbfb8aa3b, v8
	v_exp_f32_e32 v0, v0
	v_exp_f32_e32 v1, v1
	s_nop 0
	v_pk_add_f32 v[0:1], v[0:1], 1.0 op_sel_hi:[1,0]
	s_nop 0
	v_div_scale_f32 v2, s[0:1], v1, v1, v8
	v_rcp_f32_e32 v3, v2
	s_nop 0
	v_fma_f32 v11, -v2, v3, 1.0
	v_fmac_f32_e32 v3, v11, v3
	v_div_scale_f32 v11, vcc, v8, v1, v8
	v_mul_f32_e32 v13, v11, v3
	v_fma_f32 v15, -v2, v13, v11
	v_fmac_f32_e32 v13, v15, v3
	v_fma_f32 v2, -v2, v13, v11
	v_div_fmas_f32 v2, v2, v3, v13
	v_div_fixup_f32 v1, v2, v1, v8
	v_div_scale_f32 v2, s[0:1], v0, v0, 1.0
	v_rcp_f32_e32 v3, v2
	s_mov_b64 s[0:1], 0
	v_fma_f32 v8, -v2, v3, 1.0
	v_fmac_f32_e32 v3, v8, v3
	v_div_scale_f32 v8, vcc, 1.0, v0, 1.0
	v_mul_f32_e32 v11, v8, v3
	v_fma_f32 v13, -v2, v11, v8
	v_fmac_f32_e32 v11, v13, v3
	v_fma_f32 v2, -v2, v11, v8
	v_div_fmas_f32 v2, v2, v3, v11
	v_div_fixup_f32 v0, v2, v0, 1.0
	v_mul_f32_e32 v0, v0, v9
	v_mul_f32_e32 v3, v0, v1
	v_cvt_pk_bf16_f32 v0, v4, v5
	v_cvt_pk_bf16_f32 v1, v6, v7
	v_cvt_pk_bf16_f32 v2, v14, v12
	v_cvt_pk_bf16_f32 v3, v10, v3
	global_store_dwordx4 v[72:73], v[0:3], off offset:3328
	s_waitcnt vmcnt(0)
	s_barrier

; __device__ __forceinline__ float sigmoidf_(float v) { return 1.f / (1.f + __expf(-v)); }
; __device__ __forceinline__ float siluf_(float v) { return v / (1.f + __expf(-v)); }
;     __device__ __forceinline__ void operator()(const f32x4 (&acc)[2][2][4][2], const Unit& u, int wr, int wc, int fr, int fq) const {
;         const int row0 = u.pm * BM + wr * 64 + fr;
; #pragma unroll
;         for (int bj = 0; bj < 2; ++bj) {
;             const int col0 = u.pn * BM + bj * HALF + wc * 32 + 8 * fq;
;             const f32x4 b0 = *(const f32x4*)(bias + col0), b1 = *(const f32x4*)(bias + col0 + 4);
;             float bb[8] = {b0[0], b0[1], b0[2], b0[3], b1[0], b1[1], b1[2], b1[3]};
; #pragma unroll
;             for (int ai = 0; ai < 2; ++ai) {
; #pragma unroll
;                 for (int m = 0; m < 4; ++m) {
;                     const size_t row = (size_t)(row0 + ai * HALF + m * 16);
;                     const f32x4 v0 = acc[ai][bj][m][0], v1 = acc[ai][bj][m][1];
;                     float a[8] = {v0[0], v0[1], v0[2], v0[3], v1[0], v1[1], v1[2], v1[3]}, g[8], o[8];
;                     unpack8(*(const u32x4*)(R + row * RLD + (MODE == 0 ? 2560 : 1536) + col0), g);
;                     if (MODE == 0) { float y[8]; unpack8(*(const u32x4*)(YG + row * 512 + col0), y);
; #pragma unroll
;                         for (int e = 0; e < 8; ++e) o[e] = y[e] * sigmoidf_(a[e] + bb[e]) * siluf_(g[e]); }
;                     else {
; #pragma unroll
;                         for (int e = 0; e < 8; ++e) o[e] = a[e] * bb[e] * siluf_(g[e]); }
.LBB0_149:
	s_lshl_b64 s[0:1], s[20:21], 2
	v_lshl_or_b32 v76, s57, 8, v139
	s_add_u32 s0, s4, s0
	v_lshl_add_u32 v138, s56, 8, v138
	v_or_b32_e32 v143, s62, v76
	v_mov_b64_e32 v[140:141], s[14:15]
	s_movk_i32 s4, 0x1800
	v_mad_i64_i32 v[136:137], s[2:3], v138, s4, v[140:141]
	v_lshlrev_b32_e32 v180, 1, v143
	s_addc_u32 s1, s5, s1
	v_lshlrev_b32_e32 v142, 2, v143
	v_lshl_add_u64 v[136:137], v[136:137], 0, v[180:181]
	global_load_dwordx4 v[76:79], v142, s[0:1] offset:16
	global_load_dwordx4 v[84:87], v142, s[0:1]
	v_mul_u32_u24_e32 v214, 0x1800, v138
	v_add_u32_e32 v214, v214, v180
	s_add_u32 s2, s14, 0x0
	s_addc_u32 s3, s15, 0
	global_load_dwordx4 v[168:171], v214, s[2:3] offset:3072
	s_add_u32 s2, s14, 0x18000
	s_addc_u32 s3, s15, 0
	global_load_dwordx4 v[188:191], v214, s[2:3] offset:3072
	s_add_u32 s2, s14, 0x30000
	s_addc_u32 s3, s15, 0
	global_load_dwordx4 v[206:209], v214, s[2:3] offset:3072
	s_waitcnt vmcnt(2)
	s_nop 1
	v_mov_b32_e32 v146, v168
	v_mov_b32_e32 v147, v169
	v_mov_b32_e32 v148, v170
	v_mov_b32_e32 v149, v171
	v_ashrrev_i32_e32 v139, 31, v138
	v_mul_f32_e32 v128, v128, v76
	v_mul_f32_e32 v132, v132, v84
	v_lshlrev_b32_e32 v150, 16, v146
	v_and_b32_e32 v151, 0xffff0000, v146
	v_lshlrev_b32_e32 v152, 16, v147
	v_and_b32_e32 v153, 0xffff0000, v147
	v_lshlrev_b32_e32 v147, 16, v148
	v_and_b32_e32 v146, 0xffff0000, v148
	v_mul_f32_e32 v148, 0xbfb8aa3b, v150
	v_exp_f32_e32 v148, v148
	v_lshlrev_b32_e32 v145, 16, v149
	v_and_b32_e32 v143, 0xffff0000, v149
	v_mul_f32_e32 v133, v133, v85
	v_add_f32_e32 v148, 1.0, v148
	v_div_scale_f32 v149, s[2:3], v148, v148, v150
	v_rcp_f32_e32 v154, v149
	v_mul_f32_e32 v134, v134, v86
	v_mul_f32_e32 v135, v135, v87
	v_mul_f32_e32 v129, v129, v77
	v_fma_f32 v155, -v149, v154, 1.0
	v_fmac_f32_e32 v154, v155, v154
	v_div_scale_f32 v155, vcc, v150, v148, v150
	v_mul_f32_e32 v156, v155, v154
	v_fma_f32 v157, -v149, v156, v155
	v_fmac_f32_e32 v156, v157, v154
	v_fma_f32 v149, -v149, v156, v155
	v_div_fmas_f32 v149, v149, v154, v156
	v_div_fixup_f32 v148, v149, v148, v150
	v_mul_f32_e32 v132, v132, v148
	v_mul_f32_e32 v148, 0xbfb8aa3b, v151
	v_exp_f32_e32 v148, v148
	v_mul_f32_e32 v130, v130, v78
	v_mul_f32_e32 v124, v124, v84
	v_mul_f32_e32 v125, v125, v85
	v_add_f32_e32 v148, 1.0, v148
	v_div_scale_f32 v149, s[2:3], v148, v148, v151
	v_rcp_f32_e32 v150, v149
	v_mul_f32_e32 v126, v126, v86
	v_mul_f32_e32 v127, v127, v87
	v_mul_f32_e32 v120, v120, v76
	v_fma_f32 v154, -v149, v150, 1.0
	v_fmac_f32_e32 v150, v154, v150
	v_div_scale_f32 v154, vcc, v151, v148, v151
	v_mul_f32_e32 v155, v154, v150
	v_fma_f32 v156, -v149, v155, v154
	v_fmac_f32_e32 v155, v156, v150
	v_fma_f32 v149, -v149, v155, v154
	v_div_fmas_f32 v149, v149, v150, v155
	v_div_fixup_f32 v148, v149, v148, v151
	v_mul_f32_e32 v133, v133, v148
	v_mul_f32_e32 v148, 0xbfb8aa3b, v152
	v_exp_f32_e32 v148, v148
	v_mul_f32_e32 v121, v121, v77
	v_mul_f32_e32 v122, v122, v78
	v_mul_f32_e32 v116, v116, v84
	v_add_f32_e32 v148, 1.0, v148
	v_div_scale_f32 v149, s[2:3], v148, v148, v152
	v_rcp_f32_e32 v150, v149
	v_mul_f32_e32 v117, v117, v85
	v_mul_f32_e32 v118, v118, v86
	v_mul_f32_e32 v119, v119, v87
	v_fma_f32 v151, -v149, v150, 1.0
	v_fmac_f32_e32 v150, v151, v150
	v_div_scale_f32 v151, vcc, v152, v148, v152
	v_mul_f32_e32 v154, v151, v150
	v_fma_f32 v155, -v149, v154, v151
	v_fmac_f32_e32 v154, v155, v150
	v_fma_f32 v149, -v149, v154, v151
	v_div_fmas_f32 v149, v149, v150, v154
	v_div_fixup_f32 v148, v149, v148, v152
	v_mul_f32_e32 v134, v134, v148
	v_mul_f32_e32 v148, 0xbfb8aa3b, v153
	v_exp_f32_e32 v148, v148
	v_mul_f32_e32 v112, v112, v76
	v_mul_f32_e32 v113, v113, v77
	v_mul_f32_e32 v114, v114, v78
	v_add_f32_e32 v148, 1.0, v148
	v_div_scale_f32 v149, s[2:3], v148, v148, v153
	v_rcp_f32_e32 v150, v149
	v_mul_f32_e32 v108, v108, v84
	v_mul_f32_e32 v109, v109, v85
	v_mul_f32_e32 v110, v110, v86
	v_fma_f32 v151, -v149, v150, 1.0
	v_fmac_f32_e32 v150, v151, v150
	v_div_scale_f32 v151, vcc, v153, v148, v153
	v_mul_f32_e32 v152, v151, v150
	v_fma_f32 v154, -v149, v152, v151
	v_fmac_f32_e32 v152, v154, v150
	v_fma_f32 v149, -v149, v152, v151
	v_div_fmas_f32 v149, v149, v150, v152
	v_div_fixup_f32 v148, v149, v148, v153
	v_mul_f32_e32 v135, v135, v148
	v_mul_f32_e32 v148, 0xbfb8aa3b, v147
	v_exp_f32_e32 v148, v148
	v_mul_f32_e32 v111, v111, v87
	v_mul_f32_e32 v104, v104, v76
	v_mul_f32_e32 v105, v105, v77
	v_add_f32_e32 v148, 1.0, v148
	v_div_scale_f32 v149, s[2:3], v148, v148, v147
	v_rcp_f32_e32 v150, v149
	v_mul_f32_e32 v106, v106, v78
	v_mul_f32_e32 v100, v100, v84
	v_mul_f32_e32 v101, v101, v85
	v_fma_f32 v151, -v149, v150, 1.0
	v_fmac_f32_e32 v150, v151, v150
	v_div_scale_f32 v151, vcc, v147, v148, v147
	v_mul_f32_e32 v152, v151, v150
	v_fma_f32 v153, -v149, v152, v151
	v_fmac_f32_e32 v152, v153, v150
	v_fma_f32 v149, -v149, v152, v151
	v_div_fmas_f32 v149, v149, v150, v152
	v_div_fixup_f32 v147, v149, v148, v147
	v_mul_f32_e32 v128, v128, v147
	v_mul_f32_e32 v147, 0xbfb8aa3b, v146
	v_exp_f32_e32 v147, v147
	v_mul_f32_e32 v102, v102, v86
	v_mul_f32_e32 v103, v103, v87
	v_mul_f32_e32 v96, v96, v76
	v_add_f32_e32 v147, 1.0, v147
	v_div_scale_f32 v148, s[2:3], v147, v147, v146
	v_rcp_f32_e32 v149, v148
	v_mul_f32_e32 v97, v97, v77
	v_mul_f32_e32 v98, v98, v78
	v_mul_f32_e32 v92, v92, v84
	v_fma_f32 v150, -v148, v149, 1.0
	v_fmac_f32_e32 v149, v150, v149
	v_div_scale_f32 v150, vcc, v146, v147, v146
	v_mul_f32_e32 v151, v150, v149
	v_fma_f32 v152, -v148, v151, v150
	v_fmac_f32_e32 v151, v152, v149
	v_fma_f32 v148, -v148, v151, v150
	v_div_fmas_f32 v148, v148, v149, v151
	v_div_fixup_f32 v146, v148, v147, v146
	v_mul_f32_e32 v129, v129, v146
; __device__ __forceinline__ unsigned cvt_pk_bf16(float lo, float hi) { unsigned r; asm volatile("v_cvt_pk_bf16_f32 %0, %1, %2" : "=v"(r) : "v"(lo), "v"(hi)); return r; }
; __device__ __forceinline__ float sigmoidf_(float v) { return 1.f / (1.f + __expf(-v)); }
; __device__ __forceinline__ float siluf_(float v) { return v / (1.f + __expf(-v)); }
;     __device__ __forceinline__ void operator()(const f32x4 (&acc)[2][2][4][2], const Unit& u, int wr, int wc, int fr, int fq) const {
;     ...
;             for (int ai = 0; ai < 2; ++ai) {
; #pragma unroll
;                 for (int m = 0; m < 4; ++m) {
;                     const size_t row = (size_t)(row0 + ai * HALF + m * 16);
;                     const f32x4 v0 = acc[ai][bj][m][0], v1 = acc[ai][bj][m][1];
;                     float a[8] = {v0[0], v0[1], v0[2], v0[3], v1[0], v1[1], v1[2], v1[3]}, g[8], o[8];
;                     unpack8(*(const u32x4*)(R + row * RLD + (MODE == 0 ? 2560 : 1536) + col0), g);
;                     if (MODE == 0) { float y[8]; unpack8(*(const u32x4*)(YG + row * 512 + col0), y);
; #pragma unroll
;                         for (int e = 0; e < 8; ++e) o[e] = y[e] * sigmoidf_(a[e] + bb[e]) * siluf_(g[e]); }
;                     else {
; #pragma unroll
;                         for (int e = 0; e < 8; ++e) o[e] = a[e] * bb[e] * siluf_(g[e]); }
;                     u32x4 w; w.x = cvt_pk_bf16(o[0], o[1]); w.y = cvt_pk_bf16(o[2], o[3]); w.z = cvt_pk_bf16(o[4], o[5]); w.w = cvt_pk_bf16(o[6], o[7]);
;                     *(u32x4*)(Y + row * DM + (MODE == 0 ? 1536 : 1024) + col0) = w;
;                 }
	v_mul_f32_e32 v146, 0xbfb8aa3b, v145
	v_exp_f32_e32 v146, v146
	v_mul_f32_e32 v93, v93, v85
	v_mul_f32_e32 v94, v94, v86
	v_mul_f32_e32 v95, v95, v87
	v_add_f32_e32 v146, 1.0, v146
	v_div_scale_f32 v147, s[2:3], v146, v146, v145
	v_rcp_f32_e32 v148, v147
	v_mul_f32_e32 v88, v88, v76
	v_mul_f32_e32 v89, v89, v77
	v_mul_f32_e32 v90, v90, v78
	v_fma_f32 v149, -v147, v148, 1.0
	v_fmac_f32_e32 v148, v149, v148
	v_div_scale_f32 v149, vcc, v145, v146, v145
	v_mul_f32_e32 v150, v149, v148
	v_fma_f32 v151, -v147, v150, v149
	v_fmac_f32_e32 v150, v151, v148
	v_fma_f32 v147, -v147, v150, v149
	v_div_fmas_f32 v147, v147, v148, v150
	v_div_fixup_f32 v145, v147, v146, v145
	v_mul_f32_e32 v145, v130, v145
	v_mul_f32_e32 v130, v131, v79
	v_mul_f32_e32 v131, 0xbfb8aa3b, v143
	v_exp_f32_e32 v131, v131
	v_mul_f32_e32 v80, v80, v84
	v_mul_f32_e32 v81, v81, v85
	v_mul_f32_e32 v82, v82, v86
	v_add_f32_e32 v131, 1.0, v131
	v_div_scale_f32 v146, s[2:3], v131, v131, v143
	v_rcp_f32_e32 v147, v146
	v_mul_f32_e32 v83, v83, v87
	v_mul_f32_e32 v72, v72, v76
	v_mul_f32_e32 v73, v73, v77
	v_fma_f32 v148, -v146, v147, 1.0
	v_fmac_f32_e32 v147, v148, v147
	v_div_scale_f32 v148, vcc, v143, v131, v143
	v_mul_f32_e32 v149, v148, v147
	v_fma_f32 v150, -v146, v149, v148
	v_fmac_f32_e32 v149, v150, v147
	v_fma_f32 v146, -v146, v149, v148
	v_div_fmas_f32 v146, v146, v147, v149
	v_div_fixup_f32 v131, v146, v131, v143
	v_mul_f32_e32 v143, v130, v131
	v_cvt_pk_bf16_f32 v130, v132, v133
	v_cvt_pk_bf16_f32 v131, v134, v135
	v_cvt_pk_bf16_f32 v132, v128, v129
	v_lshlrev_b64 v[128:129], 12, v[138:139]
	v_lshl_add_u64 v[128:129], s[12:13], 0, v[128:129]
	v_lshl_add_u64 v[128:129], v[128:129], 0, v[180:181]
	v_cvt_pk_bf16_f32 v133, v145, v143
	global_store_dwordx4 v[128:129], v[130:133], off offset:2048
	s_add_u32 s2, s14, 0x48000
	s_addc_u32 s3, s15, 0
	global_load_dwordx4 v[168:171], v214, s[2:3] offset:3072
	v_mul_f32_e32 v74, v74, v78
	v_mul_f32_e32 v75, v75, v79
	v_or_b32_e32 v132, 16, v138
	v_mad_i64_i32 v[130:131], s[2:3], v132, s4, v[140:141]
	v_lshl_add_u64 v[130:131], v[130:131], 0, v[180:181]
	s_waitcnt vmcnt(3)
	s_nop 1
	v_mov_b32_e32 v146, v188
	v_mov_b32_e32 v147, v189
	v_mov_b32_e32 v148, v190
	v_mov_b32_e32 v149, v191
	v_ashrrev_i32_e32 v133, 31, v132
	v_mul_f32_e32 v68, v68, v84
	v_mul_f32_e32 v69, v69, v85
	v_mul_f32_e32 v70, v70, v86
	v_mul_f32_e32 v71, v71, v87
	v_mul_f32_e32 v64, v64, v76
	v_lshlrev_b32_e32 v135, 16, v146
	v_and_b32_e32 v139, 0xffff0000, v146
	v_lshlrev_b32_e32 v143, 16, v147
	v_and_b32_e32 v145, 0xffff0000, v147
	v_lshlrev_b32_e32 v146, 16, v148
	v_and_b32_e32 v147, 0xffff0000, v148
	v_lshlrev_b32_e32 v148, 16, v149
	v_and_b32_e32 v134, 0xffff0000, v149
	v_mul_f32_e32 v149, 0xbfb8aa3b, v135
	v_exp_f32_e32 v149, v149
	s_nop 0
	v_add_f32_e32 v149, 1.0, v149
	v_div_scale_f32 v150, s[2:3], v149, v149, v135
	v_rcp_f32_e32 v151, v150
	s_nop 0
	v_fma_f32 v152, -v150, v151, 1.0
	v_fmac_f32_e32 v151, v152, v151
	v_div_scale_f32 v152, vcc, v135, v149, v135
	v_mul_f32_e32 v153, v152, v151
	v_fma_f32 v154, -v150, v153, v152
	v_fmac_f32_e32 v153, v154, v151
	v_fma_f32 v150, -v150, v153, v152
	v_div_fmas_f32 v150, v150, v151, v153
	v_div_fixup_f32 v135, v150, v149, v135
	v_mul_f32_e32 v124, v124, v135
	v_mul_f32_e32 v135, 0xbfb8aa3b, v139
	v_exp_f32_e32 v135, v135
	s_nop 0
	v_add_f32_e32 v135, 1.0, v135
	v_div_scale_f32 v149, s[2:3], v135, v135, v139
	v_rcp_f32_e32 v150, v149
	s_nop 0
	v_fma_f32 v151, -v149, v150, 1.0
	v_fmac_f32_e32 v150, v151, v150
	v_div_scale_f32 v151, vcc, v139, v135, v139
	v_mul_f32_e32 v152, v151, v150
	v_fma_f32 v153, -v149, v152, v151
	v_fmac_f32_e32 v152, v153, v150
	v_fma_f32 v149, -v149, v152, v151
	v_div_fmas_f32 v149, v149, v150, v152
	v_div_fixup_f32 v135, v149, v135, v139
	v_mul_f32_e32 v125, v125, v135
	v_mul_f32_e32 v135, 0xbfb8aa3b, v143
	v_exp_f32_e32 v135, v135
	s_nop 0
	v_add_f32_e32 v135, 1.0, v135
	v_div_scale_f32 v139, s[2:3], v135, v135, v143
	v_rcp_f32_e32 v149, v139
	s_nop 0
	v_fma_f32 v150, -v139, v149, 1.0
	v_fmac_f32_e32 v149, v150, v149
	v_div_scale_f32 v150, vcc, v143, v135, v143
	v_mul_f32_e32 v151, v150, v149
	v_fma_f32 v152, -v139, v151, v150
	v_fmac_f32_e32 v151, v152, v149
	v_fma_f32 v139, -v139, v151, v150
	v_div_fmas_f32 v139, v139, v149, v151
	v_div_fixup_f32 v135, v139, v135, v143
	v_mul_f32_e32 v126, v126, v135
	v_mul_f32_e32 v135, 0xbfb8aa3b, v145
	v_exp_f32_e32 v135, v135
	s_nop 0
	v_add_f32_e32 v135, 1.0, v135
	v_div_scale_f32 v139, s[2:3], v135, v135, v145
	v_rcp_f32_e32 v143, v139
	s_nop 0
	v_fma_f32 v149, -v139, v143, 1.0
	v_fmac_f32_e32 v143, v149, v143
	v_div_scale_f32 v149, vcc, v145, v135, v145
	v_mul_f32_e32 v150, v149, v143
	v_fma_f32 v151, -v139, v150, v149
	v_fmac_f32_e32 v150, v151, v143
	v_fma_f32 v139, -v139, v150, v149
	v_div_fmas_f32 v139, v139, v143, v150
	v_div_fixup_f32 v135, v139, v135, v145
	v_mul_f32_e32 v127, v127, v135
	v_mul_f32_e32 v135, 0xbfb8aa3b, v146
	v_exp_f32_e32 v135, v135
	s_nop 0
	v_add_f32_e32 v135, 1.0, v135
	v_div_scale_f32 v139, s[2:3], v135, v135, v146
	v_rcp_f32_e32 v143, v139
	s_nop 0
	v_fma_f32 v145, -v139, v143, 1.0
	v_fmac_f32_e32 v143, v145, v143
	v_div_scale_f32 v145, vcc, v146, v135, v146
	v_mul_f32_e32 v149, v145, v143
	v_fma_f32 v150, -v139, v149, v145
	v_fmac_f32_e32 v149, v150, v143
	v_fma_f32 v139, -v139, v149, v145
	v_div_fmas_f32 v139, v139, v143, v149
	v_div_fixup_f32 v135, v139, v135, v146
	v_mul_f32_e32 v120, v120, v135
	v_mul_f32_e32 v135, 0xbfb8aa3b, v147
	v_exp_f32_e32 v135, v135
	s_nop 0
	v_add_f32_e32 v135, 1.0, v135
	v_div_scale_f32 v139, s[2:3], v135, v135, v147
	v_rcp_f32_e32 v143, v139
	s_nop 0
	v_fma_f32 v145, -v139, v143, 1.0
; __device__ __forceinline__ unsigned cvt_pk_bf16(float lo, float hi) { unsigned r; asm volatile("v_cvt_pk_bf16_f32 %0, %1, %2" : "=v"(r) : "v"(lo), "v"(hi)); return r; }
; __device__ __forceinline__ float sigmoidf_(float v) { return 1.f / (1.f + __expf(-v)); }
; __device__ __forceinline__ float siluf_(float v) { return v / (1.f + __expf(-v)); }
;     __device__ __forceinline__ void operator()(const f32x4 (&acc)[2][2][4][2], const Unit& u, int wr, int wc, int fr, int fq) const {
;     ...
;             for (int ai = 0; ai < 2; ++ai) {
; #pragma unroll
;                 for (int m = 0; m < 4; ++m) {
;                     const size_t row = (size_t)(row0 + ai * HALF + m * 16);
;                     const f32x4 v0 = acc[ai][bj][m][0], v1 = acc[ai][bj][m][1];
;                     float a[8] = {v0[0], v0[1], v0[2], v0[3], v1[0], v1[1], v1[2], v1[3]}, g[8], o[8];
;                     unpack8(*(const u32x4*)(R + row * RLD + (MODE == 0 ? 2560 : 1536) + col0), g);
;                     if (MODE == 0) { float y[8]; unpack8(*(const u32x4*)(YG + row * 512 + col0), y);
; #pragma unroll
;                         for (int e = 0; e < 8; ++e) o[e] = y[e] * sigmoidf_(a[e] + bb[e]) * siluf_(g[e]); }
;                     else {
; #pragma unroll
;                         for (int e = 0; e < 8; ++e) o[e] = a[e] * bb[e] * siluf_(g[e]); }
;                     u32x4 w; w.x = cvt_pk_bf16(o[0], o[1]); w.y = cvt_pk_bf16(o[2], o[3]); w.z = cvt_pk_bf16(o[4], o[5]); w.w = cvt_pk_bf16(o[6], o[7]);
;                     *(u32x4*)(Y + row * DM + (MODE == 0 ? 1536 : 1024) + col0) = w;
;                 }
	v_fmac_f32_e32 v143, v145, v143
	v_div_scale_f32 v145, vcc, v147, v135, v147
	v_mul_f32_e32 v146, v145, v143
	v_fma_f32 v149, -v139, v146, v145
	v_fmac_f32_e32 v146, v149, v143
	v_fma_f32 v139, -v139, v146, v145
	v_div_fmas_f32 v139, v139, v143, v146
	v_div_fixup_f32 v135, v139, v135, v147
	v_mul_f32_e32 v121, v121, v135
	v_mul_f32_e32 v135, 0xbfb8aa3b, v148
	v_exp_f32_e32 v135, v135
	s_nop 0
	v_add_f32_e32 v135, 1.0, v135
	v_div_scale_f32 v139, s[2:3], v135, v135, v148
	v_rcp_f32_e32 v143, v139
	s_nop 0
	v_fma_f32 v145, -v139, v143, 1.0
	v_fmac_f32_e32 v143, v145, v143
	v_div_scale_f32 v145, vcc, v148, v135, v148
	v_mul_f32_e32 v146, v145, v143
	v_fma_f32 v147, -v139, v146, v145
	v_fmac_f32_e32 v146, v147, v143
	v_fma_f32 v139, -v139, v146, v145
	v_div_fmas_f32 v139, v139, v143, v146
	v_div_fixup_f32 v135, v139, v135, v148
	v_mul_f32_e32 v135, v122, v135
	v_mul_f32_e32 v122, v123, v79
	v_mul_f32_e32 v123, 0xbfb8aa3b, v134
	v_exp_f32_e32 v123, v123
	s_nop 0
	v_add_f32_e32 v123, 1.0, v123
	v_div_scale_f32 v139, s[2:3], v123, v123, v134
	v_rcp_f32_e32 v143, v139
	s_nop 0
	v_fma_f32 v145, -v139, v143, 1.0
	v_fmac_f32_e32 v143, v145, v143
	v_div_scale_f32 v145, vcc, v134, v123, v134
	v_mul_f32_e32 v146, v145, v143
	v_fma_f32 v147, -v139, v146, v145
	v_fmac_f32_e32 v146, v147, v143
	v_fma_f32 v139, -v139, v146, v145
	v_div_fmas_f32 v139, v139, v143, v146
	v_div_fixup_f32 v123, v139, v123, v134
	v_mul_f32_e32 v134, v122, v123
	v_cvt_pk_bf16_f32 v122, v124, v125
	v_cvt_pk_bf16_f32 v123, v126, v127
	v_cvt_pk_bf16_f32 v124, v120, v121
	v_lshlrev_b64 v[120:121], 12, v[132:133]
	v_lshl_add_u64 v[120:121], s[12:13], 0, v[120:121]
	v_lshl_add_u64 v[120:121], v[120:121], 0, v[180:181]
	v_cvt_pk_bf16_f32 v125, v135, v134
	global_store_dwordx4 v[120:121], v[122:125], off offset:2048
	s_add_u32 s2, s14, 0xc0000
	s_addc_u32 s3, s15, 0
	global_load_dwordx4 v[188:191], v214, s[2:3] offset:3072
	s_nop 1
	v_or_b32_e32 v124, 32, v138
	v_mad_i64_i32 v[122:123], s[2:3], v124, s4, v[140:141]
	v_lshl_add_u64 v[122:123], v[122:123], 0, v[180:181]
	s_waitcnt vmcnt(4)
	s_nop 1
	v_mov_b32_e32 v132, v206
	v_mov_b32_e32 v133, v207
	v_mov_b32_e32 v134, v208
	v_mov_b32_e32 v135, v209
	v_ashrrev_i32_e32 v125, 31, v124
	v_lshlrev_b32_e32 v127, 16, v132
	v_lshlrev_b32_e32 v145, 16, v135
	v_and_b32_e32 v126, 0xffff0000, v135
	v_mul_f32_e32 v135, 0xbfb8aa3b, v127
	v_exp_f32_e32 v135, v135
	v_and_b32_e32 v132, 0xffff0000, v132
	v_lshlrev_b32_e32 v139, 16, v133
	v_and_b32_e32 v133, 0xffff0000, v133
	v_add_f32_e32 v135, 1.0, v135
	v_div_scale_f32 v146, s[2:3], v135, v135, v127
	v_rcp_f32_e32 v147, v146
	v_lshlrev_b32_e32 v143, 16, v134
	v_and_b32_e32 v134, 0xffff0000, v134
	v_fma_f32 v148, -v146, v147, 1.0
	v_fmac_f32_e32 v147, v148, v147
	v_div_scale_f32 v148, vcc, v127, v135, v127
	v_mul_f32_e32 v149, v148, v147
	v_fma_f32 v150, -v146, v149, v148
	v_fmac_f32_e32 v149, v150, v147
	v_fma_f32 v146, -v146, v149, v148
	v_div_fmas_f32 v146, v146, v147, v149
	v_div_fixup_f32 v127, v146, v135, v127
	v_mul_f32_e32 v116, v116, v127
	v_mul_f32_e32 v127, 0xbfb8aa3b, v132
	v_exp_f32_e32 v127, v127
	s_nop 0
	v_add_f32_e32 v127, 1.0, v127
	v_div_scale_f32 v135, s[2:3], v127, v127, v132
	v_rcp_f32_e32 v146, v135
	s_nop 0
	v_fma_f32 v147, -v135, v146, 1.0
	v_fmac_f32_e32 v146, v147, v146
	v_div_scale_f32 v147, vcc, v132, v127, v132
	v_mul_f32_e32 v148, v147, v146
	v_fma_f32 v149, -v135, v148, v147
	v_fmac_f32_e32 v148, v149, v146
	v_fma_f32 v135, -v135, v148, v147
	v_div_fmas_f32 v135, v135, v146, v148
	v_div_fixup_f32 v127, v135, v127, v132
	v_mul_f32_e32 v117, v117, v127
	v_mul_f32_e32 v127, 0xbfb8aa3b, v139
	v_exp_f32_e32 v127, v127
	s_nop 0
	v_add_f32_e32 v127, 1.0, v127
	v_div_scale_f32 v132, s[2:3], v127, v127, v139
	v_rcp_f32_e32 v135, v132
	s_nop 0
	v_fma_f32 v146, -v132, v135, 1.0
	v_fmac_f32_e32 v135, v146, v135
	v_div_scale_f32 v146, vcc, v139, v127, v139
	v_mul_f32_e32 v147, v146, v135
	v_fma_f32 v148, -v132, v147, v146
	v_fmac_f32_e32 v147, v148, v135
	v_fma_f32 v132, -v132, v147, v146
	v_div_fmas_f32 v132, v132, v135, v147
	v_div_fixup_f32 v127, v132, v127, v139
	v_mul_f32_e32 v118, v118, v127
	v_mul_f32_e32 v127, 0xbfb8aa3b, v133
	v_exp_f32_e32 v127, v127
	s_nop 0
	v_add_f32_e32 v127, 1.0, v127
	v_div_scale_f32 v132, s[2:3], v127, v127, v133
	v_rcp_f32_e32 v135, v132
	s_nop 0
	v_fma_f32 v139, -v132, v135, 1.0
	v_fmac_f32_e32 v135, v139, v135
	v_div_scale_f32 v139, vcc, v133, v127, v133
	v_mul_f32_e32 v146, v139, v135
	v_fma_f32 v147, -v132, v146, v139
	v_fmac_f32_e32 v146, v147, v135
	v_fma_f32 v132, -v132, v146, v139
	v_div_fmas_f32 v132, v132, v135, v146
	v_div_fixup_f32 v127, v132, v127, v133
	v_mul_f32_e32 v119, v119, v127
	v_mul_f32_e32 v127, 0xbfb8aa3b, v143
	v_exp_f32_e32 v127, v127
	s_nop 0
	v_add_f32_e32 v127, 1.0, v127
	v_div_scale_f32 v132, s[2:3], v127, v127, v143
	v_rcp_f32_e32 v133, v132
	s_nop 0
	v_fma_f32 v135, -v132, v133, 1.0
	v_fmac_f32_e32 v133, v135, v133
	v_div_scale_f32 v135, vcc, v143, v127, v143
	v_mul_f32_e32 v139, v135, v133
	v_fma_f32 v146, -v132, v139, v135
	v_fmac_f32_e32 v139, v146, v133
	v_fma_f32 v132, -v132, v139, v135
	v_div_fmas_f32 v132, v132, v133, v139
	v_div_fixup_f32 v127, v132, v127, v143
	v_mul_f32_e32 v112, v112, v127
	v_mul_f32_e32 v127, 0xbfb8aa3b, v134
	v_exp_f32_e32 v127, v127
	s_nop 0
	v_add_f32_e32 v127, 1.0, v127
	v_div_scale_f32 v132, s[2:3], v127, v127, v134
	v_rcp_f32_e32 v133, v132
	s_nop 0
	v_fma_f32 v135, -v132, v133, 1.0
	v_fmac_f32_e32 v133, v135, v133
	v_div_scale_f32 v135, vcc, v134, v127, v134
	v_mul_f32_e32 v139, v135, v133
	v_fma_f32 v143, -v132, v139, v135
	v_fmac_f32_e32 v139, v143, v133
	v_fma_f32 v132, -v132, v139, v135
; __device__ __forceinline__ unsigned cvt_pk_bf16(float lo, float hi) { unsigned r; asm volatile("v_cvt_pk_bf16_f32 %0, %1, %2" : "=v"(r) : "v"(lo), "v"(hi)); return r; }
; __device__ __forceinline__ float sigmoidf_(float v) { return 1.f / (1.f + __expf(-v)); }
; __device__ __forceinline__ float siluf_(float v) { return v / (1.f + __expf(-v)); }
;     __device__ __forceinline__ void operator()(const f32x4 (&acc)[2][2][4][2], const Unit& u, int wr, int wc, int fr, int fq) const {
;     ...
;             for (int ai = 0; ai < 2; ++ai) {
; #pragma unroll
;                 for (int m = 0; m < 4; ++m) {
;                     const size_t row = (size_t)(row0 + ai * HALF + m * 16);
;                     const f32x4 v0 = acc[ai][bj][m][0], v1 = acc[ai][bj][m][1];
;                     float a[8] = {v0[0], v0[1], v0[2], v0[3], v1[0], v1[1], v1[2], v1[3]}, g[8], o[8];
;                     unpack8(*(const u32x4*)(R + row * RLD + (MODE == 0 ? 2560 : 1536) + col0), g);
;                     if (MODE == 0) { float y[8]; unpack8(*(const u32x4*)(YG + row * 512 + col0), y);
; #pragma unroll
;                         for (int e = 0; e < 8; ++e) o[e] = y[e] * sigmoidf_(a[e] + bb[e]) * siluf_(g[e]); }
;                     else {
; #pragma unroll
;                         for (int e = 0; e < 8; ++e) o[e] = a[e] * bb[e] * siluf_(g[e]); }
;                     u32x4 w; w.x = cvt_pk_bf16(o[0], o[1]); w.y = cvt_pk_bf16(o[2], o[3]); w.z = cvt_pk_bf16(o[4], o[5]); w.w = cvt_pk_bf16(o[6], o[7]);
;                     *(u32x4*)(Y + row * DM + (MODE == 0 ? 1536 : 1024) + col0) = w;
;                 }
	v_div_fmas_f32 v132, v132, v133, v139
	v_div_fixup_f32 v127, v132, v127, v134
	v_mul_f32_e32 v113, v113, v127
	v_mul_f32_e32 v127, 0xbfb8aa3b, v145
	v_exp_f32_e32 v127, v127
	s_nop 0
	v_add_f32_e32 v127, 1.0, v127
	v_div_scale_f32 v132, s[2:3], v127, v127, v145
	v_rcp_f32_e32 v133, v132
	s_nop 0
	v_fma_f32 v134, -v132, v133, 1.0
	v_fmac_f32_e32 v133, v134, v133
	v_div_scale_f32 v134, vcc, v145, v127, v145
	v_mul_f32_e32 v135, v134, v133
	v_fma_f32 v139, -v132, v135, v134
	v_fmac_f32_e32 v135, v139, v133
	v_fma_f32 v132, -v132, v135, v134
	v_div_fmas_f32 v132, v132, v133, v135
	v_div_fixup_f32 v127, v132, v127, v145
	v_mul_f32_e32 v127, v114, v127
	v_mul_f32_e32 v114, v115, v79
	v_mul_f32_e32 v115, 0xbfb8aa3b, v126
	v_exp_f32_e32 v115, v115
	s_nop 0
	v_add_f32_e32 v115, 1.0, v115
	v_div_scale_f32 v132, s[2:3], v115, v115, v126
	v_rcp_f32_e32 v133, v132
	s_nop 0
	v_fma_f32 v134, -v132, v133, 1.0
	v_fmac_f32_e32 v133, v134, v133
	v_div_scale_f32 v134, vcc, v126, v115, v126
	v_mul_f32_e32 v135, v134, v133
	v_fma_f32 v139, -v132, v135, v134
	v_fmac_f32_e32 v135, v139, v133
	v_fma_f32 v132, -v132, v135, v134
	v_div_fmas_f32 v132, v132, v133, v135
	v_div_fixup_f32 v115, v132, v115, v126
	v_mul_f32_e32 v126, v114, v115
	v_cvt_pk_bf16_f32 v114, v116, v117
	v_cvt_pk_bf16_f32 v115, v118, v119
	v_cvt_pk_bf16_f32 v116, v112, v113
	v_lshlrev_b64 v[112:113], 12, v[124:125]
	v_lshl_add_u64 v[112:113], s[12:13], 0, v[112:113]
	v_lshl_add_u64 v[112:113], v[112:113], 0, v[180:181]
	v_cvt_pk_bf16_f32 v117, v127, v126
	global_store_dwordx4 v[112:113], v[114:117], off offset:2048
	s_add_u32 s2, s14, 0xd8000
	s_addc_u32 s3, s15, 0
	global_load_dwordx4 v[206:209], v214, s[2:3] offset:3072
	s_nop 1
	v_or_b32_e32 v116, 48, v138
	v_mad_i64_i32 v[114:115], s[2:3], v116, s4, v[140:141]
	v_lshl_add_u64 v[114:115], v[114:115], 0, v[180:181]
	s_waitcnt vmcnt(4)
	s_nop 1
	v_mov_b32_e32 v124, v168
	v_mov_b32_e32 v125, v169
	v_mov_b32_e32 v126, v170
	v_mov_b32_e32 v127, v171
	v_ashrrev_i32_e32 v117, 31, v116
	v_lshlrev_b32_e32 v119, 16, v124
	v_lshlrev_b32_e32 v134, 16, v127
	v_and_b32_e32 v118, 0xffff0000, v127
	v_mul_f32_e32 v127, 0xbfb8aa3b, v119
	v_exp_f32_e32 v127, v127
	v_and_b32_e32 v124, 0xffff0000, v124
	v_lshlrev_b32_e32 v132, 16, v125
	v_and_b32_e32 v125, 0xffff0000, v125
	v_add_f32_e32 v127, 1.0, v127
	v_div_scale_f32 v135, s[2:3], v127, v127, v119
	v_rcp_f32_e32 v139, v135
	v_lshlrev_b32_e32 v133, 16, v126
	v_and_b32_e32 v126, 0xffff0000, v126
	v_fma_f32 v143, -v135, v139, 1.0
	v_fmac_f32_e32 v139, v143, v139
	v_div_scale_f32 v143, vcc, v119, v127, v119
	v_mul_f32_e32 v145, v143, v139
	v_fma_f32 v146, -v135, v145, v143
	v_fmac_f32_e32 v145, v146, v139
	v_fma_f32 v135, -v135, v145, v143
	v_div_fmas_f32 v135, v135, v139, v145
	v_div_fixup_f32 v119, v135, v127, v119
	v_mul_f32_e32 v108, v108, v119
	v_mul_f32_e32 v119, 0xbfb8aa3b, v124
	v_exp_f32_e32 v119, v119
	s_nop 0
	v_add_f32_e32 v119, 1.0, v119
	v_div_scale_f32 v127, s[2:3], v119, v119, v124
	v_rcp_f32_e32 v135, v127
	s_nop 0
	v_fma_f32 v139, -v127, v135, 1.0
	v_fmac_f32_e32 v135, v139, v135
	v_div_scale_f32 v139, vcc, v124, v119, v124
	v_mul_f32_e32 v143, v139, v135
	v_fma_f32 v145, -v127, v143, v139
	v_fmac_f32_e32 v143, v145, v135
	v_fma_f32 v127, -v127, v143, v139
	v_div_fmas_f32 v127, v127, v135, v143
	v_div_fixup_f32 v119, v127, v119, v124
	v_mul_f32_e32 v109, v109, v119
	v_mul_f32_e32 v119, 0xbfb8aa3b, v132
	v_exp_f32_e32 v119, v119
	s_nop 0
	v_add_f32_e32 v119, 1.0, v119
	v_div_scale_f32 v124, s[2:3], v119, v119, v132
	v_rcp_f32_e32 v127, v124
	s_nop 0
	v_fma_f32 v135, -v124, v127, 1.0
	v_fmac_f32_e32 v127, v135, v127
	v_div_scale_f32 v135, vcc, v132, v119, v132
	v_mul_f32_e32 v139, v135, v127
	v_fma_f32 v143, -v124, v139, v135
	v_fmac_f32_e32 v139, v143, v127
	v_fma_f32 v124, -v124, v139, v135
	v_div_fmas_f32 v124, v124, v127, v139
	v_div_fixup_f32 v119, v124, v119, v132
	v_mul_f32_e32 v110, v110, v119
	v_mul_f32_e32 v119, 0xbfb8aa3b, v125
	v_exp_f32_e32 v119, v119
	s_nop 0
	v_add_f32_e32 v119, 1.0, v119
	v_div_scale_f32 v124, s[2:3], v119, v119, v125
	v_rcp_f32_e32 v127, v124
	s_nop 0
	v_fma_f32 v132, -v124, v127, 1.0
	v_fmac_f32_e32 v127, v132, v127
	v_div_scale_f32 v132, vcc, v125, v119, v125
	v_mul_f32_e32 v135, v132, v127
	v_fma_f32 v139, -v124, v135, v132
	v_fmac_f32_e32 v135, v139, v127
	v_fma_f32 v124, -v124, v135, v132
	v_div_fmas_f32 v124, v124, v127, v135
	v_div_fixup_f32 v119, v124, v119, v125
	v_mul_f32_e32 v111, v111, v119
	v_mul_f32_e32 v119, 0xbfb8aa3b, v133
	v_exp_f32_e32 v119, v119
	s_nop 0
	v_add_f32_e32 v119, 1.0, v119
	v_div_scale_f32 v124, s[2:3], v119, v119, v133
	v_rcp_f32_e32 v125, v124
	s_nop 0
	v_fma_f32 v127, -v124, v125, 1.0
	v_fmac_f32_e32 v125, v127, v125
	v_div_scale_f32 v127, vcc, v133, v119, v133
	v_mul_f32_e32 v132, v127, v125
	v_fma_f32 v135, -v124, v132, v127
	v_fmac_f32_e32 v132, v135, v125
	v_fma_f32 v124, -v124, v132, v127
	v_div_fmas_f32 v124, v124, v125, v132
	v_div_fixup_f32 v119, v124, v119, v133
	v_mul_f32_e32 v104, v104, v119
	v_mul_f32_e32 v119, 0xbfb8aa3b, v126
	v_exp_f32_e32 v119, v119
	s_nop 0
	v_add_f32_e32 v119, 1.0, v119
	v_div_scale_f32 v124, s[2:3], v119, v119, v126
	v_rcp_f32_e32 v125, v124
	s_nop 0
	v_fma_f32 v127, -v124, v125, 1.0
	v_fmac_f32_e32 v125, v127, v125
	v_div_scale_f32 v127, vcc, v126, v119, v126
	v_mul_f32_e32 v132, v127, v125
	v_fma_f32 v133, -v124, v132, v127
	v_fmac_f32_e32 v132, v133, v125
	v_fma_f32 v124, -v124, v132, v127
	v_div_fmas_f32 v124, v124, v125, v132
	v_div_fixup_f32 v119, v124, v119, v126
	v_mul_f32_e32 v105, v105, v119
	v_mul_f32_e32 v119, 0xbfb8aa3b, v134
	v_exp_f32_e32 v119, v119
	s_nop 0
	v_add_f32_e32 v119, 1.0, v119
; __device__ __forceinline__ unsigned cvt_pk_bf16(float lo, float hi) { unsigned r; asm volatile("v_cvt_pk_bf16_f32 %0, %1, %2" : "=v"(r) : "v"(lo), "v"(hi)); return r; }
; __device__ __forceinline__ float sigmoidf_(float v) { return 1.f / (1.f + __expf(-v)); }
; __device__ __forceinline__ float siluf_(float v) { return v / (1.f + __expf(-v)); }
;     __device__ __forceinline__ void operator()(const f32x4 (&acc)[2][2][4][2], const Unit& u, int wr, int wc, int fr, int fq) const {
;     ...
;             for (int ai = 0; ai < 2; ++ai) {
; #pragma unroll
;                 for (int m = 0; m < 4; ++m) {
;                     const size_t row = (size_t)(row0 + ai * HALF + m * 16);
;                     const f32x4 v0 = acc[ai][bj][m][0], v1 = acc[ai][bj][m][1];
;                     float a[8] = {v0[0], v0[1], v0[2], v0[3], v1[0], v1[1], v1[2], v1[3]}, g[8], o[8];
;                     unpack8(*(const u32x4*)(R + row * RLD + (MODE == 0 ? 2560 : 1536) + col0), g);
;                     if (MODE == 0) { float y[8]; unpack8(*(const u32x4*)(YG + row * 512 + col0), y);
; #pragma unroll
;                         for (int e = 0; e < 8; ++e) o[e] = y[e] * sigmoidf_(a[e] + bb[e]) * siluf_(g[e]); }
;                     else {
; #pragma unroll
;                         for (int e = 0; e < 8; ++e) o[e] = a[e] * bb[e] * siluf_(g[e]); }
;                     u32x4 w; w.x = cvt_pk_bf16(o[0], o[1]); w.y = cvt_pk_bf16(o[2], o[3]); w.z = cvt_pk_bf16(o[4], o[5]); w.w = cvt_pk_bf16(o[6], o[7]);
;                     *(u32x4*)(Y + row * DM + (MODE == 0 ? 1536 : 1024) + col0) = w;
;                 }
	v_div_scale_f32 v124, s[2:3], v119, v119, v134
	v_rcp_f32_e32 v125, v124
	s_nop 0
	v_fma_f32 v126, -v124, v125, 1.0
	v_fmac_f32_e32 v125, v126, v125
	v_div_scale_f32 v126, vcc, v134, v119, v134
	v_mul_f32_e32 v127, v126, v125
	v_fma_f32 v132, -v124, v127, v126
	v_fmac_f32_e32 v127, v132, v125
	v_fma_f32 v124, -v124, v127, v126
	v_div_fmas_f32 v124, v124, v125, v127
	v_div_fixup_f32 v119, v124, v119, v134
	v_mul_f32_e32 v119, v106, v119
	v_mul_f32_e32 v106, v107, v79
	v_mul_f32_e32 v107, 0xbfb8aa3b, v118
	v_exp_f32_e32 v107, v107
	s_nop 0
	v_add_f32_e32 v107, 1.0, v107
	v_div_scale_f32 v124, s[2:3], v107, v107, v118
	v_rcp_f32_e32 v125, v124
	s_nop 0
	v_fma_f32 v126, -v124, v125, 1.0
	v_fmac_f32_e32 v125, v126, v125
	v_div_scale_f32 v126, vcc, v118, v107, v118
	v_mul_f32_e32 v127, v126, v125
	v_fma_f32 v132, -v124, v127, v126
	v_fmac_f32_e32 v127, v132, v125
	v_fma_f32 v124, -v124, v127, v126
	v_div_fmas_f32 v124, v124, v125, v127
	v_div_fixup_f32 v107, v124, v107, v118
	v_mul_f32_e32 v118, v106, v107
	v_cvt_pk_bf16_f32 v106, v108, v109
	v_cvt_pk_bf16_f32 v107, v110, v111
	v_cvt_pk_bf16_f32 v108, v104, v105
	v_lshlrev_b64 v[104:105], 12, v[116:117]
	v_lshl_add_u64 v[104:105], s[12:13], 0, v[104:105]
	v_lshl_add_u64 v[104:105], v[104:105], 0, v[180:181]
	v_cvt_pk_bf16_f32 v109, v119, v118
	global_store_dwordx4 v[104:105], v[106:109], off offset:2048
	s_add_u32 s2, s14, 0xf0000
	s_addc_u32 s3, s15, 0
	global_load_dwordx4 v[168:171], v214, s[2:3] offset:3072
	s_nop 1
	v_add_u32_e32 v108, 0x80, v138
	v_mad_i64_i32 v[106:107], s[2:3], v108, s4, v[140:141]
	v_lshl_add_u64 v[106:107], v[106:107], 0, v[180:181]
	s_waitcnt vmcnt(4)
	s_nop 1
	v_mov_b32_e32 v116, v188
	v_mov_b32_e32 v117, v189
	v_mov_b32_e32 v118, v190
	v_mov_b32_e32 v119, v191
	v_ashrrev_i32_e32 v109, 31, v108
	v_lshlrev_b32_e32 v111, 16, v116
	v_lshlrev_b32_e32 v126, 16, v119
	v_and_b32_e32 v110, 0xffff0000, v119
	v_mul_f32_e32 v119, 0xbfb8aa3b, v111
	v_exp_f32_e32 v119, v119
	v_and_b32_e32 v116, 0xffff0000, v116
	v_lshlrev_b32_e32 v124, 16, v117
	v_and_b32_e32 v117, 0xffff0000, v117
	v_add_f32_e32 v119, 1.0, v119
	v_div_scale_f32 v127, s[2:3], v119, v119, v111
	v_rcp_f32_e32 v132, v127
	v_lshlrev_b32_e32 v125, 16, v118
	v_and_b32_e32 v118, 0xffff0000, v118
	v_fma_f32 v133, -v127, v132, 1.0
	v_fmac_f32_e32 v132, v133, v132
	v_div_scale_f32 v133, vcc, v111, v119, v111
	v_mul_f32_e32 v134, v133, v132
	v_fma_f32 v135, -v127, v134, v133
	v_fmac_f32_e32 v134, v135, v132
	v_fma_f32 v127, -v127, v134, v133
	v_div_fmas_f32 v127, v127, v132, v134
	v_div_fixup_f32 v111, v127, v119, v111
	v_mul_f32_e32 v100, v100, v111
	v_mul_f32_e32 v111, 0xbfb8aa3b, v116
	v_exp_f32_e32 v111, v111
	s_nop 0
	v_add_f32_e32 v111, 1.0, v111
	v_div_scale_f32 v119, s[2:3], v111, v111, v116
	v_rcp_f32_e32 v127, v119
	s_nop 0
	v_fma_f32 v132, -v119, v127, 1.0
	v_fmac_f32_e32 v127, v132, v127
	v_div_scale_f32 v132, vcc, v116, v111, v116
	v_mul_f32_e32 v133, v132, v127
	v_fma_f32 v134, -v119, v133, v132
	v_fmac_f32_e32 v133, v134, v127
	v_fma_f32 v119, -v119, v133, v132
	v_div_fmas_f32 v119, v119, v127, v133
	v_div_fixup_f32 v111, v119, v111, v116
	v_mul_f32_e32 v101, v101, v111
	v_mul_f32_e32 v111, 0xbfb8aa3b, v124
	v_exp_f32_e32 v111, v111
	s_nop 0
	v_add_f32_e32 v111, 1.0, v111
	v_div_scale_f32 v116, s[2:3], v111, v111, v124
	v_rcp_f32_e32 v119, v116
	s_nop 0
	v_fma_f32 v127, -v116, v119, 1.0
	v_fmac_f32_e32 v119, v127, v119
	v_div_scale_f32 v127, vcc, v124, v111, v124
	v_mul_f32_e32 v132, v127, v119
	v_fma_f32 v133, -v116, v132, v127
	v_fmac_f32_e32 v132, v133, v119
	v_fma_f32 v116, -v116, v132, v127
	v_div_fmas_f32 v116, v116, v119, v132
	v_div_fixup_f32 v111, v116, v111, v124
	v_mul_f32_e32 v102, v102, v111
	v_mul_f32_e32 v111, 0xbfb8aa3b, v117
	v_exp_f32_e32 v111, v111
	s_nop 0
	v_add_f32_e32 v111, 1.0, v111
	v_div_scale_f32 v116, s[2:3], v111, v111, v117
	v_rcp_f32_e32 v119, v116
	s_nop 0
	v_fma_f32 v124, -v116, v119, 1.0
	v_fmac_f32_e32 v119, v124, v119
	v_div_scale_f32 v124, vcc, v117, v111, v117
	v_mul_f32_e32 v127, v124, v119
	v_fma_f32 v132, -v116, v127, v124
	v_fmac_f32_e32 v127, v132, v119
	v_fma_f32 v116, -v116, v127, v124
	v_div_fmas_f32 v116, v116, v119, v127
	v_div_fixup_f32 v111, v116, v111, v117
	v_mul_f32_e32 v103, v103, v111
	v_mul_f32_e32 v111, 0xbfb8aa3b, v125
	v_exp_f32_e32 v111, v111
	s_nop 0
	v_add_f32_e32 v111, 1.0, v111
	v_div_scale_f32 v116, s[2:3], v111, v111, v125
	v_rcp_f32_e32 v117, v116
	s_nop 0
	v_fma_f32 v119, -v116, v117, 1.0
	v_fmac_f32_e32 v117, v119, v117
	v_div_scale_f32 v119, vcc, v125, v111, v125
	v_mul_f32_e32 v124, v119, v117
	v_fma_f32 v127, -v116, v124, v119
	v_fmac_f32_e32 v124, v127, v117
	v_fma_f32 v116, -v116, v124, v119
	v_div_fmas_f32 v116, v116, v117, v124
	v_div_fixup_f32 v111, v116, v111, v125
	v_mul_f32_e32 v96, v96, v111
	v_mul_f32_e32 v111, 0xbfb8aa3b, v118
	v_exp_f32_e32 v111, v111
	s_nop 0
	v_add_f32_e32 v111, 1.0, v111
	v_div_scale_f32 v116, s[2:3], v111, v111, v118
	v_rcp_f32_e32 v117, v116
	s_nop 0
	v_fma_f32 v119, -v116, v117, 1.0
	v_fmac_f32_e32 v117, v119, v117
	v_div_scale_f32 v119, vcc, v118, v111, v118
	v_mul_f32_e32 v124, v119, v117
	v_fma_f32 v125, -v116, v124, v119
	v_fmac_f32_e32 v124, v125, v117
	v_fma_f32 v116, -v116, v124, v119
	v_div_fmas_f32 v116, v116, v117, v124
	v_div_fixup_f32 v111, v116, v111, v118
	v_mul_f32_e32 v97, v97, v111
	v_mul_f32_e32 v111, 0xbfb8aa3b, v126
	v_exp_f32_e32 v111, v111
	s_nop 0
	v_add_f32_e32 v111, 1.0, v111
	v_div_scale_f32 v116, s[2:3], v111, v111, v126
	v_rcp_f32_e32 v117, v116
	s_nop 0
	v_fma_f32 v118, -v116, v117, 1.0
	v_fmac_f32_e32 v117, v118, v117
	v_div_scale_f32 v118, vcc, v126, v111, v126
; __device__ __forceinline__ unsigned cvt_pk_bf16(float lo, float hi) { unsigned r; asm volatile("v_cvt_pk_bf16_f32 %0, %1, %2" : "=v"(r) : "v"(lo), "v"(hi)); return r; }
; __device__ __forceinline__ float sigmoidf_(float v) { return 1.f / (1.f + __expf(-v)); }
; __device__ __forceinline__ float siluf_(float v) { return v / (1.f + __expf(-v)); }
;     __device__ __forceinline__ void operator()(const f32x4 (&acc)[2][2][4][2], const Unit& u, int wr, int wc, int fr, int fq) const {
;     ...
;             for (int ai = 0; ai < 2; ++ai) {
; #pragma unroll
;                 for (int m = 0; m < 4; ++m) {
;                     const size_t row = (size_t)(row0 + ai * HALF + m * 16);
;                     const f32x4 v0 = acc[ai][bj][m][0], v1 = acc[ai][bj][m][1];
;                     float a[8] = {v0[0], v0[1], v0[2], v0[3], v1[0], v1[1], v1[2], v1[3]}, g[8], o[8];
;                     unpack8(*(const u32x4*)(R + row * RLD + (MODE == 0 ? 2560 : 1536) + col0), g);
;                     if (MODE == 0) { float y[8]; unpack8(*(const u32x4*)(YG + row * 512 + col0), y);
; #pragma unroll
;                         for (int e = 0; e < 8; ++e) o[e] = y[e] * sigmoidf_(a[e] + bb[e]) * siluf_(g[e]); }
;                     else {
; #pragma unroll
;                         for (int e = 0; e < 8; ++e) o[e] = a[e] * bb[e] * siluf_(g[e]); }
;                     u32x4 w; w.x = cvt_pk_bf16(o[0], o[1]); w.y = cvt_pk_bf16(o[2], o[3]); w.z = cvt_pk_bf16(o[4], o[5]); w.w = cvt_pk_bf16(o[6], o[7]);
;                     *(u32x4*)(Y + row * DM + (MODE == 0 ? 1536 : 1024) + col0) = w;
;                 }
	v_mul_f32_e32 v119, v118, v117
	v_fma_f32 v124, -v116, v119, v118
	v_fmac_f32_e32 v119, v124, v117
	v_fma_f32 v116, -v116, v119, v118
	v_div_fmas_f32 v116, v116, v117, v119
	v_div_fixup_f32 v111, v116, v111, v126
	v_mul_f32_e32 v111, v98, v111
	v_mul_f32_e32 v98, v99, v79
	v_mul_f32_e32 v99, 0xbfb8aa3b, v110
	v_exp_f32_e32 v99, v99
	s_nop 0
	v_add_f32_e32 v99, 1.0, v99
	v_div_scale_f32 v116, s[2:3], v99, v99, v110
	v_rcp_f32_e32 v117, v116
	s_nop 0
	v_fma_f32 v118, -v116, v117, 1.0
	v_fmac_f32_e32 v117, v118, v117
	v_div_scale_f32 v118, vcc, v110, v99, v110
	v_mul_f32_e32 v119, v118, v117
	v_fma_f32 v124, -v116, v119, v118
	v_fmac_f32_e32 v119, v124, v117
	v_fma_f32 v116, -v116, v119, v118
	v_div_fmas_f32 v116, v116, v117, v119
	v_div_fixup_f32 v99, v116, v99, v110
	v_mul_f32_e32 v110, v98, v99
	v_cvt_pk_bf16_f32 v98, v100, v101
	v_cvt_pk_bf16_f32 v99, v102, v103
	v_cvt_pk_bf16_f32 v100, v96, v97
	v_lshlrev_b64 v[96:97], 12, v[108:109]
	v_lshl_add_u64 v[96:97], s[12:13], 0, v[96:97]
	v_lshl_add_u64 v[96:97], v[96:97], 0, v[180:181]
	v_cvt_pk_bf16_f32 v101, v111, v110
	global_store_dwordx4 v[96:97], v[98:101], off offset:2048
	s_add_u32 s2, s14, 0x108000
	s_addc_u32 s3, s15, 0
	global_load_dwordx4 v[188:191], v214, s[2:3] offset:3072
	s_nop 1
	v_add_u32_e32 v100, 0x90, v138
	v_mad_i64_i32 v[98:99], s[2:3], v100, s4, v[140:141]
	v_lshl_add_u64 v[98:99], v[98:99], 0, v[180:181]
	s_waitcnt vmcnt(4)
	s_nop 1
	v_mov_b32_e32 v108, v206
	v_mov_b32_e32 v109, v207
	v_mov_b32_e32 v110, v208
	v_mov_b32_e32 v111, v209
	v_ashrrev_i32_e32 v101, 31, v100
	v_lshlrev_b32_e32 v103, 16, v108
	v_lshlrev_b32_e32 v118, 16, v111
	v_and_b32_e32 v102, 0xffff0000, v111
	v_mul_f32_e32 v111, 0xbfb8aa3b, v103
	v_exp_f32_e32 v111, v111
	v_and_b32_e32 v108, 0xffff0000, v108
	v_lshlrev_b32_e32 v116, 16, v109
	v_and_b32_e32 v109, 0xffff0000, v109
	v_add_f32_e32 v111, 1.0, v111
	v_div_scale_f32 v119, s[2:3], v111, v111, v103
	v_rcp_f32_e32 v124, v119
	v_lshlrev_b32_e32 v117, 16, v110
	v_and_b32_e32 v110, 0xffff0000, v110
	v_fma_f32 v125, -v119, v124, 1.0
	v_fmac_f32_e32 v124, v125, v124
	v_div_scale_f32 v125, vcc, v103, v111, v103
	v_mul_f32_e32 v126, v125, v124
	v_fma_f32 v127, -v119, v126, v125
	v_fmac_f32_e32 v126, v127, v124
	v_fma_f32 v119, -v119, v126, v125
	v_div_fmas_f32 v119, v119, v124, v126
	v_div_fixup_f32 v103, v119, v111, v103
	v_mul_f32_e32 v92, v92, v103
	v_mul_f32_e32 v103, 0xbfb8aa3b, v108
	v_exp_f32_e32 v103, v103
	s_nop 0
	v_add_f32_e32 v103, 1.0, v103
	v_div_scale_f32 v111, s[2:3], v103, v103, v108
	v_rcp_f32_e32 v119, v111
	s_nop 0
	v_fma_f32 v124, -v111, v119, 1.0
	v_fmac_f32_e32 v119, v124, v119
	v_div_scale_f32 v124, vcc, v108, v103, v108
	v_mul_f32_e32 v125, v124, v119
	v_fma_f32 v126, -v111, v125, v124
	v_fmac_f32_e32 v125, v126, v119
	v_fma_f32 v111, -v111, v125, v124
	v_div_fmas_f32 v111, v111, v119, v125
	v_div_fixup_f32 v103, v111, v103, v108
	v_mul_f32_e32 v93, v93, v103
	v_mul_f32_e32 v103, 0xbfb8aa3b, v116
	v_exp_f32_e32 v103, v103
	s_nop 0
	v_add_f32_e32 v103, 1.0, v103
	v_div_scale_f32 v108, s[2:3], v103, v103, v116
	v_rcp_f32_e32 v111, v108
	s_nop 0
	v_fma_f32 v119, -v108, v111, 1.0
	v_fmac_f32_e32 v111, v119, v111
	v_div_scale_f32 v119, vcc, v116, v103, v116
	v_mul_f32_e32 v124, v119, v111
	v_fma_f32 v125, -v108, v124, v119
	v_fmac_f32_e32 v124, v125, v111
	v_fma_f32 v108, -v108, v124, v119
	v_div_fmas_f32 v108, v108, v111, v124
	v_div_fixup_f32 v103, v108, v103, v116
	v_mul_f32_e32 v94, v94, v103
	v_mul_f32_e32 v103, 0xbfb8aa3b, v109
	v_exp_f32_e32 v103, v103
	s_nop 0
	v_add_f32_e32 v103, 1.0, v103
	v_div_scale_f32 v108, s[2:3], v103, v103, v109
	v_rcp_f32_e32 v111, v108
	s_nop 0
	v_fma_f32 v116, -v108, v111, 1.0
	v_fmac_f32_e32 v111, v116, v111
	v_div_scale_f32 v116, vcc, v109, v103, v109
	v_mul_f32_e32 v119, v116, v111
	v_fma_f32 v124, -v108, v119, v116
	v_fmac_f32_e32 v119, v124, v111
	v_fma_f32 v108, -v108, v119, v116
	v_div_fmas_f32 v108, v108, v111, v119
	v_div_fixup_f32 v103, v108, v103, v109
	v_mul_f32_e32 v95, v95, v103
	v_mul_f32_e32 v103, 0xbfb8aa3b, v117
	v_exp_f32_e32 v103, v103
	s_nop 0
	v_add_f32_e32 v103, 1.0, v103
	v_div_scale_f32 v108, s[2:3], v103, v103, v117
	v_rcp_f32_e32 v109, v108
	s_nop 0
	v_fma_f32 v111, -v108, v109, 1.0
	v_fmac_f32_e32 v109, v111, v109
	v_div_scale_f32 v111, vcc, v117, v103, v117
	v_mul_f32_e32 v116, v111, v109
	v_fma_f32 v119, -v108, v116, v111
	v_fmac_f32_e32 v116, v119, v109
	v_fma_f32 v108, -v108, v116, v111
	v_div_fmas_f32 v108, v108, v109, v116
	v_div_fixup_f32 v103, v108, v103, v117
	v_mul_f32_e32 v88, v88, v103
	v_mul_f32_e32 v103, 0xbfb8aa3b, v110
	v_exp_f32_e32 v103, v103
	s_nop 0
	v_add_f32_e32 v103, 1.0, v103
	v_div_scale_f32 v108, s[2:3], v103, v103, v110
	v_rcp_f32_e32 v109, v108
	s_nop 0
	v_fma_f32 v111, -v108, v109, 1.0
	v_fmac_f32_e32 v109, v111, v109
	v_div_scale_f32 v111, vcc, v110, v103, v110
	v_mul_f32_e32 v116, v111, v109
	v_fma_f32 v117, -v108, v116, v111
	v_fmac_f32_e32 v116, v117, v109
	v_fma_f32 v108, -v108, v116, v111
	v_div_fmas_f32 v108, v108, v109, v116
	v_div_fixup_f32 v103, v108, v103, v110
	v_mul_f32_e32 v89, v89, v103
	v_mul_f32_e32 v103, 0xbfb8aa3b, v118
	v_exp_f32_e32 v103, v103
	s_nop 0
	v_add_f32_e32 v103, 1.0, v103
	v_div_scale_f32 v108, s[2:3], v103, v103, v118
	v_rcp_f32_e32 v109, v108
	s_nop 0
	v_fma_f32 v110, -v108, v109, 1.0
	v_fmac_f32_e32 v109, v110, v109
	v_div_scale_f32 v110, vcc, v118, v103, v118
	v_mul_f32_e32 v111, v110, v109
	v_fma_f32 v116, -v108, v111, v110
	v_fmac_f32_e32 v111, v116, v109
	v_fma_f32 v108, -v108, v111, v110
	v_div_fmas_f32 v108, v108, v109, v111
	v_div_fixup_f32 v103, v108, v103, v118
	v_mul_f32_e32 v103, v90, v103
	v_mul_f32_e32 v90, v91, v79
	v_mul_f32_e32 v91, 0xbfb8aa3b, v102
	v_exp_f32_e32 v91, v91
	s_nop 0
	v_add_f32_e32 v91, 1.0, v91
	v_div_scale_f32 v108, s[2:3], v91, v91, v102
	v_rcp_f32_e32 v109, v108
	s_nop 0
	v_fma_f32 v110, -v108, v109, 1.0
	v_fmac_f32_e32 v109, v110, v109
	v_div_scale_f32 v110, vcc, v102, v91, v102
	v_mul_f32_e32 v111, v110, v109
	v_fma_f32 v116, -v108, v111, v110
	v_fmac_f32_e32 v111, v116, v109
	v_fma_f32 v108, -v108, v111, v110
	v_div_fmas_f32 v108, v108, v109, v111
	v_div_fixup_f32 v91, v108, v91, v102
	v_mul_f32_e32 v102, v90, v91
	v_cvt_pk_bf16_f32 v90, v92, v93
	v_cvt_pk_bf16_f32 v91, v94, v95
	v_cvt_pk_bf16_f32 v92, v88, v89
	v_lshlrev_b64 v[88:89], 12, v[100:101]
	v_lshl_add_u64 v[88:89], s[12:13], 0, v[88:89]
	v_lshl_add_u64 v[88:89], v[88:89], 0, v[180:181]
	v_cvt_pk_bf16_f32 v93, v103, v102
	global_store_dwordx4 v[88:89], v[90:93], off offset:2048
	s_add_u32 s2, s14, 0x0
	s_addc_u32 s3, s15, 0
	global_load_dwordx4 v[206:209], v214, s[2:3] offset:3328
	s_nop 1
	v_add_u32_e32 v92, 0xa0, v138
	v_mad_i64_i32 v[90:91], s[2:3], v92, s4, v[140:141]
	v_lshl_add_u64 v[90:91], v[90:91], 0, v[180:181]
	s_waitcnt vmcnt(4)
; __device__ __forceinline__ unsigned cvt_pk_bf16(float lo, float hi) { unsigned r; asm volatile("v_cvt_pk_bf16_f32 %0, %1, %2" : "=v"(r) : "v"(lo), "v"(hi)); return r; }
; __device__ __forceinline__ float sigmoidf_(float v) { return 1.f / (1.f + __expf(-v)); }
; __device__ __forceinline__ float siluf_(float v) { return v / (1.f + __expf(-v)); }
;     __device__ __forceinline__ void operator()(const f32x4 (&acc)[2][2][4][2], const Unit& u, int wr, int wc, int fr, int fq) const {
;     ...
;             for (int ai = 0; ai < 2; ++ai) {
; #pragma unroll
;                 for (int m = 0; m < 4; ++m) {
;                     const size_t row = (size_t)(row0 + ai * HALF + m * 16);
;                     const f32x4 v0 = acc[ai][bj][m][0], v1 = acc[ai][bj][m][1];
;                     float a[8] = {v0[0], v0[1], v0[2], v0[3], v1[0], v1[1], v1[2], v1[3]}, g[8], o[8];
;                     unpack8(*(const u32x4*)(R + row * RLD + (MODE == 0 ? 2560 : 1536) + col0), g);
;                     if (MODE == 0) { float y[8]; unpack8(*(const u32x4*)(YG + row * 512 + col0), y);
; #pragma unroll
;                         for (int e = 0; e < 8; ++e) o[e] = y[e] * sigmoidf_(a[e] + bb[e]) * siluf_(g[e]); }
;                     else {
; #pragma unroll
;                         for (int e = 0; e < 8; ++e) o[e] = a[e] * bb[e] * siluf_(g[e]); }
;                     u32x4 w; w.x = cvt_pk_bf16(o[0], o[1]); w.y = cvt_pk_bf16(o[2], o[3]); w.z = cvt_pk_bf16(o[4], o[5]); w.w = cvt_pk_bf16(o[6], o[7]);
;                     *(u32x4*)(Y + row * DM + (MODE == 0 ? 1536 : 1024) + col0) = w;
;                 }
	s_nop 1
	v_mov_b32_e32 v100, v168
	v_mov_b32_e32 v101, v169
	v_mov_b32_e32 v102, v170
	v_mov_b32_e32 v103, v171
	v_ashrrev_i32_e32 v93, 31, v92
	v_lshlrev_b32_e32 v95, 16, v100
	v_lshlrev_b32_e32 v110, 16, v103
	v_and_b32_e32 v94, 0xffff0000, v103
	v_mul_f32_e32 v103, 0xbfb8aa3b, v95
	v_exp_f32_e32 v103, v103
	v_and_b32_e32 v100, 0xffff0000, v100
	v_lshlrev_b32_e32 v108, 16, v101
	v_and_b32_e32 v101, 0xffff0000, v101
	v_add_f32_e32 v103, 1.0, v103
	v_div_scale_f32 v111, s[2:3], v103, v103, v95
	v_rcp_f32_e32 v116, v111
	v_lshlrev_b32_e32 v109, 16, v102
	v_and_b32_e32 v102, 0xffff0000, v102
	v_fma_f32 v117, -v111, v116, 1.0
	v_fmac_f32_e32 v116, v117, v116
	v_div_scale_f32 v117, vcc, v95, v103, v95
	v_mul_f32_e32 v118, v117, v116
	v_fma_f32 v119, -v111, v118, v117
	v_fmac_f32_e32 v118, v119, v116
	v_fma_f32 v111, -v111, v118, v117
	v_div_fmas_f32 v111, v111, v116, v118
	v_div_fixup_f32 v95, v111, v103, v95
	v_mul_f32_e32 v80, v80, v95
	v_mul_f32_e32 v95, 0xbfb8aa3b, v100
	v_exp_f32_e32 v95, v95
	s_nop 0
	v_add_f32_e32 v95, 1.0, v95
	v_div_scale_f32 v103, s[2:3], v95, v95, v100
	v_rcp_f32_e32 v111, v103
	s_nop 0
	v_fma_f32 v116, -v103, v111, 1.0
	v_fmac_f32_e32 v111, v116, v111
	v_div_scale_f32 v116, vcc, v100, v95, v100
	v_mul_f32_e32 v117, v116, v111
	v_fma_f32 v118, -v103, v117, v116
	v_fmac_f32_e32 v117, v118, v111
	v_fma_f32 v103, -v103, v117, v116
	v_div_fmas_f32 v103, v103, v111, v117
	v_div_fixup_f32 v95, v103, v95, v100
	v_mul_f32_e32 v81, v81, v95
	v_mul_f32_e32 v95, 0xbfb8aa3b, v108
	v_exp_f32_e32 v95, v95
	v_cvt_pk_bf16_f32 v80, v80, v81
	s_nop 0
	v_add_f32_e32 v95, 1.0, v95
	v_div_scale_f32 v100, s[2:3], v95, v95, v108
	v_rcp_f32_e32 v103, v100
	s_nop 0
	v_fma_f32 v111, -v100, v103, 1.0
	v_fmac_f32_e32 v103, v111, v103
	v_div_scale_f32 v111, vcc, v108, v95, v108
	v_mul_f32_e32 v116, v111, v103
	v_fma_f32 v117, -v100, v116, v111
	v_fmac_f32_e32 v116, v117, v103
	v_fma_f32 v100, -v100, v116, v111
	v_div_fmas_f32 v100, v100, v103, v116
	v_div_fixup_f32 v95, v100, v95, v108
	v_mul_f32_e32 v82, v82, v95
	v_mul_f32_e32 v95, 0xbfb8aa3b, v101
	v_exp_f32_e32 v95, v95
	s_nop 0
	v_add_f32_e32 v95, 1.0, v95
	v_div_scale_f32 v100, s[2:3], v95, v95, v101
	v_rcp_f32_e32 v103, v100
	s_nop 0
	v_fma_f32 v108, -v100, v103, 1.0
	v_fmac_f32_e32 v103, v108, v103
	v_div_scale_f32 v108, vcc, v101, v95, v101
	v_mul_f32_e32 v111, v108, v103
	v_fma_f32 v116, -v100, v111, v108
	v_fmac_f32_e32 v111, v116, v103
	v_fma_f32 v100, -v100, v111, v108
	v_div_fmas_f32 v100, v100, v103, v111
	v_div_fixup_f32 v95, v100, v95, v101
	v_mul_f32_e32 v83, v83, v95
	v_mul_f32_e32 v95, 0xbfb8aa3b, v109
	v_exp_f32_e32 v95, v95
	v_cvt_pk_bf16_f32 v81, v82, v83
	s_nop 0
	v_add_f32_e32 v95, 1.0, v95
	v_div_scale_f32 v100, s[2:3], v95, v95, v109
	v_rcp_f32_e32 v101, v100
	s_nop 0
	v_fma_f32 v103, -v100, v101, 1.0
	v_fmac_f32_e32 v101, v103, v101
	v_div_scale_f32 v103, vcc, v109, v95, v109
	v_mul_f32_e32 v108, v103, v101
	v_fma_f32 v111, -v100, v108, v103
	v_fmac_f32_e32 v108, v111, v101
	v_fma_f32 v100, -v100, v108, v103
	v_div_fmas_f32 v100, v100, v101, v108
	v_div_fixup_f32 v95, v100, v95, v109
	v_mul_f32_e32 v72, v72, v95
	v_mul_f32_e32 v95, 0xbfb8aa3b, v102
	v_exp_f32_e32 v95, v95
	s_nop 0
	v_add_f32_e32 v95, 1.0, v95
	v_div_scale_f32 v100, s[2:3], v95, v95, v102
	v_rcp_f32_e32 v101, v100
	s_nop 0
	v_fma_f32 v103, -v100, v101, 1.0
	v_fmac_f32_e32 v101, v103, v101
	v_div_scale_f32 v103, vcc, v102, v95, v102
	v_mul_f32_e32 v108, v103, v101
	v_fma_f32 v109, -v100, v108, v103
	v_fmac_f32_e32 v108, v109, v101
	v_fma_f32 v100, -v100, v108, v103
	v_div_fmas_f32 v100, v100, v101, v108
	v_div_fixup_f32 v95, v100, v95, v102
	v_mul_f32_e32 v73, v73, v95
	v_mul_f32_e32 v95, 0xbfb8aa3b, v110
	v_exp_f32_e32 v95, v95
	v_cvt_pk_bf16_f32 v82, v72, v73
	v_lshlrev_b64 v[72:73], 12, v[92:93]
	v_lshl_add_u64 v[72:73], s[12:13], 0, v[72:73]
	v_add_f32_e32 v95, 1.0, v95
	v_div_scale_f32 v100, s[2:3], v95, v95, v110
	v_rcp_f32_e32 v101, v100
	v_lshl_add_u64 v[72:73], v[72:73], 0, v[180:181]
	v_fma_f32 v102, -v100, v101, 1.0
	v_fmac_f32_e32 v101, v102, v101
	v_div_scale_f32 v102, vcc, v110, v95, v110
	v_mul_f32_e32 v103, v102, v101
	v_fma_f32 v108, -v100, v103, v102
	v_fmac_f32_e32 v103, v108, v101
	v_fma_f32 v100, -v100, v103, v102
	v_div_fmas_f32 v100, v100, v101, v103
	v_div_fixup_f32 v95, v100, v95, v110
	v_mul_f32_e32 v74, v74, v95
	v_mul_f32_e32 v95, 0xbfb8aa3b, v94
	v_exp_f32_e32 v95, v95
	s_nop 0
	v_add_f32_e32 v95, 1.0, v95
	v_div_scale_f32 v100, s[2:3], v95, v95, v94
	v_rcp_f32_e32 v101, v100
	s_nop 0
	v_fma_f32 v102, -v100, v101, 1.0
	v_fmac_f32_e32 v101, v102, v101
	v_div_scale_f32 v102, vcc, v94, v95, v94
	v_mul_f32_e32 v103, v102, v101
	v_fma_f32 v108, -v100, v103, v102
	v_fmac_f32_e32 v103, v108, v101
	v_fma_f32 v100, -v100, v103, v102
	v_div_fmas_f32 v100, v100, v101, v103
	v_div_fixup_f32 v94, v100, v95, v94
	v_mul_f32_e32 v75, v75, v94
	v_cvt_pk_bf16_f32 v83, v74, v75
	global_store_dwordx4 v[72:73], v[80:83], off offset:2048
	s_add_u32 s2, s14, 0x18000
	s_addc_u32 s3, s15, 0
	global_load_dwordx4 v[168:171], v214, s[2:3] offset:3328
	s_nop 1
	v_add_u32_e32 v80, 0xb0, v138
	v_mad_i64_i32 v[74:75], s[2:3], v80, s4, v[140:141]
	v_lshl_add_u64 v[74:75], v[74:75], 0, v[180:181]
	s_waitcnt vmcnt(4)
; __device__ __forceinline__ unsigned cvt_pk_bf16(float lo, float hi) { unsigned r; asm volatile("v_cvt_pk_bf16_f32 %0, %1, %2" : "=v"(r) : "v"(lo), "v"(hi)); return r; }
; __device__ __forceinline__ float sigmoidf_(float v) { return 1.f / (1.f + __expf(-v)); }
; __device__ __forceinline__ float siluf_(float v) { return v / (1.f + __expf(-v)); }
;     __device__ __forceinline__ void operator()(const f32x4 (&acc)[2][2][4][2], const Unit& u, int wr, int wc, int fr, int fq) const {
;     ...
;             const f32x4 b0 = *(const f32x4*)(bias + col0), b1 = *(const f32x4*)(bias + col0 + 4);
;             float bb[8] = {b0[0], b0[1], b0[2], b0[3], b1[0], b1[1], b1[2], b1[3]};
; #pragma unroll
;             for (int ai = 0; ai < 2; ++ai) {
; #pragma unroll
;                 for (int m = 0; m < 4; ++m) {
;                     const size_t row = (size_t)(row0 + ai * HALF + m * 16);
;                     const f32x4 v0 = acc[ai][bj][m][0], v1 = acc[ai][bj][m][1];
;                     float a[8] = {v0[0], v0[1], v0[2], v0[3], v1[0], v1[1], v1[2], v1[3]}, g[8], o[8];
;                     unpack8(*(const u32x4*)(R + row * RLD + (MODE == 0 ? 2560 : 1536) + col0), g);
;                     if (MODE == 0) { float y[8]; unpack8(*(const u32x4*)(YG + row * 512 + col0), y);
; #pragma unroll
;                         for (int e = 0; e < 8; ++e) o[e] = y[e] * sigmoidf_(a[e] + bb[e]) * siluf_(g[e]); }
;                     else {
; #pragma unroll
;                         for (int e = 0; e < 8; ++e) o[e] = a[e] * bb[e] * siluf_(g[e]); }
;                     u32x4 w; w.x = cvt_pk_bf16(o[0], o[1]); w.y = cvt_pk_bf16(o[2], o[3]); w.z = cvt_pk_bf16(o[4], o[5]); w.w = cvt_pk_bf16(o[6], o[7]);
;                     *(u32x4*)(Y + row * DM + (MODE == 0 ? 1536 : 1024) + col0) = w;
;                 }
	s_nop 1
	v_mov_b32_e32 v92, v188
	v_mov_b32_e32 v93, v189
	v_mov_b32_e32 v94, v190
	v_mov_b32_e32 v95, v191
	v_ashrrev_i32_e32 v81, 31, v80
	v_lshlrev_b32_e32 v83, 16, v92
	v_mul_f32_e32 v84, 0xbfb8aa3b, v83
	v_exp_f32_e32 v84, v84
	v_lshlrev_b32_e32 v102, 16, v95
	v_and_b32_e32 v82, 0xffff0000, v95
	v_and_b32_e32 v92, 0xffff0000, v92
	v_add_f32_e32 v84, 1.0, v84
	v_div_scale_f32 v95, s[2:3], v84, v84, v83
	v_rcp_f32_e32 v103, v95
	v_lshlrev_b32_e32 v100, 16, v93
	v_and_b32_e32 v93, 0xffff0000, v93
	v_lshlrev_b32_e32 v101, 16, v94
	v_fma_f32 v108, -v95, v103, 1.0
	v_fmac_f32_e32 v103, v108, v103
	v_div_scale_f32 v108, vcc, v83, v84, v83
	v_mul_f32_e32 v109, v108, v103
	v_fma_f32 v110, -v95, v109, v108
	v_fmac_f32_e32 v109, v110, v103
	v_fma_f32 v95, -v95, v109, v108
	v_div_fmas_f32 v95, v95, v103, v109
	v_div_fixup_f32 v83, v95, v84, v83
	v_mul_f32_e32 v68, v68, v83
	v_mul_f32_e32 v83, 0xbfb8aa3b, v92
	v_exp_f32_e32 v83, v83
	v_mul_f32_e32 v76, 0xbfb8aa3b, v101
	v_exp_f32_e32 v76, v76
	v_and_b32_e32 v94, 0xffff0000, v94
	v_add_f32_e32 v83, 1.0, v83
	v_div_scale_f32 v84, s[2:3], v83, v83, v92
	v_rcp_f32_e32 v85, v84
	v_add_f32_e32 v76, 1.0, v76
	v_fma_f32 v95, -v84, v85, 1.0
	v_fmac_f32_e32 v85, v95, v85
	v_div_scale_f32 v95, vcc, v92, v83, v92
	v_mul_f32_e32 v103, v95, v85
	v_fma_f32 v108, -v84, v103, v95
	v_fmac_f32_e32 v103, v108, v85
	v_fma_f32 v84, -v84, v103, v95
	v_div_fmas_f32 v84, v84, v85, v103
	v_div_fixup_f32 v83, v84, v83, v92
	v_mul_f32_e32 v69, v69, v83
	v_mul_f32_e32 v83, 0xbfb8aa3b, v100
	v_exp_f32_e32 v83, v83
	s_nop 0
	v_add_f32_e32 v83, 1.0, v83
	v_div_scale_f32 v84, s[2:3], v83, v83, v100
	v_rcp_f32_e32 v85, v84
	s_nop 0
	v_fma_f32 v86, -v84, v85, 1.0
	v_fmac_f32_e32 v85, v86, v85
	v_div_scale_f32 v86, vcc, v100, v83, v100
	v_mul_f32_e32 v92, v86, v85
	v_fma_f32 v95, -v84, v92, v86
	v_fmac_f32_e32 v92, v95, v85
	v_fma_f32 v84, -v84, v92, v86
	v_div_fmas_f32 v84, v84, v85, v92
	v_div_fixup_f32 v83, v84, v83, v100
	v_mul_f32_e32 v70, v70, v83
	v_mul_f32_e32 v83, 0xbfb8aa3b, v93
	v_exp_f32_e32 v83, v83
	s_nop 0
	v_add_f32_e32 v83, 1.0, v83
	v_div_scale_f32 v84, s[2:3], v83, v83, v93
	v_rcp_f32_e32 v85, v84
	s_nop 0
	v_fma_f32 v86, -v84, v85, 1.0
	v_fmac_f32_e32 v85, v86, v85
	v_div_scale_f32 v86, vcc, v93, v83, v93
	v_mul_f32_e32 v87, v86, v85
	v_fma_f32 v92, -v84, v87, v86
	v_fmac_f32_e32 v87, v92, v85
	v_fma_f32 v84, -v84, v87, v86
	v_div_fmas_f32 v84, v84, v85, v87
	v_div_fixup_f32 v83, v84, v83, v93
	v_mul_f32_e32 v71, v71, v83
	v_div_scale_f32 v83, s[2:3], v76, v76, v101
	v_rcp_f32_e32 v84, v83
	s_nop 0
	v_fma_f32 v85, -v83, v84, 1.0
	v_fmac_f32_e32 v84, v85, v84
	v_div_scale_f32 v85, vcc, v101, v76, v101
	v_mul_f32_e32 v86, v85, v84
	v_fma_f32 v87, -v83, v86, v85
	v_fmac_f32_e32 v86, v87, v84
	v_fma_f32 v83, -v83, v86, v85
	v_div_fmas_f32 v83, v83, v84, v86
	v_div_fixup_f32 v76, v83, v76, v101
	v_mul_f32_e32 v76, v64, v76
	v_mul_f32_e32 v64, v65, v77
	v_mul_f32_e32 v65, 0xbfb8aa3b, v94
	v_exp_f32_e32 v65, v65
	s_nop 0
	v_add_f32_e32 v65, 1.0, v65
	v_div_scale_f32 v77, s[2:3], v65, v65, v94
	v_rcp_f32_e32 v83, v77
	s_nop 0
	v_fma_f32 v84, -v77, v83, 1.0
	v_fmac_f32_e32 v83, v84, v83
	v_div_scale_f32 v84, vcc, v94, v65, v94
	v_mul_f32_e32 v85, v84, v83
	v_fma_f32 v86, -v77, v85, v84
	v_fmac_f32_e32 v85, v86, v83
	v_fma_f32 v77, -v77, v85, v84
	v_div_fmas_f32 v77, v77, v83, v85
	v_div_fixup_f32 v65, v77, v65, v94
	v_mul_f32_e32 v77, v64, v65
	v_mul_f32_e32 v65, 0xbfb8aa3b, v102
	v_exp_f32_e32 v65, v65
	v_mul_f32_e32 v64, v66, v78
	v_add_f32_e32 v65, 1.0, v65
	v_div_scale_f32 v66, s[2:3], v65, v65, v102
	v_rcp_f32_e32 v78, v66
	s_nop 0
	v_fma_f32 v83, -v66, v78, 1.0
	v_fmac_f32_e32 v78, v83, v78
	v_div_scale_f32 v83, vcc, v102, v65, v102
	v_mul_f32_e32 v84, v83, v78
	v_fma_f32 v85, -v66, v84, v83
	v_fmac_f32_e32 v84, v85, v78
	v_fma_f32 v66, -v66, v84, v83
	v_div_fmas_f32 v66, v66, v78, v84
	v_div_fixup_f32 v65, v66, v65, v102
	v_mul_f32_e32 v78, v64, v65
	v_mul_f32_e32 v65, 0xbfb8aa3b, v82
	v_exp_f32_e32 v65, v65
	v_mul_f32_e32 v64, v67, v79
	v_add_f32_e32 v65, 1.0, v65
	v_div_scale_f32 v66, s[2:3], v65, v65, v82
	v_rcp_f32_e32 v67, v66
	s_nop 0
	v_fma_f32 v79, -v66, v67, 1.0
	v_fmac_f32_e32 v67, v79, v67
	v_div_scale_f32 v79, vcc, v82, v65, v82
	v_mul_f32_e32 v83, v79, v67
	v_fma_f32 v84, -v66, v83, v79
	v_fmac_f32_e32 v83, v84, v67
	v_fma_f32 v66, -v66, v83, v79
	v_div_fmas_f32 v66, v66, v67, v83
	v_div_fixup_f32 v65, v66, v65, v82
	v_mul_f32_e32 v67, v64, v65
	v_cvt_pk_bf16_f32 v64, v68, v69
	v_lshlrev_b64 v[68:69], 12, v[80:81]
	v_lshl_add_u64 v[68:69], s[12:13], 0, v[68:69]
	v_cvt_pk_bf16_f32 v65, v70, v71
	v_cvt_pk_bf16_f32 v66, v76, v77
	v_lshl_add_u64 v[76:77], v[68:69], 0, v[180:181]
	v_cvt_pk_bf16_f32 v67, v78, v67
	global_store_dwordx4 v[76:77], v[64:67], off offset:2048
	s_add_u32 s2, s14, 0x30000
	s_addc_u32 s3, s15, 0
	global_load_dwordx4 v[188:191], v214, s[2:3] offset:3328
	global_load_dwordx4 v[64:67], v142, s[0:1] offset:528
	global_load_dwordx4 v[68:71], v142, s[0:1] offset:512
	s_waitcnt vmcnt(0)
; __device__ __forceinline__ unsigned cvt_pk_bf16(float lo, float hi) { unsigned r; asm volatile("v_cvt_pk_bf16_f32 %0, %1, %2" : "=v"(r) : "v"(lo), "v"(hi)); return r; }
; __device__ __forceinline__ float sigmoidf_(float v) { return 1.f / (1.f + __expf(-v)); }
; __device__ __forceinline__ float siluf_(float v) { return v / (1.f + __expf(-v)); }
;     __device__ __forceinline__ void operator()(const f32x4 (&acc)[2][2][4][2], const Unit& u, int wr, int wc, int fr, int fq) const {
;     ...
;             const f32x4 b0 = *(const f32x4*)(bias + col0), b1 = *(const f32x4*)(bias + col0 + 4);
;             float bb[8] = {b0[0], b0[1], b0[2], b0[3], b1[0], b1[1], b1[2], b1[3]};
; #pragma unroll
;             for (int ai = 0; ai < 2; ++ai) {
; #pragma unroll
;                 for (int m = 0; m < 4; ++m) {
;                     const size_t row = (size_t)(row0 + ai * HALF + m * 16);
;                     const f32x4 v0 = acc[ai][bj][m][0], v1 = acc[ai][bj][m][1];
;                     float a[8] = {v0[0], v0[1], v0[2], v0[3], v1[0], v1[1], v1[2], v1[3]}, g[8], o[8];
;                     unpack8(*(const u32x4*)(R + row * RLD + (MODE == 0 ? 2560 : 1536) + col0), g);
;                     if (MODE == 0) { float y[8]; unpack8(*(const u32x4*)(YG + row * 512 + col0), y);
; #pragma unroll
;                         for (int e = 0; e < 8; ++e) o[e] = y[e] * sigmoidf_(a[e] + bb[e]) * siluf_(g[e]); }
;                     else {
; #pragma unroll
;                         for (int e = 0; e < 8; ++e) o[e] = a[e] * bb[e] * siluf_(g[e]); }
;                     u32x4 w; w.x = cvt_pk_bf16(o[0], o[1]); w.y = cvt_pk_bf16(o[2], o[3]); w.z = cvt_pk_bf16(o[4], o[5]); w.w = cvt_pk_bf16(o[6], o[7]);
;                     *(u32x4*)(Y + row * DM + (MODE == 0 ? 1536 : 1024) + col0) = w;
;                 }
	s_nop 1
	v_mov_b32_e32 v78, v206
	v_mov_b32_e32 v79, v207
	v_mov_b32_e32 v80, v208
	v_mov_b32_e32 v81, v209
	v_mul_f32_e32 v56, v56, v64
	v_mul_f32_e32 v60, v60, v68
	v_lshlrev_b32_e32 v82, 16, v78
	v_and_b32_e32 v83, 0xffff0000, v78
	v_lshlrev_b32_e32 v86, 16, v81
	v_and_b32_e32 v78, 0xffff0000, v81
	v_mul_f32_e32 v81, 0xbfb8aa3b, v82
	v_exp_f32_e32 v81, v81
	v_lshlrev_b32_e32 v84, 16, v79
	v_mul_f32_e32 v61, v61, v69
	v_and_b32_e32 v79, 0xffff0000, v79
	v_add_f32_e32 v81, 1.0, v81
	v_div_scale_f32 v87, s[0:1], v81, v81, v82
	v_rcp_f32_e32 v92, v87
	v_mul_f32_e32 v62, v62, v70
	v_lshlrev_b32_e32 v85, 16, v80
	v_mul_f32_e32 v63, v63, v71
	v_fma_f32 v93, -v87, v92, 1.0
	v_fmac_f32_e32 v92, v93, v92
	v_div_scale_f32 v93, vcc, v82, v81, v82
	v_mul_f32_e32 v94, v93, v92
	v_fma_f32 v95, -v87, v94, v93
	v_fmac_f32_e32 v94, v95, v92
	v_fma_f32 v87, -v87, v94, v93
	v_div_fmas_f32 v87, v87, v92, v94
	v_div_fixup_f32 v81, v87, v81, v82
	v_mul_f32_e32 v60, v60, v81
	v_mul_f32_e32 v81, 0xbfb8aa3b, v83
	v_exp_f32_e32 v81, v81
	v_and_b32_e32 v80, 0xffff0000, v80
	v_mul_f32_e32 v52, v52, v68
	v_mul_f32_e32 v53, v53, v69
	v_add_f32_e32 v81, 1.0, v81
	v_div_scale_f32 v82, s[0:1], v81, v81, v83
	v_rcp_f32_e32 v87, v82
	v_mul_f32_e32 v54, v54, v70
	v_mul_f32_e32 v55, v55, v71
	v_mul_f32_e32 v48, v48, v64
	v_fma_f32 v92, -v82, v87, 1.0
	v_fmac_f32_e32 v87, v92, v87
	v_div_scale_f32 v92, vcc, v83, v81, v83
	v_mul_f32_e32 v93, v92, v87
	v_fma_f32 v94, -v82, v93, v92
	v_fmac_f32_e32 v93, v94, v87
	v_fma_f32 v82, -v82, v93, v92
	v_div_fmas_f32 v82, v82, v87, v93
	v_div_fixup_f32 v81, v82, v81, v83
	v_mul_f32_e32 v61, v61, v81
	v_mul_f32_e32 v81, 0xbfb8aa3b, v84
	v_exp_f32_e32 v81, v81
	v_mul_f32_e32 v44, v44, v68
	v_mul_f32_e32 v45, v45, v69
	v_mul_f32_e32 v46, v46, v70
	v_add_f32_e32 v81, 1.0, v81
	v_div_scale_f32 v82, s[0:1], v81, v81, v84
	v_rcp_f32_e32 v83, v82
	v_mul_f32_e32 v47, v47, v71
	v_mul_f32_e32 v40, v40, v64
	v_mul_f32_e32 v36, v36, v68
	v_fma_f32 v87, -v82, v83, 1.0
	v_fmac_f32_e32 v83, v87, v83
	v_div_scale_f32 v87, vcc, v84, v81, v84
	v_mul_f32_e32 v92, v87, v83
	v_fma_f32 v93, -v82, v92, v87
	v_fmac_f32_e32 v92, v93, v83
	v_fma_f32 v82, -v82, v92, v87
	v_div_fmas_f32 v82, v82, v83, v92
	v_div_fixup_f32 v81, v82, v81, v84
	v_mul_f32_e32 v62, v62, v81
	v_mul_f32_e32 v81, 0xbfb8aa3b, v79
	v_exp_f32_e32 v81, v81
	v_mul_f32_e32 v37, v37, v69
	v_mul_f32_e32 v38, v38, v70
	v_mul_f32_e32 v39, v39, v71
	v_add_f32_e32 v81, 1.0, v81
	v_div_scale_f32 v82, s[0:1], v81, v81, v79
	v_rcp_f32_e32 v83, v82
	v_mul_f32_e32 v32, v32, v64
	v_mul_f32_e32 v28, v28, v68
	v_mul_f32_e32 v29, v29, v69
	v_fma_f32 v84, -v82, v83, 1.0
	v_fmac_f32_e32 v83, v84, v83
	v_div_scale_f32 v84, vcc, v79, v81, v79
	v_mul_f32_e32 v87, v84, v83
	v_fma_f32 v92, -v82, v87, v84
	v_fmac_f32_e32 v87, v92, v83
	v_fma_f32 v82, -v82, v87, v84
	v_div_fmas_f32 v82, v82, v83, v87
	v_div_fixup_f32 v79, v82, v81, v79
	v_mul_f32_e32 v63, v63, v79
	v_mul_f32_e32 v79, 0xbfb8aa3b, v85
	v_exp_f32_e32 v79, v79
	v_mul_f32_e32 v30, v30, v70
	v_mul_f32_e32 v31, v31, v71
	v_mul_f32_e32 v24, v24, v64
	v_add_f32_e32 v79, 1.0, v79
	v_div_scale_f32 v81, s[0:1], v79, v79, v85
	v_rcp_f32_e32 v82, v81
	v_mul_f32_e32 v20, v20, v68
	v_mul_f32_e32 v21, v21, v69
	v_mul_f32_e32 v22, v22, v70
	v_fma_f32 v83, -v81, v82, 1.0
	v_fmac_f32_e32 v82, v83, v82
	v_div_scale_f32 v83, vcc, v85, v79, v85
	v_mul_f32_e32 v84, v83, v82
	v_fma_f32 v87, -v81, v84, v83
	v_fmac_f32_e32 v84, v87, v82
	v_fma_f32 v81, -v81, v84, v83
	v_div_fmas_f32 v81, v81, v82, v84
	v_div_fixup_f32 v79, v81, v79, v85
	v_mul_f32_e32 v79, v56, v79
	v_mul_f32_e32 v56, v57, v65
	v_mul_f32_e32 v57, 0xbfb8aa3b, v80
	v_exp_f32_e32 v57, v57
	v_mul_f32_e32 v23, v23, v71
	v_mul_f32_e32 v16, v16, v64
	v_mul_f32_e32 v12, v12, v68
	v_add_f32_e32 v57, 1.0, v57
	v_div_scale_f32 v81, s[0:1], v57, v57, v80
	v_rcp_f32_e32 v82, v81
	v_mul_f32_e32 v13, v13, v69
	v_mul_f32_e32 v14, v14, v70
	v_mul_f32_e32 v15, v15, v71
	v_fma_f32 v83, -v81, v82, 1.0
	v_fmac_f32_e32 v82, v83, v82
	v_div_scale_f32 v83, vcc, v80, v57, v80
	v_mul_f32_e32 v84, v83, v82
	v_fma_f32 v85, -v81, v84, v83
	v_fmac_f32_e32 v84, v85, v82
	v_fma_f32 v81, -v81, v84, v83
	v_div_fmas_f32 v81, v81, v82, v84
	v_div_fixup_f32 v57, v81, v57, v80
	v_mul_f32_e32 v80, v56, v57
	v_mul_f32_e32 v57, 0xbfb8aa3b, v86
	v_exp_f32_e32 v57, v57
	v_mul_f32_e32 v56, v58, v66
	v_mul_f32_e32 v8, v8, v64
	v_mul_f32_e32 v4, v4, v68
	v_add_f32_e32 v57, 1.0, v57
	v_div_scale_f32 v58, s[0:1], v57, v57, v86
	v_rcp_f32_e32 v81, v58
	v_mul_f32_e32 v5, v5, v69
	v_mul_f32_e32 v6, v6, v70
	v_mul_f32_e32 v7, v7, v71
	v_fma_f32 v82, -v58, v81, 1.0
	v_fmac_f32_e32 v81, v82, v81
	v_div_scale_f32 v82, vcc, v86, v57, v86
	v_mul_f32_e32 v83, v82, v81
	v_fma_f32 v84, -v58, v83, v82
	v_fmac_f32_e32 v83, v84, v81
	v_fma_f32 v58, -v58, v83, v82
	v_div_fmas_f32 v58, v58, v81, v83
	v_div_fixup_f32 v57, v58, v57, v86
	v_mul_f32_e32 v81, v56, v57
	v_mul_f32_e32 v57, 0xbfb8aa3b, v78
	v_exp_f32_e32 v57, v57
	v_mul_f32_e32 v56, v59, v67
	v_mul_f32_e32 v0, v0, v64
	v_add_f32_e32 v57, 1.0, v57
	v_div_scale_f32 v58, s[0:1], v57, v57, v78
	v_rcp_f32_e32 v59, v58
	s_nop 0
	v_fma_f32 v82, -v58, v59, 1.0
	v_fmac_f32_e32 v59, v82, v59
	v_div_scale_f32 v82, vcc, v78, v57, v78
	v_mul_f32_e32 v83, v82, v59
	v_fma_f32 v84, -v58, v83, v82
	v_fmac_f32_e32 v83, v84, v59
	v_fma_f32 v58, -v58, v83, v82
	v_div_fmas_f32 v58, v58, v59, v83
	v_div_fixup_f32 v57, v58, v57, v78
	v_mul_f32_e32 v59, v56, v57
	v_cvt_pk_bf16_f32 v56, v60, v61
	v_cvt_pk_bf16_f32 v57, v62, v63
	v_cvt_pk_bf16_f32 v58, v79, v80
	v_cvt_pk_bf16_f32 v59, v81, v59
	global_store_dwordx4 v[128:129], v[56:59], off offset:2304
	s_add_u32 s2, s14, 0x48000
	s_addc_u32 s3, s15, 0
	global_load_dwordx4 v[206:209], v214, s[2:3] offset:3328
	s_waitcnt vmcnt(4)
; __device__ __forceinline__ unsigned cvt_pk_bf16(float lo, float hi) { unsigned r; asm volatile("v_cvt_pk_bf16_f32 %0, %1, %2" : "=v"(r) : "v"(lo), "v"(hi)); return r; }
; __device__ __forceinline__ float sigmoidf_(float v) { return 1.f / (1.f + __expf(-v)); }
; __device__ __forceinline__ float siluf_(float v) { return v / (1.f + __expf(-v)); }
;     __device__ __forceinline__ void operator()(const f32x4 (&acc)[2][2][4][2], const Unit& u, int wr, int wc, int fr, int fq) const {
;     ...
;             for (int ai = 0; ai < 2; ++ai) {
; #pragma unroll
;                 for (int m = 0; m < 4; ++m) {
;                     const size_t row = (size_t)(row0 + ai * HALF + m * 16);
;                     const f32x4 v0 = acc[ai][bj][m][0], v1 = acc[ai][bj][m][1];
;                     float a[8] = {v0[0], v0[1], v0[2], v0[3], v1[0], v1[1], v1[2], v1[3]}, g[8], o[8];
;                     unpack8(*(const u32x4*)(R + row * RLD + (MODE == 0 ? 2560 : 1536) + col0), g);
;                     if (MODE == 0) { float y[8]; unpack8(*(const u32x4*)(YG + row * 512 + col0), y);
; #pragma unroll
;                         for (int e = 0; e < 8; ++e) o[e] = y[e] * sigmoidf_(a[e] + bb[e]) * siluf_(g[e]); }
;                     else {
; #pragma unroll
;                         for (int e = 0; e < 8; ++e) o[e] = a[e] * bb[e] * siluf_(g[e]); }
;                     u32x4 w; w.x = cvt_pk_bf16(o[0], o[1]); w.y = cvt_pk_bf16(o[2], o[3]); w.z = cvt_pk_bf16(o[4], o[5]); w.w = cvt_pk_bf16(o[6], o[7]);
;                     *(u32x4*)(Y + row * DM + (MODE == 0 ? 1536 : 1024) + col0) = w;
;                 }
	s_nop 1
	v_mov_b32_e32 v56, v168
	v_mov_b32_e32 v57, v169
	v_mov_b32_e32 v58, v170
	v_mov_b32_e32 v59, v171
	v_lshlrev_b32_e32 v60, 16, v56
	v_and_b32_e32 v61, 0xffff0000, v56
	v_lshlrev_b32_e32 v78, 16, v59
	v_and_b32_e32 v56, 0xffff0000, v59
	v_mul_f32_e32 v59, 0xbfb8aa3b, v60
	v_exp_f32_e32 v59, v59
	v_lshlrev_b32_e32 v62, 16, v57
	v_and_b32_e32 v57, 0xffff0000, v57
	v_lshlrev_b32_e32 v63, 16, v58
	v_add_f32_e32 v59, 1.0, v59
	v_div_scale_f32 v79, s[0:1], v59, v59, v60
	v_rcp_f32_e32 v80, v79
	v_and_b32_e32 v58, 0xffff0000, v58
	v_fma_f32 v81, -v79, v80, 1.0
	v_fmac_f32_e32 v80, v81, v80
	v_div_scale_f32 v81, vcc, v60, v59, v60
	v_mul_f32_e32 v82, v81, v80
	v_fma_f32 v83, -v79, v82, v81
	v_fmac_f32_e32 v82, v83, v80
	v_fma_f32 v79, -v79, v82, v81
	v_div_fmas_f32 v79, v79, v80, v82
	v_div_fixup_f32 v59, v79, v59, v60
	v_mul_f32_e32 v52, v52, v59
	v_mul_f32_e32 v59, 0xbfb8aa3b, v61
	v_exp_f32_e32 v59, v59
	s_nop 0
	v_add_f32_e32 v59, 1.0, v59
	v_div_scale_f32 v60, s[0:1], v59, v59, v61
	v_rcp_f32_e32 v79, v60
	s_nop 0
	v_fma_f32 v80, -v60, v79, 1.0
	v_fmac_f32_e32 v79, v80, v79
	v_div_scale_f32 v80, vcc, v61, v59, v61
	v_mul_f32_e32 v81, v80, v79
	v_fma_f32 v82, -v60, v81, v80
	v_fmac_f32_e32 v81, v82, v79
	v_fma_f32 v60, -v60, v81, v80
	v_div_fmas_f32 v60, v60, v79, v81
	v_div_fixup_f32 v59, v60, v59, v61
	v_mul_f32_e32 v53, v53, v59
	v_mul_f32_e32 v59, 0xbfb8aa3b, v62
	v_exp_f32_e32 v59, v59
	s_nop 0
	v_add_f32_e32 v59, 1.0, v59
	v_div_scale_f32 v60, s[0:1], v59, v59, v62
	v_rcp_f32_e32 v61, v60
	s_nop 0
	v_fma_f32 v79, -v60, v61, 1.0
	v_fmac_f32_e32 v61, v79, v61
	v_div_scale_f32 v79, vcc, v62, v59, v62
	v_mul_f32_e32 v80, v79, v61
	v_fma_f32 v81, -v60, v80, v79
	v_fmac_f32_e32 v80, v81, v61
	v_fma_f32 v60, -v60, v80, v79
	v_div_fmas_f32 v60, v60, v61, v80
	v_div_fixup_f32 v59, v60, v59, v62
	v_mul_f32_e32 v54, v54, v59
	v_mul_f32_e32 v59, 0xbfb8aa3b, v57
	v_exp_f32_e32 v59, v59
	s_nop 0
	v_add_f32_e32 v59, 1.0, v59
	v_div_scale_f32 v60, s[0:1], v59, v59, v57
	v_rcp_f32_e32 v61, v60
	s_nop 0
	v_fma_f32 v62, -v60, v61, 1.0
	v_fmac_f32_e32 v61, v62, v61
	v_div_scale_f32 v62, vcc, v57, v59, v57
	v_mul_f32_e32 v79, v62, v61
	v_fma_f32 v80, -v60, v79, v62
	v_fmac_f32_e32 v79, v80, v61
	v_fma_f32 v60, -v60, v79, v62
	v_div_fmas_f32 v60, v60, v61, v79
	v_div_fixup_f32 v57, v60, v59, v57
	v_mul_f32_e32 v55, v55, v57
	v_mul_f32_e32 v57, 0xbfb8aa3b, v63
	v_exp_f32_e32 v57, v57
	s_nop 0
	v_add_f32_e32 v57, 1.0, v57
	v_div_scale_f32 v59, s[0:1], v57, v57, v63
	v_rcp_f32_e32 v60, v59
	s_nop 0
	v_fma_f32 v61, -v59, v60, 1.0
	v_fmac_f32_e32 v60, v61, v60
	v_div_scale_f32 v61, vcc, v63, v57, v63
	v_mul_f32_e32 v62, v61, v60
	v_fma_f32 v79, -v59, v62, v61
	v_fmac_f32_e32 v62, v79, v60
	v_fma_f32 v59, -v59, v62, v61
	v_div_fmas_f32 v59, v59, v60, v62
	v_div_fixup_f32 v57, v59, v57, v63
	v_mul_f32_e32 v57, v48, v57
	v_mul_f32_e32 v48, v49, v65
	v_mul_f32_e32 v49, 0xbfb8aa3b, v58
	v_exp_f32_e32 v49, v49
	s_nop 0
	v_add_f32_e32 v49, 1.0, v49
	v_div_scale_f32 v59, s[0:1], v49, v49, v58
	v_rcp_f32_e32 v60, v59
	s_nop 0
	v_fma_f32 v61, -v59, v60, 1.0
	v_fmac_f32_e32 v60, v61, v60
	v_div_scale_f32 v61, vcc, v58, v49, v58
	v_mul_f32_e32 v62, v61, v60
	v_fma_f32 v63, -v59, v62, v61
	v_fmac_f32_e32 v62, v63, v60
	v_fma_f32 v59, -v59, v62, v61
	v_div_fmas_f32 v59, v59, v60, v62
	v_div_fixup_f32 v49, v59, v49, v58
	v_mul_f32_e32 v58, v48, v49
	v_mul_f32_e32 v49, 0xbfb8aa3b, v78
	v_exp_f32_e32 v49, v49
	v_mul_f32_e32 v48, v50, v66
	v_add_f32_e32 v49, 1.0, v49
	v_div_scale_f32 v50, s[0:1], v49, v49, v78
	v_rcp_f32_e32 v59, v50
	s_nop 0
	v_fma_f32 v60, -v50, v59, 1.0
	v_fmac_f32_e32 v59, v60, v59
	v_div_scale_f32 v60, vcc, v78, v49, v78
	v_mul_f32_e32 v61, v60, v59
	v_fma_f32 v62, -v50, v61, v60
	v_fmac_f32_e32 v61, v62, v59
	v_fma_f32 v50, -v50, v61, v60
	v_div_fmas_f32 v50, v50, v59, v61
	v_div_fixup_f32 v49, v50, v49, v78
	v_mul_f32_e32 v59, v48, v49
	v_mul_f32_e32 v49, 0xbfb8aa3b, v56
	v_exp_f32_e32 v49, v49
	v_mul_f32_e32 v48, v51, v67
	v_add_f32_e32 v49, 1.0, v49
	v_div_scale_f32 v50, s[0:1], v49, v49, v56
	v_rcp_f32_e32 v51, v50
	s_nop 0
	v_fma_f32 v60, -v50, v51, 1.0
	v_fmac_f32_e32 v51, v60, v51
	v_div_scale_f32 v60, vcc, v56, v49, v56
	v_mul_f32_e32 v61, v60, v51
	v_fma_f32 v62, -v50, v61, v60
	v_fmac_f32_e32 v61, v62, v51
	v_fma_f32 v50, -v50, v61, v60
	v_div_fmas_f32 v50, v50, v51, v61
	v_div_fixup_f32 v49, v50, v49, v56
	v_mul_f32_e32 v51, v48, v49
	v_cvt_pk_bf16_f32 v48, v52, v53
	v_cvt_pk_bf16_f32 v49, v54, v55
	v_cvt_pk_bf16_f32 v50, v57, v58
	v_cvt_pk_bf16_f32 v51, v59, v51
	global_store_dwordx4 v[120:121], v[48:51], off offset:2304
	s_add_u32 s2, s14, 0xc0000
	s_addc_u32 s3, s15, 0
	global_load_dwordx4 v[168:171], v214, s[2:3] offset:3328
	s_waitcnt vmcnt(4)
; __device__ __forceinline__ unsigned cvt_pk_bf16(float lo, float hi) { unsigned r; asm volatile("v_cvt_pk_bf16_f32 %0, %1, %2" : "=v"(r) : "v"(lo), "v"(hi)); return r; }
; __device__ __forceinline__ float sigmoidf_(float v) { return 1.f / (1.f + __expf(-v)); }
; __device__ __forceinline__ float siluf_(float v) { return v / (1.f + __expf(-v)); }
;     __device__ __forceinline__ void operator()(const f32x4 (&acc)[2][2][4][2], const Unit& u, int wr, int wc, int fr, int fq) const {
;     ...
;             for (int ai = 0; ai < 2; ++ai) {
; #pragma unroll
;                 for (int m = 0; m < 4; ++m) {
;                     const size_t row = (size_t)(row0 + ai * HALF + m * 16);
;                     const f32x4 v0 = acc[ai][bj][m][0], v1 = acc[ai][bj][m][1];
;                     float a[8] = {v0[0], v0[1], v0[2], v0[3], v1[0], v1[1], v1[2], v1[3]}, g[8], o[8];
;                     unpack8(*(const u32x4*)(R + row * RLD + (MODE == 0 ? 2560 : 1536) + col0), g);
;                     if (MODE == 0) { float y[8]; unpack8(*(const u32x4*)(YG + row * 512 + col0), y);
; #pragma unroll
;                         for (int e = 0; e < 8; ++e) o[e] = y[e] * sigmoidf_(a[e] + bb[e]) * siluf_(g[e]); }
;                     else {
; #pragma unroll
;                         for (int e = 0; e < 8; ++e) o[e] = a[e] * bb[e] * siluf_(g[e]); }
;                     u32x4 w; w.x = cvt_pk_bf16(o[0], o[1]); w.y = cvt_pk_bf16(o[2], o[3]); w.z = cvt_pk_bf16(o[4], o[5]); w.w = cvt_pk_bf16(o[6], o[7]);
;                     *(u32x4*)(Y + row * DM + (MODE == 0 ? 1536 : 1024) + col0) = w;
;                 }
	s_nop 1
	v_mov_b32_e32 v48, v188
	v_mov_b32_e32 v49, v189
	v_mov_b32_e32 v50, v190
	v_mov_b32_e32 v51, v191
	v_lshlrev_b32_e32 v52, 16, v48
	v_and_b32_e32 v53, 0xffff0000, v48
	v_lshlrev_b32_e32 v56, 16, v51
	v_and_b32_e32 v48, 0xffff0000, v51
	v_mul_f32_e32 v51, 0xbfb8aa3b, v52
	v_exp_f32_e32 v51, v51
	v_lshlrev_b32_e32 v54, 16, v49
	v_and_b32_e32 v49, 0xffff0000, v49
	v_lshlrev_b32_e32 v55, 16, v50
	v_add_f32_e32 v51, 1.0, v51
	v_div_scale_f32 v57, s[0:1], v51, v51, v52
	v_rcp_f32_e32 v58, v57
	v_and_b32_e32 v50, 0xffff0000, v50
	v_fma_f32 v59, -v57, v58, 1.0
	v_fmac_f32_e32 v58, v59, v58
	v_div_scale_f32 v59, vcc, v52, v51, v52
	v_mul_f32_e32 v60, v59, v58
	v_fma_f32 v61, -v57, v60, v59
	v_fmac_f32_e32 v60, v61, v58
	v_fma_f32 v57, -v57, v60, v59
	v_div_fmas_f32 v57, v57, v58, v60
	v_div_fixup_f32 v51, v57, v51, v52
	v_mul_f32_e32 v44, v44, v51
	v_mul_f32_e32 v51, 0xbfb8aa3b, v53
	v_exp_f32_e32 v51, v51
	s_nop 0
	v_add_f32_e32 v51, 1.0, v51
	v_div_scale_f32 v52, s[0:1], v51, v51, v53
	v_rcp_f32_e32 v57, v52
	s_nop 0
	v_fma_f32 v58, -v52, v57, 1.0
	v_fmac_f32_e32 v57, v58, v57
	v_div_scale_f32 v58, vcc, v53, v51, v53
	v_mul_f32_e32 v59, v58, v57
	v_fma_f32 v60, -v52, v59, v58
	v_fmac_f32_e32 v59, v60, v57
	v_fma_f32 v52, -v52, v59, v58
	v_div_fmas_f32 v52, v52, v57, v59
	v_div_fixup_f32 v51, v52, v51, v53
	v_mul_f32_e32 v45, v45, v51
	v_mul_f32_e32 v51, 0xbfb8aa3b, v54
	v_exp_f32_e32 v51, v51
	s_nop 0
	v_add_f32_e32 v51, 1.0, v51
	v_div_scale_f32 v52, s[0:1], v51, v51, v54
	v_rcp_f32_e32 v53, v52
	s_nop 0
	v_fma_f32 v57, -v52, v53, 1.0
	v_fmac_f32_e32 v53, v57, v53
	v_div_scale_f32 v57, vcc, v54, v51, v54
	v_mul_f32_e32 v58, v57, v53
	v_fma_f32 v59, -v52, v58, v57
	v_fmac_f32_e32 v58, v59, v53
	v_fma_f32 v52, -v52, v58, v57
	v_div_fmas_f32 v52, v52, v53, v58
	v_div_fixup_f32 v51, v52, v51, v54
	v_mul_f32_e32 v46, v46, v51
	v_mul_f32_e32 v51, 0xbfb8aa3b, v49
	v_exp_f32_e32 v51, v51
	s_nop 0
	v_add_f32_e32 v51, 1.0, v51
	v_div_scale_f32 v52, s[0:1], v51, v51, v49
	v_rcp_f32_e32 v53, v52
	s_nop 0
	v_fma_f32 v54, -v52, v53, 1.0
	v_fmac_f32_e32 v53, v54, v53
	v_div_scale_f32 v54, vcc, v49, v51, v49
	v_mul_f32_e32 v57, v54, v53
	v_fma_f32 v58, -v52, v57, v54
	v_fmac_f32_e32 v57, v58, v53
	v_fma_f32 v52, -v52, v57, v54
	v_div_fmas_f32 v52, v52, v53, v57
	v_div_fixup_f32 v49, v52, v51, v49
	v_mul_f32_e32 v47, v47, v49
	v_mul_f32_e32 v49, 0xbfb8aa3b, v55
	v_exp_f32_e32 v49, v49
	s_nop 0
	v_add_f32_e32 v49, 1.0, v49
	v_div_scale_f32 v51, s[0:1], v49, v49, v55
	v_rcp_f32_e32 v52, v51
	s_nop 0
	v_fma_f32 v53, -v51, v52, 1.0
	v_fmac_f32_e32 v52, v53, v52
	v_div_scale_f32 v53, vcc, v55, v49, v55
	v_mul_f32_e32 v54, v53, v52
	v_fma_f32 v57, -v51, v54, v53
	v_fmac_f32_e32 v54, v57, v52
	v_fma_f32 v51, -v51, v54, v53
	v_div_fmas_f32 v51, v51, v52, v54
	v_div_fixup_f32 v49, v51, v49, v55
	v_mul_f32_e32 v49, v40, v49
	v_mul_f32_e32 v40, v41, v65
	v_mul_f32_e32 v41, 0xbfb8aa3b, v50
	v_exp_f32_e32 v41, v41
	s_nop 0
	v_add_f32_e32 v41, 1.0, v41
	v_div_scale_f32 v51, s[0:1], v41, v41, v50
	v_rcp_f32_e32 v52, v51
	s_nop 0
	v_fma_f32 v53, -v51, v52, 1.0
	v_fmac_f32_e32 v52, v53, v52
	v_div_scale_f32 v53, vcc, v50, v41, v50
	v_mul_f32_e32 v54, v53, v52
	v_fma_f32 v55, -v51, v54, v53
	v_fmac_f32_e32 v54, v55, v52
	v_fma_f32 v51, -v51, v54, v53
	v_div_fmas_f32 v51, v51, v52, v54
	v_div_fixup_f32 v41, v51, v41, v50
	v_mul_f32_e32 v50, v40, v41
	v_mul_f32_e32 v41, 0xbfb8aa3b, v56
	v_exp_f32_e32 v41, v41
	v_mul_f32_e32 v40, v42, v66
	v_add_f32_e32 v41, 1.0, v41
	v_div_scale_f32 v42, s[0:1], v41, v41, v56
	v_rcp_f32_e32 v51, v42
	s_nop 0
	v_fma_f32 v52, -v42, v51, 1.0
	v_fmac_f32_e32 v51, v52, v51
	v_div_scale_f32 v52, vcc, v56, v41, v56
	v_mul_f32_e32 v53, v52, v51
	v_fma_f32 v54, -v42, v53, v52
	v_fmac_f32_e32 v53, v54, v51
	v_fma_f32 v42, -v42, v53, v52
	v_div_fmas_f32 v42, v42, v51, v53
	v_div_fixup_f32 v41, v42, v41, v56
	v_mul_f32_e32 v51, v40, v41
	v_mul_f32_e32 v41, 0xbfb8aa3b, v48
	v_exp_f32_e32 v41, v41
	v_mul_f32_e32 v40, v43, v67
	v_add_f32_e32 v41, 1.0, v41
	v_div_scale_f32 v42, s[0:1], v41, v41, v48
	v_rcp_f32_e32 v43, v42
	s_nop 0
	v_fma_f32 v52, -v42, v43, 1.0
	v_fmac_f32_e32 v43, v52, v43
	v_div_scale_f32 v52, vcc, v48, v41, v48
	v_mul_f32_e32 v53, v52, v43
	v_fma_f32 v54, -v42, v53, v52
	v_fmac_f32_e32 v53, v54, v43
	v_fma_f32 v42, -v42, v53, v52
	v_div_fmas_f32 v42, v42, v43, v53
	v_div_fixup_f32 v41, v42, v41, v48
	v_mul_f32_e32 v43, v40, v41
	v_cvt_pk_bf16_f32 v40, v44, v45
	v_cvt_pk_bf16_f32 v41, v46, v47
	v_cvt_pk_bf16_f32 v42, v49, v50
	v_cvt_pk_bf16_f32 v43, v51, v43
	global_store_dwordx4 v[112:113], v[40:43], off offset:2304
	s_add_u32 s2, s14, 0xd8000
	s_addc_u32 s3, s15, 0
	global_load_dwordx4 v[188:191], v214, s[2:3] offset:3328
	s_waitcnt vmcnt(4)
; __device__ __forceinline__ unsigned cvt_pk_bf16(float lo, float hi) { unsigned r; asm volatile("v_cvt_pk_bf16_f32 %0, %1, %2" : "=v"(r) : "v"(lo), "v"(hi)); return r; }
; __device__ __forceinline__ float sigmoidf_(float v) { return 1.f / (1.f + __expf(-v)); }
; __device__ __forceinline__ float siluf_(float v) { return v / (1.f + __expf(-v)); }
;     __device__ __forceinline__ void operator()(const f32x4 (&acc)[2][2][4][2], const Unit& u, int wr, int wc, int fr, int fq) const {
;     ...
;             for (int ai = 0; ai < 2; ++ai) {
; #pragma unroll
;                 for (int m = 0; m < 4; ++m) {
;                     const size_t row = (size_t)(row0 + ai * HALF + m * 16);
;                     const f32x4 v0 = acc[ai][bj][m][0], v1 = acc[ai][bj][m][1];
;                     float a[8] = {v0[0], v0[1], v0[2], v0[3], v1[0], v1[1], v1[2], v1[3]}, g[8], o[8];
;                     unpack8(*(const u32x4*)(R + row * RLD + (MODE == 0 ? 2560 : 1536) + col0), g);
;                     if (MODE == 0) { float y[8]; unpack8(*(const u32x4*)(YG + row * 512 + col0), y);
; #pragma unroll
;                         for (int e = 0; e < 8; ++e) o[e] = y[e] * sigmoidf_(a[e] + bb[e]) * siluf_(g[e]); }
;                     else {
; #pragma unroll
;                         for (int e = 0; e < 8; ++e) o[e] = a[e] * bb[e] * siluf_(g[e]); }
;                     u32x4 w; w.x = cvt_pk_bf16(o[0], o[1]); w.y = cvt_pk_bf16(o[2], o[3]); w.z = cvt_pk_bf16(o[4], o[5]); w.w = cvt_pk_bf16(o[6], o[7]);
;                     *(u32x4*)(Y + row * DM + (MODE == 0 ? 1536 : 1024) + col0) = w;
;                 }
	s_nop 1
	v_mov_b32_e32 v40, v206
	v_mov_b32_e32 v41, v207
	v_mov_b32_e32 v42, v208
	v_mov_b32_e32 v43, v209
	v_lshlrev_b32_e32 v44, 16, v40
	v_and_b32_e32 v45, 0xffff0000, v40
	v_lshlrev_b32_e32 v48, 16, v43
	v_and_b32_e32 v40, 0xffff0000, v43
	v_mul_f32_e32 v43, 0xbfb8aa3b, v44
	v_exp_f32_e32 v43, v43
	v_lshlrev_b32_e32 v46, 16, v41
	v_and_b32_e32 v41, 0xffff0000, v41
	v_lshlrev_b32_e32 v47, 16, v42
	v_add_f32_e32 v43, 1.0, v43
	v_div_scale_f32 v49, s[0:1], v43, v43, v44
	v_rcp_f32_e32 v50, v49
	v_and_b32_e32 v42, 0xffff0000, v42
	v_fma_f32 v51, -v49, v50, 1.0
	v_fmac_f32_e32 v50, v51, v50
	v_div_scale_f32 v51, vcc, v44, v43, v44
	v_mul_f32_e32 v52, v51, v50
	v_fma_f32 v53, -v49, v52, v51
	v_fmac_f32_e32 v52, v53, v50
	v_fma_f32 v49, -v49, v52, v51
	v_div_fmas_f32 v49, v49, v50, v52
	v_div_fixup_f32 v43, v49, v43, v44
	v_mul_f32_e32 v36, v36, v43
	v_mul_f32_e32 v43, 0xbfb8aa3b, v45
	v_exp_f32_e32 v43, v43
	s_nop 0
	v_add_f32_e32 v43, 1.0, v43
	v_div_scale_f32 v44, s[0:1], v43, v43, v45
	v_rcp_f32_e32 v49, v44
	s_nop 0
	v_fma_f32 v50, -v44, v49, 1.0
	v_fmac_f32_e32 v49, v50, v49
	v_div_scale_f32 v50, vcc, v45, v43, v45
	v_mul_f32_e32 v51, v50, v49
	v_fma_f32 v52, -v44, v51, v50
	v_fmac_f32_e32 v51, v52, v49
	v_fma_f32 v44, -v44, v51, v50
	v_div_fmas_f32 v44, v44, v49, v51
	v_div_fixup_f32 v43, v44, v43, v45
	v_mul_f32_e32 v37, v37, v43
	v_mul_f32_e32 v43, 0xbfb8aa3b, v46
	v_exp_f32_e32 v43, v43
	s_nop 0
	v_add_f32_e32 v43, 1.0, v43
	v_div_scale_f32 v44, s[0:1], v43, v43, v46
	v_rcp_f32_e32 v45, v44
	s_nop 0
	v_fma_f32 v49, -v44, v45, 1.0
	v_fmac_f32_e32 v45, v49, v45
	v_div_scale_f32 v49, vcc, v46, v43, v46
	v_mul_f32_e32 v50, v49, v45
	v_fma_f32 v51, -v44, v50, v49
	v_fmac_f32_e32 v50, v51, v45
	v_fma_f32 v44, -v44, v50, v49
	v_div_fmas_f32 v44, v44, v45, v50
	v_div_fixup_f32 v43, v44, v43, v46
	v_mul_f32_e32 v38, v38, v43
	v_mul_f32_e32 v43, 0xbfb8aa3b, v41
	v_exp_f32_e32 v43, v43
	s_nop 0
	v_add_f32_e32 v43, 1.0, v43
	v_div_scale_f32 v44, s[0:1], v43, v43, v41
	v_rcp_f32_e32 v45, v44
	s_nop 0
	v_fma_f32 v46, -v44, v45, 1.0
	v_fmac_f32_e32 v45, v46, v45
	v_div_scale_f32 v46, vcc, v41, v43, v41
	v_mul_f32_e32 v49, v46, v45
	v_fma_f32 v50, -v44, v49, v46
	v_fmac_f32_e32 v49, v50, v45
	v_fma_f32 v44, -v44, v49, v46
	v_div_fmas_f32 v44, v44, v45, v49
	v_div_fixup_f32 v41, v44, v43, v41
	v_mul_f32_e32 v39, v39, v41
	v_mul_f32_e32 v41, 0xbfb8aa3b, v47
	v_exp_f32_e32 v41, v41
	s_nop 0
	v_add_f32_e32 v41, 1.0, v41
	v_div_scale_f32 v43, s[0:1], v41, v41, v47
	v_rcp_f32_e32 v44, v43
	s_nop 0
	v_fma_f32 v45, -v43, v44, 1.0
	v_fmac_f32_e32 v44, v45, v44
	v_div_scale_f32 v45, vcc, v47, v41, v47
	v_mul_f32_e32 v46, v45, v44
	v_fma_f32 v49, -v43, v46, v45
	v_fmac_f32_e32 v46, v49, v44
	v_fma_f32 v43, -v43, v46, v45
	v_div_fmas_f32 v43, v43, v44, v46
	v_div_fixup_f32 v41, v43, v41, v47
	v_mul_f32_e32 v41, v32, v41
	v_mul_f32_e32 v32, v33, v65
	v_mul_f32_e32 v33, 0xbfb8aa3b, v42
	v_exp_f32_e32 v33, v33
	s_nop 0
	v_add_f32_e32 v33, 1.0, v33
	v_div_scale_f32 v43, s[0:1], v33, v33, v42
	v_rcp_f32_e32 v44, v43
	s_nop 0
	v_fma_f32 v45, -v43, v44, 1.0
	v_fmac_f32_e32 v44, v45, v44
	v_div_scale_f32 v45, vcc, v42, v33, v42
	v_mul_f32_e32 v46, v45, v44
	v_fma_f32 v47, -v43, v46, v45
	v_fmac_f32_e32 v46, v47, v44
	v_fma_f32 v43, -v43, v46, v45
	v_div_fmas_f32 v43, v43, v44, v46
	v_div_fixup_f32 v33, v43, v33, v42
	v_mul_f32_e32 v42, v32, v33
	v_mul_f32_e32 v33, 0xbfb8aa3b, v48
	v_exp_f32_e32 v33, v33
	v_mul_f32_e32 v32, v34, v66
	v_add_f32_e32 v33, 1.0, v33
	v_div_scale_f32 v34, s[0:1], v33, v33, v48
	v_rcp_f32_e32 v43, v34
	s_nop 0
	v_fma_f32 v44, -v34, v43, 1.0
	v_fmac_f32_e32 v43, v44, v43
	v_div_scale_f32 v44, vcc, v48, v33, v48
	v_mul_f32_e32 v45, v44, v43
	v_fma_f32 v46, -v34, v45, v44
	v_fmac_f32_e32 v45, v46, v43
	v_fma_f32 v34, -v34, v45, v44
	v_div_fmas_f32 v34, v34, v43, v45
	v_div_fixup_f32 v33, v34, v33, v48
	v_mul_f32_e32 v43, v32, v33
	v_mul_f32_e32 v33, 0xbfb8aa3b, v40
	v_exp_f32_e32 v33, v33
	v_mul_f32_e32 v32, v35, v67
	v_add_f32_e32 v33, 1.0, v33
	v_div_scale_f32 v34, s[0:1], v33, v33, v40
	v_rcp_f32_e32 v35, v34
	s_nop 0
	v_fma_f32 v44, -v34, v35, 1.0
	v_fmac_f32_e32 v35, v44, v35
	v_div_scale_f32 v44, vcc, v40, v33, v40
	v_mul_f32_e32 v45, v44, v35
	v_fma_f32 v46, -v34, v45, v44
	v_fmac_f32_e32 v45, v46, v35
	v_fma_f32 v34, -v34, v45, v44
	v_div_fmas_f32 v34, v34, v35, v45
	v_div_fixup_f32 v33, v34, v33, v40
	v_mul_f32_e32 v35, v32, v33
	v_cvt_pk_bf16_f32 v32, v36, v37
	v_cvt_pk_bf16_f32 v33, v38, v39
	v_cvt_pk_bf16_f32 v34, v41, v42
	v_cvt_pk_bf16_f32 v35, v43, v35
	global_store_dwordx4 v[104:105], v[32:35], off offset:2304
	s_add_u32 s2, s14, 0xf0000
	s_addc_u32 s3, s15, 0
	global_load_dwordx4 v[206:209], v214, s[2:3] offset:3328
	s_waitcnt vmcnt(4)
; __device__ __forceinline__ unsigned cvt_pk_bf16(float lo, float hi) { unsigned r; asm volatile("v_cvt_pk_bf16_f32 %0, %1, %2" : "=v"(r) : "v"(lo), "v"(hi)); return r; }
; __device__ __forceinline__ float sigmoidf_(float v) { return 1.f / (1.f + __expf(-v)); }
; __device__ __forceinline__ float siluf_(float v) { return v / (1.f + __expf(-v)); }
;     __device__ __forceinline__ void operator()(const f32x4 (&acc)[2][2][4][2], const Unit& u, int wr, int wc, int fr, int fq) const {
;     ...
;             for (int ai = 0; ai < 2; ++ai) {
; #pragma unroll
;                 for (int m = 0; m < 4; ++m) {
;                     const size_t row = (size_t)(row0 + ai * HALF + m * 16);
;                     const f32x4 v0 = acc[ai][bj][m][0], v1 = acc[ai][bj][m][1];
;                     float a[8] = {v0[0], v0[1], v0[2], v0[3], v1[0], v1[1], v1[2], v1[3]}, g[8], o[8];
;                     unpack8(*(const u32x4*)(R + row * RLD + (MODE == 0 ? 2560 : 1536) + col0), g);
;                     if (MODE == 0) { float y[8]; unpack8(*(const u32x4*)(YG + row * 512 + col0), y);
; #pragma unroll
;                         for (int e = 0; e < 8; ++e) o[e] = y[e] * sigmoidf_(a[e] + bb[e]) * siluf_(g[e]); }
;                     else {
; #pragma unroll
;                         for (int e = 0; e < 8; ++e) o[e] = a[e] * bb[e] * siluf_(g[e]); }
;                     u32x4 w; w.x = cvt_pk_bf16(o[0], o[1]); w.y = cvt_pk_bf16(o[2], o[3]); w.z = cvt_pk_bf16(o[4], o[5]); w.w = cvt_pk_bf16(o[6], o[7]);
;                     *(u32x4*)(Y + row * DM + (MODE == 0 ? 1536 : 1024) + col0) = w;
;                 }
	s_nop 1
	v_mov_b32_e32 v32, v168
	v_mov_b32_e32 v33, v169
	v_mov_b32_e32 v34, v170
	v_mov_b32_e32 v35, v171
	v_lshlrev_b32_e32 v36, 16, v32
	v_and_b32_e32 v37, 0xffff0000, v32
	v_lshlrev_b32_e32 v40, 16, v35
	v_and_b32_e32 v32, 0xffff0000, v35
	v_mul_f32_e32 v35, 0xbfb8aa3b, v36
	v_exp_f32_e32 v35, v35
	v_lshlrev_b32_e32 v38, 16, v33
	v_and_b32_e32 v33, 0xffff0000, v33
	v_lshlrev_b32_e32 v39, 16, v34
	v_add_f32_e32 v35, 1.0, v35
	v_div_scale_f32 v41, s[0:1], v35, v35, v36
	v_rcp_f32_e32 v42, v41
	v_and_b32_e32 v34, 0xffff0000, v34
	v_fma_f32 v43, -v41, v42, 1.0
	v_fmac_f32_e32 v42, v43, v42
	v_div_scale_f32 v43, vcc, v36, v35, v36
	v_mul_f32_e32 v44, v43, v42
	v_fma_f32 v45, -v41, v44, v43
	v_fmac_f32_e32 v44, v45, v42
	v_fma_f32 v41, -v41, v44, v43
	v_div_fmas_f32 v41, v41, v42, v44
	v_div_fixup_f32 v35, v41, v35, v36
	v_mul_f32_e32 v28, v28, v35
	v_mul_f32_e32 v35, 0xbfb8aa3b, v37
	v_exp_f32_e32 v35, v35
	s_nop 0
	v_add_f32_e32 v35, 1.0, v35
	v_div_scale_f32 v36, s[0:1], v35, v35, v37
	v_rcp_f32_e32 v41, v36
	s_nop 0
	v_fma_f32 v42, -v36, v41, 1.0
	v_fmac_f32_e32 v41, v42, v41
	v_div_scale_f32 v42, vcc, v37, v35, v37
	v_mul_f32_e32 v43, v42, v41
	v_fma_f32 v44, -v36, v43, v42
	v_fmac_f32_e32 v43, v44, v41
	v_fma_f32 v36, -v36, v43, v42
	v_div_fmas_f32 v36, v36, v41, v43
	v_div_fixup_f32 v35, v36, v35, v37
	v_mul_f32_e32 v29, v29, v35
	v_mul_f32_e32 v35, 0xbfb8aa3b, v38
	v_exp_f32_e32 v35, v35
	s_nop 0
	v_add_f32_e32 v35, 1.0, v35
	v_div_scale_f32 v36, s[0:1], v35, v35, v38
	v_rcp_f32_e32 v37, v36
	s_nop 0
	v_fma_f32 v41, -v36, v37, 1.0
	v_fmac_f32_e32 v37, v41, v37
	v_div_scale_f32 v41, vcc, v38, v35, v38
	v_mul_f32_e32 v42, v41, v37
	v_fma_f32 v43, -v36, v42, v41
	v_fmac_f32_e32 v42, v43, v37
	v_fma_f32 v36, -v36, v42, v41
	v_div_fmas_f32 v36, v36, v37, v42
	v_div_fixup_f32 v35, v36, v35, v38
	v_mul_f32_e32 v30, v30, v35
	v_mul_f32_e32 v35, 0xbfb8aa3b, v33
	v_exp_f32_e32 v35, v35
	s_nop 0
	v_add_f32_e32 v35, 1.0, v35
	v_div_scale_f32 v36, s[0:1], v35, v35, v33
	v_rcp_f32_e32 v37, v36
	s_nop 0
	v_fma_f32 v38, -v36, v37, 1.0
	v_fmac_f32_e32 v37, v38, v37
	v_div_scale_f32 v38, vcc, v33, v35, v33
	v_mul_f32_e32 v41, v38, v37
	v_fma_f32 v42, -v36, v41, v38
	v_fmac_f32_e32 v41, v42, v37
	v_fma_f32 v36, -v36, v41, v38
	v_div_fmas_f32 v36, v36, v37, v41
	v_div_fixup_f32 v33, v36, v35, v33
	v_mul_f32_e32 v31, v31, v33
	v_mul_f32_e32 v33, 0xbfb8aa3b, v39
	v_exp_f32_e32 v33, v33
	s_nop 0
	v_add_f32_e32 v33, 1.0, v33
	v_div_scale_f32 v35, s[0:1], v33, v33, v39
	v_rcp_f32_e32 v36, v35
	s_nop 0
	v_fma_f32 v37, -v35, v36, 1.0
	v_fmac_f32_e32 v36, v37, v36
	v_div_scale_f32 v37, vcc, v39, v33, v39
	v_mul_f32_e32 v38, v37, v36
	v_fma_f32 v41, -v35, v38, v37
	v_fmac_f32_e32 v38, v41, v36
	v_fma_f32 v35, -v35, v38, v37
	v_div_fmas_f32 v35, v35, v36, v38
	v_div_fixup_f32 v33, v35, v33, v39
	v_mul_f32_e32 v33, v24, v33
	v_mul_f32_e32 v24, v25, v65
	v_mul_f32_e32 v25, 0xbfb8aa3b, v34
	v_exp_f32_e32 v25, v25
	s_nop 0
	v_add_f32_e32 v25, 1.0, v25
	v_div_scale_f32 v35, s[0:1], v25, v25, v34
	v_rcp_f32_e32 v36, v35
	s_nop 0
	v_fma_f32 v37, -v35, v36, 1.0
	v_fmac_f32_e32 v36, v37, v36
	v_div_scale_f32 v37, vcc, v34, v25, v34
	v_mul_f32_e32 v38, v37, v36
	v_fma_f32 v39, -v35, v38, v37
	v_fmac_f32_e32 v38, v39, v36
	v_fma_f32 v35, -v35, v38, v37
	v_div_fmas_f32 v35, v35, v36, v38
	v_div_fixup_f32 v25, v35, v25, v34
	v_mul_f32_e32 v34, v24, v25
	v_mul_f32_e32 v25, 0xbfb8aa3b, v40
	v_exp_f32_e32 v25, v25
	v_mul_f32_e32 v24, v26, v66
	v_add_f32_e32 v25, 1.0, v25
	v_div_scale_f32 v26, s[0:1], v25, v25, v40
	v_rcp_f32_e32 v35, v26
	s_nop 0
	v_fma_f32 v36, -v26, v35, 1.0
	v_fmac_f32_e32 v35, v36, v35
	v_div_scale_f32 v36, vcc, v40, v25, v40
	v_mul_f32_e32 v37, v36, v35
	v_fma_f32 v38, -v26, v37, v36
	v_fmac_f32_e32 v37, v38, v35
	v_fma_f32 v26, -v26, v37, v36
	v_div_fmas_f32 v26, v26, v35, v37
	v_div_fixup_f32 v25, v26, v25, v40
	v_mul_f32_e32 v35, v24, v25
	v_mul_f32_e32 v25, 0xbfb8aa3b, v32
	v_exp_f32_e32 v25, v25
	v_mul_f32_e32 v24, v27, v67
	v_add_f32_e32 v25, 1.0, v25
	v_div_scale_f32 v26, s[0:1], v25, v25, v32
	v_rcp_f32_e32 v27, v26
	s_nop 0
	v_fma_f32 v36, -v26, v27, 1.0
	v_fmac_f32_e32 v27, v36, v27
	v_div_scale_f32 v36, vcc, v32, v25, v32
	v_mul_f32_e32 v37, v36, v27
	v_fma_f32 v38, -v26, v37, v36
	v_fmac_f32_e32 v37, v38, v27
	v_fma_f32 v26, -v26, v37, v36
	v_div_fmas_f32 v26, v26, v27, v37
	v_div_fixup_f32 v25, v26, v25, v32
	v_mul_f32_e32 v27, v24, v25
	v_cvt_pk_bf16_f32 v24, v28, v29
	v_cvt_pk_bf16_f32 v25, v30, v31
	v_cvt_pk_bf16_f32 v26, v33, v34
	v_cvt_pk_bf16_f32 v27, v35, v27
	global_store_dwordx4 v[96:97], v[24:27], off offset:2304
	s_add_u32 s2, s14, 0x108000
	s_addc_u32 s3, s15, 0
	global_load_dwordx4 v[168:171], v214, s[2:3] offset:3328
	s_waitcnt vmcnt(4)
; __device__ __forceinline__ unsigned cvt_pk_bf16(float lo, float hi) { unsigned r; asm volatile("v_cvt_pk_bf16_f32 %0, %1, %2" : "=v"(r) : "v"(lo), "v"(hi)); return r; }
; __device__ __forceinline__ float sigmoidf_(float v) { return 1.f / (1.f + __expf(-v)); }
; __device__ __forceinline__ float siluf_(float v) { return v / (1.f + __expf(-v)); }
;     __device__ __forceinline__ void operator()(const f32x4 (&acc)[2][2][4][2], const Unit& u, int wr, int wc, int fr, int fq) const {
;     ...
;             for (int ai = 0; ai < 2; ++ai) {
; #pragma unroll
;                 for (int m = 0; m < 4; ++m) {
;                     const size_t row = (size_t)(row0 + ai * HALF + m * 16);
;                     const f32x4 v0 = acc[ai][bj][m][0], v1 = acc[ai][bj][m][1];
;                     float a[8] = {v0[0], v0[1], v0[2], v0[3], v1[0], v1[1], v1[2], v1[3]}, g[8], o[8];
;                     unpack8(*(const u32x4*)(R + row * RLD + (MODE == 0 ? 2560 : 1536) + col0), g);
;                     if (MODE == 0) { float y[8]; unpack8(*(const u32x4*)(YG + row * 512 + col0), y);
; #pragma unroll
;                         for (int e = 0; e < 8; ++e) o[e] = y[e] * sigmoidf_(a[e] + bb[e]) * siluf_(g[e]); }
;                     else {
; #pragma unroll
;                         for (int e = 0; e < 8; ++e) o[e] = a[e] * bb[e] * siluf_(g[e]); }
;                     u32x4 w; w.x = cvt_pk_bf16(o[0], o[1]); w.y = cvt_pk_bf16(o[2], o[3]); w.z = cvt_pk_bf16(o[4], o[5]); w.w = cvt_pk_bf16(o[6], o[7]);
;                     *(u32x4*)(Y + row * DM + (MODE == 0 ? 1536 : 1024) + col0) = w;
;                 }
	s_nop 1
	v_mov_b32_e32 v24, v188
	v_mov_b32_e32 v25, v189
	v_mov_b32_e32 v26, v190
	v_mov_b32_e32 v27, v191
	v_lshlrev_b32_e32 v28, 16, v24
	v_and_b32_e32 v29, 0xffff0000, v24
	v_lshlrev_b32_e32 v32, 16, v27
	v_and_b32_e32 v24, 0xffff0000, v27
	v_mul_f32_e32 v27, 0xbfb8aa3b, v28
	v_exp_f32_e32 v27, v27
	v_lshlrev_b32_e32 v30, 16, v25
	v_and_b32_e32 v25, 0xffff0000, v25
	v_lshlrev_b32_e32 v31, 16, v26
	v_add_f32_e32 v27, 1.0, v27
	v_div_scale_f32 v33, s[0:1], v27, v27, v28
	v_rcp_f32_e32 v34, v33
	v_and_b32_e32 v26, 0xffff0000, v26
	v_fma_f32 v35, -v33, v34, 1.0
	v_fmac_f32_e32 v34, v35, v34
	v_div_scale_f32 v35, vcc, v28, v27, v28
	v_mul_f32_e32 v36, v35, v34
	v_fma_f32 v37, -v33, v36, v35
	v_fmac_f32_e32 v36, v37, v34
	v_fma_f32 v33, -v33, v36, v35
	v_div_fmas_f32 v33, v33, v34, v36
	v_div_fixup_f32 v27, v33, v27, v28
	v_mul_f32_e32 v20, v20, v27
	v_mul_f32_e32 v27, 0xbfb8aa3b, v29
	v_exp_f32_e32 v27, v27
	s_nop 0
	v_add_f32_e32 v27, 1.0, v27
	v_div_scale_f32 v28, s[0:1], v27, v27, v29
	v_rcp_f32_e32 v33, v28
	s_nop 0
	v_fma_f32 v34, -v28, v33, 1.0
	v_fmac_f32_e32 v33, v34, v33
	v_div_scale_f32 v34, vcc, v29, v27, v29
	v_mul_f32_e32 v35, v34, v33
	v_fma_f32 v36, -v28, v35, v34
	v_fmac_f32_e32 v35, v36, v33
	v_fma_f32 v28, -v28, v35, v34
	v_div_fmas_f32 v28, v28, v33, v35
	v_div_fixup_f32 v27, v28, v27, v29
	v_mul_f32_e32 v21, v21, v27
	v_mul_f32_e32 v27, 0xbfb8aa3b, v30
	v_exp_f32_e32 v27, v27
	s_nop 0
	v_add_f32_e32 v27, 1.0, v27
	v_div_scale_f32 v28, s[0:1], v27, v27, v30
	v_rcp_f32_e32 v29, v28
	s_nop 0
	v_fma_f32 v33, -v28, v29, 1.0
	v_fmac_f32_e32 v29, v33, v29
	v_div_scale_f32 v33, vcc, v30, v27, v30
	v_mul_f32_e32 v34, v33, v29
	v_fma_f32 v35, -v28, v34, v33
	v_fmac_f32_e32 v34, v35, v29
	v_fma_f32 v28, -v28, v34, v33
	v_div_fmas_f32 v28, v28, v29, v34
	v_div_fixup_f32 v27, v28, v27, v30
	v_mul_f32_e32 v22, v22, v27
	v_mul_f32_e32 v27, 0xbfb8aa3b, v25
	v_exp_f32_e32 v27, v27
	s_nop 0
	v_add_f32_e32 v27, 1.0, v27
	v_div_scale_f32 v28, s[0:1], v27, v27, v25
	v_rcp_f32_e32 v29, v28
	s_nop 0
	v_fma_f32 v30, -v28, v29, 1.0
	v_fmac_f32_e32 v29, v30, v29
	v_div_scale_f32 v30, vcc, v25, v27, v25
	v_mul_f32_e32 v33, v30, v29
	v_fma_f32 v34, -v28, v33, v30
	v_fmac_f32_e32 v33, v34, v29
	v_fma_f32 v28, -v28, v33, v30
	v_div_fmas_f32 v28, v28, v29, v33
	v_div_fixup_f32 v25, v28, v27, v25
	v_mul_f32_e32 v23, v23, v25
	v_mul_f32_e32 v25, 0xbfb8aa3b, v31
	v_exp_f32_e32 v25, v25
	s_nop 0
	v_add_f32_e32 v25, 1.0, v25
	v_div_scale_f32 v27, s[0:1], v25, v25, v31
	v_rcp_f32_e32 v28, v27
	s_nop 0
	v_fma_f32 v29, -v27, v28, 1.0
	v_fmac_f32_e32 v28, v29, v28
	v_div_scale_f32 v29, vcc, v31, v25, v31
	v_mul_f32_e32 v30, v29, v28
	v_fma_f32 v33, -v27, v30, v29
	v_fmac_f32_e32 v30, v33, v28
	v_fma_f32 v27, -v27, v30, v29
	v_div_fmas_f32 v27, v27, v28, v30
	v_div_fixup_f32 v25, v27, v25, v31
	v_mul_f32_e32 v25, v16, v25
	v_mul_f32_e32 v16, v17, v65
	v_mul_f32_e32 v17, 0xbfb8aa3b, v26
	v_exp_f32_e32 v17, v17
	s_nop 0
	v_add_f32_e32 v17, 1.0, v17
	v_div_scale_f32 v27, s[0:1], v17, v17, v26
	v_rcp_f32_e32 v28, v27
	s_nop 0
	v_fma_f32 v29, -v27, v28, 1.0
	v_fmac_f32_e32 v28, v29, v28
	v_div_scale_f32 v29, vcc, v26, v17, v26
	v_mul_f32_e32 v30, v29, v28
	v_fma_f32 v31, -v27, v30, v29
	v_fmac_f32_e32 v30, v31, v28
	v_fma_f32 v27, -v27, v30, v29
	v_div_fmas_f32 v27, v27, v28, v30
	v_div_fixup_f32 v17, v27, v17, v26
	v_mul_f32_e32 v26, v16, v17
	v_mul_f32_e32 v17, 0xbfb8aa3b, v32
	v_exp_f32_e32 v17, v17
	v_mul_f32_e32 v16, v18, v66
	v_add_f32_e32 v17, 1.0, v17
	v_div_scale_f32 v18, s[0:1], v17, v17, v32
	v_rcp_f32_e32 v27, v18
	s_nop 0
	v_fma_f32 v28, -v18, v27, 1.0
	v_fmac_f32_e32 v27, v28, v27
	v_div_scale_f32 v28, vcc, v32, v17, v32
	v_mul_f32_e32 v29, v28, v27
	v_fma_f32 v30, -v18, v29, v28
	v_fmac_f32_e32 v29, v30, v27
	v_fma_f32 v18, -v18, v29, v28
	v_div_fmas_f32 v18, v18, v27, v29
	v_div_fixup_f32 v17, v18, v17, v32
	v_mul_f32_e32 v27, v16, v17
	v_mul_f32_e32 v17, 0xbfb8aa3b, v24
	v_exp_f32_e32 v17, v17
	v_mul_f32_e32 v16, v19, v67
	v_add_f32_e32 v17, 1.0, v17
	v_div_scale_f32 v18, s[0:1], v17, v17, v24
	v_rcp_f32_e32 v19, v18
	s_nop 0
	v_fma_f32 v28, -v18, v19, 1.0
	v_fmac_f32_e32 v19, v28, v19
	v_div_scale_f32 v28, vcc, v24, v17, v24
	v_mul_f32_e32 v29, v28, v19
	v_fma_f32 v30, -v18, v29, v28
	v_fmac_f32_e32 v29, v30, v19
	v_fma_f32 v18, -v18, v29, v28
	v_div_fmas_f32 v18, v18, v19, v29
	v_div_fixup_f32 v17, v18, v17, v24
	v_mul_f32_e32 v19, v16, v17
	v_cvt_pk_bf16_f32 v16, v20, v21
	v_cvt_pk_bf16_f32 v17, v22, v23
	v_cvt_pk_bf16_f32 v18, v25, v26
	v_cvt_pk_bf16_f32 v19, v27, v19
	global_store_dwordx4 v[88:89], v[16:19], off offset:2304
	s_waitcnt vmcnt(3)
; __device__ __forceinline__ unsigned cvt_pk_bf16(float lo, float hi) { unsigned r; asm volatile("v_cvt_pk_bf16_f32 %0, %1, %2" : "=v"(r) : "v"(lo), "v"(hi)); return r; }
; __device__ __forceinline__ float sigmoidf_(float v) { return 1.f / (1.f + __expf(-v)); }
; __device__ __forceinline__ float siluf_(float v) { return v / (1.f + __expf(-v)); }
;     __device__ __forceinline__ void operator()(const f32x4 (&acc)[2][2][4][2], const Unit& u, int wr, int wc, int fr, int fq) const {
;     ...
;             for (int ai = 0; ai < 2; ++ai) {
; #pragma unroll
;                 for (int m = 0; m < 4; ++m) {
;                     const size_t row = (size_t)(row0 + ai * HALF + m * 16);
;                     const f32x4 v0 = acc[ai][bj][m][0], v1 = acc[ai][bj][m][1];
;                     float a[8] = {v0[0], v0[1], v0[2], v0[3], v1[0], v1[1], v1[2], v1[3]}, g[8], o[8];
;                     unpack8(*(const u32x4*)(R + row * RLD + (MODE == 0 ? 2560 : 1536) + col0), g);
;                     if (MODE == 0) { float y[8]; unpack8(*(const u32x4*)(YG + row * 512 + col0), y);
; #pragma unroll
;                         for (int e = 0; e < 8; ++e) o[e] = y[e] * sigmoidf_(a[e] + bb[e]) * siluf_(g[e]); }
;                     else {
; #pragma unroll
;                         for (int e = 0; e < 8; ++e) o[e] = a[e] * bb[e] * siluf_(g[e]); }
;                     u32x4 w; w.x = cvt_pk_bf16(o[0], o[1]); w.y = cvt_pk_bf16(o[2], o[3]); w.z = cvt_pk_bf16(o[4], o[5]); w.w = cvt_pk_bf16(o[6], o[7]);
;                     *(u32x4*)(Y + row * DM + (MODE == 0 ? 1536 : 1024) + col0) = w;
;                 }
	s_nop 1
	v_mov_b32_e32 v16, v206
	v_mov_b32_e32 v17, v207
	v_mov_b32_e32 v18, v208
	v_mov_b32_e32 v19, v209
	v_lshlrev_b32_e32 v20, 16, v16
	v_and_b32_e32 v21, 0xffff0000, v16
	v_lshlrev_b32_e32 v24, 16, v19
	v_and_b32_e32 v16, 0xffff0000, v19
	v_mul_f32_e32 v19, 0xbfb8aa3b, v20
	v_exp_f32_e32 v19, v19
	v_lshlrev_b32_e32 v22, 16, v17
	v_and_b32_e32 v17, 0xffff0000, v17
	v_lshlrev_b32_e32 v23, 16, v18
	v_add_f32_e32 v19, 1.0, v19
	v_div_scale_f32 v25, s[0:1], v19, v19, v20
	v_rcp_f32_e32 v26, v25
	v_and_b32_e32 v18, 0xffff0000, v18
	v_fma_f32 v27, -v25, v26, 1.0
	v_fmac_f32_e32 v26, v27, v26
	v_div_scale_f32 v27, vcc, v20, v19, v20
	v_mul_f32_e32 v28, v27, v26
	v_fma_f32 v29, -v25, v28, v27
	v_fmac_f32_e32 v28, v29, v26
	v_fma_f32 v25, -v25, v28, v27
	v_div_fmas_f32 v25, v25, v26, v28
	v_div_fixup_f32 v19, v25, v19, v20
	v_mul_f32_e32 v12, v12, v19
	v_mul_f32_e32 v19, 0xbfb8aa3b, v21
	v_exp_f32_e32 v19, v19
	s_nop 0
	v_add_f32_e32 v19, 1.0, v19
	v_div_scale_f32 v20, s[0:1], v19, v19, v21
	v_rcp_f32_e32 v25, v20
	s_nop 0
	v_fma_f32 v26, -v20, v25, 1.0
	v_fmac_f32_e32 v25, v26, v25
	v_div_scale_f32 v26, vcc, v21, v19, v21
	v_mul_f32_e32 v27, v26, v25
	v_fma_f32 v28, -v20, v27, v26
	v_fmac_f32_e32 v27, v28, v25
	v_fma_f32 v20, -v20, v27, v26
	v_div_fmas_f32 v20, v20, v25, v27
	v_div_fixup_f32 v19, v20, v19, v21
	v_mul_f32_e32 v13, v13, v19
	v_mul_f32_e32 v19, 0xbfb8aa3b, v22
	v_exp_f32_e32 v19, v19
	s_nop 0
	v_add_f32_e32 v19, 1.0, v19
	v_div_scale_f32 v20, s[0:1], v19, v19, v22
	v_rcp_f32_e32 v21, v20
	s_nop 0
	v_fma_f32 v25, -v20, v21, 1.0
	v_fmac_f32_e32 v21, v25, v21
	v_div_scale_f32 v25, vcc, v22, v19, v22
	v_mul_f32_e32 v26, v25, v21
	v_fma_f32 v27, -v20, v26, v25
	v_fmac_f32_e32 v26, v27, v21
	v_fma_f32 v20, -v20, v26, v25
	v_div_fmas_f32 v20, v20, v21, v26
	v_div_fixup_f32 v19, v20, v19, v22
	v_mul_f32_e32 v14, v14, v19
	v_mul_f32_e32 v19, 0xbfb8aa3b, v17
	v_exp_f32_e32 v19, v19
	s_nop 0
	v_add_f32_e32 v19, 1.0, v19
	v_div_scale_f32 v20, s[0:1], v19, v19, v17
	v_rcp_f32_e32 v21, v20
	s_nop 0
	v_fma_f32 v22, -v20, v21, 1.0
	v_fmac_f32_e32 v21, v22, v21
	v_div_scale_f32 v22, vcc, v17, v19, v17
	v_mul_f32_e32 v25, v22, v21
	v_fma_f32 v26, -v20, v25, v22
	v_fmac_f32_e32 v25, v26, v21
	v_fma_f32 v20, -v20, v25, v22
	v_div_fmas_f32 v20, v20, v21, v25
	v_div_fixup_f32 v17, v20, v19, v17
	v_mul_f32_e32 v15, v15, v17
	v_mul_f32_e32 v17, 0xbfb8aa3b, v23
	v_exp_f32_e32 v17, v17
	s_nop 0
	v_add_f32_e32 v17, 1.0, v17
	v_div_scale_f32 v19, s[0:1], v17, v17, v23
	v_rcp_f32_e32 v20, v19
	s_nop 0
	v_fma_f32 v21, -v19, v20, 1.0
	v_fmac_f32_e32 v20, v21, v20
	v_div_scale_f32 v21, vcc, v23, v17, v23
	v_mul_f32_e32 v22, v21, v20
	v_fma_f32 v25, -v19, v22, v21
	v_fmac_f32_e32 v22, v25, v20
	v_fma_f32 v19, -v19, v22, v21
	v_div_fmas_f32 v19, v19, v20, v22
	v_div_fixup_f32 v17, v19, v17, v23
	v_mul_f32_e32 v17, v8, v17
	v_mul_f32_e32 v8, v9, v65
	v_mul_f32_e32 v9, 0xbfb8aa3b, v18
	v_exp_f32_e32 v9, v9
	s_nop 0
	v_add_f32_e32 v9, 1.0, v9
	v_div_scale_f32 v19, s[0:1], v9, v9, v18
	v_rcp_f32_e32 v20, v19
	s_nop 0
	v_fma_f32 v21, -v19, v20, 1.0
	v_fmac_f32_e32 v20, v21, v20
	v_div_scale_f32 v21, vcc, v18, v9, v18
	v_mul_f32_e32 v22, v21, v20
	v_fma_f32 v23, -v19, v22, v21
	v_fmac_f32_e32 v22, v23, v20
	v_fma_f32 v19, -v19, v22, v21
	v_div_fmas_f32 v19, v19, v20, v22
	v_div_fixup_f32 v9, v19, v9, v18
	v_mul_f32_e32 v18, v8, v9
	v_mul_f32_e32 v9, 0xbfb8aa3b, v24
	v_exp_f32_e32 v9, v9
	v_mul_f32_e32 v8, v10, v66
	v_add_f32_e32 v9, 1.0, v9
	v_div_scale_f32 v10, s[0:1], v9, v9, v24
	v_rcp_f32_e32 v19, v10
	s_nop 0
	v_fma_f32 v20, -v10, v19, 1.0
	v_fmac_f32_e32 v19, v20, v19
	v_div_scale_f32 v20, vcc, v24, v9, v24
	v_mul_f32_e32 v21, v20, v19
	v_fma_f32 v22, -v10, v21, v20
	v_fmac_f32_e32 v21, v22, v19
	v_fma_f32 v10, -v10, v21, v20
	v_div_fmas_f32 v10, v10, v19, v21
	v_div_fixup_f32 v9, v10, v9, v24
	v_mul_f32_e32 v19, v8, v9
	v_mul_f32_e32 v9, 0xbfb8aa3b, v16
	v_exp_f32_e32 v9, v9
	v_mul_f32_e32 v8, v11, v67
	v_add_f32_e32 v9, 1.0, v9
	v_div_scale_f32 v10, s[0:1], v9, v9, v16
	v_rcp_f32_e32 v11, v10
	s_nop 0
	v_fma_f32 v20, -v10, v11, 1.0
	v_fmac_f32_e32 v11, v20, v11
	v_div_scale_f32 v20, vcc, v16, v9, v16
	v_mul_f32_e32 v21, v20, v11
	v_fma_f32 v22, -v10, v21, v20
	v_fmac_f32_e32 v21, v22, v11
	v_fma_f32 v10, -v10, v21, v20
	v_div_fmas_f32 v10, v10, v11, v21
	v_div_fixup_f32 v9, v10, v9, v16
	v_mul_f32_e32 v11, v8, v9
	v_cvt_pk_bf16_f32 v8, v12, v13
	v_cvt_pk_bf16_f32 v9, v14, v15
	v_cvt_pk_bf16_f32 v10, v17, v18
	v_cvt_pk_bf16_f32 v11, v19, v11
	global_store_dwordx4 v[72:73], v[8:11], off offset:2304
	s_waitcnt vmcnt(2)
; __device__ __forceinline__ unsigned cvt_pk_bf16(float lo, float hi) { unsigned r; asm volatile("v_cvt_pk_bf16_f32 %0, %1, %2" : "=v"(r) : "v"(lo), "v"(hi)); return r; }
; __device__ __forceinline__ float sigmoidf_(float v) { return 1.f / (1.f + __expf(-v)); }
; __device__ __forceinline__ float siluf_(float v) { return v / (1.f + __expf(-v)); }
; #define PG8_WAIT_V(n) asm volatile("s_waitcnt vmcnt(" #n ")" ::: "memory")
; #define PG8_BAR __builtin_amdgcn_s_barrier()
;     __device__ __forceinline__ void operator()(const f32x4 (&acc)[2][2][4][2], const Unit& u, int wr, int wc, int fr, int fq) const {
;     ...
;             for (int ai = 0; ai < 2; ++ai) {
; #pragma unroll
;                 for (int m = 0; m < 4; ++m) {
;                     const size_t row = (size_t)(row0 + ai * HALF + m * 16);
;                     const f32x4 v0 = acc[ai][bj][m][0], v1 = acc[ai][bj][m][1];
;                     float a[8] = {v0[0], v0[1], v0[2], v0[3], v1[0], v1[1], v1[2], v1[3]}, g[8], o[8];
;                     unpack8(*(const u32x4*)(R + row * RLD + (MODE == 0 ? 2560 : 1536) + col0), g);
;                     if (MODE == 0) { float y[8]; unpack8(*(const u32x4*)(YG + row * 512 + col0), y);
; #pragma unroll
;                         for (int e = 0; e < 8; ++e) o[e] = y[e] * sigmoidf_(a[e] + bb[e]) * siluf_(g[e]); }
;                     else {
; #pragma unroll
;                         for (int e = 0; e < 8; ++e) o[e] = a[e] * bb[e] * siluf_(g[e]); }
;                     u32x4 w; w.x = cvt_pk_bf16(o[0], o[1]); w.y = cvt_pk_bf16(o[2], o[3]); w.z = cvt_pk_bf16(o[4], o[5]); w.w = cvt_pk_bf16(o[6], o[7]);
;                     *(u32x4*)(Y + row * DM + (MODE == 0 ? 1536 : 1024) + col0) = w;
;                 }
; template <class Epi, class Sched>
; __device__ __forceinline__ void gemm_phase(LAS unsigned char* lds, const Gemm g, const Sched& S, const Epi& E, const int tid) {
;     ...
;     PG8_WAIT_V(0);
;     PG8_BAR;
	s_nop 1
	v_mov_b32_e32 v8, v168
	v_mov_b32_e32 v9, v169
	v_mov_b32_e32 v10, v170
	v_mov_b32_e32 v11, v171
	v_lshlrev_b32_e32 v12, 16, v8
	v_and_b32_e32 v13, 0xffff0000, v8
	v_lshlrev_b32_e32 v16, 16, v11
	v_and_b32_e32 v8, 0xffff0000, v11
	v_mul_f32_e32 v11, 0xbfb8aa3b, v12
	v_exp_f32_e32 v11, v11
	v_lshlrev_b32_e32 v14, 16, v9
	v_and_b32_e32 v9, 0xffff0000, v9
	v_lshlrev_b32_e32 v15, 16, v10
	v_add_f32_e32 v11, 1.0, v11
	v_div_scale_f32 v17, s[0:1], v11, v11, v12
	v_rcp_f32_e32 v18, v17
	v_and_b32_e32 v10, 0xffff0000, v10
	v_fma_f32 v19, -v17, v18, 1.0
	v_fmac_f32_e32 v18, v19, v18
	v_div_scale_f32 v19, vcc, v12, v11, v12
	v_mul_f32_e32 v20, v19, v18
	v_fma_f32 v21, -v17, v20, v19
	v_fmac_f32_e32 v20, v21, v18
	v_fma_f32 v17, -v17, v20, v19
	v_div_fmas_f32 v17, v17, v18, v20
	v_div_fixup_f32 v11, v17, v11, v12
	v_mul_f32_e32 v4, v4, v11
	v_mul_f32_e32 v11, 0xbfb8aa3b, v13
	v_exp_f32_e32 v11, v11
	s_nop 0
	v_add_f32_e32 v11, 1.0, v11
	v_div_scale_f32 v12, s[0:1], v11, v11, v13
	v_rcp_f32_e32 v17, v12
	s_nop 0
	v_fma_f32 v18, -v12, v17, 1.0
	v_fmac_f32_e32 v17, v18, v17
	v_div_scale_f32 v18, vcc, v13, v11, v13
	v_mul_f32_e32 v19, v18, v17
	v_fma_f32 v20, -v12, v19, v18
	v_fmac_f32_e32 v19, v20, v17
	v_fma_f32 v12, -v12, v19, v18
	v_div_fmas_f32 v12, v12, v17, v19
	v_div_fixup_f32 v11, v12, v11, v13
	v_mul_f32_e32 v5, v5, v11
	v_mul_f32_e32 v11, 0xbfb8aa3b, v14
	v_exp_f32_e32 v11, v11
	s_nop 0
	v_add_f32_e32 v11, 1.0, v11
	v_div_scale_f32 v12, s[0:1], v11, v11, v14
	v_rcp_f32_e32 v13, v12
	s_nop 0
	v_fma_f32 v17, -v12, v13, 1.0
	v_fmac_f32_e32 v13, v17, v13
	v_div_scale_f32 v17, vcc, v14, v11, v14
	v_mul_f32_e32 v18, v17, v13
	v_fma_f32 v19, -v12, v18, v17
	v_fmac_f32_e32 v18, v19, v13
	v_fma_f32 v12, -v12, v18, v17
	v_div_fmas_f32 v12, v12, v13, v18
	v_div_fixup_f32 v11, v12, v11, v14
	v_mul_f32_e32 v6, v6, v11
	v_mul_f32_e32 v11, 0xbfb8aa3b, v9
	v_exp_f32_e32 v11, v11
	s_nop 0
	v_add_f32_e32 v11, 1.0, v11
	v_div_scale_f32 v12, s[0:1], v11, v11, v9
	v_rcp_f32_e32 v13, v12
	s_nop 0
	v_fma_f32 v14, -v12, v13, 1.0
	v_fmac_f32_e32 v13, v14, v13
	v_div_scale_f32 v14, vcc, v9, v11, v9
	v_mul_f32_e32 v17, v14, v13
	v_fma_f32 v18, -v12, v17, v14
	v_fmac_f32_e32 v17, v18, v13
	v_fma_f32 v12, -v12, v17, v14
	v_div_fmas_f32 v12, v12, v13, v17
	v_div_fixup_f32 v9, v12, v11, v9
	v_mul_f32_e32 v7, v7, v9
	v_mul_f32_e32 v9, 0xbfb8aa3b, v15
	v_exp_f32_e32 v9, v9
	s_nop 0
	v_add_f32_e32 v9, 1.0, v9
	v_div_scale_f32 v11, s[0:1], v9, v9, v15
	v_rcp_f32_e32 v12, v11
	s_nop 0
	v_fma_f32 v13, -v11, v12, 1.0
	v_fmac_f32_e32 v12, v13, v12
	v_div_scale_f32 v13, vcc, v15, v9, v15
	v_mul_f32_e32 v14, v13, v12
	v_fma_f32 v17, -v11, v14, v13
	v_fmac_f32_e32 v14, v17, v12
	v_fma_f32 v11, -v11, v14, v13
	v_div_fmas_f32 v11, v11, v12, v14
	v_div_fixup_f32 v9, v11, v9, v15
	v_mul_f32_e32 v9, v0, v9
	v_mul_f32_e32 v0, v1, v65
	v_mul_f32_e32 v1, 0xbfb8aa3b, v10
	v_exp_f32_e32 v1, v1
	s_nop 0
	v_add_f32_e32 v1, 1.0, v1
	v_div_scale_f32 v11, s[0:1], v1, v1, v10
	v_rcp_f32_e32 v12, v11
	s_nop 0
	v_fma_f32 v13, -v11, v12, 1.0
	v_fmac_f32_e32 v12, v13, v12
	v_div_scale_f32 v13, vcc, v10, v1, v10
	v_mul_f32_e32 v14, v13, v12
	v_fma_f32 v15, -v11, v14, v13
	v_fmac_f32_e32 v14, v15, v12
	v_fma_f32 v11, -v11, v14, v13
	v_div_fmas_f32 v11, v11, v12, v14
	v_div_fixup_f32 v1, v11, v1, v10
	v_mul_f32_e32 v10, v0, v1
	v_mul_f32_e32 v1, 0xbfb8aa3b, v16
	v_exp_f32_e32 v1, v1
	v_mul_f32_e32 v0, v2, v66
	v_add_f32_e32 v1, 1.0, v1
	v_div_scale_f32 v2, s[0:1], v1, v1, v16
	v_rcp_f32_e32 v11, v2
	s_nop 0
	v_fma_f32 v12, -v2, v11, 1.0
	v_fmac_f32_e32 v11, v12, v11
	v_div_scale_f32 v12, vcc, v16, v1, v16
	v_mul_f32_e32 v13, v12, v11
	v_fma_f32 v14, -v2, v13, v12
	v_fmac_f32_e32 v13, v14, v11
	v_fma_f32 v2, -v2, v13, v12
	v_div_fmas_f32 v2, v2, v11, v13
	v_div_fixup_f32 v1, v2, v1, v16
	v_mul_f32_e32 v11, v0, v1
	v_mul_f32_e32 v1, 0xbfb8aa3b, v8
	v_exp_f32_e32 v1, v1
	v_mul_f32_e32 v0, v3, v67
	v_add_f32_e32 v1, 1.0, v1
	v_div_scale_f32 v2, s[0:1], v1, v1, v8
	v_rcp_f32_e32 v3, v2
	v_readlane_b32 s0, v255, 23
	v_readlane_b32 s1, v255, 24
	v_fma_f32 v12, -v2, v3, 1.0
	v_fmac_f32_e32 v3, v12, v3
	v_div_scale_f32 v12, vcc, v8, v1, v8
	v_mul_f32_e32 v13, v12, v3
	v_fma_f32 v14, -v2, v13, v12
	v_fmac_f32_e32 v13, v14, v3
	v_fma_f32 v2, -v2, v13, v12
	v_div_fmas_f32 v2, v2, v3, v13
	v_div_fixup_f32 v1, v2, v1, v8
	v_mul_f32_e32 v3, v0, v1
	v_cvt_pk_bf16_f32 v0, v4, v5
	v_cvt_pk_bf16_f32 v1, v6, v7
	v_cvt_pk_bf16_f32 v2, v9, v10
	v_cvt_pk_bf16_f32 v3, v11, v3
	global_store_dwordx4 v[76:77], v[0:3], off offset:2304
	s_waitcnt vmcnt(0)
	s_barrier
	s_load_dwordx2 s[72:73], s[0:1], 0xb0
	s_mov_b64 s[0:1], 0
